# v62 + M0 hazard-pad folding: 117 LDS-DMA pieces write M0 before the address VALU so that the VALU is the wait state (s_nop 0 removed) in all GEMM load segments
# baseline (speedup 1.0000x reference)
; #define GPROBE_BEGIN(id) do { if (((PROBE_GEMM_SEL >> (id)) & 1) && blockIdx.x == 0 && tid_in < 64 && g.N == 20480) { volatile PG8_LAS unsigned long long* PW_ = (volatile PG8_LAS unsigned long long*)(lds + 163840 - 512 + 64); PW_[0] = __builtin_amdgcn_s_memrealtime(); } } while (0)
; #define GPROBE_END(id) do { if (((PROBE_GEMM_SEL >> (id)) & 1) && blockIdx.x == 0 && tid_in < 64 && g.N == 20480) { volatile PG8_LAS unsigned long long* PW_ = (volatile PG8_LAS unsigned long long*)(lds + 163840 - 512 + 64); PW_[1] += __builtin_amdgcn_s_memrealtime() - PW_[0]; } } while (0)
; #define PG8_STAGE(bufoff, gbase, voff) do { _Pragma("unroll") for (int _i = 0; _i < 2; ++_i) \
;         __builtin_amdgcn_global_load_lds((const unsigned*)((const char*)(gbase) + (voff)[_i]), (PG8_LAS unsigned*)(lds + (bufoff) + ldsw + _i * 8192), 16, 0, 0); } while (0)
; #define PG8_BAR __builtin_amdgcn_s_barrier()
; template <class Epi, class Sched, bool ALIGN_EPI = false, bool SP2 = false, bool KHOOK = false>
; __device__ __forceinline__ void gemm_phase(PG8_LAS unsigned char* lds, const Gemm g, const Sched& S, const Epi& E, const int tid_in) {
;     ...
;         const char* nA = has_next ? (const char*)g.A + (size_t)nxt.pm * tstep + (size_t)nxt.pn * ksl : cA; const char* nB = has_next ? (const char*)g.Bt + (size_t)nxt.pn * bts + (size_t)nxt.pn * ksl + (gdv ? (size_t)(nxt.pm / gdv) * gst : 0) : cB;
;         GPROBE_END(2); GPROBE_BEGIN(1);
;         for (int t = 0; t < nt; t += 2) {
;             const bool last = (t == nt - 2);
;             const char* a1 = cA + (size_t)(t + 1) * kstep;
;             const char* a2 = last ? nA : cA + (size_t)(t + 2) * kstep; const char* b2 = last ? nB : cB + (size_t)(t + 2) * kstep;
;             const char* a3 = a2 + kstep; const char* b3 = b2 + kstep;
;             if (last && has_next) S.a_ready(nxt);
;             if constexpr (SP2) {
;             PG8_LDB(B0, 0, 0); PG8_LDB(B1, 0, 1); PG8_SCHED; PG8_LDA(At, 0, 0); PG8_STAGE(PG8_SA(1, 1), a1 + hstep, voffA);
;             PG8_WAIT_V(8); PG8_WAIT_L(0); PG8_BAR; PG8_MMA(0, 0, At, B0); PG8_MMA(0, 1, At, B1); PG8_BAR; PG8_SCHED;
;             PG8_LDA(At, 0, 1); PG8_STAGE(PG8_SB(0, 0), b2, voffB); PG8_STAGE(PG8_SB(0, 1), b2 + hstep, voffB); PG8_STAGE(PG8_SA(0, 0), a2, voffA);
;             PG8_WAIT_V(8); PG8_WAIT_L(0); PG8_BAR; PG8_MMA(1, 0, At, B0); PG8_MMA(1, 1, At, B1); PG8_BAR; PG8_SCHED;
.LBB0_262:
	s_ashr_i32 s17, s16, 31
	s_lshl_b64 s[18:19], s[16:17], 20
	s_add_u32 s26, s78, s18
	s_addc_u32 s27, s79, s19
	s_and_b64 s[18:19], s[22:23], exec
	s_cselect_b32 s11, s27, s49
	s_cselect_b32 s17, s26, s48
	s_ashr_i32 s15, s14, 31
	s_lshl_b64 s[18:19], s[14:15], 20
	v_readlane_b32 s5, v255, 25
	s_add_u32 s30, s5, s18
	v_readlane_b32 s5, v255, 26
	s_addc_u32 s31, s5, s19
	s_and_b64 s[18:19], s[22:23], exec
	s_cselect_b32 s15, s31, s53
	s_cselect_b32 s18, s30, s52
	s_add_u32 s48, s48, 0x80080
	s_addc_u32 s49, s49, 0
	s_add_u32 s19, s52, 0x100
	s_addc_u32 s42, s53, 0
	s_mov_b32 s44, -2
	s_cmp_lg_u32 s60, 0
	s_cbranch_scc1 .Lg1_peel_e1
	s_add_u32 s45, s48, 0xfff80080
	s_addc_u32 s46, s49, -1
	s_add_i32 s47, 0, 0x10000
	s_cmp_eq_u32 s44, 28
	s_cselect_b32 s57, s11, s46
	s_cselect_b32 s56, s17, s45
	s_cselect_b32 s53, s15, s42
	s_cselect_b32 s52, s18, s19
	s_add_i32 s45, 0, 0x14000
	v_add_u32_e32 v156, s47, v141
	v_add_u32_e32 v172, s45, v141
	ds_read_b128 v[144:147], v156
	ds_read_b128 v[148:151], v156 offset:1024
	ds_read_b128 v[152:155], v156 offset:2048
	ds_read_b128 v[156:159], v156 offset:3072
	ds_read_b128 v[160:163], v172
	ds_read_b128 v[164:167], v172 offset:1024
	ds_read_b128 v[168:171], v172 offset:2048
	ds_read_b128 v[172:175], v172 offset:3072
	v_lshl_add_u64 v[192:193], s[48:49], 0, v[136:137]
	s_add_i32 m0, s13, 0xc000
	ds_read_b128 v[176:179], v143
	ds_read_b128 v[180:183], v143 offset:1024
	ds_read_b128 v[184:187], v143 offset:2048
	ds_read_b128 v[188:191], v143 offset:3072
	ds_read_b128 v[198:201], v143 offset:4096
	ds_read_b128 v[202:205], v143 offset:5120
	ds_read_b128 v[206:209], v143 offset:6144
	ds_read_b128 v[210:213], v143 offset:7168
	global_load_lds_dwordx4 v[192:193], off
	s_add_i32 m0, s13, 0xe000
	v_lshl_add_u64 v[192:193], s[48:49], 0, v[138:139]
	global_load_lds_dwordx4 v[192:193], off
	s_waitcnt vmcnt(18)
	s_waitcnt lgkmcnt(0)
	s_barrier
	s_setprio 1
	s_waitcnt lgkmcnt(0)
	v_mfma_f32_16x16x32_bf16 v[126:129], v[144:147], v[176:179], 0
	v_mfma_f32_16x16x32_bf16 v[122:125], v[152:155], v[176:179], 0
	v_mfma_f32_16x16x32_bf16 v[118:121], v[144:147], v[184:187], 0
	v_mfma_f32_16x16x32_bf16 v[114:117], v[152:155], v[184:187], 0
	v_mfma_f32_16x16x32_bf16 v[102:105], v[144:147], v[198:201], 0
	v_mfma_f32_16x16x32_bf16 v[98:101], v[152:155], v[198:201], 0
	v_mfma_f32_16x16x32_bf16 v[86:89], v[144:147], v[206:209], 0
	v_mfma_f32_16x16x32_bf16 v[82:85], v[152:155], v[206:209], 0
	v_mfma_f32_16x16x32_bf16 v[126:129], v[148:151], v[180:183], v[126:129]
	v_mfma_f32_16x16x32_bf16 v[122:125], v[156:159], v[180:183], v[122:125]
	v_mfma_f32_16x16x32_bf16 v[118:121], v[148:151], v[188:191], v[118:121]
	v_mfma_f32_16x16x32_bf16 v[114:117], v[156:159], v[188:191], v[114:117]
	v_mfma_f32_16x16x32_bf16 v[102:105], v[148:151], v[202:205], v[102:105]
	v_mfma_f32_16x16x32_bf16 v[98:101], v[156:159], v[202:205], v[98:101]
	v_mfma_f32_16x16x32_bf16 v[86:89], v[148:151], v[210:213], v[86:89]
	v_mfma_f32_16x16x32_bf16 v[82:85], v[156:159], v[210:213], v[82:85]
	s_setprio 0
	s_setprio 1
	v_mfma_f32_16x16x32_bf16 v[110:113], v[160:163], v[176:179], 0
	v_mfma_f32_16x16x32_bf16 v[106:109], v[168:171], v[176:179], 0
	v_mfma_f32_16x16x32_bf16 v[94:97], v[160:163], v[184:187], 0
	v_mfma_f32_16x16x32_bf16 v[90:93], v[168:171], v[184:187], 0
	v_mfma_f32_16x16x32_bf16 v[78:81], v[160:163], v[198:201], 0
	v_mfma_f32_16x16x32_bf16 v[74:77], v[168:171], v[198:201], 0
	v_mfma_f32_16x16x32_bf16 v[70:73], v[160:163], v[206:209], 0
	v_mfma_f32_16x16x32_bf16 v[66:69], v[168:171], v[206:209], 0
	v_mfma_f32_16x16x32_bf16 v[110:113], v[164:167], v[180:183], v[110:113]
	v_mfma_f32_16x16x32_bf16 v[106:109], v[172:175], v[180:183], v[106:109]
	v_mfma_f32_16x16x32_bf16 v[94:97], v[164:167], v[188:191], v[94:97]
	v_mfma_f32_16x16x32_bf16 v[90:93], v[172:175], v[188:191], v[90:93]
	v_mfma_f32_16x16x32_bf16 v[78:81], v[164:167], v[202:205], v[78:81]
	v_mfma_f32_16x16x32_bf16 v[74:77], v[172:175], v[202:205], v[74:77]
	v_mfma_f32_16x16x32_bf16 v[70:73], v[164:167], v[210:213], v[70:73]
	v_mfma_f32_16x16x32_bf16 v[66:69], v[172:175], v[210:213], v[66:69]
	s_setprio 0
	s_barrier
	s_add_i32 s46, s47, s37
	v_lshl_add_u64 v[192:193], s[52:53], 0, v[32:33]
	s_mov_b32 m0, s46
	ds_read_b128 v[176:179], v143 offset:16384
	ds_read_b128 v[180:183], v143 offset:17408
	ds_read_b128 v[184:187], v143 offset:18432
	ds_read_b128 v[188:191], v143 offset:19456
	ds_read_b128 v[198:201], v143 offset:20480
	ds_read_b128 v[202:205], v143 offset:21504
	ds_read_b128 v[206:209], v143 offset:22528
	ds_read_b128 v[210:213], v143 offset:23552
	global_load_lds_dwordx4 v[192:193], off
	s_add_i32 m0, s46, 0x2000
	s_add_u32 s46, s52, 0x80000
	v_lshl_add_u64 v[214:215], s[52:53], 0, v[134:135]
	s_addc_u32 s47, s53, 0
	s_add_i32 s45, s45, s37
	global_load_lds_dwordx4 v[214:215], off
	v_lshl_add_u64 v[216:217], s[46:47], 0, v[32:33]
	s_mov_b32 m0, s45
	v_lshl_add_u64 v[218:219], s[56:57], 0, v[132:133]
	global_load_lds_dwordx4 v[216:217], off
	s_add_i32 m0, s45, 0x2000
	v_lshl_add_u64 v[216:217], s[46:47], 0, v[134:135]
	global_load_lds_dwordx4 v[216:217], off
	s_mov_b32 m0, s13
	v_lshl_add_u64 v[216:217], s[56:57], 0, v[130:131]
	global_load_lds_dwordx4 v[216:217], off
	s_mov_b32 m0, s24
	s_nop 0
	global_load_lds_dwordx4 v[218:219], off
	s_waitcnt vmcnt(24)
	s_waitcnt lgkmcnt(0)
	s_barrier
; #define PG8_STAGE(bufoff, gbase, voff) do { _Pragma("unroll") for (int _i = 0; _i < 2; ++_i) \
;         __builtin_amdgcn_global_load_lds((const unsigned*)((const char*)(gbase) + (voff)[_i]), (PG8_LAS unsigned*)(lds + (bufoff) + ldsw + _i * 8192), 16, 0, 0); } while (0)
; #define PG8_LDA(dst, b, h) do { _Pragma("unroll") for (int m = 0; m < 4; ++m) _Pragma("unroll") for (int k = 0; k < 2; ++k) dst[m][k] = *(const PG8_LAS bf16x8*)(lds + PG8_SA(b, h) + aoff + m * 2048 + k * 1024); } while (0)
; #define PG8_LDB(dst, b, h) do { _Pragma("unroll") for (int n = 0; n < 2; ++n) _Pragma("unroll") for (int k = 0; k < 2; ++k) dst[n][k] = *(const PG8_LAS bf16x8*)(lds + PG8_SB(b, h) + boff + n * 2048 + k * 1024); } while (0)
; #define PG8_MMA(ai, bj, At, Bt) do { __builtin_amdgcn_s_setprio(1); _Pragma("unroll") for (int m = 0; m < 4; ++m) _Pragma("unroll") for (int n = 0; n < 2; ++n) _Pragma("unroll") for (int k = 0; k < 2; ++k) \
;         acc[ai][bj][m][n] = __builtin_amdgcn_mfma_f32_16x16x32_bf16(Bt[n][k], At[m][k], acc[ai][bj][m][n], 0, 0, 0); __builtin_amdgcn_s_setprio(0); } while (0)
; #define PG8_WAIT_V(n) asm volatile("s_waitcnt vmcnt(" #n ")" ::: "memory")
; #define PG8_WAIT_L(n) asm volatile("s_waitcnt lgkmcnt(" #n ")" ::: "memory")
; #define PG8_BAR __builtin_amdgcn_s_barrier()
; #define PG8_SCHED __builtin_amdgcn_sched_barrier(0)
; template <class Epi, class Sched, bool ALIGN_EPI = false, bool SP2 = false, bool KHOOK = false>
; __device__ __forceinline__ void gemm_phase(PG8_LAS unsigned char* lds, const Gemm g, const Sched& S, const Epi& E, const int tid_in) {
;     ...
;             PG8_WAIT_V(8); PG8_WAIT_L(0); PG8_BAR; PG8_MMA(1, 0, At, B0); PG8_MMA(1, 1, At, B1); PG8_BAR; PG8_SCHED;
;             PG8_LDB(B0, 1, 0); PG8_LDB(B1, 1, 1); PG8_SCHED; PG8_LDA(At, 1, 0); PG8_STAGE(PG8_SA(0, 1), a2 + hstep, voffA);
;             PG8_WAIT_V(8); PG8_WAIT_L(0); PG8_BAR; PG8_MMA(0, 0, At, B0); PG8_MMA(0, 1, At, B1); PG8_BAR; PG8_SCHED;
	s_setprio 1
	s_waitcnt lgkmcnt(0)
	v_mfma_f32_16x16x32_bf16 v[62:65], v[144:147], v[176:179], 0
	v_mfma_f32_16x16x32_bf16 v[58:61], v[152:155], v[176:179], 0
	v_mfma_f32_16x16x32_bf16 v[54:57], v[144:147], v[184:187], 0
	v_mfma_f32_16x16x32_bf16 v[50:53], v[152:155], v[184:187], 0
	v_mfma_f32_16x16x32_bf16 v[38:41], v[144:147], v[198:201], 0
	v_mfma_f32_16x16x32_bf16 v[34:37], v[152:155], v[198:201], 0
	v_mfma_f32_16x16x32_bf16 v[20:23], v[144:147], v[206:209], 0
	v_mfma_f32_16x16x32_bf16 v[16:19], v[152:155], v[206:209], 0
	v_mfma_f32_16x16x32_bf16 v[62:65], v[148:151], v[180:183], v[62:65]
	v_mfma_f32_16x16x32_bf16 v[58:61], v[156:159], v[180:183], v[58:61]
	v_mfma_f32_16x16x32_bf16 v[54:57], v[148:151], v[188:191], v[54:57]
	v_mfma_f32_16x16x32_bf16 v[50:53], v[156:159], v[188:191], v[50:53]
	v_mfma_f32_16x16x32_bf16 v[38:41], v[148:151], v[202:205], v[38:41]
	v_mfma_f32_16x16x32_bf16 v[34:37], v[156:159], v[202:205], v[34:37]
	v_mfma_f32_16x16x32_bf16 v[20:23], v[148:151], v[210:213], v[20:23]
	v_mfma_f32_16x16x32_bf16 v[16:19], v[156:159], v[210:213], v[16:19]
	s_setprio 0
	s_setprio 1
	v_mfma_f32_16x16x32_bf16 v[46:49], v[160:163], v[176:179], 0
	v_mfma_f32_16x16x32_bf16 v[42:45], v[168:171], v[176:179], 0
	v_mfma_f32_16x16x32_bf16 v[28:31], v[160:163], v[184:187], 0
	v_mfma_f32_16x16x32_bf16 v[24:27], v[168:171], v[184:187], 0
	v_mfma_f32_16x16x32_bf16 v[12:15], v[160:163], v[198:201], 0
	v_mfma_f32_16x16x32_bf16 v[8:11], v[168:171], v[198:201], 0
	v_mfma_f32_16x16x32_bf16 v[4:7], v[160:163], v[206:209], 0
	v_mfma_f32_16x16x32_bf16 v[0:3], v[168:171], v[206:209], 0
	v_mfma_f32_16x16x32_bf16 v[46:49], v[164:167], v[180:183], v[46:49]
	v_mfma_f32_16x16x32_bf16 v[42:45], v[172:175], v[180:183], v[42:45]
	v_mfma_f32_16x16x32_bf16 v[28:31], v[164:167], v[188:191], v[28:31]
	v_mfma_f32_16x16x32_bf16 v[24:27], v[172:175], v[188:191], v[24:27]
	v_mfma_f32_16x16x32_bf16 v[12:15], v[164:167], v[202:205], v[12:15]
	v_mfma_f32_16x16x32_bf16 v[8:11], v[172:175], v[202:205], v[8:11]
	v_mfma_f32_16x16x32_bf16 v[4:7], v[164:167], v[210:213], v[4:7]
	v_mfma_f32_16x16x32_bf16 v[0:3], v[172:175], v[210:213], v[0:3]
	s_setprio 0
	s_barrier
	s_add_i32 s45, 0, 0x18000
	s_add_i32 s50, 0, 0x1c000
	v_add_u32_e32 v156, s45, v141
	v_add_u32_e32 v172, s50, v141
	ds_read_b128 v[144:147], v156
	ds_read_b128 v[148:151], v156 offset:1024
	ds_read_b128 v[152:155], v156 offset:2048
	ds_read_b128 v[156:159], v156 offset:3072
	ds_read_b128 v[160:163], v172
	ds_read_b128 v[164:167], v172 offset:1024
	ds_read_b128 v[168:171], v172 offset:2048
	ds_read_b128 v[172:175], v172 offset:3072
	s_add_u32 s46, s56, 0x80000
	s_addc_u32 s47, s57, 0
	s_mov_b32 m0, s25
	v_lshl_add_u64 v[220:221], s[46:47], 0, v[130:131]
	ds_read_b128 v[176:179], v143 offset:32768
	ds_read_b128 v[180:183], v143 offset:33792
	ds_read_b128 v[184:187], v143 offset:34816
	ds_read_b128 v[188:191], v143 offset:35840
	ds_read_b128 v[198:201], v143 offset:36864
	ds_read_b128 v[202:205], v143 offset:37888
	ds_read_b128 v[206:209], v143 offset:38912
	ds_read_b128 v[210:213], v143 offset:39936
	global_load_lds_dwordx4 v[220:221], off
	s_mov_b32 m0, s38
	v_lshl_add_u64 v[220:221], s[46:47], 0, v[132:133]
	global_load_lds_dwordx4 v[220:221], off
	s_waitcnt vmcnt(8)
	s_waitcnt lgkmcnt(0)
	s_barrier
	s_setprio 1
	s_waitcnt lgkmcnt(0)
	v_mfma_f32_16x16x32_bf16 v[126:129], v[144:147], v[176:179], v[126:129]
	v_mfma_f32_16x16x32_bf16 v[122:125], v[152:155], v[176:179], v[122:125]
	v_mfma_f32_16x16x32_bf16 v[118:121], v[144:147], v[184:187], v[118:121]
	v_mfma_f32_16x16x32_bf16 v[114:117], v[152:155], v[184:187], v[114:117]
	v_mfma_f32_16x16x32_bf16 v[102:105], v[144:147], v[198:201], v[102:105]
	v_mfma_f32_16x16x32_bf16 v[98:101], v[152:155], v[198:201], v[98:101]
	v_mfma_f32_16x16x32_bf16 v[86:89], v[144:147], v[206:209], v[86:89]
	v_mfma_f32_16x16x32_bf16 v[82:85], v[152:155], v[206:209], v[82:85]
	v_mfma_f32_16x16x32_bf16 v[126:129], v[148:151], v[180:183], v[126:129]
	v_mfma_f32_16x16x32_bf16 v[122:125], v[156:159], v[180:183], v[122:125]
	v_mfma_f32_16x16x32_bf16 v[118:121], v[148:151], v[188:191], v[118:121]
	v_mfma_f32_16x16x32_bf16 v[114:117], v[156:159], v[188:191], v[114:117]
	v_mfma_f32_16x16x32_bf16 v[102:105], v[148:151], v[202:205], v[102:105]
	v_mfma_f32_16x16x32_bf16 v[98:101], v[156:159], v[202:205], v[98:101]
	v_mfma_f32_16x16x32_bf16 v[86:89], v[148:151], v[210:213], v[86:89]
	v_mfma_f32_16x16x32_bf16 v[82:85], v[156:159], v[210:213], v[82:85]
	s_setprio 0
	s_setprio 1
	v_mfma_f32_16x16x32_bf16 v[110:113], v[160:163], v[176:179], v[110:113]
	v_mfma_f32_16x16x32_bf16 v[106:109], v[168:171], v[176:179], v[106:109]
	v_mfma_f32_16x16x32_bf16 v[94:97], v[160:163], v[184:187], v[94:97]
	v_mfma_f32_16x16x32_bf16 v[90:93], v[168:171], v[184:187], v[90:93]
	v_mfma_f32_16x16x32_bf16 v[78:81], v[160:163], v[198:201], v[78:81]
	v_mfma_f32_16x16x32_bf16 v[74:77], v[168:171], v[198:201], v[74:77]
	v_mfma_f32_16x16x32_bf16 v[70:73], v[160:163], v[206:209], v[70:73]
	v_mfma_f32_16x16x32_bf16 v[66:69], v[168:171], v[206:209], v[66:69]
	v_mfma_f32_16x16x32_bf16 v[110:113], v[164:167], v[180:183], v[110:113]
	v_mfma_f32_16x16x32_bf16 v[106:109], v[172:175], v[180:183], v[106:109]
	v_mfma_f32_16x16x32_bf16 v[94:97], v[164:167], v[188:191], v[94:97]
	v_mfma_f32_16x16x32_bf16 v[90:93], v[172:175], v[188:191], v[90:93]
	v_mfma_f32_16x16x32_bf16 v[78:81], v[164:167], v[202:205], v[78:81]
	v_mfma_f32_16x16x32_bf16 v[74:77], v[172:175], v[202:205], v[74:77]
	v_mfma_f32_16x16x32_bf16 v[70:73], v[164:167], v[210:213], v[70:73]
	v_mfma_f32_16x16x32_bf16 v[66:69], v[172:175], v[210:213], v[66:69]
	s_setprio 0
	s_barrier
; __device__ __forceinline__ unsigned cvt_pk_bf16(float lo, float hi) { const f32x2_t v = {lo, hi}; const bf16x2_t c = __builtin_convertvector(v, bf16x2_t); return __builtin_bit_cast(unsigned, c); }
; #define PG8_STAGE(bufoff, gbase, voff) do { _Pragma("unroll") for (int _i = 0; _i < 2; ++_i) \
;         __builtin_amdgcn_global_load_lds((const unsigned*)((const char*)(gbase) + (voff)[_i]), (PG8_LAS unsigned*)(lds + (bufoff) + ldsw + _i * 8192), 16, 0, 0); } while (0)
; #define PG8_BAR __builtin_amdgcn_s_barrier()
;     __device__ __forceinline__ void operator()(const f32x4 (&acc)[2][2][4][2], const Unit& u, int wr, int wc, int fr, int fq) const {
;     ...
;             for (int m = 0; m < 4; ++m) { bf16_t* rowp = O + (size_t)(row0 + ai * HALF + m * 16) * ldc + col0;
; #pragma unroll
;                 for (int bj = 0; bj < 2; ++bj) { const f32x4 v0 = acc[ai][bj][m][0], v1 = acc[ai][bj][m][1];
;                     u32x4 w; w.x = cvt_pk_bf16(v0[0], v0[1]); w.y = cvt_pk_bf16(v0[2], v0[3]); w.z = cvt_pk_bf16(v1[0], v1[1]); w.w = cvt_pk_bf16(v1[2], v1[3]);
;                     *(u32x4*)(rowp + bj * HALF) = w; } }
; template <class Epi, class Sched, bool ALIGN_EPI = false, bool SP2 = false, bool KHOOK = false>
; __device__ __forceinline__ void gemm_phase(PG8_LAS unsigned char* lds, const Gemm g, const Sched& S, const Epi& E, const int tid_in) {
;     ...
;             PG8_LDB(B0, 0, 0); PG8_LDB(B1, 0, 1); PG8_SCHED; PG8_LDA(At, 0, 0); PG8_STAGE(PG8_SA(1, 1), a1 + hstep, voffA);
;             PG8_WAIT_V(8); PG8_WAIT_L(0); PG8_BAR; PG8_MMA(0, 0, At, B0); PG8_MMA(0, 1, At, B1); PG8_BAR; PG8_SCHED;
;             PG8_LDA(At, 0, 1); PG8_STAGE(PG8_SB(0, 0), b2, voffB); PG8_STAGE(PG8_SB(0, 1), b2 + hstep, voffB); PG8_STAGE(PG8_SA(0, 0), a2, voffA);
;             PG8_WAIT_V(8); PG8_WAIT_L(0); PG8_BAR; PG8_MMA(1, 0, At, B0); PG8_MMA(1, 1, At, B1); PG8_BAR; PG8_SCHED;
;             PG8_LDB(B0, 1, 0); PG8_LDB(B1, 1, 1); PG8_SCHED; PG8_LDA(At, 1, 0); PG8_STAGE(PG8_SA(0, 1), a2 + hstep, voffA);
;             PG8_WAIT_V(8); PG8_WAIT_L(0); PG8_BAR; PG8_MMA(0, 0, At, B0); PG8_MMA(0, 1, At, B1); PG8_BAR; PG8_SCHED;
;             PG8_LDA(At, 1, 1); PG8_STAGE(PG8_SB(1, 0), b3, voffB); PG8_STAGE(PG8_SB(1, 1), b3 + hstep, voffB); PG8_STAGE(PG8_SA(1, 0), a3, voffA);
;             PG8_WAIT_V(8); PG8_WAIT_L(0); PG8_BAR; PG8_MMA(1, 0, At, B0); PG8_MMA(1, 1, At, B1); PG8_BAR; PG8_SCHED;
	s_add_i32 s45, s45, s37
	v_lshl_add_u64 v[192:193], v[192:193], 0, s[90:91]
	s_mov_b32 m0, s45
	ds_read_b128 v[176:179], v143 offset:49152
	ds_read_b128 v[180:183], v143 offset:50176
	ds_read_b128 v[184:187], v143 offset:51200
	ds_read_b128 v[188:191], v143 offset:52224
	ds_read_b128 v[198:201], v143 offset:53248
	ds_read_b128 v[202:205], v143 offset:54272
	ds_read_b128 v[206:209], v143 offset:55296
	ds_read_b128 v[210:213], v143 offset:56320
	global_load_lds_dwordx4 v[192:193], off
	s_add_i32 m0, s45, 0x2000
	s_add_u32 s46, s52, 0x80080
	v_lshl_add_u64 v[192:193], v[214:215], 0, s[90:91]
	s_addc_u32 s47, s53, 0
	s_add_i32 s45, s50, s37
	global_load_lds_dwordx4 v[192:193], off
	s_mov_b32 m0, s45
	v_lshl_add_u64 v[192:193], s[46:47], 0, v[32:33]
	global_load_lds_dwordx4 v[192:193], off
	s_add_i32 m0, s45, 0x2000
	v_lshl_add_u64 v[192:193], s[46:47], 0, v[134:135]
	global_load_lds_dwordx4 v[192:193], off
	s_mov_b32 m0, s39
	v_lshl_add_u64 v[192:193], v[216:217], 0, s[90:91]
	global_load_lds_dwordx4 v[192:193], off
	s_mov_b32 m0, s40
	v_lshl_add_u64 v[192:193], v[218:219], 0, s[90:91]
	global_load_lds_dwordx4 v[192:193], off
	s_waitcnt vmcnt(8)
	s_waitcnt lgkmcnt(0)
	s_barrier
	s_setprio 1
	s_waitcnt lgkmcnt(0)
	v_mfma_f32_16x16x32_bf16 v[62:65], v[144:147], v[176:179], v[62:65]
	v_mfma_f32_16x16x32_bf16 v[58:61], v[152:155], v[176:179], v[58:61]
	v_mfma_f32_16x16x32_bf16 v[54:57], v[144:147], v[184:187], v[54:57]
	v_mfma_f32_16x16x32_bf16 v[50:53], v[152:155], v[184:187], v[50:53]
	v_mfma_f32_16x16x32_bf16 v[38:41], v[144:147], v[198:201], v[38:41]
	v_mfma_f32_16x16x32_bf16 v[34:37], v[152:155], v[198:201], v[34:37]
	v_mfma_f32_16x16x32_bf16 v[20:23], v[144:147], v[206:209], v[20:23]
	v_mfma_f32_16x16x32_bf16 v[16:19], v[152:155], v[206:209], v[16:19]
	v_mfma_f32_16x16x32_bf16 v[62:65], v[148:151], v[180:183], v[62:65]
	v_mfma_f32_16x16x32_bf16 v[58:61], v[156:159], v[180:183], v[58:61]
	v_mfma_f32_16x16x32_bf16 v[54:57], v[148:151], v[188:191], v[54:57]
	v_mfma_f32_16x16x32_bf16 v[50:53], v[156:159], v[188:191], v[50:53]
	v_mfma_f32_16x16x32_bf16 v[38:41], v[148:151], v[202:205], v[38:41]
	v_mfma_f32_16x16x32_bf16 v[34:37], v[156:159], v[202:205], v[34:37]
	v_mfma_f32_16x16x32_bf16 v[20:23], v[148:151], v[210:213], v[20:23]
	v_mfma_f32_16x16x32_bf16 v[16:19], v[156:159], v[210:213], v[16:19]
	s_setprio 0
	s_setprio 1
	v_mfma_f32_16x16x32_bf16 v[46:49], v[160:163], v[176:179], v[46:49]
	v_mfma_f32_16x16x32_bf16 v[42:45], v[168:171], v[176:179], v[42:45]
	v_mfma_f32_16x16x32_bf16 v[28:31], v[160:163], v[184:187], v[28:31]
	v_mfma_f32_16x16x32_bf16 v[24:27], v[168:171], v[184:187], v[24:27]
	v_mfma_f32_16x16x32_bf16 v[12:15], v[160:163], v[198:201], v[12:15]
	v_mfma_f32_16x16x32_bf16 v[8:11], v[168:171], v[198:201], v[8:11]
	v_mfma_f32_16x16x32_bf16 v[4:7], v[160:163], v[206:209], v[4:7]
	v_mfma_f32_16x16x32_bf16 v[0:3], v[168:171], v[206:209], v[0:3]
	v_mfma_f32_16x16x32_bf16 v[46:49], v[164:167], v[180:183], v[46:49]
	v_mfma_f32_16x16x32_bf16 v[42:45], v[172:175], v[180:183], v[42:45]
	v_mfma_f32_16x16x32_bf16 v[28:31], v[164:167], v[188:191], v[28:31]
	v_mfma_f32_16x16x32_bf16 v[24:27], v[172:175], v[188:191], v[24:27]
	v_mfma_f32_16x16x32_bf16 v[12:15], v[164:167], v[202:205], v[12:15]
	v_mfma_f32_16x16x32_bf16 v[8:11], v[172:175], v[202:205], v[8:11]
	v_mfma_f32_16x16x32_bf16 v[4:7], v[164:167], v[210:213], v[4:7]
	v_mfma_f32_16x16x32_bf16 v[0:3], v[172:175], v[210:213], v[0:3]
	s_setprio 0
	s_barrier
	s_add_i32 s44, s44, 2
	s_add_u32 s48, s48, 0x100
	s_addc_u32 s49, s49, 0
	s_add_u32 s19, s19, 0x100
	s_addc_u32 s42, s42, 0
	s_cmp_gt_u32 s44, 29
	s_branch .LBB0_263
.Lg1_peel_e1:
	s_add_u32 s45, s48, 0xfff80080
	s_addc_u32 s46, s49, -1
	s_add_i32 s47, 0, 0x10000
	s_cmp_eq_u32 s44, 28
	s_cselect_b32 s57, s11, s46
	s_cselect_b32 s56, s17, s45
	s_cselect_b32 s53, s15, s42
	s_cselect_b32 s52, s18, s19
	s_add_i32 s45, 0, 0x14000
	v_add_u32_e32 v156, s47, v141
	v_add_u32_e32 v172, s45, v141
	ds_read_b128 v[144:147], v156
	ds_read_b128 v[148:151], v156 offset:1024
	ds_read_b128 v[152:155], v156 offset:2048
	ds_read_b128 v[156:159], v156 offset:3072
	ds_read_b128 v[160:163], v172
	ds_read_b128 v[164:167], v172 offset:1024
	ds_read_b128 v[168:171], v172 offset:2048
	ds_read_b128 v[172:175], v172 offset:3072
	v_lshl_add_u64 v[192:193], s[48:49], 0, v[136:137]
	s_add_i32 m0, s13, 0xc000
	ds_read_b128 v[176:179], v143
	ds_read_b128 v[180:183], v143 offset:1024
	ds_read_b128 v[184:187], v143 offset:2048
	ds_read_b128 v[188:191], v143 offset:3072
	ds_read_b128 v[198:201], v143 offset:4096
	ds_read_b128 v[202:205], v143 offset:5120
	ds_read_b128 v[206:209], v143 offset:6144
	ds_read_b128 v[210:213], v143 offset:7168
	global_load_lds_dwordx4 v[192:193], off
	s_add_i32 m0, s13, 0xe000
	v_lshl_add_u64 v[192:193], s[48:49], 0, v[138:139]
	global_load_lds_dwordx4 v[192:193], off
	v_lshl_add_u32 v246, s68, 8, v140
	v_add_u32_e32 v246, 0x80, v246
	v_lshl_or_b32 v222, s69, 8, v142
	v_lshlrev_b32_e32 v222, 1, v222
	v_mov_b32_e32 v223, 0
	v_mad_u64_u32 v[248:249], s[70:71], v246, s67, v[222:223]
	s_mov_b32 s72, 0xa2000
	s_mov_b32 s73, 0
	v_lshl_add_u64 v[248:249], v[248:249], 0, s[76:77]
	v_cvt_pk_bf16_f32 v62, v62, v63
	v_cvt_pk_bf16_f32 v63, v64, v65
	v_cvt_pk_bf16_f32 v64, v58, v59
	v_cvt_pk_bf16_f32 v65, v60, v61
	global_store_dwordx4 v[248:249], v[62:65], off
	v_cvt_pk_bf16_f32 v46, v46, v47
	v_cvt_pk_bf16_f32 v47, v48, v49
	v_cvt_pk_bf16_f32 v48, v42, v43
	v_cvt_pk_bf16_f32 v49, v44, v45
	global_store_dwordx4 v[248:249], v[46:49], off offset:256
	v_lshl_add_u64 v[248:249], v[248:249], 0, s[72:73]
	v_cvt_pk_bf16_f32 v54, v54, v55
	v_cvt_pk_bf16_f32 v55, v56, v57
	v_cvt_pk_bf16_f32 v56, v50, v51
	v_cvt_pk_bf16_f32 v57, v52, v53
	global_store_dwordx4 v[248:249], v[54:57], off
	v_cvt_pk_bf16_f32 v28, v28, v29
	v_cvt_pk_bf16_f32 v29, v30, v31
	v_cvt_pk_bf16_f32 v30, v24, v25
	v_cvt_pk_bf16_f32 v31, v26, v27
	global_store_dwordx4 v[248:249], v[28:31], off offset:256
	v_lshl_add_u64 v[248:249], v[248:249], 0, s[72:73]
	v_cvt_pk_bf16_f32 v38, v38, v39
	v_cvt_pk_bf16_f32 v39, v40, v41
	v_cvt_pk_bf16_f32 v40, v34, v35
	v_cvt_pk_bf16_f32 v41, v36, v37
	global_store_dwordx4 v[248:249], v[38:41], off
	v_cvt_pk_bf16_f32 v12, v12, v13
	v_cvt_pk_bf16_f32 v13, v14, v15
	v_cvt_pk_bf16_f32 v14, v8, v9
	v_cvt_pk_bf16_f32 v15, v10, v11
	global_store_dwordx4 v[248:249], v[12:15], off offset:256
	v_lshl_add_u64 v[248:249], v[248:249], 0, s[72:73]
	v_cvt_pk_bf16_f32 v20, v20, v21
	v_cvt_pk_bf16_f32 v21, v22, v23
	v_cvt_pk_bf16_f32 v22, v16, v17
	v_cvt_pk_bf16_f32 v23, v18, v19
	global_store_dwordx4 v[248:249], v[20:23], off
	v_cvt_pk_bf16_f32 v4, v4, v5
	v_cvt_pk_bf16_f32 v5, v6, v7
	v_cvt_pk_bf16_f32 v6, v0, v1
	v_cvt_pk_bf16_f32 v7, v2, v3
	global_store_dwordx4 v[248:249], v[4:7], off offset:256
	s_waitcnt vmcnt(24)
	s_waitcnt lgkmcnt(0)
	s_barrier
; #define PG8_STAGE(bufoff, gbase, voff) do { _Pragma("unroll") for (int _i = 0; _i < 2; ++_i) \
;         __builtin_amdgcn_global_load_lds((const unsigned*)((const char*)(gbase) + (voff)[_i]), (PG8_LAS unsigned*)(lds + (bufoff) + ldsw + _i * 8192), 16, 0, 0); } while (0)
; #define PG8_LDA(dst, b, h) do { _Pragma("unroll") for (int m = 0; m < 4; ++m) _Pragma("unroll") for (int k = 0; k < 2; ++k) dst[m][k] = *(const PG8_LAS bf16x8*)(lds + PG8_SA(b, h) + aoff + m * 2048 + k * 1024); } while (0)
; #define PG8_MMA(ai, bj, At, Bt) do { __builtin_amdgcn_s_setprio(1); _Pragma("unroll") for (int m = 0; m < 4; ++m) _Pragma("unroll") for (int n = 0; n < 2; ++n) _Pragma("unroll") for (int k = 0; k < 2; ++k) \
;         acc[ai][bj][m][n] = __builtin_amdgcn_mfma_f32_16x16x32_bf16(Bt[n][k], At[m][k], acc[ai][bj][m][n], 0, 0, 0); __builtin_amdgcn_s_setprio(0); } while (0)
; #define PG8_WAIT_V(n) asm volatile("s_waitcnt vmcnt(" #n ")" ::: "memory")
; #define PG8_WAIT_L(n) asm volatile("s_waitcnt lgkmcnt(" #n ")" ::: "memory")
; #define PG8_BAR __builtin_amdgcn_s_barrier()
; #define PG8_SCHED __builtin_amdgcn_sched_barrier(0)
; template <class Epi, class Sched, bool ALIGN_EPI = false, bool SP2 = false, bool KHOOK = false>
; __device__ __forceinline__ void gemm_phase(PG8_LAS unsigned char* lds, const Gemm g, const Sched& S, const Epi& E, const int tid_in) {
;     ...
;             PG8_WAIT_V(8); PG8_WAIT_L(0); PG8_BAR; PG8_MMA(0, 0, At, B0); PG8_MMA(0, 1, At, B1); PG8_BAR; PG8_SCHED;
;             PG8_LDA(At, 0, 1); PG8_STAGE(PG8_SB(0, 0), b2, voffB); PG8_STAGE(PG8_SB(0, 1), b2 + hstep, voffB); PG8_STAGE(PG8_SA(0, 0), a2, voffA);
;             PG8_WAIT_V(8); PG8_WAIT_L(0); PG8_BAR; PG8_MMA(1, 0, At, B0); PG8_MMA(1, 1, At, B1); PG8_BAR; PG8_SCHED;
	s_setprio 1
	s_waitcnt lgkmcnt(0)
	v_mfma_f32_16x16x32_bf16 v[126:129], v[144:147], v[176:179], 0
	v_mfma_f32_16x16x32_bf16 v[122:125], v[152:155], v[176:179], 0
	v_mfma_f32_16x16x32_bf16 v[118:121], v[144:147], v[184:187], 0
	v_mfma_f32_16x16x32_bf16 v[114:117], v[152:155], v[184:187], 0
	v_mfma_f32_16x16x32_bf16 v[102:105], v[144:147], v[198:201], 0
	v_mfma_f32_16x16x32_bf16 v[98:101], v[152:155], v[198:201], 0
	v_mfma_f32_16x16x32_bf16 v[86:89], v[144:147], v[206:209], 0
	v_mfma_f32_16x16x32_bf16 v[82:85], v[152:155], v[206:209], 0
	v_mfma_f32_16x16x32_bf16 v[126:129], v[148:151], v[180:183], v[126:129]
	v_mfma_f32_16x16x32_bf16 v[122:125], v[156:159], v[180:183], v[122:125]
	v_mfma_f32_16x16x32_bf16 v[118:121], v[148:151], v[188:191], v[118:121]
	v_mfma_f32_16x16x32_bf16 v[114:117], v[156:159], v[188:191], v[114:117]
	v_mfma_f32_16x16x32_bf16 v[102:105], v[148:151], v[202:205], v[102:105]
	v_mfma_f32_16x16x32_bf16 v[98:101], v[156:159], v[202:205], v[98:101]
	v_mfma_f32_16x16x32_bf16 v[86:89], v[148:151], v[210:213], v[86:89]
	v_mfma_f32_16x16x32_bf16 v[82:85], v[156:159], v[210:213], v[82:85]
	s_setprio 0
	s_setprio 1
	v_mfma_f32_16x16x32_bf16 v[110:113], v[160:163], v[176:179], 0
	v_mfma_f32_16x16x32_bf16 v[106:109], v[168:171], v[176:179], 0
	v_mfma_f32_16x16x32_bf16 v[94:97], v[160:163], v[184:187], 0
	v_mfma_f32_16x16x32_bf16 v[90:93], v[168:171], v[184:187], 0
	v_mfma_f32_16x16x32_bf16 v[78:81], v[160:163], v[198:201], 0
	v_mfma_f32_16x16x32_bf16 v[74:77], v[168:171], v[198:201], 0
	v_mfma_f32_16x16x32_bf16 v[70:73], v[160:163], v[206:209], 0
	v_mfma_f32_16x16x32_bf16 v[66:69], v[168:171], v[206:209], 0
	v_mfma_f32_16x16x32_bf16 v[110:113], v[164:167], v[180:183], v[110:113]
	v_mfma_f32_16x16x32_bf16 v[106:109], v[172:175], v[180:183], v[106:109]
	v_mfma_f32_16x16x32_bf16 v[94:97], v[164:167], v[188:191], v[94:97]
	v_mfma_f32_16x16x32_bf16 v[90:93], v[172:175], v[188:191], v[90:93]
	v_mfma_f32_16x16x32_bf16 v[78:81], v[164:167], v[202:205], v[78:81]
	v_mfma_f32_16x16x32_bf16 v[74:77], v[172:175], v[202:205], v[74:77]
	v_mfma_f32_16x16x32_bf16 v[70:73], v[164:167], v[210:213], v[70:73]
	v_mfma_f32_16x16x32_bf16 v[66:69], v[172:175], v[210:213], v[66:69]
	s_setprio 0
	s_barrier
	s_add_i32 s46, s47, s37
	v_lshl_add_u64 v[192:193], s[52:53], 0, v[32:33]
	s_mov_b32 m0, s46
	ds_read_b128 v[176:179], v143 offset:16384
	ds_read_b128 v[180:183], v143 offset:17408
	ds_read_b128 v[184:187], v143 offset:18432
	ds_read_b128 v[188:191], v143 offset:19456
	ds_read_b128 v[198:201], v143 offset:20480
	ds_read_b128 v[202:205], v143 offset:21504
	ds_read_b128 v[206:209], v143 offset:22528
	ds_read_b128 v[210:213], v143 offset:23552
	global_load_lds_dwordx4 v[192:193], off
	s_add_i32 m0, s46, 0x2000
	s_add_u32 s46, s52, 0x80000
	v_lshl_add_u64 v[214:215], s[52:53], 0, v[134:135]
	s_addc_u32 s47, s53, 0
	s_add_i32 s45, s45, s37
	global_load_lds_dwordx4 v[214:215], off
	v_lshl_add_u64 v[216:217], s[46:47], 0, v[32:33]
	s_mov_b32 m0, s45
	v_lshl_add_u64 v[218:219], s[56:57], 0, v[132:133]
	global_load_lds_dwordx4 v[216:217], off
	s_add_i32 m0, s45, 0x2000
	v_lshl_add_u64 v[216:217], s[46:47], 0, v[134:135]
	global_load_lds_dwordx4 v[216:217], off
	s_mov_b32 m0, s13
	v_lshl_add_u64 v[216:217], s[56:57], 0, v[130:131]
	global_load_lds_dwordx4 v[216:217], off
	s_mov_b32 m0, s24
	s_nop 0
	global_load_lds_dwordx4 v[218:219], off
	s_waitcnt vmcnt(24)
	s_waitcnt lgkmcnt(0)
	s_barrier
	s_setprio 1
	s_waitcnt lgkmcnt(0)
	v_mfma_f32_16x16x32_bf16 v[62:65], v[144:147], v[176:179], 0
	v_mfma_f32_16x16x32_bf16 v[58:61], v[152:155], v[176:179], 0
	v_mfma_f32_16x16x32_bf16 v[54:57], v[144:147], v[184:187], 0
	v_mfma_f32_16x16x32_bf16 v[50:53], v[152:155], v[184:187], 0
	v_mfma_f32_16x16x32_bf16 v[38:41], v[144:147], v[198:201], 0
	v_mfma_f32_16x16x32_bf16 v[34:37], v[152:155], v[198:201], 0
	v_mfma_f32_16x16x32_bf16 v[20:23], v[144:147], v[206:209], 0
	v_mfma_f32_16x16x32_bf16 v[16:19], v[152:155], v[206:209], 0
	v_mfma_f32_16x16x32_bf16 v[62:65], v[148:151], v[180:183], v[62:65]
	v_mfma_f32_16x16x32_bf16 v[58:61], v[156:159], v[180:183], v[58:61]
	v_mfma_f32_16x16x32_bf16 v[54:57], v[148:151], v[188:191], v[54:57]
	v_mfma_f32_16x16x32_bf16 v[50:53], v[156:159], v[188:191], v[50:53]
	v_mfma_f32_16x16x32_bf16 v[38:41], v[148:151], v[202:205], v[38:41]
	v_mfma_f32_16x16x32_bf16 v[34:37], v[156:159], v[202:205], v[34:37]
	v_mfma_f32_16x16x32_bf16 v[20:23], v[148:151], v[210:213], v[20:23]
	v_mfma_f32_16x16x32_bf16 v[16:19], v[156:159], v[210:213], v[16:19]
	s_setprio 0
	s_setprio 1
	v_mfma_f32_16x16x32_bf16 v[46:49], v[160:163], v[176:179], 0
	v_mfma_f32_16x16x32_bf16 v[42:45], v[168:171], v[176:179], 0
	v_mfma_f32_16x16x32_bf16 v[28:31], v[160:163], v[184:187], 0
	v_mfma_f32_16x16x32_bf16 v[24:27], v[168:171], v[184:187], 0
	v_mfma_f32_16x16x32_bf16 v[12:15], v[160:163], v[198:201], 0
	v_mfma_f32_16x16x32_bf16 v[8:11], v[168:171], v[198:201], 0
	v_mfma_f32_16x16x32_bf16 v[4:7], v[160:163], v[206:209], 0
	v_mfma_f32_16x16x32_bf16 v[0:3], v[168:171], v[206:209], 0
	v_mfma_f32_16x16x32_bf16 v[46:49], v[164:167], v[180:183], v[46:49]
	v_mfma_f32_16x16x32_bf16 v[42:45], v[172:175], v[180:183], v[42:45]
	v_mfma_f32_16x16x32_bf16 v[28:31], v[164:167], v[188:191], v[28:31]
	v_mfma_f32_16x16x32_bf16 v[24:27], v[172:175], v[188:191], v[24:27]
	v_mfma_f32_16x16x32_bf16 v[12:15], v[164:167], v[202:205], v[12:15]
	v_mfma_f32_16x16x32_bf16 v[8:11], v[172:175], v[202:205], v[8:11]
	v_mfma_f32_16x16x32_bf16 v[4:7], v[164:167], v[210:213], v[4:7]
	v_mfma_f32_16x16x32_bf16 v[0:3], v[172:175], v[210:213], v[0:3]
	s_setprio 0
	s_barrier
; #define PG8_STAGE(bufoff, gbase, voff) do { _Pragma("unroll") for (int _i = 0; _i < 2; ++_i) \
;         __builtin_amdgcn_global_load_lds((const unsigned*)((const char*)(gbase) + (voff)[_i]), (PG8_LAS unsigned*)(lds + (bufoff) + ldsw + _i * 8192), 16, 0, 0); } while (0)
; #define PG8_LDA(dst, b, h) do { _Pragma("unroll") for (int m = 0; m < 4; ++m) _Pragma("unroll") for (int k = 0; k < 2; ++k) dst[m][k] = *(const PG8_LAS bf16x8*)(lds + PG8_SA(b, h) + aoff + m * 2048 + k * 1024); } while (0)
; #define PG8_LDB(dst, b, h) do { _Pragma("unroll") for (int n = 0; n < 2; ++n) _Pragma("unroll") for (int k = 0; k < 2; ++k) dst[n][k] = *(const PG8_LAS bf16x8*)(lds + PG8_SB(b, h) + boff + n * 2048 + k * 1024); } while (0)
; #define PG8_MMA(ai, bj, At, Bt) do { __builtin_amdgcn_s_setprio(1); _Pragma("unroll") for (int m = 0; m < 4; ++m) _Pragma("unroll") for (int n = 0; n < 2; ++n) _Pragma("unroll") for (int k = 0; k < 2; ++k) \
;         acc[ai][bj][m][n] = __builtin_amdgcn_mfma_f32_16x16x32_bf16(Bt[n][k], At[m][k], acc[ai][bj][m][n], 0, 0, 0); __builtin_amdgcn_s_setprio(0); } while (0)
; #define PG8_WAIT_V(n) asm volatile("s_waitcnt vmcnt(" #n ")" ::: "memory")
; #define PG8_WAIT_L(n) asm volatile("s_waitcnt lgkmcnt(" #n ")" ::: "memory")
; #define PG8_BAR __builtin_amdgcn_s_barrier()
; #define PG8_SCHED __builtin_amdgcn_sched_barrier(0)
; template <class Epi, class Sched, bool ALIGN_EPI = false, bool SP2 = false, bool KHOOK = false>
; __device__ __forceinline__ void gemm_phase(PG8_LAS unsigned char* lds, const Gemm g, const Sched& S, const Epi& E, const int tid_in) {
;     ...
;             PG8_LDB(B0, 1, 0); PG8_LDB(B1, 1, 1); PG8_SCHED; PG8_LDA(At, 1, 0); PG8_STAGE(PG8_SA(0, 1), a2 + hstep, voffA);
;             PG8_WAIT_V(8); PG8_WAIT_L(0); PG8_BAR; PG8_MMA(0, 0, At, B0); PG8_MMA(0, 1, At, B1); PG8_BAR; PG8_SCHED;
;             PG8_LDA(At, 1, 1); PG8_STAGE(PG8_SB(1, 0), b3, voffB); PG8_STAGE(PG8_SB(1, 1), b3 + hstep, voffB); PG8_STAGE(PG8_SA(1, 0), a3, voffA);
;             PG8_WAIT_V(8); PG8_WAIT_L(0); PG8_BAR; PG8_MMA(1, 0, At, B0); PG8_MMA(1, 1, At, B1); PG8_BAR; PG8_SCHED;
	s_add_i32 s45, 0, 0x18000
	s_add_i32 s50, 0, 0x1c000
	v_add_u32_e32 v156, s45, v141
	v_add_u32_e32 v172, s50, v141
	ds_read_b128 v[144:147], v156
	ds_read_b128 v[148:151], v156 offset:1024
	ds_read_b128 v[152:155], v156 offset:2048
	ds_read_b128 v[156:159], v156 offset:3072
	ds_read_b128 v[160:163], v172
	ds_read_b128 v[164:167], v172 offset:1024
	ds_read_b128 v[168:171], v172 offset:2048
	ds_read_b128 v[172:175], v172 offset:3072
	s_add_u32 s46, s56, 0x80000
	s_addc_u32 s47, s57, 0
	s_mov_b32 m0, s25
	v_lshl_add_u64 v[220:221], s[46:47], 0, v[130:131]
	ds_read_b128 v[176:179], v143 offset:32768
	ds_read_b128 v[180:183], v143 offset:33792
	ds_read_b128 v[184:187], v143 offset:34816
	ds_read_b128 v[188:191], v143 offset:35840
	ds_read_b128 v[198:201], v143 offset:36864
	ds_read_b128 v[202:205], v143 offset:37888
	ds_read_b128 v[206:209], v143 offset:38912
	ds_read_b128 v[210:213], v143 offset:39936
	global_load_lds_dwordx4 v[220:221], off
	s_mov_b32 m0, s38
	v_lshl_add_u64 v[220:221], s[46:47], 0, v[132:133]
	global_load_lds_dwordx4 v[220:221], off
	s_waitcnt vmcnt(16)
	s_waitcnt lgkmcnt(0)
	s_barrier
	s_setprio 1
	s_waitcnt lgkmcnt(0)
	v_mfma_f32_16x16x32_bf16 v[126:129], v[144:147], v[176:179], v[126:129]
	v_mfma_f32_16x16x32_bf16 v[122:125], v[152:155], v[176:179], v[122:125]
	v_mfma_f32_16x16x32_bf16 v[118:121], v[144:147], v[184:187], v[118:121]
	v_mfma_f32_16x16x32_bf16 v[114:117], v[152:155], v[184:187], v[114:117]
	v_mfma_f32_16x16x32_bf16 v[102:105], v[144:147], v[198:201], v[102:105]
	v_mfma_f32_16x16x32_bf16 v[98:101], v[152:155], v[198:201], v[98:101]
	v_mfma_f32_16x16x32_bf16 v[86:89], v[144:147], v[206:209], v[86:89]
	v_mfma_f32_16x16x32_bf16 v[82:85], v[152:155], v[206:209], v[82:85]
	v_mfma_f32_16x16x32_bf16 v[126:129], v[148:151], v[180:183], v[126:129]
	v_mfma_f32_16x16x32_bf16 v[122:125], v[156:159], v[180:183], v[122:125]
	v_mfma_f32_16x16x32_bf16 v[118:121], v[148:151], v[188:191], v[118:121]
	v_mfma_f32_16x16x32_bf16 v[114:117], v[156:159], v[188:191], v[114:117]
	v_mfma_f32_16x16x32_bf16 v[102:105], v[148:151], v[202:205], v[102:105]
	v_mfma_f32_16x16x32_bf16 v[98:101], v[156:159], v[202:205], v[98:101]
	v_mfma_f32_16x16x32_bf16 v[86:89], v[148:151], v[210:213], v[86:89]
	v_mfma_f32_16x16x32_bf16 v[82:85], v[156:159], v[210:213], v[82:85]
	s_setprio 0
	s_setprio 1
	v_mfma_f32_16x16x32_bf16 v[110:113], v[160:163], v[176:179], v[110:113]
	v_mfma_f32_16x16x32_bf16 v[106:109], v[168:171], v[176:179], v[106:109]
	v_mfma_f32_16x16x32_bf16 v[94:97], v[160:163], v[184:187], v[94:97]
	v_mfma_f32_16x16x32_bf16 v[90:93], v[168:171], v[184:187], v[90:93]
	v_mfma_f32_16x16x32_bf16 v[78:81], v[160:163], v[198:201], v[78:81]
	v_mfma_f32_16x16x32_bf16 v[74:77], v[168:171], v[198:201], v[74:77]
	v_mfma_f32_16x16x32_bf16 v[70:73], v[160:163], v[206:209], v[70:73]
	v_mfma_f32_16x16x32_bf16 v[66:69], v[168:171], v[206:209], v[66:69]
	v_mfma_f32_16x16x32_bf16 v[110:113], v[164:167], v[180:183], v[110:113]
	v_mfma_f32_16x16x32_bf16 v[106:109], v[172:175], v[180:183], v[106:109]
	v_mfma_f32_16x16x32_bf16 v[94:97], v[164:167], v[188:191], v[94:97]
	v_mfma_f32_16x16x32_bf16 v[90:93], v[172:175], v[188:191], v[90:93]
	v_mfma_f32_16x16x32_bf16 v[78:81], v[164:167], v[202:205], v[78:81]
	v_mfma_f32_16x16x32_bf16 v[74:77], v[172:175], v[202:205], v[74:77]
	v_mfma_f32_16x16x32_bf16 v[70:73], v[164:167], v[210:213], v[70:73]
	v_mfma_f32_16x16x32_bf16 v[66:69], v[172:175], v[210:213], v[66:69]
	s_setprio 0
	s_barrier
	s_add_i32 s45, s45, s37
	v_lshl_add_u64 v[192:193], v[192:193], 0, s[90:91]
	s_mov_b32 m0, s45
	ds_read_b128 v[176:179], v143 offset:49152
	ds_read_b128 v[180:183], v143 offset:50176
	ds_read_b128 v[184:187], v143 offset:51200
	ds_read_b128 v[188:191], v143 offset:52224
	ds_read_b128 v[198:201], v143 offset:53248
	ds_read_b128 v[202:205], v143 offset:54272
	ds_read_b128 v[206:209], v143 offset:55296
	ds_read_b128 v[210:213], v143 offset:56320
	global_load_lds_dwordx4 v[192:193], off
	s_add_i32 m0, s45, 0x2000
	s_add_u32 s46, s52, 0x80080
	v_lshl_add_u64 v[192:193], v[214:215], 0, s[90:91]
	s_addc_u32 s47, s53, 0
	s_add_i32 s45, s50, s37
	global_load_lds_dwordx4 v[192:193], off
	s_mov_b32 m0, s45
	v_lshl_add_u64 v[192:193], s[46:47], 0, v[32:33]
	global_load_lds_dwordx4 v[192:193], off
	s_add_i32 m0, s45, 0x2000
	v_lshl_add_u64 v[192:193], s[46:47], 0, v[134:135]
	global_load_lds_dwordx4 v[192:193], off
	s_mov_b32 m0, s39
	v_lshl_add_u64 v[192:193], v[216:217], 0, s[90:91]
	global_load_lds_dwordx4 v[192:193], off
	s_mov_b32 m0, s40
	v_lshl_add_u64 v[192:193], v[218:219], 0, s[90:91]
	global_load_lds_dwordx4 v[192:193], off
	s_waitcnt vmcnt(8)
	s_waitcnt lgkmcnt(0)
	s_barrier
; #define PG8_STAGE(bufoff, gbase, voff) do { _Pragma("unroll") for (int _i = 0; _i < 2; ++_i) \
;         __builtin_amdgcn_global_load_lds((const unsigned*)((const char*)(gbase) + (voff)[_i]), (PG8_LAS unsigned*)(lds + (bufoff) + ldsw + _i * 8192), 16, 0, 0); } while (0)
; #define PG8_LDA(dst, b, h) do { _Pragma("unroll") for (int m = 0; m < 4; ++m) _Pragma("unroll") for (int k = 0; k < 2; ++k) dst[m][k] = *(const PG8_LAS bf16x8*)(lds + PG8_SA(b, h) + aoff + m * 2048 + k * 1024); } while (0)
; #define PG8_LDB(dst, b, h) do { _Pragma("unroll") for (int n = 0; n < 2; ++n) _Pragma("unroll") for (int k = 0; k < 2; ++k) dst[n][k] = *(const PG8_LAS bf16x8*)(lds + PG8_SB(b, h) + boff + n * 2048 + k * 1024); } while (0)
; #define PG8_MMA(ai, bj, At, Bt) do { __builtin_amdgcn_s_setprio(1); _Pragma("unroll") for (int m = 0; m < 4; ++m) _Pragma("unroll") for (int n = 0; n < 2; ++n) _Pragma("unroll") for (int k = 0; k < 2; ++k) \
;         acc[ai][bj][m][n] = __builtin_amdgcn_mfma_f32_16x16x32_bf16(Bt[n][k], At[m][k], acc[ai][bj][m][n], 0, 0, 0); __builtin_amdgcn_s_setprio(0); } while (0)
; template <class Epi, class Sched, bool ALIGN_EPI = false, bool SP2 = false, bool KHOOK = false>
; __device__ __forceinline__ void gemm_phase(PG8_LAS unsigned char* lds, const Gemm g, const Sched& S, const Epi& E, const int tid_in) {
;     ...
;             PG8_LDB(B0, 0, 0); PG8_LDB(B1, 0, 1); PG8_SCHED; PG8_LDA(At, 0, 0); PG8_STAGE(PG8_SA(1, 1), a1 + hstep, voffA);
;             PG8_WAIT_V(8); PG8_WAIT_L(0); PG8_BAR; PG8_MMA(0, 0, At, B0); PG8_MMA(0, 1, At, B1); PG8_BAR; PG8_SCHED;
;             PG8_LDA(At, 0, 1); PG8_STAGE(PG8_SB(0, 0), b2, voffB); PG8_STAGE(PG8_SB(0, 1), b2 + hstep, voffB); PG8_STAGE(PG8_SA(0, 0), a2, voffA);
;             PG8_WAIT_V(8); PG8_WAIT_L(0); PG8_BAR; PG8_MMA(1, 0, At, B0); PG8_MMA(1, 1, At, B1); PG8_BAR; PG8_SCHED;
;             PG8_LDB(B0, 1, 0); PG8_LDB(B1, 1, 1); PG8_SCHED; PG8_LDA(At, 1, 0); PG8_STAGE(PG8_SA(0, 1), a2 + hstep, voffA);
;             PG8_WAIT_V(8); PG8_WAIT_L(0); PG8_BAR; PG8_MMA(0, 0, At, B0); PG8_MMA(0, 1, At, B1); PG8_BAR; PG8_SCHED;
;             PG8_LDA(At, 1, 1); PG8_STAGE(PG8_SB(1, 0), b3, voffB); PG8_STAGE(PG8_SB(1, 1), b3 + hstep, voffB); PG8_STAGE(PG8_SA(1, 0), a3, voffA);
;             PG8_WAIT_V(8); PG8_WAIT_L(0); PG8_BAR; PG8_MMA(1, 0, At, B0); PG8_MMA(1, 1, At, B1); PG8_BAR; PG8_SCHED;
	s_setprio 1
	s_waitcnt lgkmcnt(0)
	v_mfma_f32_16x16x32_bf16 v[62:65], v[144:147], v[176:179], v[62:65]
	v_mfma_f32_16x16x32_bf16 v[58:61], v[152:155], v[176:179], v[58:61]
	v_mfma_f32_16x16x32_bf16 v[54:57], v[144:147], v[184:187], v[54:57]
	v_mfma_f32_16x16x32_bf16 v[50:53], v[152:155], v[184:187], v[50:53]
	v_mfma_f32_16x16x32_bf16 v[38:41], v[144:147], v[198:201], v[38:41]
	v_mfma_f32_16x16x32_bf16 v[34:37], v[152:155], v[198:201], v[34:37]
	v_mfma_f32_16x16x32_bf16 v[20:23], v[144:147], v[206:209], v[20:23]
	v_mfma_f32_16x16x32_bf16 v[16:19], v[152:155], v[206:209], v[16:19]
	v_mfma_f32_16x16x32_bf16 v[62:65], v[148:151], v[180:183], v[62:65]
	v_mfma_f32_16x16x32_bf16 v[58:61], v[156:159], v[180:183], v[58:61]
	v_mfma_f32_16x16x32_bf16 v[54:57], v[148:151], v[188:191], v[54:57]
	v_mfma_f32_16x16x32_bf16 v[50:53], v[156:159], v[188:191], v[50:53]
	v_mfma_f32_16x16x32_bf16 v[38:41], v[148:151], v[202:205], v[38:41]
	v_mfma_f32_16x16x32_bf16 v[34:37], v[156:159], v[202:205], v[34:37]
	v_mfma_f32_16x16x32_bf16 v[20:23], v[148:151], v[210:213], v[20:23]
	v_mfma_f32_16x16x32_bf16 v[16:19], v[156:159], v[210:213], v[16:19]
	s_setprio 0
	s_setprio 1
	v_mfma_f32_16x16x32_bf16 v[46:49], v[160:163], v[176:179], v[46:49]
	v_mfma_f32_16x16x32_bf16 v[42:45], v[168:171], v[176:179], v[42:45]
	v_mfma_f32_16x16x32_bf16 v[28:31], v[160:163], v[184:187], v[28:31]
	v_mfma_f32_16x16x32_bf16 v[24:27], v[168:171], v[184:187], v[24:27]
	v_mfma_f32_16x16x32_bf16 v[12:15], v[160:163], v[198:201], v[12:15]
	v_mfma_f32_16x16x32_bf16 v[8:11], v[168:171], v[198:201], v[8:11]
	v_mfma_f32_16x16x32_bf16 v[4:7], v[160:163], v[206:209], v[4:7]
	v_mfma_f32_16x16x32_bf16 v[0:3], v[168:171], v[206:209], v[0:3]
	v_mfma_f32_16x16x32_bf16 v[46:49], v[164:167], v[180:183], v[46:49]
	v_mfma_f32_16x16x32_bf16 v[42:45], v[172:175], v[180:183], v[42:45]
	v_mfma_f32_16x16x32_bf16 v[28:31], v[164:167], v[188:191], v[28:31]
	v_mfma_f32_16x16x32_bf16 v[24:27], v[172:175], v[188:191], v[24:27]
	v_mfma_f32_16x16x32_bf16 v[12:15], v[164:167], v[202:205], v[12:15]
	v_mfma_f32_16x16x32_bf16 v[8:11], v[172:175], v[202:205], v[8:11]
	v_mfma_f32_16x16x32_bf16 v[4:7], v[164:167], v[210:213], v[4:7]
	v_mfma_f32_16x16x32_bf16 v[0:3], v[172:175], v[210:213], v[0:3]
	s_setprio 0
	s_barrier
	s_add_i32 s44, s44, 2
	s_add_u32 s48, s48, 0x100
	s_addc_u32 s49, s49, 0
	s_add_u32 s19, s19, 0x100
	s_addc_u32 s42, s42, 0
	s_cmp_gt_u32 s44, 29
.LBB0_263:
	s_add_u32 s45, s48, 0xfff80080
	s_addc_u32 s46, s49, -1
	s_add_i32 s47, 0, 0x10000
	s_cmp_eq_u32 s44, 28
	s_cselect_b32 s57, s11, s46
	s_cselect_b32 s56, s17, s45
	s_cselect_b32 s53, s15, s42
	s_cselect_b32 s52, s18, s19
	s_add_i32 s45, 0, 0x14000
	v_add_u32_e32 v156, s47, v141
	v_add_u32_e32 v172, s45, v141
	ds_read_b128 v[144:147], v156
	ds_read_b128 v[148:151], v156 offset:1024
	ds_read_b128 v[152:155], v156 offset:2048
	ds_read_b128 v[156:159], v156 offset:3072
	ds_read_b128 v[160:163], v172
	ds_read_b128 v[164:167], v172 offset:1024
	ds_read_b128 v[168:171], v172 offset:2048
	ds_read_b128 v[172:175], v172 offset:3072
	v_lshl_add_u64 v[192:193], s[48:49], 0, v[136:137]
	s_add_i32 m0, s13, 0xc000
	ds_read_b128 v[176:179], v143
	ds_read_b128 v[180:183], v143 offset:1024
	ds_read_b128 v[184:187], v143 offset:2048
	ds_read_b128 v[188:191], v143 offset:3072
	ds_read_b128 v[198:201], v143 offset:4096
	ds_read_b128 v[202:205], v143 offset:5120
	ds_read_b128 v[206:209], v143 offset:6144
	ds_read_b128 v[210:213], v143 offset:7168
	global_load_lds_dwordx4 v[192:193], off
	s_add_i32 m0, s13, 0xe000
	v_lshl_add_u64 v[192:193], s[48:49], 0, v[138:139]
	global_load_lds_dwordx4 v[192:193], off
	s_waitcnt vmcnt(8)
	s_waitcnt lgkmcnt(0)
	s_barrier
	s_setprio 1
	s_waitcnt lgkmcnt(0)
	v_mfma_f32_16x16x32_bf16 v[126:129], v[144:147], v[176:179], v[126:129]
	v_mfma_f32_16x16x32_bf16 v[122:125], v[152:155], v[176:179], v[122:125]
	v_mfma_f32_16x16x32_bf16 v[118:121], v[144:147], v[184:187], v[118:121]
	v_mfma_f32_16x16x32_bf16 v[114:117], v[152:155], v[184:187], v[114:117]
	v_mfma_f32_16x16x32_bf16 v[102:105], v[144:147], v[198:201], v[102:105]
	v_mfma_f32_16x16x32_bf16 v[98:101], v[152:155], v[198:201], v[98:101]
	v_mfma_f32_16x16x32_bf16 v[86:89], v[144:147], v[206:209], v[86:89]
	v_mfma_f32_16x16x32_bf16 v[82:85], v[152:155], v[206:209], v[82:85]
	v_mfma_f32_16x16x32_bf16 v[126:129], v[148:151], v[180:183], v[126:129]
	v_mfma_f32_16x16x32_bf16 v[122:125], v[156:159], v[180:183], v[122:125]
	v_mfma_f32_16x16x32_bf16 v[118:121], v[148:151], v[188:191], v[118:121]
	v_mfma_f32_16x16x32_bf16 v[114:117], v[156:159], v[188:191], v[114:117]
	v_mfma_f32_16x16x32_bf16 v[102:105], v[148:151], v[202:205], v[102:105]
	v_mfma_f32_16x16x32_bf16 v[98:101], v[156:159], v[202:205], v[98:101]
	v_mfma_f32_16x16x32_bf16 v[86:89], v[148:151], v[210:213], v[86:89]
	v_mfma_f32_16x16x32_bf16 v[82:85], v[156:159], v[210:213], v[82:85]
	s_setprio 0
	s_setprio 1
	v_mfma_f32_16x16x32_bf16 v[110:113], v[160:163], v[176:179], v[110:113]
	v_mfma_f32_16x16x32_bf16 v[106:109], v[168:171], v[176:179], v[106:109]
	v_mfma_f32_16x16x32_bf16 v[94:97], v[160:163], v[184:187], v[94:97]
	v_mfma_f32_16x16x32_bf16 v[90:93], v[168:171], v[184:187], v[90:93]
	v_mfma_f32_16x16x32_bf16 v[78:81], v[160:163], v[198:201], v[78:81]
	v_mfma_f32_16x16x32_bf16 v[74:77], v[168:171], v[198:201], v[74:77]
	v_mfma_f32_16x16x32_bf16 v[70:73], v[160:163], v[206:209], v[70:73]
	v_mfma_f32_16x16x32_bf16 v[66:69], v[168:171], v[206:209], v[66:69]
	v_mfma_f32_16x16x32_bf16 v[110:113], v[164:167], v[180:183], v[110:113]
	v_mfma_f32_16x16x32_bf16 v[106:109], v[172:175], v[180:183], v[106:109]
	v_mfma_f32_16x16x32_bf16 v[94:97], v[164:167], v[188:191], v[94:97]
	v_mfma_f32_16x16x32_bf16 v[90:93], v[172:175], v[188:191], v[90:93]
	v_mfma_f32_16x16x32_bf16 v[78:81], v[164:167], v[202:205], v[78:81]
	v_mfma_f32_16x16x32_bf16 v[74:77], v[172:175], v[202:205], v[74:77]
	v_mfma_f32_16x16x32_bf16 v[70:73], v[164:167], v[210:213], v[70:73]
	v_mfma_f32_16x16x32_bf16 v[66:69], v[172:175], v[210:213], v[66:69]
	s_setprio 0
	s_barrier
; #define PG8_STAGE(bufoff, gbase, voff) do { _Pragma("unroll") for (int _i = 0; _i < 2; ++_i) \
;         __builtin_amdgcn_global_load_lds((const unsigned*)((const char*)(gbase) + (voff)[_i]), (PG8_LAS unsigned*)(lds + (bufoff) + ldsw + _i * 8192), 16, 0, 0); } while (0)
; #define PG8_LDA(dst, b, h) do { _Pragma("unroll") for (int m = 0; m < 4; ++m) _Pragma("unroll") for (int k = 0; k < 2; ++k) dst[m][k] = *(const PG8_LAS bf16x8*)(lds + PG8_SA(b, h) + aoff + m * 2048 + k * 1024); } while (0)
; #define PG8_LDB(dst, b, h) do { _Pragma("unroll") for (int n = 0; n < 2; ++n) _Pragma("unroll") for (int k = 0; k < 2; ++k) dst[n][k] = *(const PG8_LAS bf16x8*)(lds + PG8_SB(b, h) + boff + n * 2048 + k * 1024); } while (0)
; #define PG8_MMA(ai, bj, At, Bt) do { __builtin_amdgcn_s_setprio(1); _Pragma("unroll") for (int m = 0; m < 4; ++m) _Pragma("unroll") for (int n = 0; n < 2; ++n) _Pragma("unroll") for (int k = 0; k < 2; ++k) \
;         acc[ai][bj][m][n] = __builtin_amdgcn_mfma_f32_16x16x32_bf16(Bt[n][k], At[m][k], acc[ai][bj][m][n], 0, 0, 0); __builtin_amdgcn_s_setprio(0); } while (0)
; #define PG8_WAIT_V(n) asm volatile("s_waitcnt vmcnt(" #n ")" ::: "memory")
; #define PG8_WAIT_L(n) asm volatile("s_waitcnt lgkmcnt(" #n ")" ::: "memory")
; #define PG8_BAR __builtin_amdgcn_s_barrier()
; #define PG8_SCHED __builtin_amdgcn_sched_barrier(0)
; template <class Epi, class Sched, bool ALIGN_EPI = false, bool SP2 = false, bool KHOOK = false>
; __device__ __forceinline__ void gemm_phase(PG8_LAS unsigned char* lds, const Gemm g, const Sched& S, const Epi& E, const int tid_in) {
;     ...
;             PG8_LDA(At, 0, 1); PG8_STAGE(PG8_SB(0, 0), b2, voffB); PG8_STAGE(PG8_SB(0, 1), b2 + hstep, voffB); PG8_STAGE(PG8_SA(0, 0), a2, voffA);
;             PG8_WAIT_V(8); PG8_WAIT_L(0); PG8_BAR; PG8_MMA(1, 0, At, B0); PG8_MMA(1, 1, At, B1); PG8_BAR; PG8_SCHED;
;             PG8_LDB(B0, 1, 0); PG8_LDB(B1, 1, 1); PG8_SCHED; PG8_LDA(At, 1, 0); PG8_STAGE(PG8_SA(0, 1), a2 + hstep, voffA);
;             PG8_WAIT_V(8); PG8_WAIT_L(0); PG8_BAR; PG8_MMA(0, 0, At, B0); PG8_MMA(0, 1, At, B1); PG8_BAR; PG8_SCHED;
	s_add_i32 s46, s47, s37
	v_lshl_add_u64 v[192:193], s[52:53], 0, v[32:33]
	s_mov_b32 m0, s46
	ds_read_b128 v[176:179], v143 offset:16384
	ds_read_b128 v[180:183], v143 offset:17408
	ds_read_b128 v[184:187], v143 offset:18432
	ds_read_b128 v[188:191], v143 offset:19456
	ds_read_b128 v[198:201], v143 offset:20480
	ds_read_b128 v[202:205], v143 offset:21504
	ds_read_b128 v[206:209], v143 offset:22528
	ds_read_b128 v[210:213], v143 offset:23552
	global_load_lds_dwordx4 v[192:193], off
	s_add_i32 m0, s46, 0x2000
	s_add_u32 s46, s52, 0x80000
	v_lshl_add_u64 v[214:215], s[52:53], 0, v[134:135]
	s_addc_u32 s47, s53, 0
	s_add_i32 s45, s45, s37
	global_load_lds_dwordx4 v[214:215], off
	v_lshl_add_u64 v[216:217], s[46:47], 0, v[32:33]
	s_mov_b32 m0, s45
	v_lshl_add_u64 v[218:219], s[56:57], 0, v[132:133]
	global_load_lds_dwordx4 v[216:217], off
	s_add_i32 m0, s45, 0x2000
	v_lshl_add_u64 v[216:217], s[46:47], 0, v[134:135]
	global_load_lds_dwordx4 v[216:217], off
	s_mov_b32 m0, s13
	v_lshl_add_u64 v[216:217], s[56:57], 0, v[130:131]
	global_load_lds_dwordx4 v[216:217], off
	s_mov_b32 m0, s24
	s_nop 0
	global_load_lds_dwordx4 v[218:219], off
	s_waitcnt vmcnt(8)
	s_waitcnt lgkmcnt(0)
	s_barrier
	s_setprio 1
	s_waitcnt lgkmcnt(0)
	v_mfma_f32_16x16x32_bf16 v[62:65], v[144:147], v[176:179], v[62:65]
	v_mfma_f32_16x16x32_bf16 v[58:61], v[152:155], v[176:179], v[58:61]
	v_mfma_f32_16x16x32_bf16 v[54:57], v[144:147], v[184:187], v[54:57]
	v_mfma_f32_16x16x32_bf16 v[50:53], v[152:155], v[184:187], v[50:53]
	v_mfma_f32_16x16x32_bf16 v[38:41], v[144:147], v[198:201], v[38:41]
	v_mfma_f32_16x16x32_bf16 v[34:37], v[152:155], v[198:201], v[34:37]
	v_mfma_f32_16x16x32_bf16 v[20:23], v[144:147], v[206:209], v[20:23]
	v_mfma_f32_16x16x32_bf16 v[16:19], v[152:155], v[206:209], v[16:19]
	v_mfma_f32_16x16x32_bf16 v[62:65], v[148:151], v[180:183], v[62:65]
	v_mfma_f32_16x16x32_bf16 v[58:61], v[156:159], v[180:183], v[58:61]
	v_mfma_f32_16x16x32_bf16 v[54:57], v[148:151], v[188:191], v[54:57]
	v_mfma_f32_16x16x32_bf16 v[50:53], v[156:159], v[188:191], v[50:53]
	v_mfma_f32_16x16x32_bf16 v[38:41], v[148:151], v[202:205], v[38:41]
	v_mfma_f32_16x16x32_bf16 v[34:37], v[156:159], v[202:205], v[34:37]
	v_mfma_f32_16x16x32_bf16 v[20:23], v[148:151], v[210:213], v[20:23]
	v_mfma_f32_16x16x32_bf16 v[16:19], v[156:159], v[210:213], v[16:19]
	s_setprio 0
	s_setprio 1
	v_mfma_f32_16x16x32_bf16 v[46:49], v[160:163], v[176:179], v[46:49]
	v_mfma_f32_16x16x32_bf16 v[42:45], v[168:171], v[176:179], v[42:45]
	v_mfma_f32_16x16x32_bf16 v[28:31], v[160:163], v[184:187], v[28:31]
	v_mfma_f32_16x16x32_bf16 v[24:27], v[168:171], v[184:187], v[24:27]
	v_mfma_f32_16x16x32_bf16 v[12:15], v[160:163], v[198:201], v[12:15]
	v_mfma_f32_16x16x32_bf16 v[8:11], v[168:171], v[198:201], v[8:11]
	v_mfma_f32_16x16x32_bf16 v[4:7], v[160:163], v[206:209], v[4:7]
	v_mfma_f32_16x16x32_bf16 v[0:3], v[168:171], v[206:209], v[0:3]
	v_mfma_f32_16x16x32_bf16 v[46:49], v[164:167], v[180:183], v[46:49]
	v_mfma_f32_16x16x32_bf16 v[42:45], v[172:175], v[180:183], v[42:45]
	v_mfma_f32_16x16x32_bf16 v[28:31], v[164:167], v[188:191], v[28:31]
	v_mfma_f32_16x16x32_bf16 v[24:27], v[172:175], v[188:191], v[24:27]
	v_mfma_f32_16x16x32_bf16 v[12:15], v[164:167], v[202:205], v[12:15]
	v_mfma_f32_16x16x32_bf16 v[8:11], v[172:175], v[202:205], v[8:11]
	v_mfma_f32_16x16x32_bf16 v[4:7], v[164:167], v[210:213], v[4:7]
	v_mfma_f32_16x16x32_bf16 v[0:3], v[172:175], v[210:213], v[0:3]
	s_setprio 0
	s_barrier
	s_add_i32 s45, 0, 0x18000
	s_add_i32 s50, 0, 0x1c000
	v_add_u32_e32 v156, s45, v141
	v_add_u32_e32 v172, s50, v141
	ds_read_b128 v[144:147], v156
	ds_read_b128 v[148:151], v156 offset:1024
	ds_read_b128 v[152:155], v156 offset:2048
	ds_read_b128 v[156:159], v156 offset:3072
	ds_read_b128 v[160:163], v172
	ds_read_b128 v[164:167], v172 offset:1024
	ds_read_b128 v[168:171], v172 offset:2048
	ds_read_b128 v[172:175], v172 offset:3072
	s_add_u32 s46, s56, 0x80000
	s_addc_u32 s47, s57, 0
	s_mov_b32 m0, s25
	v_lshl_add_u64 v[220:221], s[46:47], 0, v[130:131]
	ds_read_b128 v[176:179], v143 offset:32768
	ds_read_b128 v[180:183], v143 offset:33792
	ds_read_b128 v[184:187], v143 offset:34816
	ds_read_b128 v[188:191], v143 offset:35840
	ds_read_b128 v[198:201], v143 offset:36864
	ds_read_b128 v[202:205], v143 offset:37888
	ds_read_b128 v[206:209], v143 offset:38912
	ds_read_b128 v[210:213], v143 offset:39936
	global_load_lds_dwordx4 v[220:221], off
	s_mov_b32 m0, s38
	v_lshl_add_u64 v[220:221], s[46:47], 0, v[132:133]
	global_load_lds_dwordx4 v[220:221], off
	s_waitcnt vmcnt(8)
	s_waitcnt lgkmcnt(0)
	s_barrier
; #define PG8_STAGE(bufoff, gbase, voff) do { _Pragma("unroll") for (int _i = 0; _i < 2; ++_i) \
;         __builtin_amdgcn_global_load_lds((const unsigned*)((const char*)(gbase) + (voff)[_i]), (PG8_LAS unsigned*)(lds + (bufoff) + ldsw + _i * 8192), 16, 0, 0); } while (0)
; #define PG8_LDA(dst, b, h) do { _Pragma("unroll") for (int m = 0; m < 4; ++m) _Pragma("unroll") for (int k = 0; k < 2; ++k) dst[m][k] = *(const PG8_LAS bf16x8*)(lds + PG8_SA(b, h) + aoff + m * 2048 + k * 1024); } while (0)
; #define PG8_LDB(dst, b, h) do { _Pragma("unroll") for (int n = 0; n < 2; ++n) _Pragma("unroll") for (int k = 0; k < 2; ++k) dst[n][k] = *(const PG8_LAS bf16x8*)(lds + PG8_SB(b, h) + boff + n * 2048 + k * 1024); } while (0)
; #define PG8_WAIT_V(n) asm volatile("s_waitcnt vmcnt(" #n ")" ::: "memory")
; #define PG8_BAR __builtin_amdgcn_s_barrier()
; template <class Epi, class Sched, bool ALIGN_EPI = false, bool SP2 = false, bool KHOOK = false>
; __device__ __forceinline__ void gemm_phase(PG8_LAS unsigned char* lds, const Gemm g, const Sched& S, const Epi& E, const int tid_in) {
;     ...
;             const char* a2 = last ? nA : cA + (size_t)(t + 2) * kstep; const char* b2 = last ? nB : cB + (size_t)(t + 2) * kstep;
;             const char* a3 = a2 + kstep; const char* b3 = b2 + kstep;
;             if (last && has_next) S.a_ready(nxt);
;             if constexpr (SP2) {
;             PG8_LDB(B0, 0, 0); PG8_LDB(B1, 0, 1); PG8_SCHED; PG8_LDA(At, 0, 0); PG8_STAGE(PG8_SA(1, 1), a1 + hstep, voffA);
;             PG8_WAIT_V(8); PG8_WAIT_L(0); PG8_BAR; PG8_MMA(0, 0, At, B0); PG8_MMA(0, 1, At, B1); PG8_BAR; PG8_SCHED;
;             PG8_LDA(At, 0, 1); PG8_STAGE(PG8_SB(0, 0), b2, voffB); PG8_STAGE(PG8_SB(0, 1), b2 + hstep, voffB); PG8_STAGE(PG8_SA(0, 0), a2, voffA);
;             PG8_WAIT_V(8); PG8_WAIT_L(0); PG8_BAR; PG8_MMA(1, 0, At, B0); PG8_MMA(1, 1, At, B1); PG8_BAR; PG8_SCHED;
;             PG8_LDB(B0, 1, 0); PG8_LDB(B1, 1, 1); PG8_SCHED; PG8_LDA(At, 1, 0); PG8_STAGE(PG8_SA(0, 1), a2 + hstep, voffA);
;             PG8_WAIT_V(8); PG8_WAIT_L(0); PG8_BAR; PG8_MMA(0, 0, At, B0); PG8_MMA(0, 1, At, B1); PG8_BAR; PG8_SCHED;
;             PG8_LDA(At, 1, 1); PG8_STAGE(PG8_SB(1, 0), b3, voffB); PG8_STAGE(PG8_SB(1, 1), b3 + hstep, voffB); PG8_STAGE(PG8_SA(1, 0), a3, voffA);
;             PG8_WAIT_V(8); PG8_WAIT_L(0); PG8_BAR; PG8_MMA(1, 0, At, B0); PG8_MMA(1, 1, At, B1); PG8_BAR; PG8_SCHED;
	s_setprio 1
	s_waitcnt lgkmcnt(0)
	v_mfma_f32_16x16x32_bf16 v[126:129], v[144:147], v[176:179], v[126:129]
	v_mfma_f32_16x16x32_bf16 v[122:125], v[152:155], v[176:179], v[122:125]
	v_mfma_f32_16x16x32_bf16 v[118:121], v[144:147], v[184:187], v[118:121]
	v_mfma_f32_16x16x32_bf16 v[114:117], v[152:155], v[184:187], v[114:117]
	v_mfma_f32_16x16x32_bf16 v[102:105], v[144:147], v[198:201], v[102:105]
	v_mfma_f32_16x16x32_bf16 v[98:101], v[152:155], v[198:201], v[98:101]
	v_mfma_f32_16x16x32_bf16 v[86:89], v[144:147], v[206:209], v[86:89]
	v_mfma_f32_16x16x32_bf16 v[82:85], v[152:155], v[206:209], v[82:85]
	v_mfma_f32_16x16x32_bf16 v[126:129], v[148:151], v[180:183], v[126:129]
	v_mfma_f32_16x16x32_bf16 v[122:125], v[156:159], v[180:183], v[122:125]
	v_mfma_f32_16x16x32_bf16 v[118:121], v[148:151], v[188:191], v[118:121]
	v_mfma_f32_16x16x32_bf16 v[114:117], v[156:159], v[188:191], v[114:117]
	v_mfma_f32_16x16x32_bf16 v[102:105], v[148:151], v[202:205], v[102:105]
	v_mfma_f32_16x16x32_bf16 v[98:101], v[156:159], v[202:205], v[98:101]
	v_mfma_f32_16x16x32_bf16 v[86:89], v[148:151], v[210:213], v[86:89]
	v_mfma_f32_16x16x32_bf16 v[82:85], v[156:159], v[210:213], v[82:85]
	s_setprio 0
	s_setprio 1
	v_mfma_f32_16x16x32_bf16 v[110:113], v[160:163], v[176:179], v[110:113]
	v_mfma_f32_16x16x32_bf16 v[106:109], v[168:171], v[176:179], v[106:109]
	v_mfma_f32_16x16x32_bf16 v[94:97], v[160:163], v[184:187], v[94:97]
	v_mfma_f32_16x16x32_bf16 v[90:93], v[168:171], v[184:187], v[90:93]
	v_mfma_f32_16x16x32_bf16 v[78:81], v[160:163], v[198:201], v[78:81]
	v_mfma_f32_16x16x32_bf16 v[74:77], v[168:171], v[198:201], v[74:77]
	v_mfma_f32_16x16x32_bf16 v[70:73], v[160:163], v[206:209], v[70:73]
	v_mfma_f32_16x16x32_bf16 v[66:69], v[168:171], v[206:209], v[66:69]
	v_mfma_f32_16x16x32_bf16 v[110:113], v[164:167], v[180:183], v[110:113]
	v_mfma_f32_16x16x32_bf16 v[106:109], v[172:175], v[180:183], v[106:109]
	v_mfma_f32_16x16x32_bf16 v[94:97], v[164:167], v[188:191], v[94:97]
	v_mfma_f32_16x16x32_bf16 v[90:93], v[172:175], v[188:191], v[90:93]
	v_mfma_f32_16x16x32_bf16 v[78:81], v[164:167], v[202:205], v[78:81]
	v_mfma_f32_16x16x32_bf16 v[74:77], v[172:175], v[202:205], v[74:77]
	v_mfma_f32_16x16x32_bf16 v[70:73], v[164:167], v[210:213], v[70:73]
	v_mfma_f32_16x16x32_bf16 v[66:69], v[172:175], v[210:213], v[66:69]
	s_setprio 0
	s_barrier
	s_add_i32 s45, s45, s37
	v_lshl_add_u64 v[192:193], v[192:193], 0, s[90:91]
	s_mov_b32 m0, s45
	ds_read_b128 v[176:179], v143 offset:49152
	ds_read_b128 v[180:183], v143 offset:50176
	ds_read_b128 v[184:187], v143 offset:51200
	ds_read_b128 v[188:191], v143 offset:52224
	ds_read_b128 v[198:201], v143 offset:53248
	ds_read_b128 v[202:205], v143 offset:54272
	ds_read_b128 v[206:209], v143 offset:55296
	ds_read_b128 v[210:213], v143 offset:56320
	global_load_lds_dwordx4 v[192:193], off
	s_add_i32 m0, s45, 0x2000
	s_add_u32 s46, s52, 0x80080
	v_lshl_add_u64 v[192:193], v[214:215], 0, s[90:91]
	s_addc_u32 s47, s53, 0
	s_add_i32 s45, s50, s37
	global_load_lds_dwordx4 v[192:193], off
	s_mov_b32 m0, s45
	v_lshl_add_u64 v[192:193], s[46:47], 0, v[32:33]
	global_load_lds_dwordx4 v[192:193], off
	s_add_i32 m0, s45, 0x2000
	v_lshl_add_u64 v[192:193], s[46:47], 0, v[134:135]
	global_load_lds_dwordx4 v[192:193], off
	s_mov_b32 m0, s39
	v_lshl_add_u64 v[192:193], v[216:217], 0, s[90:91]
	global_load_lds_dwordx4 v[192:193], off
	s_mov_b32 m0, s40
	v_lshl_add_u64 v[192:193], v[218:219], 0, s[90:91]
	global_load_lds_dwordx4 v[192:193], off
	s_waitcnt vmcnt(8)
	s_waitcnt lgkmcnt(0)
	s_barrier
	s_setprio 1
	s_waitcnt lgkmcnt(0)
	v_mfma_f32_16x16x32_bf16 v[62:65], v[144:147], v[176:179], v[62:65]
	v_mfma_f32_16x16x32_bf16 v[58:61], v[152:155], v[176:179], v[58:61]
	v_mfma_f32_16x16x32_bf16 v[54:57], v[144:147], v[184:187], v[54:57]
	v_mfma_f32_16x16x32_bf16 v[50:53], v[152:155], v[184:187], v[50:53]
	v_mfma_f32_16x16x32_bf16 v[38:41], v[144:147], v[198:201], v[38:41]
	v_mfma_f32_16x16x32_bf16 v[34:37], v[152:155], v[198:201], v[34:37]
	v_mfma_f32_16x16x32_bf16 v[20:23], v[144:147], v[206:209], v[20:23]
	v_mfma_f32_16x16x32_bf16 v[16:19], v[152:155], v[206:209], v[16:19]
	v_mfma_f32_16x16x32_bf16 v[62:65], v[148:151], v[180:183], v[62:65]
	v_mfma_f32_16x16x32_bf16 v[58:61], v[156:159], v[180:183], v[58:61]
	v_mfma_f32_16x16x32_bf16 v[54:57], v[148:151], v[188:191], v[54:57]
	v_mfma_f32_16x16x32_bf16 v[50:53], v[156:159], v[188:191], v[50:53]
	v_mfma_f32_16x16x32_bf16 v[38:41], v[148:151], v[202:205], v[38:41]
	v_mfma_f32_16x16x32_bf16 v[34:37], v[156:159], v[202:205], v[34:37]
	v_mfma_f32_16x16x32_bf16 v[20:23], v[148:151], v[210:213], v[20:23]
	v_mfma_f32_16x16x32_bf16 v[16:19], v[156:159], v[210:213], v[16:19]
	s_setprio 0
	s_setprio 1
	v_mfma_f32_16x16x32_bf16 v[46:49], v[160:163], v[176:179], v[46:49]
	v_mfma_f32_16x16x32_bf16 v[42:45], v[168:171], v[176:179], v[42:45]
	v_mfma_f32_16x16x32_bf16 v[28:31], v[160:163], v[184:187], v[28:31]
	v_mfma_f32_16x16x32_bf16 v[24:27], v[168:171], v[184:187], v[24:27]
	v_mfma_f32_16x16x32_bf16 v[12:15], v[160:163], v[198:201], v[12:15]
	v_mfma_f32_16x16x32_bf16 v[8:11], v[168:171], v[198:201], v[8:11]
	v_mfma_f32_16x16x32_bf16 v[4:7], v[160:163], v[206:209], v[4:7]
	v_mfma_f32_16x16x32_bf16 v[0:3], v[168:171], v[206:209], v[0:3]
	v_mfma_f32_16x16x32_bf16 v[46:49], v[164:167], v[180:183], v[46:49]
	v_mfma_f32_16x16x32_bf16 v[42:45], v[172:175], v[180:183], v[42:45]
	v_mfma_f32_16x16x32_bf16 v[28:31], v[164:167], v[188:191], v[28:31]
	v_mfma_f32_16x16x32_bf16 v[24:27], v[172:175], v[188:191], v[24:27]
	v_mfma_f32_16x16x32_bf16 v[12:15], v[164:167], v[202:205], v[12:15]
	v_mfma_f32_16x16x32_bf16 v[8:11], v[172:175], v[202:205], v[8:11]
	v_mfma_f32_16x16x32_bf16 v[4:7], v[164:167], v[210:213], v[4:7]
	v_mfma_f32_16x16x32_bf16 v[0:3], v[172:175], v[210:213], v[0:3]
	s_setprio 0
	s_barrier
	s_add_i32 s44, s44, 2
	s_add_u32 s48, s48, 0x100
	s_addc_u32 s49, s49, 0
	s_add_u32 s19, s19, 0x100
	s_addc_u32 s42, s42, 0
	s_cmp_lg_u32 s44, 28
	s_cbranch_scc1 .Lg1_cont
	s_cmp_lg_u64 s[22:23], 0
	s_cbranch_scc1 .Lg1_last

; #define PG8_STAGE(bufoff, gbase, voff) do { _Pragma("unroll") for (int _i = 0; _i < 2; ++_i) \
;         __builtin_amdgcn_global_load_lds((const unsigned*)((const char*)(gbase) + (voff)[_i]), (PG8_LAS unsigned*)(lds + (bufoff) + ldsw + _i * 8192), 16, 0, 0); } while (0)
; #define PG8_LDA(dst, b, h) do { _Pragma("unroll") for (int m = 0; m < 4; ++m) _Pragma("unroll") for (int k = 0; k < 2; ++k) dst[m][k] = *(const PG8_LAS bf16x8*)(lds + PG8_SA(b, h) + aoff + m * 2048 + k * 1024); } while (0)
; #define PG8_LDB(dst, b, h) do { _Pragma("unroll") for (int n = 0; n < 2; ++n) _Pragma("unroll") for (int k = 0; k < 2; ++k) dst[n][k] = *(const PG8_LAS bf16x8*)(lds + PG8_SB(b, h) + boff + n * 2048 + k * 1024); } while (0)
; #define PG8_MMA(ai, bj, At, Bt) do { __builtin_amdgcn_s_setprio(1); _Pragma("unroll") for (int m = 0; m < 4; ++m) _Pragma("unroll") for (int n = 0; n < 2; ++n) _Pragma("unroll") for (int k = 0; k < 2; ++k) \
;         acc[ai][bj][m][n] = __builtin_amdgcn_mfma_f32_16x16x32_bf16(Bt[n][k], At[m][k], acc[ai][bj][m][n], 0, 0, 0); __builtin_amdgcn_s_setprio(0); } while (0)
; #define PG8_WAIT_V(n) asm volatile("s_waitcnt vmcnt(" #n ")" ::: "memory")
; #define PG8_WAIT_L(n) asm volatile("s_waitcnt lgkmcnt(" #n ")" ::: "memory")
; #define PG8_BAR __builtin_amdgcn_s_barrier()
; #define PG8_SCHED __builtin_amdgcn_sched_barrier(0)
; template <class Epi, class Sched, bool ALIGN_EPI = false, bool SP2 = false, bool KHOOK = false>
; __device__ __forceinline__ void gemm_phase(PG8_LAS unsigned char* lds, const Gemm g, const Sched& S, const Epi& E, const int tid_in) {
;     ...
;             PG8_LDB(B0, 0, 0); PG8_LDB(B1, 0, 1); PG8_SCHED; PG8_LDA(At, 0, 0); PG8_STAGE(PG8_SA(1, 1), a1 + hstep, voffA);
;             PG8_WAIT_V(8); PG8_WAIT_L(0); PG8_BAR; PG8_MMA(0, 0, At, B0); PG8_MMA(0, 1, At, B1); PG8_BAR; PG8_SCHED;
;             PG8_LDA(At, 0, 1); PG8_STAGE(PG8_SB(0, 0), b2, voffB); PG8_STAGE(PG8_SB(0, 1), b2 + hstep, voffB); PG8_STAGE(PG8_SA(0, 0), a2, voffA);
;             PG8_WAIT_V(8); PG8_WAIT_L(0); PG8_BAR; PG8_MMA(1, 0, At, B0); PG8_MMA(1, 1, At, B1); PG8_BAR; PG8_SCHED;
.Lg1_last:
	s_add_u32 s45, s48, 0xfff80080
	s_addc_u32 s46, s49, -1
	s_add_i32 s47, 0, 0x10000
	s_cmp_eq_u32 s44, 28
	s_cselect_b32 s57, s11, s46
	s_cselect_b32 s56, s17, s45
	s_cselect_b32 s53, s15, s42
	s_cselect_b32 s52, s18, s19
	s_add_i32 s45, 0, 0x14000
	v_add_u32_e32 v156, s47, v141
	v_add_u32_e32 v172, s45, v141
	ds_read_b128 v[144:147], v156
	ds_read_b128 v[148:151], v156 offset:1024
	ds_read_b128 v[152:155], v156 offset:2048
	ds_read_b128 v[156:159], v156 offset:3072
	ds_read_b128 v[160:163], v172
	ds_read_b128 v[164:167], v172 offset:1024
	ds_read_b128 v[168:171], v172 offset:2048
	ds_read_b128 v[172:175], v172 offset:3072
	v_lshl_add_u64 v[192:193], s[48:49], 0, v[136:137]
	s_add_i32 m0, s13, 0xc000
	ds_read_b128 v[176:179], v143
	ds_read_b128 v[180:183], v143 offset:1024
	ds_read_b128 v[184:187], v143 offset:2048
	ds_read_b128 v[188:191], v143 offset:3072
	ds_read_b128 v[198:201], v143 offset:4096
	ds_read_b128 v[202:205], v143 offset:5120
	ds_read_b128 v[206:209], v143 offset:6144
	ds_read_b128 v[210:213], v143 offset:7168
	global_load_lds_dwordx4 v[192:193], off
	s_add_i32 m0, s13, 0xe000
	v_lshl_add_u64 v[192:193], s[48:49], 0, v[138:139]
	global_load_lds_dwordx4 v[192:193], off
	s_waitcnt vmcnt(8)
	s_waitcnt lgkmcnt(0)
	s_barrier
	s_setprio 1
	s_waitcnt lgkmcnt(0)
	v_mfma_f32_16x16x32_bf16 v[126:129], v[144:147], v[176:179], v[126:129]
	v_mfma_f32_16x16x32_bf16 v[122:125], v[152:155], v[176:179], v[122:125]
	v_mfma_f32_16x16x32_bf16 v[118:121], v[144:147], v[184:187], v[118:121]
	v_mfma_f32_16x16x32_bf16 v[114:117], v[152:155], v[184:187], v[114:117]
	v_mfma_f32_16x16x32_bf16 v[102:105], v[144:147], v[198:201], v[102:105]
	v_mfma_f32_16x16x32_bf16 v[98:101], v[152:155], v[198:201], v[98:101]
	v_mfma_f32_16x16x32_bf16 v[86:89], v[144:147], v[206:209], v[86:89]
	v_mfma_f32_16x16x32_bf16 v[82:85], v[152:155], v[206:209], v[82:85]
	v_mfma_f32_16x16x32_bf16 v[126:129], v[148:151], v[180:183], v[126:129]
	v_mfma_f32_16x16x32_bf16 v[122:125], v[156:159], v[180:183], v[122:125]
	v_mfma_f32_16x16x32_bf16 v[118:121], v[148:151], v[188:191], v[118:121]
	v_mfma_f32_16x16x32_bf16 v[114:117], v[156:159], v[188:191], v[114:117]
	v_mfma_f32_16x16x32_bf16 v[102:105], v[148:151], v[202:205], v[102:105]
	v_mfma_f32_16x16x32_bf16 v[98:101], v[156:159], v[202:205], v[98:101]
	v_mfma_f32_16x16x32_bf16 v[86:89], v[148:151], v[210:213], v[86:89]
	v_mfma_f32_16x16x32_bf16 v[82:85], v[156:159], v[210:213], v[82:85]
	s_setprio 0
	s_setprio 1
	v_mfma_f32_16x16x32_bf16 v[110:113], v[160:163], v[176:179], v[110:113]
	v_mfma_f32_16x16x32_bf16 v[106:109], v[168:171], v[176:179], v[106:109]
	v_mfma_f32_16x16x32_bf16 v[94:97], v[160:163], v[184:187], v[94:97]
	v_mfma_f32_16x16x32_bf16 v[90:93], v[168:171], v[184:187], v[90:93]
	v_mfma_f32_16x16x32_bf16 v[78:81], v[160:163], v[198:201], v[78:81]
	v_mfma_f32_16x16x32_bf16 v[74:77], v[168:171], v[198:201], v[74:77]
	v_mfma_f32_16x16x32_bf16 v[70:73], v[160:163], v[206:209], v[70:73]
	v_mfma_f32_16x16x32_bf16 v[66:69], v[168:171], v[206:209], v[66:69]
	v_mfma_f32_16x16x32_bf16 v[110:113], v[164:167], v[180:183], v[110:113]
	v_mfma_f32_16x16x32_bf16 v[106:109], v[172:175], v[180:183], v[106:109]
	v_mfma_f32_16x16x32_bf16 v[94:97], v[164:167], v[188:191], v[94:97]
	v_mfma_f32_16x16x32_bf16 v[90:93], v[172:175], v[188:191], v[90:93]
	v_mfma_f32_16x16x32_bf16 v[78:81], v[164:167], v[202:205], v[78:81]
	v_mfma_f32_16x16x32_bf16 v[74:77], v[172:175], v[202:205], v[74:77]
	v_mfma_f32_16x16x32_bf16 v[70:73], v[164:167], v[210:213], v[70:73]
	v_mfma_f32_16x16x32_bf16 v[66:69], v[172:175], v[210:213], v[66:69]
	s_setprio 0
	s_barrier
	s_add_i32 s46, s47, s37
	v_lshl_add_u64 v[192:193], s[52:53], 0, v[32:33]
	s_mov_b32 m0, s46
	ds_read_b128 v[176:179], v143 offset:16384
	ds_read_b128 v[180:183], v143 offset:17408
	ds_read_b128 v[184:187], v143 offset:18432
	ds_read_b128 v[188:191], v143 offset:19456
	ds_read_b128 v[198:201], v143 offset:20480
	ds_read_b128 v[202:205], v143 offset:21504
	ds_read_b128 v[206:209], v143 offset:22528
	ds_read_b128 v[210:213], v143 offset:23552
	global_load_lds_dwordx4 v[192:193], off
	s_add_i32 m0, s46, 0x2000
	s_add_u32 s46, s52, 0x80000
	v_lshl_add_u64 v[214:215], s[52:53], 0, v[134:135]
	s_addc_u32 s47, s53, 0
	s_add_i32 s45, s45, s37
	global_load_lds_dwordx4 v[214:215], off
	v_lshl_add_u64 v[216:217], s[46:47], 0, v[32:33]
	s_mov_b32 m0, s45
	v_lshl_add_u64 v[218:219], s[56:57], 0, v[132:133]
	global_load_lds_dwordx4 v[216:217], off
	s_add_i32 m0, s45, 0x2000
	v_lshl_add_u64 v[216:217], s[46:47], 0, v[134:135]
	global_load_lds_dwordx4 v[216:217], off
	s_mov_b32 m0, s13
	v_lshl_add_u64 v[216:217], s[56:57], 0, v[130:131]
	global_load_lds_dwordx4 v[216:217], off
	s_mov_b32 m0, s24
	s_nop 0
	global_load_lds_dwordx4 v[218:219], off
	s_waitcnt vmcnt(8)
	s_waitcnt lgkmcnt(0)
	s_barrier
; #define PG8_STAGE(bufoff, gbase, voff) do { _Pragma("unroll") for (int _i = 0; _i < 2; ++_i) \
;         __builtin_amdgcn_global_load_lds((const unsigned*)((const char*)(gbase) + (voff)[_i]), (PG8_LAS unsigned*)(lds + (bufoff) + ldsw + _i * 8192), 16, 0, 0); } while (0)
; #define PG8_LDA(dst, b, h) do { _Pragma("unroll") for (int m = 0; m < 4; ++m) _Pragma("unroll") for (int k = 0; k < 2; ++k) dst[m][k] = *(const PG8_LAS bf16x8*)(lds + PG8_SA(b, h) + aoff + m * 2048 + k * 1024); } while (0)
; #define PG8_LDB(dst, b, h) do { _Pragma("unroll") for (int n = 0; n < 2; ++n) _Pragma("unroll") for (int k = 0; k < 2; ++k) dst[n][k] = *(const PG8_LAS bf16x8*)(lds + PG8_SB(b, h) + boff + n * 2048 + k * 1024); } while (0)
; #define PG8_MMA(ai, bj, At, Bt) do { __builtin_amdgcn_s_setprio(1); _Pragma("unroll") for (int m = 0; m < 4; ++m) _Pragma("unroll") for (int n = 0; n < 2; ++n) _Pragma("unroll") for (int k = 0; k < 2; ++k) \
;         acc[ai][bj][m][n] = __builtin_amdgcn_mfma_f32_16x16x32_bf16(Bt[n][k], At[m][k], acc[ai][bj][m][n], 0, 0, 0); __builtin_amdgcn_s_setprio(0); } while (0)
; template <class Epi, class Sched, bool ALIGN_EPI = false, bool SP2 = false, bool KHOOK = false>
; __device__ __forceinline__ void gemm_phase(PG8_LAS unsigned char* lds, const Gemm g, const Sched& S, const Epi& E, const int tid_in) {
;     ...
;             PG8_LDB(B0, 0, 0); PG8_LDB(B1, 0, 1); PG8_SCHED; PG8_LDA(At, 0, 0); PG8_STAGE(PG8_SA(1, 1), a1 + hstep, voffA);
;             PG8_WAIT_V(8); PG8_WAIT_L(0); PG8_BAR; PG8_MMA(0, 0, At, B0); PG8_MMA(0, 1, At, B1); PG8_BAR; PG8_SCHED;
;             PG8_LDA(At, 0, 1); PG8_STAGE(PG8_SB(0, 0), b2, voffB); PG8_STAGE(PG8_SB(0, 1), b2 + hstep, voffB); PG8_STAGE(PG8_SA(0, 0), a2, voffA);
;             PG8_WAIT_V(8); PG8_WAIT_L(0); PG8_BAR; PG8_MMA(1, 0, At, B0); PG8_MMA(1, 1, At, B1); PG8_BAR; PG8_SCHED;
;             PG8_LDB(B0, 1, 0); PG8_LDB(B1, 1, 1); PG8_SCHED; PG8_LDA(At, 1, 0); PG8_STAGE(PG8_SA(0, 1), a2 + hstep, voffA);
;             PG8_WAIT_V(8); PG8_WAIT_L(0); PG8_BAR; PG8_MMA(0, 0, At, B0); PG8_MMA(0, 1, At, B1); PG8_BAR; PG8_SCHED;
;             PG8_LDA(At, 1, 1); PG8_STAGE(PG8_SB(1, 0), b3, voffB); PG8_STAGE(PG8_SB(1, 1), b3 + hstep, voffB); PG8_STAGE(PG8_SA(1, 0), a3, voffA);
;             PG8_WAIT_V(8); PG8_WAIT_L(0); PG8_BAR; PG8_MMA(1, 0, At, B0); PG8_MMA(1, 1, At, B1); PG8_BAR; PG8_SCHED;
	s_setprio 1
	s_waitcnt lgkmcnt(0)
	v_mfma_f32_16x16x32_bf16 v[62:65], v[144:147], v[176:179], v[62:65]
	v_mfma_f32_16x16x32_bf16 v[58:61], v[152:155], v[176:179], v[58:61]
	v_mfma_f32_16x16x32_bf16 v[54:57], v[144:147], v[184:187], v[54:57]
	v_mfma_f32_16x16x32_bf16 v[50:53], v[152:155], v[184:187], v[50:53]
	v_mfma_f32_16x16x32_bf16 v[38:41], v[144:147], v[198:201], v[38:41]
	v_mfma_f32_16x16x32_bf16 v[34:37], v[152:155], v[198:201], v[34:37]
	v_mfma_f32_16x16x32_bf16 v[20:23], v[144:147], v[206:209], v[20:23]
	v_mfma_f32_16x16x32_bf16 v[16:19], v[152:155], v[206:209], v[16:19]
	v_mfma_f32_16x16x32_bf16 v[62:65], v[148:151], v[180:183], v[62:65]
	v_mfma_f32_16x16x32_bf16 v[58:61], v[156:159], v[180:183], v[58:61]
	v_mfma_f32_16x16x32_bf16 v[54:57], v[148:151], v[188:191], v[54:57]
	v_mfma_f32_16x16x32_bf16 v[50:53], v[156:159], v[188:191], v[50:53]
	v_mfma_f32_16x16x32_bf16 v[38:41], v[148:151], v[202:205], v[38:41]
	v_mfma_f32_16x16x32_bf16 v[34:37], v[156:159], v[202:205], v[34:37]
	v_mfma_f32_16x16x32_bf16 v[20:23], v[148:151], v[210:213], v[20:23]
	v_mfma_f32_16x16x32_bf16 v[16:19], v[156:159], v[210:213], v[16:19]
	s_setprio 0
	s_setprio 1
	v_mfma_f32_16x16x32_bf16 v[46:49], v[160:163], v[176:179], v[46:49]
	v_mfma_f32_16x16x32_bf16 v[42:45], v[168:171], v[176:179], v[42:45]
	v_mfma_f32_16x16x32_bf16 v[28:31], v[160:163], v[184:187], v[28:31]
	v_mfma_f32_16x16x32_bf16 v[24:27], v[168:171], v[184:187], v[24:27]
	v_mfma_f32_16x16x32_bf16 v[12:15], v[160:163], v[198:201], v[12:15]
	v_mfma_f32_16x16x32_bf16 v[8:11], v[168:171], v[198:201], v[8:11]
	v_mfma_f32_16x16x32_bf16 v[4:7], v[160:163], v[206:209], v[4:7]
	v_mfma_f32_16x16x32_bf16 v[0:3], v[168:171], v[206:209], v[0:3]
	v_mfma_f32_16x16x32_bf16 v[46:49], v[164:167], v[180:183], v[46:49]
	v_mfma_f32_16x16x32_bf16 v[42:45], v[172:175], v[180:183], v[42:45]
	v_mfma_f32_16x16x32_bf16 v[28:31], v[164:167], v[188:191], v[28:31]
	v_mfma_f32_16x16x32_bf16 v[24:27], v[172:175], v[188:191], v[24:27]
	v_mfma_f32_16x16x32_bf16 v[12:15], v[164:167], v[202:205], v[12:15]
	v_mfma_f32_16x16x32_bf16 v[8:11], v[172:175], v[202:205], v[8:11]
	v_mfma_f32_16x16x32_bf16 v[4:7], v[164:167], v[210:213], v[4:7]
	v_mfma_f32_16x16x32_bf16 v[0:3], v[172:175], v[210:213], v[0:3]
	s_setprio 0
	s_barrier
	s_add_i32 s45, 0, 0x18000
	s_add_i32 s50, 0, 0x1c000
	v_add_u32_e32 v156, s45, v141
	v_add_u32_e32 v172, s50, v141
	ds_read_b128 v[144:147], v156
	ds_read_b128 v[148:151], v156 offset:1024
	ds_read_b128 v[152:155], v156 offset:2048
	ds_read_b128 v[156:159], v156 offset:3072
	ds_read_b128 v[160:163], v172
	ds_read_b128 v[164:167], v172 offset:1024
	ds_read_b128 v[168:171], v172 offset:2048
	ds_read_b128 v[172:175], v172 offset:3072
	s_add_u32 s46, s56, 0x80000
	s_addc_u32 s47, s57, 0
	s_mov_b32 m0, s25
	v_lshl_add_u64 v[220:221], s[46:47], 0, v[130:131]
	ds_read_b128 v[176:179], v143 offset:32768
	ds_read_b128 v[180:183], v143 offset:33792
	ds_read_b128 v[184:187], v143 offset:34816
	ds_read_b128 v[188:191], v143 offset:35840
	ds_read_b128 v[198:201], v143 offset:36864
	ds_read_b128 v[202:205], v143 offset:37888
	ds_read_b128 v[206:209], v143 offset:38912
	ds_read_b128 v[210:213], v143 offset:39936
	global_load_lds_dwordx4 v[220:221], off
	s_mov_b32 m0, s38
	v_lshl_add_u64 v[220:221], s[46:47], 0, v[132:133]
	global_load_lds_dwordx4 v[220:221], off
	s_waitcnt vmcnt(8)
	s_waitcnt lgkmcnt(0)
	s_barrier
	s_setprio 1
	s_waitcnt lgkmcnt(0)
	v_mfma_f32_16x16x32_bf16 v[126:129], v[144:147], v[176:179], v[126:129]
	v_mfma_f32_16x16x32_bf16 v[122:125], v[152:155], v[176:179], v[122:125]
	v_mfma_f32_16x16x32_bf16 v[118:121], v[144:147], v[184:187], v[118:121]
	v_mfma_f32_16x16x32_bf16 v[114:117], v[152:155], v[184:187], v[114:117]
	v_mfma_f32_16x16x32_bf16 v[102:105], v[144:147], v[198:201], v[102:105]
	v_mfma_f32_16x16x32_bf16 v[98:101], v[152:155], v[198:201], v[98:101]
	v_mfma_f32_16x16x32_bf16 v[86:89], v[144:147], v[206:209], v[86:89]
	v_mfma_f32_16x16x32_bf16 v[82:85], v[152:155], v[206:209], v[82:85]
	v_mfma_f32_16x16x32_bf16 v[126:129], v[148:151], v[180:183], v[126:129]
	v_mfma_f32_16x16x32_bf16 v[122:125], v[156:159], v[180:183], v[122:125]
	v_mfma_f32_16x16x32_bf16 v[118:121], v[148:151], v[188:191], v[118:121]
	v_mfma_f32_16x16x32_bf16 v[114:117], v[156:159], v[188:191], v[114:117]
	v_mfma_f32_16x16x32_bf16 v[102:105], v[148:151], v[202:205], v[102:105]
	v_mfma_f32_16x16x32_bf16 v[98:101], v[156:159], v[202:205], v[98:101]
	v_mfma_f32_16x16x32_bf16 v[86:89], v[148:151], v[210:213], v[86:89]
	v_mfma_f32_16x16x32_bf16 v[82:85], v[156:159], v[210:213], v[82:85]
	s_setprio 0
	s_setprio 1
	v_mfma_f32_16x16x32_bf16 v[110:113], v[160:163], v[176:179], v[110:113]
	v_mfma_f32_16x16x32_bf16 v[106:109], v[168:171], v[176:179], v[106:109]
	v_mfma_f32_16x16x32_bf16 v[94:97], v[160:163], v[184:187], v[94:97]
	v_mfma_f32_16x16x32_bf16 v[90:93], v[168:171], v[184:187], v[90:93]
	v_mfma_f32_16x16x32_bf16 v[78:81], v[160:163], v[198:201], v[78:81]
	v_mfma_f32_16x16x32_bf16 v[74:77], v[168:171], v[198:201], v[74:77]
	v_mfma_f32_16x16x32_bf16 v[70:73], v[160:163], v[206:209], v[70:73]
	v_mfma_f32_16x16x32_bf16 v[66:69], v[168:171], v[206:209], v[66:69]
	v_mfma_f32_16x16x32_bf16 v[110:113], v[164:167], v[180:183], v[110:113]
	v_mfma_f32_16x16x32_bf16 v[106:109], v[172:175], v[180:183], v[106:109]
	v_mfma_f32_16x16x32_bf16 v[94:97], v[164:167], v[188:191], v[94:97]
	v_mfma_f32_16x16x32_bf16 v[90:93], v[172:175], v[188:191], v[90:93]
	v_mfma_f32_16x16x32_bf16 v[78:81], v[164:167], v[202:205], v[78:81]
	v_mfma_f32_16x16x32_bf16 v[74:77], v[172:175], v[202:205], v[74:77]
	v_mfma_f32_16x16x32_bf16 v[70:73], v[164:167], v[210:213], v[70:73]
	v_mfma_f32_16x16x32_bf16 v[66:69], v[172:175], v[210:213], v[66:69]
	s_setprio 0
	s_barrier
; __device__ __forceinline__ unsigned cvt_pk_bf16(float lo, float hi) { const f32x2_t v = {lo, hi}; const bf16x2_t c = __builtin_convertvector(v, bf16x2_t); return __builtin_bit_cast(unsigned, c); }
; #define PG8_STAGE(bufoff, gbase, voff) do { _Pragma("unroll") for (int _i = 0; _i < 2; ++_i) \
;         __builtin_amdgcn_global_load_lds((const unsigned*)((const char*)(gbase) + (voff)[_i]), (PG8_LAS unsigned*)(lds + (bufoff) + ldsw + _i * 8192), 16, 0, 0); } while (0)
; #define PG8_BAR __builtin_amdgcn_s_barrier()
;     __device__ __forceinline__ void operator()(const f32x4 (&acc)[2][2][4][2], const Unit& u, int wr, int wc, int fr, int fq) const {
;     ...
;             for (int m = 0; m < 4; ++m) { bf16_t* rowp = O + (size_t)(row0 + ai * HALF + m * 16) * ldc + col0;
; #pragma unroll
;                 for (int bj = 0; bj < 2; ++bj) { const f32x4 v0 = acc[ai][bj][m][0], v1 = acc[ai][bj][m][1];
;                     u32x4 w; w.x = cvt_pk_bf16(v0[0], v0[1]); w.y = cvt_pk_bf16(v0[2], v0[3]); w.z = cvt_pk_bf16(v1[0], v1[1]); w.w = cvt_pk_bf16(v1[2], v1[3]);
;                     *(u32x4*)(rowp + bj * HALF) = w; } }
; template <class Epi, class Sched, bool ALIGN_EPI = false, bool SP2 = false, bool KHOOK = false>
; __device__ __forceinline__ void gemm_phase(PG8_LAS unsigned char* lds, const Gemm g, const Sched& S, const Epi& E, const int tid_in) {
;     ...
;             PG8_LDB(B0, 0, 0); PG8_LDB(B1, 0, 1); PG8_SCHED; PG8_LDA(At, 0, 0); PG8_STAGE(PG8_SA(1, 1), a1 + hstep, voffA);
;             PG8_WAIT_V(8); PG8_WAIT_L(0); PG8_BAR; PG8_MMA(0, 0, At, B0); PG8_MMA(0, 1, At, B1); PG8_BAR; PG8_SCHED;
;             PG8_LDA(At, 0, 1); PG8_STAGE(PG8_SB(0, 0), b2, voffB); PG8_STAGE(PG8_SB(0, 1), b2 + hstep, voffB); PG8_STAGE(PG8_SA(0, 0), a2, voffA);
;             PG8_WAIT_V(8); PG8_WAIT_L(0); PG8_BAR; PG8_MMA(1, 0, At, B0); PG8_MMA(1, 1, At, B1); PG8_BAR; PG8_SCHED;
;             PG8_LDB(B0, 1, 0); PG8_LDB(B1, 1, 1); PG8_SCHED; PG8_LDA(At, 1, 0); PG8_STAGE(PG8_SA(0, 1), a2 + hstep, voffA);
;             PG8_WAIT_V(8); PG8_WAIT_L(0); PG8_BAR; PG8_MMA(0, 0, At, B0); PG8_MMA(0, 1, At, B1); PG8_BAR; PG8_SCHED;
;             PG8_LDA(At, 1, 1); PG8_STAGE(PG8_SB(1, 0), b3, voffB); PG8_STAGE(PG8_SB(1, 1), b3 + hstep, voffB); PG8_STAGE(PG8_SA(1, 0), a3, voffA);
;             PG8_WAIT_V(8); PG8_WAIT_L(0); PG8_BAR; PG8_MMA(1, 0, At, B0); PG8_MMA(1, 1, At, B1); PG8_BAR; PG8_SCHED;
	s_add_i32 s45, s45, s37
	v_lshl_add_u64 v[192:193], v[192:193], 0, s[90:91]
	s_mov_b32 m0, s45
	ds_read_b128 v[176:179], v143 offset:49152
	ds_read_b128 v[180:183], v143 offset:50176
	ds_read_b128 v[184:187], v143 offset:51200
	ds_read_b128 v[188:191], v143 offset:52224
	ds_read_b128 v[198:201], v143 offset:53248
	ds_read_b128 v[202:205], v143 offset:54272
	ds_read_b128 v[206:209], v143 offset:55296
	ds_read_b128 v[210:213], v143 offset:56320
	global_load_lds_dwordx4 v[192:193], off
	s_add_i32 m0, s45, 0x2000
	s_add_u32 s46, s52, 0x80080
	v_lshl_add_u64 v[192:193], v[214:215], 0, s[90:91]
	s_addc_u32 s47, s53, 0
	s_add_i32 s45, s50, s37
	global_load_lds_dwordx4 v[192:193], off
	s_mov_b32 m0, s45
	v_lshl_add_u64 v[192:193], s[46:47], 0, v[32:33]
	global_load_lds_dwordx4 v[192:193], off
	s_add_i32 m0, s45, 0x2000
	v_lshl_add_u64 v[192:193], s[46:47], 0, v[134:135]
	global_load_lds_dwordx4 v[192:193], off
	s_mov_b32 m0, s39
	v_lshl_add_u64 v[192:193], v[216:217], 0, s[90:91]
	global_load_lds_dwordx4 v[192:193], off
	s_mov_b32 m0, s40
	v_lshl_add_u64 v[192:193], v[218:219], 0, s[90:91]
	global_load_lds_dwordx4 v[192:193], off
	v_lshl_add_u32 v246, s12, 8, v140
	v_lshl_or_b32 v222, s10, 8, v142
	v_lshlrev_b32_e32 v222, 1, v222
	v_mov_b32_e32 v223, 0
	v_mad_u64_u32 v[248:249], s[70:71], v246, s67, v[222:223]
	s_mov_b32 s72, 0xa2000
	s_mov_b32 s73, 0
	v_lshl_add_u64 v[248:249], v[248:249], 0, s[76:77]
	v_cvt_pk_bf16_f32 v126, v126, v127
	v_cvt_pk_bf16_f32 v127, v128, v129
	v_cvt_pk_bf16_f32 v128, v122, v123
	v_cvt_pk_bf16_f32 v129, v124, v125
	global_store_dwordx4 v[248:249], v[126:129], off
	v_cvt_pk_bf16_f32 v110, v110, v111
	v_cvt_pk_bf16_f32 v111, v112, v113
	v_cvt_pk_bf16_f32 v112, v106, v107
	v_cvt_pk_bf16_f32 v113, v108, v109
	global_store_dwordx4 v[248:249], v[110:113], off offset:256
	v_lshl_add_u64 v[248:249], v[248:249], 0, s[72:73]
	v_cvt_pk_bf16_f32 v118, v118, v119
	v_cvt_pk_bf16_f32 v119, v120, v121
	v_cvt_pk_bf16_f32 v120, v114, v115
	v_cvt_pk_bf16_f32 v121, v116, v117
	global_store_dwordx4 v[248:249], v[118:121], off
	v_cvt_pk_bf16_f32 v94, v94, v95
	v_cvt_pk_bf16_f32 v95, v96, v97
	v_cvt_pk_bf16_f32 v96, v90, v91
	v_cvt_pk_bf16_f32 v97, v92, v93
	global_store_dwordx4 v[248:249], v[94:97], off offset:256
	v_lshl_add_u64 v[248:249], v[248:249], 0, s[72:73]
	v_cvt_pk_bf16_f32 v102, v102, v103
	v_cvt_pk_bf16_f32 v103, v104, v105
	v_cvt_pk_bf16_f32 v104, v98, v99
	v_cvt_pk_bf16_f32 v105, v100, v101
	global_store_dwordx4 v[248:249], v[102:105], off
	v_cvt_pk_bf16_f32 v78, v78, v79
	v_cvt_pk_bf16_f32 v79, v80, v81
	v_cvt_pk_bf16_f32 v80, v74, v75
	v_cvt_pk_bf16_f32 v81, v76, v77
	global_store_dwordx4 v[248:249], v[78:81], off offset:256
	v_lshl_add_u64 v[248:249], v[248:249], 0, s[72:73]
	v_cvt_pk_bf16_f32 v86, v86, v87
	v_cvt_pk_bf16_f32 v87, v88, v89
	v_cvt_pk_bf16_f32 v88, v82, v83
	v_cvt_pk_bf16_f32 v89, v84, v85
	global_store_dwordx4 v[248:249], v[86:89], off
	v_cvt_pk_bf16_f32 v70, v70, v71
	v_cvt_pk_bf16_f32 v71, v72, v73
	v_cvt_pk_bf16_f32 v72, v66, v67
	v_cvt_pk_bf16_f32 v73, v68, v69
	global_store_dwordx4 v[248:249], v[70:73], off offset:256
	s_waitcnt vmcnt(16)
	s_waitcnt lgkmcnt(0)
	s_barrier
	s_setprio 1
	s_waitcnt lgkmcnt(0)
	v_mfma_f32_16x16x32_bf16 v[62:65], v[144:147], v[176:179], v[62:65]
	v_mfma_f32_16x16x32_bf16 v[58:61], v[152:155], v[176:179], v[58:61]
	v_mfma_f32_16x16x32_bf16 v[54:57], v[144:147], v[184:187], v[54:57]
	v_mfma_f32_16x16x32_bf16 v[50:53], v[152:155], v[184:187], v[50:53]
	v_mfma_f32_16x16x32_bf16 v[38:41], v[144:147], v[198:201], v[38:41]
	v_mfma_f32_16x16x32_bf16 v[34:37], v[152:155], v[198:201], v[34:37]
	v_mfma_f32_16x16x32_bf16 v[20:23], v[144:147], v[206:209], v[20:23]
	v_mfma_f32_16x16x32_bf16 v[16:19], v[152:155], v[206:209], v[16:19]
	v_mfma_f32_16x16x32_bf16 v[62:65], v[148:151], v[180:183], v[62:65]
	v_mfma_f32_16x16x32_bf16 v[58:61], v[156:159], v[180:183], v[58:61]
	v_mfma_f32_16x16x32_bf16 v[54:57], v[148:151], v[188:191], v[54:57]
	v_mfma_f32_16x16x32_bf16 v[50:53], v[156:159], v[188:191], v[50:53]
	v_mfma_f32_16x16x32_bf16 v[38:41], v[148:151], v[202:205], v[38:41]
	v_mfma_f32_16x16x32_bf16 v[34:37], v[156:159], v[202:205], v[34:37]
	v_mfma_f32_16x16x32_bf16 v[20:23], v[148:151], v[210:213], v[20:23]
	v_mfma_f32_16x16x32_bf16 v[16:19], v[156:159], v[210:213], v[16:19]
	s_setprio 0
	s_setprio 1
	v_mfma_f32_16x16x32_bf16 v[46:49], v[160:163], v[176:179], v[46:49]
	v_mfma_f32_16x16x32_bf16 v[42:45], v[168:171], v[176:179], v[42:45]
	v_mfma_f32_16x16x32_bf16 v[28:31], v[160:163], v[184:187], v[28:31]
	v_mfma_f32_16x16x32_bf16 v[24:27], v[168:171], v[184:187], v[24:27]
	v_mfma_f32_16x16x32_bf16 v[12:15], v[160:163], v[198:201], v[12:15]
	v_mfma_f32_16x16x32_bf16 v[8:11], v[168:171], v[198:201], v[8:11]
	v_mfma_f32_16x16x32_bf16 v[4:7], v[160:163], v[206:209], v[4:7]
	v_mfma_f32_16x16x32_bf16 v[0:3], v[168:171], v[206:209], v[0:3]
	v_mfma_f32_16x16x32_bf16 v[46:49], v[164:167], v[180:183], v[46:49]
	v_mfma_f32_16x16x32_bf16 v[42:45], v[172:175], v[180:183], v[42:45]
	v_mfma_f32_16x16x32_bf16 v[28:31], v[164:167], v[188:191], v[28:31]
	v_mfma_f32_16x16x32_bf16 v[24:27], v[172:175], v[188:191], v[24:27]
	v_mfma_f32_16x16x32_bf16 v[12:15], v[164:167], v[202:205], v[12:15]
	v_mfma_f32_16x16x32_bf16 v[8:11], v[172:175], v[202:205], v[8:11]
	v_mfma_f32_16x16x32_bf16 v[4:7], v[164:167], v[210:213], v[4:7]
	v_mfma_f32_16x16x32_bf16 v[0:3], v[172:175], v[210:213], v[0:3]
	s_setprio 0
	s_barrier
	s_add_i32 s44, s44, 2
	s_add_u32 s48, s48, 0x100
	s_addc_u32 s49, s49, 0
	s_add_u32 s19, s19, 0x100
	s_addc_u32 s42, s42, 0
	s_mov_b32 s68, s12
	s_mov_b32 s69, s10
	s_mov_b32 s60, 1
	s_branch .LBB0_257

; #define GPROBE_BEGIN(id) do { if (((PROBE_GEMM_SEL >> (id)) & 1) && blockIdx.x == 0 && tid_in < 64 && g.N == 20480) { volatile PG8_LAS unsigned long long* PW_ = (volatile PG8_LAS unsigned long long*)(lds + 163840 - 512 + 64); PW_[0] = __builtin_amdgcn_s_memrealtime(); } } while (0)
; #define PG8_BAR __builtin_amdgcn_s_barrier()
; template <class Epi, class Sched, bool ALIGN_EPI = false, bool SP2 = false, bool KHOOK = false>
; __device__ __forceinline__ void gemm_phase(PG8_LAS unsigned char* lds, const Gemm g, const Sched& S, const Epi& E, const int tid_in) {
;     ...
;         const bool has_next = S.next(ui + 1, nxt);
;         const char* nA = has_next ? (const char*)g.A + (size_t)nxt.pm * tstep + (size_t)nxt.pn * ksl : cA; const char* nB = has_next ? (const char*)g.Bt + (size_t)nxt.pn * bts + (size_t)nxt.pn * ksl + (gdv ? (size_t)(nxt.pm / gdv) * gst : 0) : cB;
;         GPROBE_END(2); GPROBE_BEGIN(1);
;         for (int t = 0; t < nt; t += 2) {
;             const bool last = (t == nt - 2);
;             const char* a1 = cA + (size_t)(t + 1) * kstep;
;             const char* a2 = last ? nA : cA + (size_t)(t + 2) * kstep; const char* b2 = last ? nB : cB + (size_t)(t + 2) * kstep;
;             const char* a3 = a2 + kstep; const char* b3 = b2 + kstep;
;             if (last && has_next) S.a_ready(nxt);
;             if constexpr (SP2) {
;             PG8_LDB(B0, 0, 0); PG8_LDB(B1, 0, 1); PG8_SCHED; PG8_LDA(At, 0, 0); PG8_STAGE(PG8_SA(1, 1), a1 + hstep, voffA);
;             PG8_WAIT_V(8); PG8_WAIT_L(0); PG8_BAR; PG8_MMA(0, 0, At, B0); PG8_MMA(0, 1, At, B1); PG8_BAR; PG8_SCHED;
;             PG8_LDA(At, 0, 1); PG8_STAGE(PG8_SB(0, 0), b2, voffB); PG8_STAGE(PG8_SB(0, 1), b2 + hstep, voffB); PG8_STAGE(PG8_SA(0, 0), a2, voffA);
;             PG8_WAIT_V(8); PG8_WAIT_L(0); PG8_BAR; PG8_MMA(1, 0, At, B0); PG8_MMA(1, 1, At, B1); PG8_BAR; PG8_SCHED;
;             PG8_LDB(B0, 1, 0); PG8_LDB(B1, 1, 1); PG8_SCHED; PG8_LDA(At, 1, 0); PG8_STAGE(PG8_SA(0, 1), a2 + hstep, voffA);
;             PG8_WAIT_V(8); PG8_WAIT_L(0); PG8_BAR; PG8_MMA(0, 0, At, B0); PG8_MMA(0, 1, At, B1); PG8_BAR; PG8_SCHED;
;             PG8_LDA(At, 1, 1); PG8_STAGE(PG8_SB(1, 0), b3, voffB); PG8_STAGE(PG8_SB(1, 1), b3 + hstep, voffB); PG8_STAGE(PG8_SA(1, 0), a3, voffA);
;             PG8_WAIT_V(8); PG8_WAIT_L(0); PG8_BAR; PG8_MMA(1, 0, At, B0); PG8_MMA(1, 1, At, B1); PG8_BAR; PG8_SCHED;
.LBB0_416:
	s_ashr_i32 s13, s12, 31
	s_lshl_b64 s[22:23], s[12:13], 20
	s_add_u32 s13, s78, s22
	s_addc_u32 s23, s79, s23
	s_ashr_i32 s11, s10, 31
	s_lshl_b64 s[26:27], s[10:11], 9
	s_add_u32 s22, s13, s26
	s_addc_u32 s23, s23, s27
	s_and_b64 s[44:45], s[16:17], exec
	s_cselect_b32 s57, s23, s53
	s_cselect_b32 s56, s22, s52
	s_add_u32 s26, s2, s26
	s_addc_u32 s27, s18, s27
	s_and_b64 s[44:45], s[16:17], exec
	s_cselect_b32 s49, s27, s31
	s_cselect_b32 s48, s26, s30
	s_add_i32 s44, 0, 0x10000
	v_add_u32_e32 v132, s44, v71
	ds_read_b128 v[0:3], v132
	ds_read_b128 v[4:7], v132 offset:1024
	ds_read_b128 v[8:11], v132 offset:2048
	ds_read_b128 v[12:15], v132 offset:3072
	s_add_u32 s46, s52, 0x80080
	s_addc_u32 s47, s53, 0
	s_add_i32 s45, s20, 0xc000
	v_lshl_add_u64 v[50:51], s[46:47], 0, v[32:33]
	s_mov_b32 m0, s45
	s_add_i32 s11, s20, 0xe000
	ds_read_b128 v[16:19], v72
	ds_read_b128 v[20:23], v72 offset:1024
	ds_read_b128 v[24:27], v72 offset:2048
	ds_read_b128 v[28:31], v72 offset:3072
	ds_read_b128 v[34:37], v72 offset:4096
	ds_read_b128 v[38:41], v72 offset:5120
	ds_read_b128 v[42:45], v72 offset:6144
	ds_read_b128 v[46:49], v72 offset:7168
	global_load_lds_dwordx4 v[50:51], off
	s_mov_b32 m0, s11
	v_lshl_add_u64 v[50:51], s[46:47], 0, v[66:67]
	global_load_lds_dwordx4 v[50:51], off
	s_waitcnt vmcnt(8)
	s_waitcnt lgkmcnt(0)
	s_barrier
	s_setprio 1
	s_waitcnt lgkmcnt(0)
	v_mfma_f32_16x16x32_bf16 v[50:53], v[0:3], v[16:19], 0
	v_mfma_f32_16x16x32_bf16 v[16:19], v[8:11], v[16:19], 0
	v_mfma_f32_16x16x32_bf16 v[50:53], v[4:7], v[20:23], v[50:53]
	v_mfma_f32_16x16x32_bf16 v[16:19], v[12:15], v[20:23], v[16:19]
	v_mfma_f32_16x16x32_bf16 v[20:23], v[0:3], v[24:27], 0
	v_mfma_f32_16x16x32_bf16 v[24:27], v[8:11], v[24:27], 0
	v_mfma_f32_16x16x32_bf16 v[20:23], v[4:7], v[28:31], v[20:23]
	v_mfma_f32_16x16x32_bf16 v[24:27], v[12:15], v[28:31], v[24:27]
	v_mfma_f32_16x16x32_bf16 v[28:31], v[0:3], v[34:37], 0
	v_mfma_f32_16x16x32_bf16 v[34:37], v[8:11], v[34:37], 0
	v_mfma_f32_16x16x32_bf16 v[28:31], v[4:7], v[38:41], v[28:31]
	v_mfma_f32_16x16x32_bf16 v[34:37], v[12:15], v[38:41], v[34:37]
	v_mfma_f32_16x16x32_bf16 v[38:41], v[0:3], v[42:45], 0
	v_mfma_f32_16x16x32_bf16 v[42:45], v[8:11], v[42:45], 0
	v_mfma_f32_16x16x32_bf16 v[38:41], v[4:7], v[46:49], v[38:41]
	v_mfma_f32_16x16x32_bf16 v[42:45], v[12:15], v[46:49], v[42:45]
	s_setprio 0
	s_setprio 1
	s_setprio 0
	s_barrier
	s_add_i32 s44, s44, s19
	v_lshl_add_u64 v[122:123], s[30:31], 0, v[32:33]
	s_mov_b64 s[50:51], 0x100
	s_add_i32 s13, s44, 0x2000
	v_lshl_add_u64 v[90:91], v[122:123], 0, s[50:51]
	s_mov_b32 m0, s44
	v_lshl_add_u64 v[124:125], s[30:31], 0, v[66:67]
	s_add_u32 s46, s30, 0x80100
	ds_read_b128 v[46:49], v72 offset:16384
	ds_read_b128 v[54:57], v72 offset:17408
	ds_read_b128 v[58:61], v72 offset:18432
	ds_read_b128 v[62:65], v72 offset:19456
	ds_read_b128 v[74:77], v72 offset:20480
	ds_read_b128 v[78:81], v72 offset:21504
	ds_read_b128 v[82:85], v72 offset:22528
	ds_read_b128 v[86:89], v72 offset:23552
	global_load_lds_dwordx4 v[90:91], off
	v_lshl_add_u64 v[90:91], v[124:125], 0, s[50:51]
	s_mov_b32 m0, s13
	s_addc_u32 s47, s31, 0
	global_load_lds_dwordx4 v[90:91], off
	v_lshl_add_u64 v[90:91], s[46:47], 0, v[32:33]
	s_mov_b32 m0, s24
	v_lshl_add_u64 v[126:127], s[52:53], 0, v[32:33]
	global_load_lds_dwordx4 v[90:91], off
	v_lshl_add_u64 v[90:91], s[46:47], 0, v[66:67]
	s_mov_b32 m0, s25
	v_lshl_add_u64 v[128:129], s[52:53], 0, v[66:67]
	global_load_lds_dwordx4 v[90:91], off
	s_mov_b32 m0, s20
	v_lshl_add_u64 v[90:91], v[126:127], 0, s[50:51]
	global_load_lds_dwordx4 v[90:91], off
	s_mov_b32 m0, s33
	v_lshl_add_u64 v[90:91], v[128:129], 0, s[50:51]
	global_load_lds_dwordx4 v[90:91], off
	s_waitcnt vmcnt(8)
	s_waitcnt lgkmcnt(0)
	s_barrier
	s_setprio 1
	s_waitcnt lgkmcnt(0)
	v_mfma_f32_16x16x32_bf16 v[90:93], v[0:3], v[46:49], 0
	v_mfma_f32_16x16x32_bf16 v[46:49], v[8:11], v[46:49], 0
	v_mfma_f32_16x16x32_bf16 v[90:93], v[4:7], v[54:57], v[90:93]
	v_mfma_f32_16x16x32_bf16 v[46:49], v[12:15], v[54:57], v[46:49]
	v_mfma_f32_16x16x32_bf16 v[54:57], v[0:3], v[58:61], 0
	v_mfma_f32_16x16x32_bf16 v[58:61], v[8:11], v[58:61], 0
	v_mfma_f32_16x16x32_bf16 v[54:57], v[4:7], v[62:65], v[54:57]
	v_mfma_f32_16x16x32_bf16 v[58:61], v[12:15], v[62:65], v[58:61]
	v_mfma_f32_16x16x32_bf16 v[62:65], v[0:3], v[74:77], 0
	v_mfma_f32_16x16x32_bf16 v[0:3], v[0:3], v[82:85], 0
	v_mfma_f32_16x16x32_bf16 v[62:65], v[4:7], v[78:81], v[62:65]
	v_mfma_f32_16x16x32_bf16 v[0:3], v[4:7], v[86:89], v[0:3]
	v_mfma_f32_16x16x32_bf16 v[4:7], v[8:11], v[82:85], 0
	v_mfma_f32_16x16x32_bf16 v[74:77], v[8:11], v[74:77], 0
	v_mfma_f32_16x16x32_bf16 v[4:7], v[12:15], v[86:89], v[4:7]
	v_mfma_f32_16x16x32_bf16 v[74:77], v[12:15], v[78:81], v[74:77]
	s_setprio 0
	s_setprio 1
	s_setprio 0
	s_barrier
	s_add_i32 s42, 0, 0x18000
	v_add_u32_e32 v133, s42, v71
	ds_read_b128 v[8:11], v133
	ds_read_b128 v[12:15], v133 offset:1024
	ds_read_b128 v[78:81], v133 offset:2048
	ds_read_b128 v[82:85], v133 offset:3072
	s_add_u32 s46, s52, 0x80100
	s_addc_u32 s47, s53, 0
	s_mov_b32 m0, s36
	v_lshl_add_u64 v[130:131], s[46:47], 0, v[32:33]
	ds_read_b128 v[86:89], v72 offset:32768
	ds_read_b128 v[94:97], v72 offset:33792
	ds_read_b128 v[98:101], v72 offset:34816
	ds_read_b128 v[102:105], v72 offset:35840
	ds_read_b128 v[106:109], v72 offset:36864
	ds_read_b128 v[110:113], v72 offset:37888
	ds_read_b128 v[114:117], v72 offset:38912
	ds_read_b128 v[118:121], v72 offset:39936
	global_load_lds_dwordx4 v[130:131], off
	s_mov_b32 m0, s37
	v_lshl_add_u64 v[130:131], s[46:47], 0, v[66:67]
	global_load_lds_dwordx4 v[130:131], off
	s_waitcnt vmcnt(8)
	s_waitcnt lgkmcnt(0)
	s_barrier
; #define PG8_STAGE(bufoff, gbase, voff) do { _Pragma("unroll") for (int _i = 0; _i < 2; ++_i) \
;         __builtin_amdgcn_global_load_lds((const unsigned*)((const char*)(gbase) + (voff)[_i]), (PG8_LAS unsigned*)(lds + (bufoff) + ldsw + _i * 8192), 16, 0, 0); } while (0)
; #define PG8_LDA(dst, b, h) do { _Pragma("unroll") for (int m = 0; m < 4; ++m) _Pragma("unroll") for (int k = 0; k < 2; ++k) dst[m][k] = *(const PG8_LAS bf16x8*)(lds + PG8_SA(b, h) + aoff + m * 2048 + k * 1024); } while (0)
; #define PG8_WAIT_V(n) asm volatile("s_waitcnt vmcnt(" #n ")" ::: "memory")
; #define PG8_WAIT_L(n) asm volatile("s_waitcnt lgkmcnt(" #n ")" ::: "memory")
; template <class Epi, class Sched, bool ALIGN_EPI = false, bool SP2 = false, bool KHOOK = false>
; __device__ __forceinline__ void gemm_phase(PG8_LAS unsigned char* lds, const Gemm g, const Sched& S, const Epi& E, const int tid_in) {
;     ...
;         for (int t = 0; t < nt; t += 2) {
;             const bool last = (t == nt - 2);
;             const char* a1 = cA + (size_t)(t + 1) * kstep;
;             const char* a2 = last ? nA : cA + (size_t)(t + 2) * kstep; const char* b2 = last ? nB : cB + (size_t)(t + 2) * kstep;
;             const char* a3 = a2 + kstep; const char* b3 = b2 + kstep;
;             if (last && has_next) S.a_ready(nxt);
;             if constexpr (SP2) {
;             PG8_LDB(B0, 0, 0); PG8_LDB(B1, 0, 1); PG8_SCHED; PG8_LDA(At, 0, 0); PG8_STAGE(PG8_SA(1, 1), a1 + hstep, voffA);
;             PG8_WAIT_V(8); PG8_WAIT_L(0); PG8_BAR; PG8_MMA(0, 0, At, B0); PG8_MMA(0, 1, At, B1); PG8_BAR; PG8_SCHED;
;             PG8_LDA(At, 0, 1); PG8_STAGE(PG8_SB(0, 0), b2, voffB); PG8_STAGE(PG8_SB(0, 1), b2 + hstep, voffB); PG8_STAGE(PG8_SA(0, 0), a2, voffA);
;             PG8_WAIT_V(8); PG8_WAIT_L(0); PG8_BAR; PG8_MMA(1, 0, At, B0); PG8_MMA(1, 1, At, B1); PG8_BAR; PG8_SCHED;
;             PG8_LDB(B0, 1, 0); PG8_LDB(B1, 1, 1); PG8_SCHED; PG8_LDA(At, 1, 0); PG8_STAGE(PG8_SA(0, 1), a2 + hstep, voffA);
;             PG8_WAIT_V(8); PG8_WAIT_L(0); PG8_BAR; PG8_MMA(0, 0, At, B0); PG8_MMA(0, 1, At, B1); PG8_BAR; PG8_SCHED;
;             PG8_LDA(At, 1, 1); PG8_STAGE(PG8_SB(1, 0), b3, voffB); PG8_STAGE(PG8_SB(1, 1), b3 + hstep, voffB); PG8_STAGE(PG8_SA(1, 0), a3, voffA);
;             PG8_WAIT_V(8); PG8_WAIT_L(0); PG8_BAR; PG8_MMA(1, 0, At, B0); PG8_MMA(1, 1, At, B1); PG8_BAR; PG8_SCHED;
	s_setprio 1
	s_waitcnt lgkmcnt(0)
	v_mfma_f32_16x16x32_bf16 v[50:53], v[8:11], v[86:89], v[50:53]
	v_mfma_f32_16x16x32_bf16 v[16:19], v[78:81], v[86:89], v[16:19]
	v_mfma_f32_16x16x32_bf16 v[20:23], v[8:11], v[98:101], v[20:23]
	v_mfma_f32_16x16x32_bf16 v[24:27], v[78:81], v[98:101], v[24:27]
	v_mfma_f32_16x16x32_bf16 v[28:31], v[8:11], v[106:109], v[28:31]
	v_mfma_f32_16x16x32_bf16 v[34:37], v[78:81], v[106:109], v[34:37]
	v_mfma_f32_16x16x32_bf16 v[38:41], v[8:11], v[114:117], v[38:41]
	v_mfma_f32_16x16x32_bf16 v[42:45], v[78:81], v[114:117], v[42:45]
	v_mfma_f32_16x16x32_bf16 v[50:53], v[12:15], v[94:97], v[50:53]
	v_mfma_f32_16x16x32_bf16 v[16:19], v[82:85], v[94:97], v[16:19]
	v_mfma_f32_16x16x32_bf16 v[20:23], v[12:15], v[102:105], v[20:23]
	v_mfma_f32_16x16x32_bf16 v[24:27], v[82:85], v[102:105], v[24:27]
	v_mfma_f32_16x16x32_bf16 v[28:31], v[12:15], v[110:113], v[28:31]
	v_mfma_f32_16x16x32_bf16 v[34:37], v[82:85], v[110:113], v[34:37]
	v_mfma_f32_16x16x32_bf16 v[38:41], v[12:15], v[118:121], v[38:41]
	v_mfma_f32_16x16x32_bf16 v[42:45], v[82:85], v[118:121], v[42:45]
	s_setprio 0
	s_setprio 1
	s_setprio 0
	s_barrier
	s_add_i32 s46, s42, s19
	s_mov_b64 s[50:51], 0x180
	s_add_i32 s42, s46, 0x2000
	v_lshl_add_u64 v[122:123], v[122:123], 0, s[50:51]
	s_mov_b32 m0, s46
	s_add_u32 s30, s30, 0x80180
	ds_read_b128 v[86:89], v72 offset:49152
	ds_read_b128 v[94:97], v72 offset:50176
	ds_read_b128 v[98:101], v72 offset:51200
	ds_read_b128 v[102:105], v72 offset:52224
	ds_read_b128 v[106:109], v72 offset:53248
	ds_read_b128 v[110:113], v72 offset:54272
	ds_read_b128 v[114:117], v72 offset:55296
	ds_read_b128 v[118:121], v72 offset:56320
	global_load_lds_dwordx4 v[122:123], off
	v_lshl_add_u64 v[122:123], v[124:125], 0, s[50:51]
	s_mov_b32 m0, s42
	s_addc_u32 s31, s31, 0
	global_load_lds_dwordx4 v[122:123], off
	s_mov_b32 m0, s40
	v_lshl_add_u64 v[122:123], s[30:31], 0, v[32:33]
	global_load_lds_dwordx4 v[122:123], off
	s_mov_b32 m0, s41
	v_lshl_add_u64 v[122:123], s[30:31], 0, v[66:67]
	global_load_lds_dwordx4 v[122:123], off
	s_mov_b32 m0, s38
	v_lshl_add_u64 v[122:123], v[126:127], 0, s[50:51]
	global_load_lds_dwordx4 v[122:123], off
	s_mov_b32 m0, s39
	v_lshl_add_u64 v[122:123], v[128:129], 0, s[50:51]
	global_load_lds_dwordx4 v[122:123], off
	s_waitcnt vmcnt(8)
	s_waitcnt lgkmcnt(0)
	s_barrier
	s_setprio 1
	s_waitcnt lgkmcnt(0)
	v_mfma_f32_16x16x32_bf16 v[46:49], v[78:81], v[86:89], v[46:49]
	v_mfma_f32_16x16x32_bf16 v[54:57], v[8:11], v[98:101], v[54:57]
	v_mfma_f32_16x16x32_bf16 v[58:61], v[78:81], v[98:101], v[58:61]
	v_mfma_f32_16x16x32_bf16 v[62:65], v[8:11], v[106:109], v[62:65]
	v_mfma_f32_16x16x32_bf16 v[0:3], v[8:11], v[114:117], v[0:3]
	v_mfma_f32_16x16x32_bf16 v[4:7], v[78:81], v[114:117], v[4:7]
	v_mfma_f32_16x16x32_bf16 v[90:93], v[8:11], v[86:89], v[90:93]
	v_mfma_f32_16x16x32_bf16 v[46:49], v[82:85], v[94:97], v[46:49]
	v_mfma_f32_16x16x32_bf16 v[54:57], v[12:15], v[102:105], v[54:57]
	v_mfma_f32_16x16x32_bf16 v[58:61], v[82:85], v[102:105], v[58:61]
	v_mfma_f32_16x16x32_bf16 v[62:65], v[12:15], v[110:113], v[62:65]
	v_mfma_f32_16x16x32_bf16 v[74:77], v[78:81], v[106:109], v[74:77]
	v_mfma_f32_16x16x32_bf16 v[0:3], v[12:15], v[118:121], v[0:3]
	v_mfma_f32_16x16x32_bf16 v[4:7], v[82:85], v[118:121], v[4:7]
	v_mfma_f32_16x16x32_bf16 v[90:93], v[12:15], v[94:97], v[90:93]
	v_mfma_f32_16x16x32_bf16 v[74:77], v[82:85], v[110:113], v[74:77]
	s_setprio 0
	s_setprio 1
	s_setprio 0
	s_barrier
	ds_read_b128 v[8:11], v132
	ds_read_b128 v[12:15], v132 offset:1024
	ds_read_b128 v[78:81], v132 offset:2048
	ds_read_b128 v[82:85], v132 offset:3072
	s_add_u32 s30, s52, 0x80180
	s_addc_u32 s31, s53, 0
	s_mov_b32 m0, s45
	v_lshl_add_u64 v[122:123], s[30:31], 0, v[32:33]
	ds_read_b128 v[86:89], v72
	ds_read_b128 v[94:97], v72 offset:1024
	ds_read_b128 v[98:101], v72 offset:2048
	ds_read_b128 v[102:105], v72 offset:3072
	ds_read_b128 v[106:109], v72 offset:4096
	ds_read_b128 v[110:113], v72 offset:5120
	ds_read_b128 v[114:117], v72 offset:6144
	ds_read_b128 v[118:121], v72 offset:7168
	global_load_lds_dwordx4 v[122:123], off
	s_mov_b32 m0, s11
	v_lshl_add_u64 v[122:123], s[30:31], 0, v[66:67]
	global_load_lds_dwordx4 v[122:123], off
	s_waitcnt vmcnt(8)
	s_waitcnt lgkmcnt(0)
	s_barrier
	s_setprio 1
	s_waitcnt lgkmcnt(0)
	v_mfma_f32_16x16x32_bf16 v[24:27], v[78:81], v[98:101], v[24:27]
	v_mfma_f32_16x16x32_bf16 v[50:53], v[8:11], v[86:89], v[50:53]
	v_mfma_f32_16x16x32_bf16 v[16:19], v[78:81], v[86:89], v[16:19]
	v_mfma_f32_16x16x32_bf16 v[86:89], v[82:85], v[102:105], v[24:27]
	v_mfma_f32_16x16x32_bf16 v[24:27], v[8:11], v[106:109], v[28:31]
	v_mfma_f32_16x16x32_bf16 v[50:53], v[12:15], v[94:97], v[50:53]
	v_mfma_f32_16x16x32_bf16 v[16:19], v[82:85], v[94:97], v[16:19]
	v_mfma_f32_16x16x32_bf16 v[94:97], v[12:15], v[110:113], v[24:27]
	v_mfma_f32_16x16x32_bf16 v[24:27], v[78:81], v[106:109], v[34:37]
	v_mfma_f32_16x16x32_bf16 v[34:37], v[82:85], v[110:113], v[24:27]
	v_mfma_f32_16x16x32_bf16 v[24:27], v[8:11], v[114:117], v[38:41]
	v_mfma_f32_16x16x32_bf16 v[20:23], v[8:11], v[98:101], v[20:23]
	v_mfma_f32_16x16x32_bf16 v[38:41], v[12:15], v[118:121], v[24:27]
	v_mfma_f32_16x16x32_bf16 v[24:27], v[78:81], v[114:117], v[42:45]
	v_mfma_f32_16x16x32_bf16 v[20:23], v[12:15], v[102:105], v[20:23]
	v_mfma_f32_16x16x32_bf16 v[42:45], v[82:85], v[118:121], v[24:27]
	s_setprio 0
	s_setprio 1
	s_setprio 0
	s_barrier
; #define PG8_STAGE(bufoff, gbase, voff) do { _Pragma("unroll") for (int _i = 0; _i < 2; ++_i) \
;         __builtin_amdgcn_global_load_lds((const unsigned*)((const char*)(gbase) + (voff)[_i]), (PG8_LAS unsigned*)(lds + (bufoff) + ldsw + _i * 8192), 16, 0, 0); } while (0)
; #define PG8_LDA(dst, b, h) do { _Pragma("unroll") for (int m = 0; m < 4; ++m) _Pragma("unroll") for (int k = 0; k < 2; ++k) dst[m][k] = *(const PG8_LAS bf16x8*)(lds + PG8_SA(b, h) + aoff + m * 2048 + k * 1024); } while (0)
; #define PG8_LDB(dst, b, h) do { _Pragma("unroll") for (int n = 0; n < 2; ++n) _Pragma("unroll") for (int k = 0; k < 2; ++k) dst[n][k] = *(const PG8_LAS bf16x8*)(lds + PG8_SB(b, h) + boff + n * 2048 + k * 1024); } while (0)
; #define PG8_WAIT_V(n) asm volatile("s_waitcnt vmcnt(" #n ")" ::: "memory")
; #define PG8_WAIT_L(n) asm volatile("s_waitcnt lgkmcnt(" #n ")" ::: "memory")
; #define PG8_BAR __builtin_amdgcn_s_barrier()
; template <class Epi, class Sched, bool ALIGN_EPI = false, bool SP2 = false, bool KHOOK = false>
; __device__ __forceinline__ void gemm_phase(PG8_LAS unsigned char* lds, const Gemm g, const Sched& S, const Epi& E, const int tid_in) {
;     ...
;             PG8_LDB(B0, 0, 0); PG8_LDB(B1, 0, 1); PG8_SCHED; PG8_LDA(At, 0, 0); PG8_STAGE(PG8_SA(1, 1), a1 + hstep, voffA);
;             PG8_WAIT_V(8); PG8_WAIT_L(0); PG8_BAR; PG8_MMA(0, 0, At, B0); PG8_MMA(0, 1, At, B1); PG8_BAR; PG8_SCHED;
;             PG8_LDA(At, 0, 1); PG8_STAGE(PG8_SB(0, 0), b2, voffB); PG8_STAGE(PG8_SB(0, 1), b2 + hstep, voffB); PG8_STAGE(PG8_SA(0, 0), a2, voffA);
;             PG8_WAIT_V(8); PG8_WAIT_L(0); PG8_BAR; PG8_MMA(1, 0, At, B0); PG8_MMA(1, 1, At, B1); PG8_BAR; PG8_SCHED;
;             PG8_LDB(B0, 1, 0); PG8_LDB(B1, 1, 1); PG8_SCHED; PG8_LDA(At, 1, 0); PG8_STAGE(PG8_SA(0, 1), a2 + hstep, voffA);
;             PG8_WAIT_V(8); PG8_WAIT_L(0); PG8_BAR; PG8_MMA(0, 0, At, B0); PG8_MMA(0, 1, At, B1); PG8_BAR; PG8_SCHED;
;             PG8_LDA(At, 1, 1); PG8_STAGE(PG8_SB(1, 0), b3, voffB); PG8_STAGE(PG8_SB(1, 1), b3 + hstep, voffB); PG8_STAGE(PG8_SA(1, 0), a3, voffA);
;             PG8_WAIT_V(8); PG8_WAIT_L(0); PG8_BAR; PG8_MMA(1, 0, At, B0); PG8_MMA(1, 1, At, B1); PG8_BAR; PG8_SCHED;
;     ...
;         if constexpr (ALIGN_EPI) { if (wr == 0) PG8_BAR; }
;         if constexpr (!Epi::AFTER_DRAIN) { E(acc, cur, wr, wc, fr, fq); S.done(cur); }
;         if (!has_next) break;
	s_mov_b32 m0, s44
	v_lshl_add_u64 v[134:135], s[48:49], 0, v[32:33]
	s_add_u32 s30, s48, 0x80000
	ds_read_b128 v[24:27], v72 offset:16384
	ds_read_b128 v[28:31], v72 offset:17408
	ds_read_b128 v[98:101], v72 offset:18432
	ds_read_b128 v[102:105], v72 offset:19456
	ds_read_b128 v[106:109], v72 offset:20480
	ds_read_b128 v[110:113], v72 offset:21504
	ds_read_b128 v[114:117], v72 offset:22528
	ds_read_b128 v[118:121], v72 offset:23552
	global_load_lds_dwordx4 v[134:135], off
	v_lshl_add_u64 v[136:137], s[48:49], 0, v[66:67]
	s_mov_b32 m0, s13
	s_addc_u32 s31, s49, 0
	global_load_lds_dwordx4 v[136:137], off
	v_lshl_add_u64 v[122:123], s[30:31], 0, v[32:33]
	s_mov_b32 m0, s24
	v_lshl_add_u64 v[138:139], s[56:57], 0, v[32:33]
	global_load_lds_dwordx4 v[122:123], off
	v_lshl_add_u64 v[122:123], s[30:31], 0, v[66:67]
	s_mov_b32 m0, s25
	v_lshl_add_u64 v[140:141], s[56:57], 0, v[66:67]
	global_load_lds_dwordx4 v[122:123], off
	s_mov_b32 m0, s20
	s_nop 0
	global_load_lds_dwordx4 v[138:139], off
	s_mov_b32 m0, s33
	s_nop 0
	global_load_lds_dwordx4 v[140:141], off
	s_waitcnt vmcnt(8)
	s_waitcnt lgkmcnt(0)
	s_barrier
	s_setprio 1
	s_waitcnt lgkmcnt(0)
	v_mfma_f32_16x16x32_bf16 v[90:93], v[8:11], v[24:27], v[90:93]
	v_mfma_f32_16x16x32_bf16 v[24:27], v[78:81], v[24:27], v[46:49]
	v_mfma_f32_16x16x32_bf16 v[46:49], v[82:85], v[28:31], v[24:27]
	v_mfma_f32_16x16x32_bf16 v[24:27], v[8:11], v[98:101], v[54:57]
	v_mfma_f32_16x16x32_bf16 v[54:57], v[12:15], v[102:105], v[24:27]
	v_mfma_f32_16x16x32_bf16 v[24:27], v[78:81], v[98:101], v[58:61]
	v_mfma_f32_16x16x32_bf16 v[98:101], v[82:85], v[102:105], v[24:27]
	v_mfma_f32_16x16x32_bf16 v[24:27], v[8:11], v[106:109], v[62:65]
	v_mfma_f32_16x16x32_bf16 v[0:3], v[8:11], v[114:117], v[0:3]
	v_mfma_f32_16x16x32_bf16 v[102:105], v[12:15], v[110:113], v[24:27]
	v_mfma_f32_16x16x32_bf16 v[24:27], v[78:81], v[106:109], v[74:77]
	v_mfma_f32_16x16x32_bf16 v[106:109], v[12:15], v[118:121], v[0:3]
	v_mfma_f32_16x16x32_bf16 v[0:3], v[78:81], v[114:117], v[4:7]
	v_mfma_f32_16x16x32_bf16 v[90:93], v[12:15], v[28:31], v[90:93]
	v_mfma_f32_16x16x32_bf16 v[74:77], v[82:85], v[110:113], v[24:27]
	v_mfma_f32_16x16x32_bf16 v[78:81], v[82:85], v[118:121], v[0:3]
	s_setprio 0
	s_setprio 1
	s_setprio 0
	s_barrier
	ds_read_b128 v[82:85], v133
	ds_read_b128 v[110:113], v133 offset:1024
	ds_read_b128 v[114:117], v133 offset:2048
	ds_read_b128 v[118:121], v133 offset:3072
	s_add_u32 s30, s56, 0x80000
	s_addc_u32 s31, s57, 0
	s_mov_b32 m0, s36
	v_lshl_add_u64 v[24:25], s[30:31], 0, v[32:33]
	ds_read_b128 v[0:3], v72 offset:32768
	ds_read_b128 v[4:7], v72 offset:33792
	ds_read_b128 v[8:11], v72 offset:34816
	ds_read_b128 v[12:15], v72 offset:35840
	ds_read_b128 v[58:61], v72 offset:36864
	ds_read_b128 v[62:65], v72 offset:37888
	ds_read_b128 v[122:125], v72 offset:38912
	ds_read_b128 v[126:129], v72 offset:39936
	global_load_lds_dwordx4 v[24:25], off
	s_mov_b32 m0, s37
	v_lshl_add_u64 v[24:25], s[30:31], 0, v[66:67]
	global_load_lds_dwordx4 v[24:25], off
	s_waitcnt vmcnt(8)
	s_waitcnt lgkmcnt(0)
	s_barrier
	s_setprio 1
	s_waitcnt lgkmcnt(0)
	v_mfma_f32_16x16x32_bf16 v[24:27], v[82:85], v[0:3], v[50:53]
	v_mfma_f32_16x16x32_bf16 v[0:3], v[114:117], v[0:3], v[16:19]
	v_mfma_f32_16x16x32_bf16 v[28:31], v[118:121], v[4:7], v[0:3]
	v_mfma_f32_16x16x32_bf16 v[0:3], v[82:85], v[8:11], v[20:23]
	v_mfma_f32_16x16x32_bf16 v[16:19], v[110:113], v[12:15], v[0:3]
	v_mfma_f32_16x16x32_bf16 v[0:3], v[114:117], v[8:11], v[86:89]
	v_mfma_f32_16x16x32_bf16 v[20:23], v[118:121], v[12:15], v[0:3]
	v_mfma_f32_16x16x32_bf16 v[0:3], v[82:85], v[58:61], v[94:97]
	v_mfma_f32_16x16x32_bf16 v[8:11], v[110:113], v[62:65], v[0:3]
	v_mfma_f32_16x16x32_bf16 v[0:3], v[114:117], v[58:61], v[34:37]
	v_mfma_f32_16x16x32_bf16 v[24:27], v[110:113], v[4:7], v[24:27]
	v_mfma_f32_16x16x32_bf16 v[12:15], v[118:121], v[62:65], v[0:3]
	v_mfma_f32_16x16x32_bf16 v[0:3], v[82:85], v[122:125], v[38:41]
	v_mfma_f32_16x16x32_bf16 v[4:7], v[114:117], v[122:125], v[42:45]
	v_mfma_f32_16x16x32_bf16 v[0:3], v[110:113], v[126:129], v[0:3]
	v_mfma_f32_16x16x32_bf16 v[4:7], v[118:121], v[126:129], v[4:7]
	s_setprio 0
	s_setprio 1
	s_setprio 0
	s_barrier
	s_mov_b32 m0, s46
	v_lshl_add_u64 v[50:51], v[134:135], 0, s[90:91]
	s_add_u32 s30, s48, 0x80080
	ds_read_b128 v[34:37], v72 offset:49152
	ds_read_b128 v[38:41], v72 offset:50176
	ds_read_b128 v[42:45], v72 offset:51200
	ds_read_b128 v[86:89], v72 offset:52224
	ds_read_b128 v[94:97], v72 offset:53248
	ds_read_b128 v[122:125], v72 offset:54272
	ds_read_b128 v[126:129], v72 offset:55296
	ds_read_b128 v[130:133], v72 offset:56320
	global_load_lds_dwordx4 v[50:51], off
	v_lshl_add_u64 v[50:51], v[136:137], 0, s[90:91]
	s_mov_b32 m0, s42
	s_addc_u32 s31, s49, 0
	global_load_lds_dwordx4 v[50:51], off
	s_mov_b32 m0, s40
	v_lshl_add_u64 v[50:51], s[30:31], 0, v[32:33]
	global_load_lds_dwordx4 v[50:51], off
	s_mov_b32 m0, s41
	v_lshl_add_u64 v[50:51], s[30:31], 0, v[66:67]
	global_load_lds_dwordx4 v[50:51], off
	s_mov_b32 m0, s38
	v_lshl_add_u64 v[50:51], v[138:139], 0, s[90:91]
	global_load_lds_dwordx4 v[50:51], off
	s_mov_b32 m0, s39
	v_lshl_add_u64 v[50:51], v[140:141], 0, s[90:91]
	global_load_lds_dwordx4 v[50:51], off
	s_waitcnt vmcnt(8)
	s_waitcnt lgkmcnt(0)
	s_barrier
	s_setprio 1
	s_waitcnt lgkmcnt(0)
	v_mfma_f32_16x16x32_bf16 v[50:53], v[82:85], v[34:37], v[90:93]
	v_mfma_f32_16x16x32_bf16 v[34:37], v[114:117], v[34:37], v[46:49]
	v_mfma_f32_16x16x32_bf16 v[62:65], v[118:121], v[38:41], v[34:37]
	v_mfma_f32_16x16x32_bf16 v[34:37], v[82:85], v[42:45], v[54:57]
	v_mfma_f32_16x16x32_bf16 v[58:61], v[110:113], v[38:41], v[50:53]
	v_mfma_f32_16x16x32_bf16 v[50:53], v[110:113], v[86:89], v[34:37]
	v_mfma_f32_16x16x32_bf16 v[34:37], v[114:117], v[42:45], v[98:101]
	v_mfma_f32_16x16x32_bf16 v[54:57], v[118:121], v[86:89], v[34:37]
	v_mfma_f32_16x16x32_bf16 v[34:37], v[82:85], v[94:97], v[102:105]
	v_mfma_f32_16x16x32_bf16 v[42:45], v[110:113], v[122:125], v[34:37]
	v_mfma_f32_16x16x32_bf16 v[34:37], v[114:117], v[94:97], v[74:77]
	v_mfma_f32_16x16x32_bf16 v[46:49], v[118:121], v[122:125], v[34:37]
	v_mfma_f32_16x16x32_bf16 v[34:37], v[82:85], v[126:129], v[106:109]
	v_mfma_f32_16x16x32_bf16 v[38:41], v[114:117], v[126:129], v[78:81]
	v_mfma_f32_16x16x32_bf16 v[34:37], v[110:113], v[130:133], v[34:37]
	v_mfma_f32_16x16x32_bf16 v[38:41], v[118:121], v[130:133], v[38:41]
	s_setprio 0
	s_setprio 1
	s_setprio 0
	s_barrier
	s_andn2_b64 vcc, exec, s[4:5]
	s_cbranch_vccnz .LBB0_421
	s_barrier
	s_andn2_b64 vcc, exec, s[6:7]
	s_cbranch_vccz .LBB0_422

; #define GPROBE_BEGIN(id) do { if (((PROBE_GEMM_SEL >> (id)) & 1) && blockIdx.x == 0 && tid_in < 64 && g.N == 20480) { volatile PG8_LAS unsigned long long* PW_ = (volatile PG8_LAS unsigned long long*)(lds + 163840 - 512 + 64); PW_[0] = __builtin_amdgcn_s_memrealtime(); } } while (0)
; #define PG8_BAR __builtin_amdgcn_s_barrier()
; template <class Epi, class Sched, bool ALIGN_EPI = false, bool SP2 = false, bool KHOOK = false>
; __device__ __forceinline__ void gemm_phase(PG8_LAS unsigned char* lds, const Gemm g, const Sched& S, const Epi& E, const int tid_in) {
;     ...
;         const bool has_next = S.next(ui + 1, nxt);
;         const char* nA = has_next ? (const char*)g.A + (size_t)nxt.pm * tstep + (size_t)nxt.pn * ksl : cA; const char* nB = has_next ? (const char*)g.Bt + (size_t)nxt.pn * bts + (size_t)nxt.pn * ksl + (gdv ? (size_t)(nxt.pm / gdv) * gst : 0) : cB;
;         GPROBE_END(2); GPROBE_BEGIN(1);
;         for (int t = 0; t < nt; t += 2) {
;             const bool last = (t == nt - 2);
;             const char* a1 = cA + (size_t)(t + 1) * kstep;
;             const char* a2 = last ? nA : cA + (size_t)(t + 2) * kstep; const char* b2 = last ? nB : cB + (size_t)(t + 2) * kstep;
;             const char* a3 = a2 + kstep; const char* b3 = b2 + kstep;
;             if (last && has_next) S.a_ready(nxt);
;             if constexpr (SP2) {
;             PG8_LDB(B0, 0, 0); PG8_LDB(B1, 0, 1); PG8_SCHED; PG8_LDA(At, 0, 0); PG8_STAGE(PG8_SA(1, 1), a1 + hstep, voffA);
;             PG8_WAIT_V(8); PG8_WAIT_L(0); PG8_BAR; PG8_MMA(0, 0, At, B0); PG8_MMA(0, 1, At, B1); PG8_BAR; PG8_SCHED;
;             PG8_LDA(At, 0, 1); PG8_STAGE(PG8_SB(0, 0), b2, voffB); PG8_STAGE(PG8_SB(0, 1), b2 + hstep, voffB); PG8_STAGE(PG8_SA(0, 0), a2, voffA);
;             PG8_WAIT_V(8); PG8_WAIT_L(0); PG8_BAR; PG8_MMA(1, 0, At, B0); PG8_MMA(1, 1, At, B1); PG8_BAR; PG8_SCHED;
;             PG8_LDB(B0, 1, 0); PG8_LDB(B1, 1, 1); PG8_SCHED; PG8_LDA(At, 1, 0); PG8_STAGE(PG8_SA(0, 1), a2 + hstep, voffA);
;             PG8_WAIT_V(8); PG8_WAIT_L(0); PG8_BAR; PG8_MMA(0, 0, At, B0); PG8_MMA(0, 1, At, B1); PG8_BAR; PG8_SCHED;
;             PG8_LDA(At, 1, 1); PG8_STAGE(PG8_SB(1, 0), b3, voffB); PG8_STAGE(PG8_SB(1, 1), b3 + hstep, voffB); PG8_STAGE(PG8_SA(1, 0), a3, voffA);
;             PG8_WAIT_V(8); PG8_WAIT_L(0); PG8_BAR; PG8_MMA(1, 0, At, B0); PG8_MMA(1, 1, At, B1); PG8_BAR; PG8_SCHED;
.LBB0_845:
	s_add_i32 s47, s47, 2
	s_add_u32 s26, s16, s22
	s_addc_u32 s27, s17, s23
	s_add_u32 s26, s26, 0x100
	s_addc_u32 s27, s27, 0
	s_add_u32 s48, s44, s22
	s_addc_u32 s49, s45, s23
	s_add_i32 s50, 0, 0x10000
	s_cmpk_eq_i32 s22, 0x1f00
	s_cselect_b32 s31, s9, s27
	s_cselect_b32 s30, s41, s26
	v_add_u32_e32 v32, s50, v187
	s_cselect_b32 s27, s7, s49
	s_cselect_b32 s26, s42, s48
	s_add_i32 s51, 0, 0x14000
	ds_read_b128 v[112:115], v32
	ds_read_b128 v[124:127], v32 offset:1024
	ds_read_b128 v[136:139], v32 offset:2048
	ds_read_b128 v[140:143], v32 offset:3072
	v_add_u32_e32 v32, s51, v187
	ds_read_b128 v[144:147], v32
	ds_read_b128 v[152:155], v32 offset:1024
	ds_read_b128 v[174:177], v32 offset:2048
	ds_read_b128 v[178:181], v32 offset:3072
	v_lshl_add_u64 v[34:35], v[100:101], 0, s[22:23]
	s_add_i32 m0, s20, 0xc000
	ds_read_b128 v[202:205], v190
	ds_read_b128 v[206:209], v190 offset:1024
	ds_read_b128 v[210:213], v190 offset:2048
	ds_read_b128 v[214:217], v190 offset:3072
	ds_read_b128 v[218:221], v190 offset:4096
	ds_read_b128 v[222:225], v190 offset:5120
	ds_read_b128 v[246:249], v190 offset:6144
	ds_read_b128 v[198:201], v190 offset:7168
	global_load_lds_dwordx4 v[34:35], off
	s_add_i32 m0, s20, 0xe000
	v_lshl_add_u64 v[34:35], v[102:103], 0, s[22:23]
	global_load_lds_dwordx4 v[34:35], off
	s_waitcnt vmcnt(8)
	s_waitcnt lgkmcnt(0)
	s_barrier
	s_setprio 1
	s_waitcnt lgkmcnt(0)
	v_mfma_f32_16x16x32_bf16 v[156:159], v[112:115], v[202:205], v[156:159]
	v_mfma_f32_16x16x32_bf16 v[148:151], v[136:139], v[202:205], v[148:151]
	v_mfma_f32_16x16x32_bf16 v[120:123], v[112:115], v[210:213], v[120:123]
	v_mfma_f32_16x16x32_bf16 v[116:119], v[136:139], v[210:213], v[116:119]
	v_mfma_f32_16x16x32_bf16 v[96:99], v[112:115], v[218:221], v[96:99]
	v_mfma_f32_16x16x32_bf16 v[92:95], v[136:139], v[218:221], v[92:95]
	v_mfma_f32_16x16x32_bf16 v[80:83], v[112:115], v[246:249], v[80:83]
	v_mfma_f32_16x16x32_bf16 v[76:79], v[136:139], v[246:249], v[76:79]
	v_mfma_f32_16x16x32_bf16 v[156:159], v[124:127], v[206:209], v[156:159]
	v_mfma_f32_16x16x32_bf16 v[148:151], v[140:143], v[206:209], v[148:151]
	v_mfma_f32_16x16x32_bf16 v[120:123], v[124:127], v[214:217], v[120:123]
	v_mfma_f32_16x16x32_bf16 v[116:119], v[140:143], v[214:217], v[116:119]
	v_mfma_f32_16x16x32_bf16 v[96:99], v[124:127], v[222:225], v[96:99]
	v_mfma_f32_16x16x32_bf16 v[92:95], v[140:143], v[222:225], v[92:95]
	v_mfma_f32_16x16x32_bf16 v[80:83], v[124:127], v[198:201], v[80:83]
	v_mfma_f32_16x16x32_bf16 v[76:79], v[140:143], v[198:201], v[76:79]
	s_setprio 0
	s_setprio 1
	v_mfma_f32_16x16x32_bf16 v[132:135], v[144:147], v[202:205], v[132:135]
	v_mfma_f32_16x16x32_bf16 v[128:131], v[174:177], v[202:205], v[128:131]
	v_mfma_f32_16x16x32_bf16 v[108:111], v[144:147], v[210:213], v[108:111]
	v_mfma_f32_16x16x32_bf16 v[104:107], v[174:177], v[210:213], v[104:107]
	v_mfma_f32_16x16x32_bf16 v[88:91], v[144:147], v[218:221], v[88:91]
	v_mfma_f32_16x16x32_bf16 v[84:87], v[174:177], v[218:221], v[84:87]
	v_mfma_f32_16x16x32_bf16 v[72:75], v[144:147], v[246:249], v[72:75]
	v_mfma_f32_16x16x32_bf16 v[68:71], v[174:177], v[246:249], v[68:71]
	v_mfma_f32_16x16x32_bf16 v[132:135], v[152:155], v[206:209], v[132:135]
	v_mfma_f32_16x16x32_bf16 v[128:131], v[178:181], v[206:209], v[128:131]
	v_mfma_f32_16x16x32_bf16 v[108:111], v[152:155], v[214:217], v[108:111]
	v_mfma_f32_16x16x32_bf16 v[104:107], v[178:181], v[214:217], v[104:107]
	v_mfma_f32_16x16x32_bf16 v[88:91], v[152:155], v[222:225], v[88:91]
	v_mfma_f32_16x16x32_bf16 v[84:87], v[178:181], v[222:225], v[84:87]
	v_mfma_f32_16x16x32_bf16 v[72:75], v[152:155], v[198:201], v[72:75]
	v_mfma_f32_16x16x32_bf16 v[68:71], v[178:181], v[198:201], v[68:71]
	s_setprio 0
	s_barrier
	s_add_i32 s48, s50, s19
	v_lshl_add_u64 v[182:183], s[26:27], 0, v[164:165]
	s_mov_b32 m0, s48
	ds_read_b128 v[198:201], v190 offset:16384
	ds_read_b128 v[202:205], v190 offset:17408
	ds_read_b128 v[206:209], v190 offset:18432
	ds_read_b128 v[210:213], v190 offset:19456
	ds_read_b128 v[214:217], v190 offset:20480
	ds_read_b128 v[218:221], v190 offset:21504
	ds_read_b128 v[222:225], v190 offset:22528
	ds_read_b128 v[246:249], v190 offset:23552
	global_load_lds_dwordx4 v[182:183], off
	s_add_i32 m0, s48, 0x2000
	s_add_u32 s48, s26, 0x100000
	v_lshl_add_u64 v[192:193], s[26:27], 0, v[160:161]
	s_addc_u32 s49, s27, 0
	s_add_i32 s50, s51, s19
	global_load_lds_dwordx4 v[192:193], off
	v_lshl_add_u64 v[34:35], s[48:49], 0, v[164:165]
	s_mov_b32 m0, s50
	v_lshl_add_u64 v[226:227], s[30:31], 0, v[166:167]
	global_load_lds_dwordx4 v[34:35], off
	v_lshl_add_u64 v[34:35], s[48:49], 0, v[160:161]
	s_add_i32 m0, s50, 0x2000
	v_lshl_add_u64 v[230:231], s[30:31], 0, v[162:163]
	global_load_lds_dwordx4 v[34:35], off
	s_mov_b32 m0, s20
	s_nop 0
	global_load_lds_dwordx4 v[226:227], off
	s_mov_b32 m0, s33
	s_nop 0
	global_load_lds_dwordx4 v[230:231], off
	s_waitcnt vmcnt(8)
	s_waitcnt lgkmcnt(0)
	s_barrier
; #define PG8_STAGE(bufoff, gbase, voff) do { _Pragma("unroll") for (int _i = 0; _i < 2; ++_i) \
;         __builtin_amdgcn_global_load_lds((const unsigned*)((const char*)(gbase) + (voff)[_i]), (PG8_LAS unsigned*)(lds + (bufoff) + ldsw + _i * 8192), 16, 0, 0); } while (0)
; #define PG8_LDA(dst, b, h) do { _Pragma("unroll") for (int m = 0; m < 4; ++m) _Pragma("unroll") for (int k = 0; k < 2; ++k) dst[m][k] = *(const PG8_LAS bf16x8*)(lds + PG8_SA(b, h) + aoff + m * 2048 + k * 1024); } while (0)
; #define PG8_LDB(dst, b, h) do { _Pragma("unroll") for (int n = 0; n < 2; ++n) _Pragma("unroll") for (int k = 0; k < 2; ++k) dst[n][k] = *(const PG8_LAS bf16x8*)(lds + PG8_SB(b, h) + boff + n * 2048 + k * 1024); } while (0)
; #define PG8_MMA(ai, bj, At, Bt) do { __builtin_amdgcn_s_setprio(1); _Pragma("unroll") for (int m = 0; m < 4; ++m) _Pragma("unroll") for (int n = 0; n < 2; ++n) _Pragma("unroll") for (int k = 0; k < 2; ++k) \
;         acc[ai][bj][m][n] = __builtin_amdgcn_mfma_f32_16x16x32_bf16(Bt[n][k], At[m][k], acc[ai][bj][m][n], 0, 0, 0); __builtin_amdgcn_s_setprio(0); } while (0)
; template <class Epi, class Sched, bool ALIGN_EPI = false, bool SP2 = false, bool KHOOK = false>
; __device__ __forceinline__ void gemm_phase(PG8_LAS unsigned char* lds, const Gemm g, const Sched& S, const Epi& E, const int tid_in) {
;     ...
;             PG8_LDB(B0, 0, 0); PG8_LDB(B1, 0, 1); PG8_SCHED; PG8_LDA(At, 0, 0); PG8_STAGE(PG8_SA(1, 1), a1 + hstep, voffA);
;             PG8_WAIT_V(8); PG8_WAIT_L(0); PG8_BAR; PG8_MMA(0, 0, At, B0); PG8_MMA(0, 1, At, B1); PG8_BAR; PG8_SCHED;
;             PG8_LDA(At, 0, 1); PG8_STAGE(PG8_SB(0, 0), b2, voffB); PG8_STAGE(PG8_SB(0, 1), b2 + hstep, voffB); PG8_STAGE(PG8_SA(0, 0), a2, voffA);
;             PG8_WAIT_V(8); PG8_WAIT_L(0); PG8_BAR; PG8_MMA(1, 0, At, B0); PG8_MMA(1, 1, At, B1); PG8_BAR; PG8_SCHED;
;             PG8_LDB(B0, 1, 0); PG8_LDB(B1, 1, 1); PG8_SCHED; PG8_LDA(At, 1, 0); PG8_STAGE(PG8_SA(0, 1), a2 + hstep, voffA);
;             PG8_WAIT_V(8); PG8_WAIT_L(0); PG8_BAR; PG8_MMA(0, 0, At, B0); PG8_MMA(0, 1, At, B1); PG8_BAR; PG8_SCHED;
;             PG8_LDA(At, 1, 1); PG8_STAGE(PG8_SB(1, 0), b3, voffB); PG8_STAGE(PG8_SB(1, 1), b3 + hstep, voffB); PG8_STAGE(PG8_SA(1, 0), a3, voffA);
;             PG8_WAIT_V(8); PG8_WAIT_L(0); PG8_BAR; PG8_MMA(1, 0, At, B0); PG8_MMA(1, 1, At, B1); PG8_BAR; PG8_SCHED;
	s_setprio 1
	s_waitcnt lgkmcnt(0)
	v_mfma_f32_16x16x32_bf16 v[64:67], v[112:115], v[198:201], v[64:67]
	v_mfma_f32_16x16x32_bf16 v[60:63], v[136:139], v[198:201], v[60:63]
	v_mfma_f32_16x16x32_bf16 v[48:51], v[112:115], v[206:209], v[48:51]
	v_mfma_f32_16x16x32_bf16 v[44:47], v[136:139], v[206:209], v[44:47]
	v_mfma_f32_16x16x32_bf16 v[28:31], v[112:115], v[214:217], v[28:31]
	v_mfma_f32_16x16x32_bf16 v[24:27], v[136:139], v[214:217], v[24:27]
	v_mfma_f32_16x16x32_bf16 v[12:15], v[112:115], v[222:225], v[12:15]
	v_mfma_f32_16x16x32_bf16 v[8:11], v[136:139], v[222:225], v[8:11]
	v_mfma_f32_16x16x32_bf16 v[64:67], v[124:127], v[202:205], v[64:67]
	v_mfma_f32_16x16x32_bf16 v[60:63], v[140:143], v[202:205], v[60:63]
	v_mfma_f32_16x16x32_bf16 v[48:51], v[124:127], v[210:213], v[48:51]
	v_mfma_f32_16x16x32_bf16 v[44:47], v[140:143], v[210:213], v[44:47]
	v_mfma_f32_16x16x32_bf16 v[28:31], v[124:127], v[218:221], v[28:31]
	v_mfma_f32_16x16x32_bf16 v[24:27], v[140:143], v[218:221], v[24:27]
	v_mfma_f32_16x16x32_bf16 v[12:15], v[124:127], v[246:249], v[12:15]
	v_mfma_f32_16x16x32_bf16 v[8:11], v[140:143], v[246:249], v[8:11]
	s_setprio 0
	s_setprio 1
	v_mfma_f32_16x16x32_bf16 v[56:59], v[144:147], v[198:201], v[56:59]
	v_mfma_f32_16x16x32_bf16 v[52:55], v[174:177], v[198:201], v[52:55]
	v_mfma_f32_16x16x32_bf16 v[40:43], v[144:147], v[206:209], v[40:43]
	v_mfma_f32_16x16x32_bf16 v[34:37], v[174:177], v[206:209], v[36:39]
	v_mfma_f32_16x16x32_bf16 v[20:23], v[144:147], v[214:217], v[20:23]
	v_mfma_f32_16x16x32_bf16 v[16:19], v[174:177], v[214:217], v[16:19]
	v_mfma_f32_16x16x32_bf16 v[4:7], v[144:147], v[222:225], v[4:7]
	v_mfma_f32_16x16x32_bf16 v[0:3], v[174:177], v[222:225], v[0:3]
	v_mfma_f32_16x16x32_bf16 v[56:59], v[152:155], v[202:205], v[56:59]
	v_mfma_f32_16x16x32_bf16 v[52:55], v[178:181], v[202:205], v[52:55]
	v_mfma_f32_16x16x32_bf16 v[40:43], v[152:155], v[210:213], v[40:43]
	v_mfma_f32_16x16x32_bf16 v[34:37], v[178:181], v[210:213], v[34:37]
	v_mfma_f32_16x16x32_bf16 v[20:23], v[152:155], v[218:221], v[20:23]
	v_mfma_f32_16x16x32_bf16 v[16:19], v[178:181], v[218:221], v[16:19]
	v_mfma_f32_16x16x32_bf16 v[4:7], v[152:155], v[246:249], v[4:7]
	v_mfma_f32_16x16x32_bf16 v[0:3], v[178:181], v[246:249], v[0:3]
	s_setprio 0
	s_barrier
	s_add_i32 s48, 0, 0x18000
	v_add_u32_e32 v32, s48, v187
	s_add_i32 s49, 0, 0x1c000
	ds_read_b128 v[112:115], v32
	ds_read_b128 v[124:127], v32 offset:1024
	ds_read_b128 v[136:139], v32 offset:2048
	ds_read_b128 v[140:143], v32 offset:3072
	v_add_u32_e32 v32, s49, v187
	ds_read_b128 v[144:147], v32
	ds_read_b128 v[152:155], v32 offset:1024
	ds_read_b128 v[174:177], v32 offset:2048
	ds_read_b128 v[178:181], v32 offset:3072
	s_add_u32 s30, s30, 0x100000
	s_addc_u32 s31, s31, 0
	s_mov_b32 m0, s36
	v_lshl_add_u64 v[38:39], s[30:31], 0, v[166:167]
	ds_read_b128 v[198:201], v190 offset:32768
	ds_read_b128 v[202:205], v190 offset:33792
	ds_read_b128 v[206:209], v190 offset:34816
	ds_read_b128 v[210:213], v190 offset:35840
	ds_read_b128 v[214:217], v190 offset:36864
	ds_read_b128 v[218:221], v190 offset:37888
	ds_read_b128 v[222:225], v190 offset:38912
	ds_read_b128 v[246:249], v190 offset:39936
	global_load_lds_dwordx4 v[38:39], off
	s_mov_b32 m0, s37
	v_lshl_add_u64 v[38:39], s[30:31], 0, v[162:163]
	global_load_lds_dwordx4 v[38:39], off
	s_waitcnt vmcnt(8)
	s_waitcnt lgkmcnt(0)
	s_barrier
	s_setprio 1
	s_waitcnt lgkmcnt(0)
	v_mfma_f32_16x16x32_bf16 v[156:159], v[112:115], v[198:201], v[156:159]
	v_mfma_f32_16x16x32_bf16 v[148:151], v[136:139], v[198:201], v[148:151]
	v_mfma_f32_16x16x32_bf16 v[120:123], v[112:115], v[206:209], v[120:123]
	v_mfma_f32_16x16x32_bf16 v[116:119], v[136:139], v[206:209], v[116:119]
	v_mfma_f32_16x16x32_bf16 v[96:99], v[112:115], v[214:217], v[96:99]
	v_mfma_f32_16x16x32_bf16 v[92:95], v[136:139], v[214:217], v[92:95]
	v_mfma_f32_16x16x32_bf16 v[80:83], v[112:115], v[222:225], v[80:83]
	v_mfma_f32_16x16x32_bf16 v[76:79], v[136:139], v[222:225], v[76:79]
	v_mfma_f32_16x16x32_bf16 v[156:159], v[124:127], v[202:205], v[156:159]
	v_mfma_f32_16x16x32_bf16 v[148:151], v[140:143], v[202:205], v[148:151]
	v_mfma_f32_16x16x32_bf16 v[120:123], v[124:127], v[210:213], v[120:123]
	v_mfma_f32_16x16x32_bf16 v[116:119], v[140:143], v[210:213], v[116:119]
	v_mfma_f32_16x16x32_bf16 v[96:99], v[124:127], v[218:221], v[96:99]
	v_mfma_f32_16x16x32_bf16 v[92:95], v[140:143], v[218:221], v[92:95]
	v_mfma_f32_16x16x32_bf16 v[80:83], v[124:127], v[246:249], v[80:83]
	v_mfma_f32_16x16x32_bf16 v[76:79], v[140:143], v[246:249], v[76:79]
	s_setprio 0
	s_setprio 1
	v_mfma_f32_16x16x32_bf16 v[132:135], v[144:147], v[198:201], v[132:135]
	v_mfma_f32_16x16x32_bf16 v[128:131], v[174:177], v[198:201], v[128:131]
	v_mfma_f32_16x16x32_bf16 v[108:111], v[144:147], v[206:209], v[108:111]
	v_mfma_f32_16x16x32_bf16 v[104:107], v[174:177], v[206:209], v[104:107]
	v_mfma_f32_16x16x32_bf16 v[88:91], v[144:147], v[214:217], v[88:91]
	v_mfma_f32_16x16x32_bf16 v[84:87], v[174:177], v[214:217], v[84:87]
	v_mfma_f32_16x16x32_bf16 v[72:75], v[144:147], v[222:225], v[72:75]
	v_mfma_f32_16x16x32_bf16 v[68:71], v[174:177], v[222:225], v[68:71]
	v_mfma_f32_16x16x32_bf16 v[132:135], v[152:155], v[202:205], v[132:135]
	v_mfma_f32_16x16x32_bf16 v[128:131], v[178:181], v[202:205], v[128:131]
	v_mfma_f32_16x16x32_bf16 v[108:111], v[152:155], v[210:213], v[108:111]
	v_mfma_f32_16x16x32_bf16 v[104:107], v[178:181], v[210:213], v[104:107]
	v_mfma_f32_16x16x32_bf16 v[88:91], v[152:155], v[218:221], v[88:91]
	v_mfma_f32_16x16x32_bf16 v[84:87], v[178:181], v[218:221], v[84:87]
	v_mfma_f32_16x16x32_bf16 v[72:75], v[152:155], v[246:249], v[72:75]
	v_mfma_f32_16x16x32_bf16 v[68:71], v[178:181], v[246:249], v[68:71]
	s_setprio 0
	s_barrier
; #define PG8_STAGE(bufoff, gbase, voff) do { _Pragma("unroll") for (int _i = 0; _i < 2; ++_i) \
;         __builtin_amdgcn_global_load_lds((const unsigned*)((const char*)(gbase) + (voff)[_i]), (PG8_LAS unsigned*)(lds + (bufoff) + ldsw + _i * 8192), 16, 0, 0); } while (0)
; #define PG8_LDA(dst, b, h) do { _Pragma("unroll") for (int m = 0; m < 4; ++m) _Pragma("unroll") for (int k = 0; k < 2; ++k) dst[m][k] = *(const PG8_LAS bf16x8*)(lds + PG8_SA(b, h) + aoff + m * 2048 + k * 1024); } while (0)
; #define PG8_MMA(ai, bj, At, Bt) do { __builtin_amdgcn_s_setprio(1); _Pragma("unroll") for (int m = 0; m < 4; ++m) _Pragma("unroll") for (int n = 0; n < 2; ++n) _Pragma("unroll") for (int k = 0; k < 2; ++k) \
;         acc[ai][bj][m][n] = __builtin_amdgcn_mfma_f32_16x16x32_bf16(Bt[n][k], At[m][k], acc[ai][bj][m][n], 0, 0, 0); __builtin_amdgcn_s_setprio(0); } while (0)
; #define PG8_WAIT_V(n) asm volatile("s_waitcnt vmcnt(" #n ")" ::: "memory")
; #define PG8_WAIT_L(n) asm volatile("s_waitcnt lgkmcnt(" #n ")" ::: "memory")
; #define PG8_BAR __builtin_amdgcn_s_barrier()
; #define PG8_SCHED __builtin_amdgcn_sched_barrier(0)
; template <class Epi, class Sched, bool ALIGN_EPI = false, bool SP2 = false, bool KHOOK = false>
; __device__ __forceinline__ void gemm_phase(PG8_LAS unsigned char* lds, const Gemm g, const Sched& S, const Epi& E, const int tid_in) {
;     ...
;             PG8_LDA(At, 1, 1); PG8_STAGE(PG8_SB(1, 0), b3, voffB); PG8_STAGE(PG8_SB(1, 1), b3 + hstep, voffB); PG8_STAGE(PG8_SA(1, 0), a3, voffA);
;             PG8_WAIT_V(8); PG8_WAIT_L(0); PG8_BAR; PG8_MMA(1, 0, At, B0); PG8_MMA(1, 1, At, B1); PG8_BAR; PG8_SCHED;
;             if constexpr (KHOOK) { if ((t & 7) == 6) {
	s_add_i32 s30, s48, s19
	v_lshl_add_u64 v[38:39], v[182:183], 0, s[90:91]
	s_mov_b32 m0, s30
	ds_read_b128 v[198:201], v190 offset:49152
	ds_read_b128 v[202:205], v190 offset:50176
	ds_read_b128 v[206:209], v190 offset:51200
	ds_read_b128 v[210:213], v190 offset:52224
	ds_read_b128 v[214:217], v190 offset:53248
	ds_read_b128 v[218:221], v190 offset:54272
	ds_read_b128 v[222:225], v190 offset:55296
	ds_read_b128 v[246:249], v190 offset:56320
	global_load_lds_dwordx4 v[38:39], off
	s_add_i32 m0, s30, 0x2000
	s_add_u32 s26, s26, 0x100080
	v_lshl_add_u64 v[38:39], v[192:193], 0, s[90:91]
	s_addc_u32 s27, s27, 0
	s_add_i32 s30, s49, s19
	global_load_lds_dwordx4 v[38:39], off
	s_mov_b32 m0, s30
	v_lshl_add_u64 v[38:39], s[26:27], 0, v[164:165]
	global_load_lds_dwordx4 v[38:39], off
	s_add_i32 m0, s30, 0x2000
	v_lshl_add_u64 v[38:39], s[26:27], 0, v[160:161]
	global_load_lds_dwordx4 v[38:39], off
	s_mov_b32 m0, s38
	v_lshl_add_u64 v[38:39], v[226:227], 0, s[90:91]
	global_load_lds_dwordx4 v[38:39], off
	s_mov_b32 m0, s39
	v_lshl_add_u64 v[38:39], v[230:231], 0, s[90:91]
	global_load_lds_dwordx4 v[38:39], off
	s_waitcnt vmcnt(8)
	s_waitcnt lgkmcnt(0)
	s_barrier
	s_setprio 1
	s_waitcnt lgkmcnt(0)
	v_mfma_f32_16x16x32_bf16 v[64:67], v[112:115], v[198:201], v[64:67]
	v_mfma_f32_16x16x32_bf16 v[60:63], v[136:139], v[198:201], v[60:63]
	v_mfma_f32_16x16x32_bf16 v[48:51], v[112:115], v[206:209], v[48:51]
	v_mfma_f32_16x16x32_bf16 v[44:47], v[136:139], v[206:209], v[44:47]
	v_mfma_f32_16x16x32_bf16 v[28:31], v[112:115], v[214:217], v[28:31]
	v_mfma_f32_16x16x32_bf16 v[24:27], v[136:139], v[214:217], v[24:27]
	v_mfma_f32_16x16x32_bf16 v[12:15], v[112:115], v[222:225], v[12:15]
	v_mfma_f32_16x16x32_bf16 v[8:11], v[136:139], v[222:225], v[8:11]
	v_mfma_f32_16x16x32_bf16 v[64:67], v[124:127], v[202:205], v[64:67]
	v_mfma_f32_16x16x32_bf16 v[60:63], v[140:143], v[202:205], v[60:63]
	v_mfma_f32_16x16x32_bf16 v[48:51], v[124:127], v[210:213], v[48:51]
	v_mfma_f32_16x16x32_bf16 v[44:47], v[140:143], v[210:213], v[44:47]
	v_mfma_f32_16x16x32_bf16 v[28:31], v[124:127], v[218:221], v[28:31]
	v_mfma_f32_16x16x32_bf16 v[24:27], v[140:143], v[218:221], v[24:27]
	v_mfma_f32_16x16x32_bf16 v[12:15], v[124:127], v[246:249], v[12:15]
	v_mfma_f32_16x16x32_bf16 v[8:11], v[140:143], v[246:249], v[8:11]
	s_setprio 0
	s_setprio 1
	v_mfma_f32_16x16x32_bf16 v[56:59], v[144:147], v[198:201], v[56:59]
	v_mfma_f32_16x16x32_bf16 v[52:55], v[174:177], v[198:201], v[52:55]
	v_mfma_f32_16x16x32_bf16 v[38:41], v[144:147], v[206:209], v[40:43]
	v_mfma_f32_16x16x32_bf16 v[34:37], v[174:177], v[206:209], v[34:37]
	v_mfma_f32_16x16x32_bf16 v[20:23], v[144:147], v[214:217], v[20:23]
	v_mfma_f32_16x16x32_bf16 v[16:19], v[174:177], v[214:217], v[16:19]
	v_mfma_f32_16x16x32_bf16 v[4:7], v[144:147], v[222:225], v[4:7]
	v_mfma_f32_16x16x32_bf16 v[0:3], v[174:177], v[222:225], v[0:3]
	v_mfma_f32_16x16x32_bf16 v[56:59], v[152:155], v[202:205], v[56:59]
	v_mfma_f32_16x16x32_bf16 v[52:55], v[178:181], v[202:205], v[52:55]
	v_mfma_f32_16x16x32_bf16 v[40:43], v[152:155], v[210:213], v[38:41]
	v_mfma_f32_16x16x32_bf16 v[36:39], v[178:181], v[210:213], v[34:37]
	v_mfma_f32_16x16x32_bf16 v[20:23], v[152:155], v[218:221], v[20:23]
	v_mfma_f32_16x16x32_bf16 v[16:19], v[178:181], v[218:221], v[16:19]
	v_mfma_f32_16x16x32_bf16 v[4:7], v[152:155], v[246:249], v[4:7]
	v_mfma_f32_16x16x32_bf16 v[0:3], v[178:181], v[246:249], v[0:3]
	s_setprio 0
	s_barrier
	s_and_b32 s26, s47, 6
	s_cmp_lg_u32 s26, 6
	s_cbranch_scc1 .LBB0_844
; #define PG8_LAS __attribute__((address_space(3)))
; template <class Epi, class Sched, bool ALIGN_EPI = false, bool SP2 = false, bool KHOOK = false>
; __device__ __forceinline__ void gemm_phase(PG8_LAS unsigned char* lds, const Gemm g, const Sched& S, const Epi& E, const int tid_in) {
;     ...
;             if constexpr (KHOOK) { if ((t & 7) == 6) {
;                 const PG8_LAS float* RT = (const PG8_LAS float*)(lds + 8 * 16384) + (t >> 3) * 256 + wr * 64 + fr; float f[2][4];
; #pragma unroll
;                 for (int a = 0; a < 2; ++a)
; #pragma unroll
;                     for (int m = 0; m < 4; ++m) f[a][m] = RT[a * HALF + m * 16];
; #pragma unroll
;                 for (int a = 0; a < 2; ++a)
; #pragma unroll
;                     for (int b = 0; b < 2; ++b)
; #pragma unroll
;                         for (int m = 0; m < 4; ++m)
; #pragma unroll
;                             for (int n = 0; n < 2; ++n) acc[a][b][m][n] *= f[a][m]; } }
	s_and_b32 s26, s46, 0x700
	v_lshl_add_u32 v32, s26, 2, v188
	ds_read2_b32 v[112:113], v32 offset1:16
	ds_read2_b32 v[114:115], v32 offset0:32 offset1:48
	ds_read2_b32 v[124:125], v32 offset0:128 offset1:144
	ds_read2_b32 v[34:35], v32 offset0:160 offset1:176
	s_waitcnt lgkmcnt(0)
	v_mov_b32_e32 v32, v113
	v_pk_mul_f32 v[158:159], v[158:159], v[112:113] op_sel_hi:[1,0]
	v_pk_mul_f32 v[156:157], v[156:157], v[112:113] op_sel_hi:[1,0]
	v_pk_mul_f32 v[150:151], v[150:151], v[112:113] op_sel_hi:[1,0]
	v_pk_mul_f32 v[148:149], v[148:149], v[112:113] op_sel_hi:[1,0]
	v_pk_mul_f32 v[122:123], v[122:123], v[32:33] op_sel_hi:[1,0]
	v_pk_mul_f32 v[120:121], v[120:121], v[32:33] op_sel_hi:[1,0]
	v_pk_mul_f32 v[118:119], v[118:119], v[32:33] op_sel_hi:[1,0]
	v_pk_mul_f32 v[116:117], v[116:117], v[32:33] op_sel_hi:[1,0]
	v_mov_b32_e32 v126, v115
	v_pk_mul_f32 v[134:135], v[134:135], v[112:113] op_sel_hi:[1,0]
	v_pk_mul_f32 v[132:133], v[132:133], v[112:113] op_sel_hi:[1,0]
	v_pk_mul_f32 v[130:131], v[130:131], v[112:113] op_sel_hi:[1,0]
	v_pk_mul_f32 v[128:129], v[128:129], v[112:113] op_sel_hi:[1,0]
	v_pk_mul_f32 v[110:111], v[110:111], v[32:33] op_sel_hi:[1,0]
	v_pk_mul_f32 v[108:109], v[108:109], v[32:33] op_sel_hi:[1,0]
	v_pk_mul_f32 v[106:107], v[106:107], v[32:33] op_sel_hi:[1,0]
	v_pk_mul_f32 v[104:105], v[104:105], v[32:33] op_sel_hi:[1,0]
	v_mov_b32_e32 v32, v125
	v_mov_b32_e32 v112, v35
	v_pk_mul_f32 v[98:99], v[98:99], v[114:115] op_sel_hi:[1,0]
	v_pk_mul_f32 v[96:97], v[96:97], v[114:115] op_sel_hi:[1,0]
	v_pk_mul_f32 v[94:95], v[94:95], v[114:115] op_sel_hi:[1,0]
	v_pk_mul_f32 v[92:93], v[92:93], v[114:115] op_sel_hi:[1,0]
	v_pk_mul_f32 v[82:83], v[82:83], v[126:127] op_sel_hi:[1,0]
	v_pk_mul_f32 v[80:81], v[80:81], v[126:127] op_sel_hi:[1,0]
	v_pk_mul_f32 v[78:79], v[78:79], v[126:127] op_sel_hi:[1,0]
	v_pk_mul_f32 v[76:77], v[76:77], v[126:127] op_sel_hi:[1,0]
	v_pk_mul_f32 v[90:91], v[90:91], v[114:115] op_sel_hi:[1,0]
	v_pk_mul_f32 v[88:89], v[88:89], v[114:115] op_sel_hi:[1,0]
	v_pk_mul_f32 v[86:87], v[86:87], v[114:115] op_sel_hi:[1,0]
	v_pk_mul_f32 v[84:85], v[84:85], v[114:115] op_sel_hi:[1,0]
	v_pk_mul_f32 v[74:75], v[74:75], v[126:127] op_sel_hi:[1,0]
	v_pk_mul_f32 v[72:73], v[72:73], v[126:127] op_sel_hi:[1,0]
	v_pk_mul_f32 v[70:71], v[70:71], v[126:127] op_sel_hi:[1,0]
	v_pk_mul_f32 v[68:69], v[68:69], v[126:127] op_sel_hi:[1,0]
	v_pk_mul_f32 v[66:67], v[66:67], v[124:125] op_sel_hi:[1,0]
	v_pk_mul_f32 v[64:65], v[64:65], v[124:125] op_sel_hi:[1,0]
	v_pk_mul_f32 v[62:63], v[62:63], v[124:125] op_sel_hi:[1,0]
	v_pk_mul_f32 v[60:61], v[60:61], v[124:125] op_sel_hi:[1,0]
	v_pk_mul_f32 v[50:51], v[50:51], v[32:33] op_sel_hi:[1,0]
	v_pk_mul_f32 v[48:49], v[48:49], v[32:33] op_sel_hi:[1,0]
	v_pk_mul_f32 v[46:47], v[46:47], v[32:33] op_sel_hi:[1,0]
	v_pk_mul_f32 v[44:45], v[44:45], v[32:33] op_sel_hi:[1,0]
	v_pk_mul_f32 v[30:31], v[30:31], v[34:35] op_sel_hi:[1,0]
	v_pk_mul_f32 v[28:29], v[28:29], v[34:35] op_sel_hi:[1,0]
	v_pk_mul_f32 v[26:27], v[26:27], v[34:35] op_sel_hi:[1,0]
	v_pk_mul_f32 v[24:25], v[24:25], v[34:35] op_sel_hi:[1,0]
	v_pk_mul_f32 v[14:15], v[14:15], v[112:113] op_sel_hi:[1,0]
	v_pk_mul_f32 v[12:13], v[12:13], v[112:113] op_sel_hi:[1,0]
	v_pk_mul_f32 v[10:11], v[10:11], v[112:113] op_sel_hi:[1,0]
	v_pk_mul_f32 v[8:9], v[8:9], v[112:113] op_sel_hi:[1,0]
	v_pk_mul_f32 v[58:59], v[58:59], v[124:125] op_sel_hi:[1,0]
	v_pk_mul_f32 v[56:57], v[56:57], v[124:125] op_sel_hi:[1,0]
	v_pk_mul_f32 v[54:55], v[54:55], v[124:125] op_sel_hi:[1,0]
	v_pk_mul_f32 v[52:53], v[52:53], v[124:125] op_sel_hi:[1,0]
	v_pk_mul_f32 v[42:43], v[42:43], v[32:33] op_sel_hi:[1,0]
	v_pk_mul_f32 v[40:41], v[40:41], v[32:33] op_sel_hi:[1,0]
	v_pk_mul_f32 v[38:39], v[38:39], v[32:33] op_sel_hi:[1,0]
	v_pk_mul_f32 v[36:37], v[36:37], v[32:33] op_sel_hi:[1,0]
	v_pk_mul_f32 v[22:23], v[22:23], v[34:35] op_sel_hi:[1,0]
	v_pk_mul_f32 v[20:21], v[20:21], v[34:35] op_sel_hi:[1,0]
	v_pk_mul_f32 v[18:19], v[18:19], v[34:35] op_sel_hi:[1,0]
	v_pk_mul_f32 v[16:17], v[16:17], v[34:35] op_sel_hi:[1,0]
	v_pk_mul_f32 v[6:7], v[6:7], v[112:113] op_sel_hi:[1,0]
	v_pk_mul_f32 v[4:5], v[4:5], v[112:113] op_sel_hi:[1,0]
	v_pk_mul_f32 v[2:3], v[2:3], v[112:113] op_sel_hi:[1,0]
	v_pk_mul_f32 v[0:1], v[0:1], v[112:113] op_sel_hi:[1,0]
	s_branch .LBB0_844

; #define GPROBE_BEGIN(id) do { if (((PROBE_GEMM_SEL >> (id)) & 1) && blockIdx.x == 0 && tid_in < 64 && g.N == 20480) { volatile PG8_LAS unsigned long long* PW_ = (volatile PG8_LAS unsigned long long*)(lds + 163840 - 512 + 64); PW_[0] = __builtin_amdgcn_s_memrealtime(); } } while (0)
; #define PG8_BAR __builtin_amdgcn_s_barrier()
; template <class Epi, class Sched, bool ALIGN_EPI = false, bool SP2 = false, bool KHOOK = false>
; __device__ __forceinline__ void gemm_phase(PG8_LAS unsigned char* lds, const Gemm g, const Sched& S, const Epi& E, const int tid_in) {
;     ...
;         const bool has_next = S.next(ui + 1, nxt);
;         const char* nA = has_next ? (const char*)g.A + (size_t)nxt.pm * tstep + (size_t)nxt.pn * ksl : cA; const char* nB = has_next ? (const char*)g.Bt + (size_t)nxt.pn * bts + (size_t)nxt.pn * ksl + (gdv ? (size_t)(nxt.pm / gdv) * gst : 0) : cB;
;         GPROBE_END(2); GPROBE_BEGIN(1);
;         for (int t = 0; t < nt; t += 2) {
;             const bool last = (t == nt - 2);
;             const char* a1 = cA + (size_t)(t + 1) * kstep;
;             const char* a2 = last ? nA : cA + (size_t)(t + 2) * kstep; const char* b2 = last ? nB : cB + (size_t)(t + 2) * kstep;
;             const char* a3 = a2 + kstep; const char* b3 = b2 + kstep;
;             if (last && has_next) S.a_ready(nxt);
;             if constexpr (SP2) {
;             PG8_LDB(B0, 0, 0); PG8_LDB(B1, 0, 1); PG8_SCHED; PG8_LDA(At, 0, 0); PG8_STAGE(PG8_SA(1, 1), a1 + hstep, voffA);
;             PG8_WAIT_V(8); PG8_WAIT_L(0); PG8_BAR; PG8_MMA(0, 0, At, B0); PG8_MMA(0, 1, At, B1); PG8_BAR; PG8_SCHED;
;             PG8_LDA(At, 0, 1); PG8_STAGE(PG8_SB(0, 0), b2, voffB); PG8_STAGE(PG8_SB(0, 1), b2 + hstep, voffB); PG8_STAGE(PG8_SA(0, 0), a2, voffA);
;             PG8_WAIT_V(8); PG8_WAIT_L(0); PG8_BAR; PG8_MMA(1, 0, At, B0); PG8_MMA(1, 1, At, B1); PG8_BAR; PG8_SCHED;
;             PG8_LDB(B0, 1, 0); PG8_LDB(B1, 1, 1); PG8_SCHED; PG8_LDA(At, 1, 0); PG8_STAGE(PG8_SA(0, 1), a2 + hstep, voffA);
;             PG8_WAIT_V(8); PG8_WAIT_L(0); PG8_BAR; PG8_MMA(0, 0, At, B0); PG8_MMA(0, 1, At, B1); PG8_BAR; PG8_SCHED;
;             PG8_LDA(At, 1, 1); PG8_STAGE(PG8_SB(1, 0), b3, voffB); PG8_STAGE(PG8_SB(1, 1), b3 + hstep, voffB); PG8_STAGE(PG8_SA(1, 0), a3, voffA);
;             PG8_WAIT_V(8); PG8_WAIT_L(0); PG8_BAR; PG8_MMA(1, 0, At, B0); PG8_MMA(1, 1, At, B1); PG8_BAR; PG8_SCHED;
.LBB0_866:
	s_ashr_i32 s9, s8, 31
	s_lshl_b64 s[12:13], s[8:9], 20
	s_add_u32 s12, s55, s12
	v_readlane_b32 s7, v253, 61
	s_addc_u32 s13, s7, s13
	s_and_b64 s[14:15], s[10:11], exec
	s_cselect_b32 s9, s13, s17
	s_cselect_b32 s39, s12, s16
	s_ashr_i32 s7, s6, 31
	s_lshl_b64 s[14:15], s[6:7], 20
	s_add_u32 s14, s2, s14
	s_addc_u32 s15, s18, s15
	s_and_b64 s[26:27], s[10:11], exec
	s_cselect_b32 s7, s15, s23
	s_cselect_b32 s40, s14, s22
	s_add_u32 s16, s16, 0x80080
	s_addc_u32 s17, s17, 0
	s_add_u32 s41, s22, 0x100
	s_addc_u32 s42, s23, 0
	s_mov_b32 s44, -2
	s_add_u32 s22, s16, 0xfff80080
	s_addc_u32 s23, s17, -1
	s_add_i32 s45, 0, 0x10000
	s_cmp_eq_u32 s44, 28
	s_cselect_b32 s27, s9, s23
	s_cselect_b32 s26, s39, s22
	s_cselect_b32 s23, s7, s42
	s_cselect_b32 s22, s40, s41
	s_add_i32 s48, 0, 0x14000
	v_add_u32_e32 v130, s45, v247
	v_add_u32_e32 v154, s48, v247
	ds_read_b128 v[106:109], v130
	ds_read_b128 v[110:113], v130 offset:1024
	ds_read_b128 v[122:125], v130 offset:2048
	ds_read_b128 v[130:133], v130 offset:3072
	ds_read_b128 v[134:137], v154
	ds_read_b128 v[138:141], v154 offset:1024
	ds_read_b128 v[150:153], v154 offset:2048
	ds_read_b128 v[154:157], v154 offset:3072
	v_lshl_add_u64 v[198:199], s[16:17], 0, v[208:209]
	s_add_i32 m0, s20, 0xc000
	ds_read_b128 v[158:161], v249
	ds_read_b128 v[162:165], v249 offset:1024
	ds_read_b128 v[170:173], v249 offset:2048
	ds_read_b128 v[174:177], v249 offset:3072
	ds_read_b128 v[178:181], v249 offset:4096
	ds_read_b128 v[182:185], v249 offset:5120
	ds_read_b128 v[186:189], v249 offset:6144
	ds_read_b128 v[190:193], v249 offset:7168
	global_load_lds_dwordx4 v[198:199], off
	s_add_i32 m0, s20, 0xe000
	v_lshl_add_u64 v[198:199], s[16:17], 0, v[210:211]
	global_load_lds_dwordx4 v[198:199], off
	s_waitcnt vmcnt(8)
	s_waitcnt lgkmcnt(0)
	s_barrier
	s_setprio 1
	s_waitcnt lgkmcnt(0)
	v_mfma_f32_16x16x32_bf16 v[166:169], v[106:109], v[158:161], 0
	v_mfma_f32_16x16x32_bf16 v[146:149], v[122:125], v[158:161], 0
	v_mfma_f32_16x16x32_bf16 v[118:121], v[106:109], v[170:173], 0
	v_mfma_f32_16x16x32_bf16 v[114:117], v[122:125], v[170:173], 0
	v_mfma_f32_16x16x32_bf16 v[94:97], v[106:109], v[178:181], 0
	v_mfma_f32_16x16x32_bf16 v[90:93], v[122:125], v[178:181], 0
	v_mfma_f32_16x16x32_bf16 v[78:81], v[106:109], v[186:189], 0
	v_mfma_f32_16x16x32_bf16 v[74:77], v[122:125], v[186:189], 0
	v_mfma_f32_16x16x32_bf16 v[166:169], v[110:113], v[162:165], v[166:169]
	v_mfma_f32_16x16x32_bf16 v[146:149], v[130:133], v[162:165], v[146:149]
	v_mfma_f32_16x16x32_bf16 v[118:121], v[110:113], v[174:177], v[118:121]
	v_mfma_f32_16x16x32_bf16 v[114:117], v[130:133], v[174:177], v[114:117]
	v_mfma_f32_16x16x32_bf16 v[94:97], v[110:113], v[182:185], v[94:97]
	v_mfma_f32_16x16x32_bf16 v[90:93], v[130:133], v[182:185], v[90:93]
	v_mfma_f32_16x16x32_bf16 v[78:81], v[110:113], v[190:193], v[78:81]
	v_mfma_f32_16x16x32_bf16 v[74:77], v[130:133], v[190:193], v[74:77]
	s_setprio 0
	s_setprio 1
	v_mfma_f32_16x16x32_bf16 v[142:145], v[134:137], v[158:161], 0
	v_mfma_f32_16x16x32_bf16 v[126:129], v[150:153], v[158:161], 0
	v_mfma_f32_16x16x32_bf16 v[102:105], v[134:137], v[170:173], 0
	v_mfma_f32_16x16x32_bf16 v[98:101], v[150:153], v[170:173], 0
	v_mfma_f32_16x16x32_bf16 v[86:89], v[134:137], v[178:181], 0
	v_mfma_f32_16x16x32_bf16 v[82:85], v[150:153], v[178:181], 0
	v_mfma_f32_16x16x32_bf16 v[70:73], v[134:137], v[186:189], 0
	v_mfma_f32_16x16x32_bf16 v[66:69], v[150:153], v[186:189], 0
	v_mfma_f32_16x16x32_bf16 v[142:145], v[138:141], v[162:165], v[142:145]
	v_mfma_f32_16x16x32_bf16 v[126:129], v[154:157], v[162:165], v[126:129]
	v_mfma_f32_16x16x32_bf16 v[102:105], v[138:141], v[174:177], v[102:105]
	v_mfma_f32_16x16x32_bf16 v[98:101], v[154:157], v[174:177], v[98:101]
	v_mfma_f32_16x16x32_bf16 v[86:89], v[138:141], v[182:185], v[86:89]
	v_mfma_f32_16x16x32_bf16 v[82:85], v[154:157], v[182:185], v[82:85]
	v_mfma_f32_16x16x32_bf16 v[70:73], v[138:141], v[190:193], v[70:73]
	v_mfma_f32_16x16x32_bf16 v[66:69], v[154:157], v[190:193], v[66:69]
	s_setprio 0
	s_barrier
	s_add_i32 s45, s45, s19
	v_lshl_add_u64 v[198:199], s[22:23], 0, v[32:33]
	s_mov_b32 m0, s45
	ds_read_b128 v[158:161], v249 offset:16384
	ds_read_b128 v[162:165], v249 offset:17408
	ds_read_b128 v[170:173], v249 offset:18432
	ds_read_b128 v[174:177], v249 offset:19456
	ds_read_b128 v[178:181], v249 offset:20480
	ds_read_b128 v[182:185], v249 offset:21504
	ds_read_b128 v[186:189], v249 offset:22528
	ds_read_b128 v[190:193], v249 offset:23552
	global_load_lds_dwordx4 v[198:199], off
	s_add_i32 m0, s45, 0x2000
	s_add_u32 s46, s22, 0x80000
	v_lshl_add_u64 v[200:201], s[22:23], 0, v[202:203]
	s_addc_u32 s47, s23, 0
	s_add_i32 s45, s48, s19
	global_load_lds_dwordx4 v[200:201], off
	v_lshl_add_u64 v[212:213], s[46:47], 0, v[32:33]
	s_mov_b32 m0, s45
	v_lshl_add_u64 v[214:215], s[26:27], 0, v[204:205]
	global_load_lds_dwordx4 v[212:213], off
	s_add_i32 m0, s45, 0x2000
	v_lshl_add_u64 v[212:213], s[46:47], 0, v[202:203]
	global_load_lds_dwordx4 v[212:213], off
	s_mov_b32 m0, s20
	v_lshl_add_u64 v[212:213], s[26:27], 0, v[206:207]
	global_load_lds_dwordx4 v[212:213], off
	s_mov_b32 m0, s30
	s_nop 0
	global_load_lds_dwordx4 v[214:215], off
	s_waitcnt vmcnt(8)
	s_waitcnt lgkmcnt(0)
	s_barrier
; #define PG8_STAGE(bufoff, gbase, voff) do { _Pragma("unroll") for (int _i = 0; _i < 2; ++_i) \
;         __builtin_amdgcn_global_load_lds((const unsigned*)((const char*)(gbase) + (voff)[_i]), (PG8_LAS unsigned*)(lds + (bufoff) + ldsw + _i * 8192), 16, 0, 0); } while (0)
; #define PG8_LDA(dst, b, h) do { _Pragma("unroll") for (int m = 0; m < 4; ++m) _Pragma("unroll") for (int k = 0; k < 2; ++k) dst[m][k] = *(const PG8_LAS bf16x8*)(lds + PG8_SA(b, h) + aoff + m * 2048 + k * 1024); } while (0)
; #define PG8_LDB(dst, b, h) do { _Pragma("unroll") for (int n = 0; n < 2; ++n) _Pragma("unroll") for (int k = 0; k < 2; ++k) dst[n][k] = *(const PG8_LAS bf16x8*)(lds + PG8_SB(b, h) + boff + n * 2048 + k * 1024); } while (0)
; #define PG8_MMA(ai, bj, At, Bt) do { __builtin_amdgcn_s_setprio(1); _Pragma("unroll") for (int m = 0; m < 4; ++m) _Pragma("unroll") for (int n = 0; n < 2; ++n) _Pragma("unroll") for (int k = 0; k < 2; ++k) \
;         acc[ai][bj][m][n] = __builtin_amdgcn_mfma_f32_16x16x32_bf16(Bt[n][k], At[m][k], acc[ai][bj][m][n], 0, 0, 0); __builtin_amdgcn_s_setprio(0); } while (0)
; template <class Epi, class Sched, bool ALIGN_EPI = false, bool SP2 = false, bool KHOOK = false>
; __device__ __forceinline__ void gemm_phase(PG8_LAS unsigned char* lds, const Gemm g, const Sched& S, const Epi& E, const int tid_in) {
;     ...
;             PG8_LDB(B0, 0, 0); PG8_LDB(B1, 0, 1); PG8_SCHED; PG8_LDA(At, 0, 0); PG8_STAGE(PG8_SA(1, 1), a1 + hstep, voffA);
;             PG8_WAIT_V(8); PG8_WAIT_L(0); PG8_BAR; PG8_MMA(0, 0, At, B0); PG8_MMA(0, 1, At, B1); PG8_BAR; PG8_SCHED;
;             PG8_LDA(At, 0, 1); PG8_STAGE(PG8_SB(0, 0), b2, voffB); PG8_STAGE(PG8_SB(0, 1), b2 + hstep, voffB); PG8_STAGE(PG8_SA(0, 0), a2, voffA);
;             PG8_WAIT_V(8); PG8_WAIT_L(0); PG8_BAR; PG8_MMA(1, 0, At, B0); PG8_MMA(1, 1, At, B1); PG8_BAR; PG8_SCHED;
;             PG8_LDB(B0, 1, 0); PG8_LDB(B1, 1, 1); PG8_SCHED; PG8_LDA(At, 1, 0); PG8_STAGE(PG8_SA(0, 1), a2 + hstep, voffA);
;             PG8_WAIT_V(8); PG8_WAIT_L(0); PG8_BAR; PG8_MMA(0, 0, At, B0); PG8_MMA(0, 1, At, B1); PG8_BAR; PG8_SCHED;
;             PG8_LDA(At, 1, 1); PG8_STAGE(PG8_SB(1, 0), b3, voffB); PG8_STAGE(PG8_SB(1, 1), b3 + hstep, voffB); PG8_STAGE(PG8_SA(1, 0), a3, voffA);
;             PG8_WAIT_V(8); PG8_WAIT_L(0); PG8_BAR; PG8_MMA(1, 0, At, B0); PG8_MMA(1, 1, At, B1); PG8_BAR; PG8_SCHED;
	s_setprio 1
	s_waitcnt lgkmcnt(0)
	v_mfma_f32_16x16x32_bf16 v[62:65], v[106:109], v[158:161], 0
	v_mfma_f32_16x16x32_bf16 v[58:61], v[122:125], v[158:161], 0
	v_mfma_f32_16x16x32_bf16 v[46:49], v[106:109], v[170:173], 0
	v_mfma_f32_16x16x32_bf16 v[42:45], v[122:125], v[170:173], 0
	v_mfma_f32_16x16x32_bf16 v[28:31], v[106:109], v[178:181], 0
	v_mfma_f32_16x16x32_bf16 v[24:27], v[122:125], v[178:181], 0
	v_mfma_f32_16x16x32_bf16 v[12:15], v[106:109], v[186:189], 0
	v_mfma_f32_16x16x32_bf16 v[8:11], v[122:125], v[186:189], 0
	v_mfma_f32_16x16x32_bf16 v[62:65], v[110:113], v[162:165], v[62:65]
	v_mfma_f32_16x16x32_bf16 v[58:61], v[130:133], v[162:165], v[58:61]
	v_mfma_f32_16x16x32_bf16 v[46:49], v[110:113], v[174:177], v[46:49]
	v_mfma_f32_16x16x32_bf16 v[42:45], v[130:133], v[174:177], v[42:45]
	v_mfma_f32_16x16x32_bf16 v[28:31], v[110:113], v[182:185], v[28:31]
	v_mfma_f32_16x16x32_bf16 v[24:27], v[130:133], v[182:185], v[24:27]
	v_mfma_f32_16x16x32_bf16 v[12:15], v[110:113], v[190:193], v[12:15]
	v_mfma_f32_16x16x32_bf16 v[8:11], v[130:133], v[190:193], v[8:11]
	s_setprio 0
	s_setprio 1
	v_mfma_f32_16x16x32_bf16 v[54:57], v[134:137], v[158:161], 0
	v_mfma_f32_16x16x32_bf16 v[50:53], v[150:153], v[158:161], 0
	v_mfma_f32_16x16x32_bf16 v[38:41], v[134:137], v[170:173], 0
	v_mfma_f32_16x16x32_bf16 v[34:37], v[150:153], v[170:173], 0
	v_mfma_f32_16x16x32_bf16 v[20:23], v[134:137], v[178:181], 0
	v_mfma_f32_16x16x32_bf16 v[16:19], v[150:153], v[178:181], 0
	v_mfma_f32_16x16x32_bf16 v[4:7], v[134:137], v[186:189], 0
	v_mfma_f32_16x16x32_bf16 v[0:3], v[150:153], v[186:189], 0
	v_mfma_f32_16x16x32_bf16 v[54:57], v[138:141], v[162:165], v[54:57]
	v_mfma_f32_16x16x32_bf16 v[50:53], v[154:157], v[162:165], v[50:53]
	v_mfma_f32_16x16x32_bf16 v[38:41], v[138:141], v[174:177], v[38:41]
	v_mfma_f32_16x16x32_bf16 v[34:37], v[154:157], v[174:177], v[34:37]
	v_mfma_f32_16x16x32_bf16 v[20:23], v[138:141], v[182:185], v[20:23]
	v_mfma_f32_16x16x32_bf16 v[16:19], v[154:157], v[182:185], v[16:19]
	v_mfma_f32_16x16x32_bf16 v[4:7], v[138:141], v[190:193], v[4:7]
	v_mfma_f32_16x16x32_bf16 v[0:3], v[154:157], v[190:193], v[0:3]
	s_setprio 0
	s_barrier
	s_add_i32 s45, 0, 0x18000
	s_add_i32 s46, 0, 0x1c000
	v_add_u32_e32 v130, s45, v247
	v_add_u32_e32 v154, s46, v247
	ds_read_b128 v[106:109], v130
	ds_read_b128 v[110:113], v130 offset:1024
	ds_read_b128 v[122:125], v130 offset:2048
	ds_read_b128 v[130:133], v130 offset:3072
	ds_read_b128 v[134:137], v154
	ds_read_b128 v[138:141], v154 offset:1024
	ds_read_b128 v[150:153], v154 offset:2048
	ds_read_b128 v[154:157], v154 offset:3072
	s_add_u32 s26, s26, 0x80000
	s_addc_u32 s27, s27, 0
	s_mov_b32 m0, s31
	v_lshl_add_u64 v[216:217], s[26:27], 0, v[206:207]
	ds_read_b128 v[158:161], v249 offset:32768
	ds_read_b128 v[162:165], v249 offset:33792
	ds_read_b128 v[170:173], v249 offset:34816
	ds_read_b128 v[174:177], v249 offset:35840
	ds_read_b128 v[178:181], v249 offset:36864
	ds_read_b128 v[182:185], v249 offset:37888
	ds_read_b128 v[186:189], v249 offset:38912
	ds_read_b128 v[190:193], v249 offset:39936
	global_load_lds_dwordx4 v[216:217], off
	s_mov_b32 m0, s33
	v_lshl_add_u64 v[216:217], s[26:27], 0, v[204:205]
	global_load_lds_dwordx4 v[216:217], off
	s_waitcnt vmcnt(8)
	s_waitcnt lgkmcnt(0)
	s_barrier
	s_setprio 1
	s_waitcnt lgkmcnt(0)
	v_mfma_f32_16x16x32_bf16 v[166:169], v[106:109], v[158:161], v[166:169]
	v_mfma_f32_16x16x32_bf16 v[146:149], v[122:125], v[158:161], v[146:149]
	v_mfma_f32_16x16x32_bf16 v[118:121], v[106:109], v[170:173], v[118:121]
	v_mfma_f32_16x16x32_bf16 v[114:117], v[122:125], v[170:173], v[114:117]
	v_mfma_f32_16x16x32_bf16 v[94:97], v[106:109], v[178:181], v[94:97]
	v_mfma_f32_16x16x32_bf16 v[90:93], v[122:125], v[178:181], v[90:93]
	v_mfma_f32_16x16x32_bf16 v[78:81], v[106:109], v[186:189], v[78:81]
	v_mfma_f32_16x16x32_bf16 v[74:77], v[122:125], v[186:189], v[74:77]
	v_mfma_f32_16x16x32_bf16 v[166:169], v[110:113], v[162:165], v[166:169]
	v_mfma_f32_16x16x32_bf16 v[146:149], v[130:133], v[162:165], v[146:149]
	v_mfma_f32_16x16x32_bf16 v[118:121], v[110:113], v[174:177], v[118:121]
	v_mfma_f32_16x16x32_bf16 v[114:117], v[130:133], v[174:177], v[114:117]
	v_mfma_f32_16x16x32_bf16 v[94:97], v[110:113], v[182:185], v[94:97]
	v_mfma_f32_16x16x32_bf16 v[90:93], v[130:133], v[182:185], v[90:93]
	v_mfma_f32_16x16x32_bf16 v[78:81], v[110:113], v[190:193], v[78:81]
	v_mfma_f32_16x16x32_bf16 v[74:77], v[130:133], v[190:193], v[74:77]
	s_setprio 0
	s_setprio 1
	v_mfma_f32_16x16x32_bf16 v[142:145], v[134:137], v[158:161], v[142:145]
	v_mfma_f32_16x16x32_bf16 v[126:129], v[150:153], v[158:161], v[126:129]
	v_mfma_f32_16x16x32_bf16 v[102:105], v[134:137], v[170:173], v[102:105]
	v_mfma_f32_16x16x32_bf16 v[98:101], v[150:153], v[170:173], v[98:101]
	v_mfma_f32_16x16x32_bf16 v[86:89], v[134:137], v[178:181], v[86:89]
	v_mfma_f32_16x16x32_bf16 v[82:85], v[150:153], v[178:181], v[82:85]
	v_mfma_f32_16x16x32_bf16 v[70:73], v[134:137], v[186:189], v[70:73]
	v_mfma_f32_16x16x32_bf16 v[66:69], v[150:153], v[186:189], v[66:69]
	v_mfma_f32_16x16x32_bf16 v[142:145], v[138:141], v[162:165], v[142:145]
	v_mfma_f32_16x16x32_bf16 v[126:129], v[154:157], v[162:165], v[126:129]
	v_mfma_f32_16x16x32_bf16 v[102:105], v[138:141], v[174:177], v[102:105]
	v_mfma_f32_16x16x32_bf16 v[98:101], v[154:157], v[174:177], v[98:101]
	v_mfma_f32_16x16x32_bf16 v[86:89], v[138:141], v[182:185], v[86:89]
	v_mfma_f32_16x16x32_bf16 v[82:85], v[154:157], v[182:185], v[82:85]
	v_mfma_f32_16x16x32_bf16 v[70:73], v[138:141], v[190:193], v[70:73]
	v_mfma_f32_16x16x32_bf16 v[66:69], v[154:157], v[190:193], v[66:69]
	s_setprio 0
	s_barrier
; #define PG8_STAGE(bufoff, gbase, voff) do { _Pragma("unroll") for (int _i = 0; _i < 2; ++_i) \
;         __builtin_amdgcn_global_load_lds((const unsigned*)((const char*)(gbase) + (voff)[_i]), (PG8_LAS unsigned*)(lds + (bufoff) + ldsw + _i * 8192), 16, 0, 0); } while (0)
; #define PG8_LDA(dst, b, h) do { _Pragma("unroll") for (int m = 0; m < 4; ++m) _Pragma("unroll") for (int k = 0; k < 2; ++k) dst[m][k] = *(const PG8_LAS bf16x8*)(lds + PG8_SA(b, h) + aoff + m * 2048 + k * 1024); } while (0)
; #define PG8_LDB(dst, b, h) do { _Pragma("unroll") for (int n = 0; n < 2; ++n) _Pragma("unroll") for (int k = 0; k < 2; ++k) dst[n][k] = *(const PG8_LAS bf16x8*)(lds + PG8_SB(b, h) + boff + n * 2048 + k * 1024); } while (0)
; #define PG8_MMA(ai, bj, At, Bt) do { __builtin_amdgcn_s_setprio(1); _Pragma("unroll") for (int m = 0; m < 4; ++m) _Pragma("unroll") for (int n = 0; n < 2; ++n) _Pragma("unroll") for (int k = 0; k < 2; ++k) \
;         acc[ai][bj][m][n] = __builtin_amdgcn_mfma_f32_16x16x32_bf16(Bt[n][k], At[m][k], acc[ai][bj][m][n], 0, 0, 0); __builtin_amdgcn_s_setprio(0); } while (0)
; template <class Epi, class Sched, bool ALIGN_EPI = false, bool SP2 = false, bool KHOOK = false>
; __device__ __forceinline__ void gemm_phase(PG8_LAS unsigned char* lds, const Gemm g, const Sched& S, const Epi& E, const int tid_in) {
;     ...
;         for (int t = 0; t < nt; t += 2) {
;     ...
;             PG8_LDB(B0, 0, 0); PG8_LDB(B1, 0, 1); PG8_SCHED; PG8_LDA(At, 0, 0); PG8_STAGE(PG8_SA(1, 1), a1 + hstep, voffA);
;             PG8_WAIT_V(8); PG8_WAIT_L(0); PG8_BAR; PG8_MMA(0, 0, At, B0); PG8_MMA(0, 1, At, B1); PG8_BAR; PG8_SCHED;
;             PG8_LDA(At, 0, 1); PG8_STAGE(PG8_SB(0, 0), b2, voffB); PG8_STAGE(PG8_SB(0, 1), b2 + hstep, voffB); PG8_STAGE(PG8_SA(0, 0), a2, voffA);
;             PG8_WAIT_V(8); PG8_WAIT_L(0); PG8_BAR; PG8_MMA(1, 0, At, B0); PG8_MMA(1, 1, At, B1); PG8_BAR; PG8_SCHED;
;             PG8_LDB(B0, 1, 0); PG8_LDB(B1, 1, 1); PG8_SCHED; PG8_LDA(At, 1, 0); PG8_STAGE(PG8_SA(0, 1), a2 + hstep, voffA);
;             PG8_WAIT_V(8); PG8_WAIT_L(0); PG8_BAR; PG8_MMA(0, 0, At, B0); PG8_MMA(0, 1, At, B1); PG8_BAR; PG8_SCHED;
;             PG8_LDA(At, 1, 1); PG8_STAGE(PG8_SB(1, 0), b3, voffB); PG8_STAGE(PG8_SB(1, 1), b3 + hstep, voffB); PG8_STAGE(PG8_SA(1, 0), a3, voffA);
;             PG8_WAIT_V(8); PG8_WAIT_L(0); PG8_BAR; PG8_MMA(1, 0, At, B0); PG8_MMA(1, 1, At, B1); PG8_BAR; PG8_SCHED;
	s_add_i32 s26, s45, s19
	v_lshl_add_u64 v[198:199], v[198:199], 0, s[90:91]
	s_mov_b32 m0, s26
	ds_read_b128 v[158:161], v249 offset:49152
	ds_read_b128 v[162:165], v249 offset:50176
	ds_read_b128 v[170:173], v249 offset:51200
	ds_read_b128 v[174:177], v249 offset:52224
	ds_read_b128 v[178:181], v249 offset:53248
	ds_read_b128 v[182:185], v249 offset:54272
	ds_read_b128 v[186:189], v249 offset:55296
	ds_read_b128 v[190:193], v249 offset:56320
	global_load_lds_dwordx4 v[198:199], off
	s_add_i32 m0, s26, 0x2000
	s_add_u32 s22, s22, 0x80080
	v_lshl_add_u64 v[198:199], v[200:201], 0, s[90:91]
	s_addc_u32 s23, s23, 0
	s_add_i32 s26, s46, s19
	global_load_lds_dwordx4 v[198:199], off
	s_mov_b32 m0, s26
	v_lshl_add_u64 v[198:199], s[22:23], 0, v[32:33]
	global_load_lds_dwordx4 v[198:199], off
	s_add_i32 m0, s26, 0x2000
	v_lshl_add_u64 v[198:199], s[22:23], 0, v[202:203]
	global_load_lds_dwordx4 v[198:199], off
	s_mov_b32 m0, s36
	v_lshl_add_u64 v[198:199], v[212:213], 0, s[90:91]
	global_load_lds_dwordx4 v[198:199], off
	s_mov_b32 m0, s37
	v_lshl_add_u64 v[198:199], v[214:215], 0, s[90:91]
	global_load_lds_dwordx4 v[198:199], off
	s_waitcnt vmcnt(8)
	s_waitcnt lgkmcnt(0)
	s_barrier
	s_setprio 1
	s_waitcnt lgkmcnt(0)
	v_mfma_f32_16x16x32_bf16 v[62:65], v[106:109], v[158:161], v[62:65]
	v_mfma_f32_16x16x32_bf16 v[58:61], v[122:125], v[158:161], v[58:61]
	v_mfma_f32_16x16x32_bf16 v[46:49], v[106:109], v[170:173], v[46:49]
	v_mfma_f32_16x16x32_bf16 v[42:45], v[122:125], v[170:173], v[42:45]
	v_mfma_f32_16x16x32_bf16 v[28:31], v[106:109], v[178:181], v[28:31]
	v_mfma_f32_16x16x32_bf16 v[24:27], v[122:125], v[178:181], v[24:27]
	v_mfma_f32_16x16x32_bf16 v[12:15], v[106:109], v[186:189], v[12:15]
	v_mfma_f32_16x16x32_bf16 v[8:11], v[122:125], v[186:189], v[8:11]
	v_mfma_f32_16x16x32_bf16 v[62:65], v[110:113], v[162:165], v[62:65]
	v_mfma_f32_16x16x32_bf16 v[58:61], v[130:133], v[162:165], v[58:61]
	v_mfma_f32_16x16x32_bf16 v[46:49], v[110:113], v[174:177], v[46:49]
	v_mfma_f32_16x16x32_bf16 v[42:45], v[130:133], v[174:177], v[42:45]
	v_mfma_f32_16x16x32_bf16 v[28:31], v[110:113], v[182:185], v[28:31]
	v_mfma_f32_16x16x32_bf16 v[24:27], v[130:133], v[182:185], v[24:27]
	v_mfma_f32_16x16x32_bf16 v[12:15], v[110:113], v[190:193], v[12:15]
	v_mfma_f32_16x16x32_bf16 v[8:11], v[130:133], v[190:193], v[8:11]
	s_setprio 0
	s_setprio 1
	v_mfma_f32_16x16x32_bf16 v[54:57], v[134:137], v[158:161], v[54:57]
	v_mfma_f32_16x16x32_bf16 v[50:53], v[150:153], v[158:161], v[50:53]
	v_mfma_f32_16x16x32_bf16 v[38:41], v[134:137], v[170:173], v[38:41]
	v_mfma_f32_16x16x32_bf16 v[34:37], v[150:153], v[170:173], v[34:37]
	v_mfma_f32_16x16x32_bf16 v[20:23], v[134:137], v[178:181], v[20:23]
	v_mfma_f32_16x16x32_bf16 v[16:19], v[150:153], v[178:181], v[16:19]
	v_mfma_f32_16x16x32_bf16 v[4:7], v[134:137], v[186:189], v[4:7]
	v_mfma_f32_16x16x32_bf16 v[0:3], v[150:153], v[186:189], v[0:3]
	v_mfma_f32_16x16x32_bf16 v[54:57], v[138:141], v[162:165], v[54:57]
	v_mfma_f32_16x16x32_bf16 v[50:53], v[154:157], v[162:165], v[50:53]
	v_mfma_f32_16x16x32_bf16 v[38:41], v[138:141], v[174:177], v[38:41]
	v_mfma_f32_16x16x32_bf16 v[34:37], v[154:157], v[174:177], v[34:37]
	v_mfma_f32_16x16x32_bf16 v[20:23], v[138:141], v[182:185], v[20:23]
	v_mfma_f32_16x16x32_bf16 v[16:19], v[154:157], v[182:185], v[16:19]
	v_mfma_f32_16x16x32_bf16 v[4:7], v[138:141], v[190:193], v[4:7]
	v_mfma_f32_16x16x32_bf16 v[0:3], v[154:157], v[190:193], v[0:3]
	s_setprio 0
	s_barrier
	s_add_i32 s44, s44, 2
	s_add_u32 s16, s16, 0x100
	s_addc_u32 s17, s17, 0
	s_add_u32 s41, s41, 0x100
	s_addc_u32 s42, s42, 0
	s_cmp_gt_u32 s44, 29
.LBB0_867:
	s_add_u32 s22, s16, 0xfff80080
	s_addc_u32 s23, s17, -1
	s_add_i32 s45, 0, 0x10000
	s_cmp_eq_u32 s44, 28
	s_cselect_b32 s27, s9, s23
	s_cselect_b32 s26, s39, s22
	s_cselect_b32 s23, s7, s42
	s_cselect_b32 s22, s40, s41
	s_add_i32 s48, 0, 0x14000
	v_add_u32_e32 v130, s45, v247
	v_add_u32_e32 v154, s48, v247
	ds_read_b128 v[106:109], v130
	ds_read_b128 v[110:113], v130 offset:1024
	ds_read_b128 v[122:125], v130 offset:2048
	ds_read_b128 v[130:133], v130 offset:3072
	ds_read_b128 v[134:137], v154
	ds_read_b128 v[138:141], v154 offset:1024
	ds_read_b128 v[150:153], v154 offset:2048
	ds_read_b128 v[154:157], v154 offset:3072
	v_lshl_add_u64 v[198:199], s[16:17], 0, v[208:209]
	s_add_i32 m0, s20, 0xc000
	ds_read_b128 v[158:161], v249
	ds_read_b128 v[162:165], v249 offset:1024
	ds_read_b128 v[170:173], v249 offset:2048
	ds_read_b128 v[174:177], v249 offset:3072
	ds_read_b128 v[178:181], v249 offset:4096
	ds_read_b128 v[182:185], v249 offset:5120
	ds_read_b128 v[186:189], v249 offset:6144
	ds_read_b128 v[190:193], v249 offset:7168
	global_load_lds_dwordx4 v[198:199], off
	s_add_i32 m0, s20, 0xe000
	v_lshl_add_u64 v[198:199], s[16:17], 0, v[210:211]
	global_load_lds_dwordx4 v[198:199], off
	s_waitcnt vmcnt(8)
	s_waitcnt lgkmcnt(0)
	s_barrier
; #define PG8_STAGE(bufoff, gbase, voff) do { _Pragma("unroll") for (int _i = 0; _i < 2; ++_i) \
;         __builtin_amdgcn_global_load_lds((const unsigned*)((const char*)(gbase) + (voff)[_i]), (PG8_LAS unsigned*)(lds + (bufoff) + ldsw + _i * 8192), 16, 0, 0); } while (0)
; #define PG8_LDA(dst, b, h) do { _Pragma("unroll") for (int m = 0; m < 4; ++m) _Pragma("unroll") for (int k = 0; k < 2; ++k) dst[m][k] = *(const PG8_LAS bf16x8*)(lds + PG8_SA(b, h) + aoff + m * 2048 + k * 1024); } while (0)
; #define PG8_LDB(dst, b, h) do { _Pragma("unroll") for (int n = 0; n < 2; ++n) _Pragma("unroll") for (int k = 0; k < 2; ++k) dst[n][k] = *(const PG8_LAS bf16x8*)(lds + PG8_SB(b, h) + boff + n * 2048 + k * 1024); } while (0)
; #define PG8_MMA(ai, bj, At, Bt) do { __builtin_amdgcn_s_setprio(1); _Pragma("unroll") for (int m = 0; m < 4; ++m) _Pragma("unroll") for (int n = 0; n < 2; ++n) _Pragma("unroll") for (int k = 0; k < 2; ++k) \
;         acc[ai][bj][m][n] = __builtin_amdgcn_mfma_f32_16x16x32_bf16(Bt[n][k], At[m][k], acc[ai][bj][m][n], 0, 0, 0); __builtin_amdgcn_s_setprio(0); } while (0)
; #define PG8_WAIT_V(n) asm volatile("s_waitcnt vmcnt(" #n ")" ::: "memory")
; #define PG8_WAIT_L(n) asm volatile("s_waitcnt lgkmcnt(" #n ")" ::: "memory")
; #define PG8_BAR __builtin_amdgcn_s_barrier()
; #define PG8_SCHED __builtin_amdgcn_sched_barrier(0)
; template <class Epi, class Sched, bool ALIGN_EPI = false, bool SP2 = false, bool KHOOK = false>
; __device__ __forceinline__ void gemm_phase(PG8_LAS unsigned char* lds, const Gemm g, const Sched& S, const Epi& E, const int tid_in) {
;     ...
;             PG8_LDB(B0, 0, 0); PG8_LDB(B1, 0, 1); PG8_SCHED; PG8_LDA(At, 0, 0); PG8_STAGE(PG8_SA(1, 1), a1 + hstep, voffA);
;             PG8_WAIT_V(8); PG8_WAIT_L(0); PG8_BAR; PG8_MMA(0, 0, At, B0); PG8_MMA(0, 1, At, B1); PG8_BAR; PG8_SCHED;
;             PG8_LDA(At, 0, 1); PG8_STAGE(PG8_SB(0, 0), b2, voffB); PG8_STAGE(PG8_SB(0, 1), b2 + hstep, voffB); PG8_STAGE(PG8_SA(0, 0), a2, voffA);
;             PG8_WAIT_V(8); PG8_WAIT_L(0); PG8_BAR; PG8_MMA(1, 0, At, B0); PG8_MMA(1, 1, At, B1); PG8_BAR; PG8_SCHED;
	s_setprio 1
	s_waitcnt lgkmcnt(0)
	v_mfma_f32_16x16x32_bf16 v[166:169], v[106:109], v[158:161], v[166:169]
	v_mfma_f32_16x16x32_bf16 v[146:149], v[122:125], v[158:161], v[146:149]
	v_mfma_f32_16x16x32_bf16 v[118:121], v[106:109], v[170:173], v[118:121]
	v_mfma_f32_16x16x32_bf16 v[114:117], v[122:125], v[170:173], v[114:117]
	v_mfma_f32_16x16x32_bf16 v[94:97], v[106:109], v[178:181], v[94:97]
	v_mfma_f32_16x16x32_bf16 v[90:93], v[122:125], v[178:181], v[90:93]
	v_mfma_f32_16x16x32_bf16 v[78:81], v[106:109], v[186:189], v[78:81]
	v_mfma_f32_16x16x32_bf16 v[74:77], v[122:125], v[186:189], v[74:77]
	v_mfma_f32_16x16x32_bf16 v[166:169], v[110:113], v[162:165], v[166:169]
	v_mfma_f32_16x16x32_bf16 v[146:149], v[130:133], v[162:165], v[146:149]
	v_mfma_f32_16x16x32_bf16 v[118:121], v[110:113], v[174:177], v[118:121]
	v_mfma_f32_16x16x32_bf16 v[114:117], v[130:133], v[174:177], v[114:117]
	v_mfma_f32_16x16x32_bf16 v[94:97], v[110:113], v[182:185], v[94:97]
	v_mfma_f32_16x16x32_bf16 v[90:93], v[130:133], v[182:185], v[90:93]
	v_mfma_f32_16x16x32_bf16 v[78:81], v[110:113], v[190:193], v[78:81]
	v_mfma_f32_16x16x32_bf16 v[74:77], v[130:133], v[190:193], v[74:77]
	s_setprio 0
	s_setprio 1
	v_mfma_f32_16x16x32_bf16 v[142:145], v[134:137], v[158:161], v[142:145]
	v_mfma_f32_16x16x32_bf16 v[126:129], v[150:153], v[158:161], v[126:129]
	v_mfma_f32_16x16x32_bf16 v[102:105], v[134:137], v[170:173], v[102:105]
	v_mfma_f32_16x16x32_bf16 v[98:101], v[150:153], v[170:173], v[98:101]
	v_mfma_f32_16x16x32_bf16 v[86:89], v[134:137], v[178:181], v[86:89]
	v_mfma_f32_16x16x32_bf16 v[82:85], v[150:153], v[178:181], v[82:85]
	v_mfma_f32_16x16x32_bf16 v[70:73], v[134:137], v[186:189], v[70:73]
	v_mfma_f32_16x16x32_bf16 v[66:69], v[150:153], v[186:189], v[66:69]
	v_mfma_f32_16x16x32_bf16 v[142:145], v[138:141], v[162:165], v[142:145]
	v_mfma_f32_16x16x32_bf16 v[126:129], v[154:157], v[162:165], v[126:129]
	v_mfma_f32_16x16x32_bf16 v[102:105], v[138:141], v[174:177], v[102:105]
	v_mfma_f32_16x16x32_bf16 v[98:101], v[154:157], v[174:177], v[98:101]
	v_mfma_f32_16x16x32_bf16 v[86:89], v[138:141], v[182:185], v[86:89]
	v_mfma_f32_16x16x32_bf16 v[82:85], v[154:157], v[182:185], v[82:85]
	v_mfma_f32_16x16x32_bf16 v[70:73], v[138:141], v[190:193], v[70:73]
	v_mfma_f32_16x16x32_bf16 v[66:69], v[154:157], v[190:193], v[66:69]
	s_setprio 0
	s_barrier
	s_add_i32 s45, s45, s19
	v_lshl_add_u64 v[198:199], s[22:23], 0, v[32:33]
	s_mov_b32 m0, s45
	ds_read_b128 v[158:161], v249 offset:16384
	ds_read_b128 v[162:165], v249 offset:17408
	ds_read_b128 v[170:173], v249 offset:18432
	ds_read_b128 v[174:177], v249 offset:19456
	ds_read_b128 v[178:181], v249 offset:20480
	ds_read_b128 v[182:185], v249 offset:21504
	ds_read_b128 v[186:189], v249 offset:22528
	ds_read_b128 v[190:193], v249 offset:23552
	global_load_lds_dwordx4 v[198:199], off
	s_add_i32 m0, s45, 0x2000
	s_add_u32 s46, s22, 0x80000
	v_lshl_add_u64 v[200:201], s[22:23], 0, v[202:203]
	s_addc_u32 s47, s23, 0
	s_add_i32 s45, s48, s19
	global_load_lds_dwordx4 v[200:201], off
	v_lshl_add_u64 v[212:213], s[46:47], 0, v[32:33]
	s_mov_b32 m0, s45
	v_lshl_add_u64 v[214:215], s[26:27], 0, v[204:205]
	global_load_lds_dwordx4 v[212:213], off
	s_add_i32 m0, s45, 0x2000
	v_lshl_add_u64 v[212:213], s[46:47], 0, v[202:203]
	global_load_lds_dwordx4 v[212:213], off
	s_mov_b32 m0, s20
	v_lshl_add_u64 v[212:213], s[26:27], 0, v[206:207]
	global_load_lds_dwordx4 v[212:213], off
	s_mov_b32 m0, s30
	s_nop 0
	global_load_lds_dwordx4 v[214:215], off
	s_waitcnt vmcnt(8)
	s_waitcnt lgkmcnt(0)
	s_barrier
	s_setprio 1
	s_waitcnt lgkmcnt(0)
	v_mfma_f32_16x16x32_bf16 v[62:65], v[106:109], v[158:161], v[62:65]
	v_mfma_f32_16x16x32_bf16 v[58:61], v[122:125], v[158:161], v[58:61]
	v_mfma_f32_16x16x32_bf16 v[46:49], v[106:109], v[170:173], v[46:49]
	v_mfma_f32_16x16x32_bf16 v[42:45], v[122:125], v[170:173], v[42:45]
	v_mfma_f32_16x16x32_bf16 v[28:31], v[106:109], v[178:181], v[28:31]
	v_mfma_f32_16x16x32_bf16 v[24:27], v[122:125], v[178:181], v[24:27]
	v_mfma_f32_16x16x32_bf16 v[12:15], v[106:109], v[186:189], v[12:15]
	v_mfma_f32_16x16x32_bf16 v[8:11], v[122:125], v[186:189], v[8:11]
	v_mfma_f32_16x16x32_bf16 v[62:65], v[110:113], v[162:165], v[62:65]
	v_mfma_f32_16x16x32_bf16 v[58:61], v[130:133], v[162:165], v[58:61]
	v_mfma_f32_16x16x32_bf16 v[46:49], v[110:113], v[174:177], v[46:49]
	v_mfma_f32_16x16x32_bf16 v[42:45], v[130:133], v[174:177], v[42:45]
	v_mfma_f32_16x16x32_bf16 v[28:31], v[110:113], v[182:185], v[28:31]
	v_mfma_f32_16x16x32_bf16 v[24:27], v[130:133], v[182:185], v[24:27]
	v_mfma_f32_16x16x32_bf16 v[12:15], v[110:113], v[190:193], v[12:15]
	v_mfma_f32_16x16x32_bf16 v[8:11], v[130:133], v[190:193], v[8:11]
	s_setprio 0
	s_setprio 1
	v_mfma_f32_16x16x32_bf16 v[54:57], v[134:137], v[158:161], v[54:57]
	v_mfma_f32_16x16x32_bf16 v[50:53], v[150:153], v[158:161], v[50:53]
	v_mfma_f32_16x16x32_bf16 v[38:41], v[134:137], v[170:173], v[38:41]
	v_mfma_f32_16x16x32_bf16 v[34:37], v[150:153], v[170:173], v[34:37]
	v_mfma_f32_16x16x32_bf16 v[20:23], v[134:137], v[178:181], v[20:23]
	v_mfma_f32_16x16x32_bf16 v[16:19], v[150:153], v[178:181], v[16:19]
	v_mfma_f32_16x16x32_bf16 v[4:7], v[134:137], v[186:189], v[4:7]
	v_mfma_f32_16x16x32_bf16 v[0:3], v[150:153], v[186:189], v[0:3]
	v_mfma_f32_16x16x32_bf16 v[54:57], v[138:141], v[162:165], v[54:57]
	v_mfma_f32_16x16x32_bf16 v[50:53], v[154:157], v[162:165], v[50:53]
	v_mfma_f32_16x16x32_bf16 v[38:41], v[138:141], v[174:177], v[38:41]
	v_mfma_f32_16x16x32_bf16 v[34:37], v[154:157], v[174:177], v[34:37]
	v_mfma_f32_16x16x32_bf16 v[20:23], v[138:141], v[182:185], v[20:23]
	v_mfma_f32_16x16x32_bf16 v[16:19], v[154:157], v[182:185], v[16:19]
	v_mfma_f32_16x16x32_bf16 v[4:7], v[138:141], v[190:193], v[4:7]
	v_mfma_f32_16x16x32_bf16 v[0:3], v[154:157], v[190:193], v[0:3]
	s_setprio 0
	s_barrier
; #define PG8_STAGE(bufoff, gbase, voff) do { _Pragma("unroll") for (int _i = 0; _i < 2; ++_i) \
;         __builtin_amdgcn_global_load_lds((const unsigned*)((const char*)(gbase) + (voff)[_i]), (PG8_LAS unsigned*)(lds + (bufoff) + ldsw + _i * 8192), 16, 0, 0); } while (0)
; #define PG8_LDA(dst, b, h) do { _Pragma("unroll") for (int m = 0; m < 4; ++m) _Pragma("unroll") for (int k = 0; k < 2; ++k) dst[m][k] = *(const PG8_LAS bf16x8*)(lds + PG8_SA(b, h) + aoff + m * 2048 + k * 1024); } while (0)
; #define PG8_LDB(dst, b, h) do { _Pragma("unroll") for (int n = 0; n < 2; ++n) _Pragma("unroll") for (int k = 0; k < 2; ++k) dst[n][k] = *(const PG8_LAS bf16x8*)(lds + PG8_SB(b, h) + boff + n * 2048 + k * 1024); } while (0)
; #define PG8_MMA(ai, bj, At, Bt) do { __builtin_amdgcn_s_setprio(1); _Pragma("unroll") for (int m = 0; m < 4; ++m) _Pragma("unroll") for (int n = 0; n < 2; ++n) _Pragma("unroll") for (int k = 0; k < 2; ++k) \
;         acc[ai][bj][m][n] = __builtin_amdgcn_mfma_f32_16x16x32_bf16(Bt[n][k], At[m][k], acc[ai][bj][m][n], 0, 0, 0); __builtin_amdgcn_s_setprio(0); } while (0)
; #define PG8_WAIT_V(n) asm volatile("s_waitcnt vmcnt(" #n ")" ::: "memory")
; #define PG8_WAIT_L(n) asm volatile("s_waitcnt lgkmcnt(" #n ")" ::: "memory")
; #define PG8_BAR __builtin_amdgcn_s_barrier()
; #define PG8_SCHED __builtin_amdgcn_sched_barrier(0)
; template <class Epi, class Sched, bool ALIGN_EPI = false, bool SP2 = false, bool KHOOK = false>
; __device__ __forceinline__ void gemm_phase(PG8_LAS unsigned char* lds, const Gemm g, const Sched& S, const Epi& E, const int tid_in) {
;     ...
;             PG8_LDB(B0, 1, 0); PG8_LDB(B1, 1, 1); PG8_SCHED; PG8_LDA(At, 1, 0); PG8_STAGE(PG8_SA(0, 1), a2 + hstep, voffA);
;             PG8_WAIT_V(8); PG8_WAIT_L(0); PG8_BAR; PG8_MMA(0, 0, At, B0); PG8_MMA(0, 1, At, B1); PG8_BAR; PG8_SCHED;
	s_add_i32 s45, 0, 0x18000
	s_add_i32 s46, 0, 0x1c000
	v_add_u32_e32 v130, s45, v247
	v_add_u32_e32 v154, s46, v247
	ds_read_b128 v[106:109], v130
	ds_read_b128 v[110:113], v130 offset:1024
	ds_read_b128 v[122:125], v130 offset:2048
	ds_read_b128 v[130:133], v130 offset:3072
	ds_read_b128 v[134:137], v154
	ds_read_b128 v[138:141], v154 offset:1024
	ds_read_b128 v[150:153], v154 offset:2048
	ds_read_b128 v[154:157], v154 offset:3072
	s_add_u32 s26, s26, 0x80000
	s_addc_u32 s27, s27, 0
	s_mov_b32 m0, s31
	v_lshl_add_u64 v[216:217], s[26:27], 0, v[206:207]
	ds_read_b128 v[158:161], v249 offset:32768
	ds_read_b128 v[162:165], v249 offset:33792
	ds_read_b128 v[170:173], v249 offset:34816
	ds_read_b128 v[174:177], v249 offset:35840
	ds_read_b128 v[178:181], v249 offset:36864
	ds_read_b128 v[182:185], v249 offset:37888
	ds_read_b128 v[186:189], v249 offset:38912
	ds_read_b128 v[190:193], v249 offset:39936
	global_load_lds_dwordx4 v[216:217], off
	s_mov_b32 m0, s33
	v_lshl_add_u64 v[216:217], s[26:27], 0, v[204:205]
	global_load_lds_dwordx4 v[216:217], off
	s_waitcnt vmcnt(8)
	s_waitcnt lgkmcnt(0)
	s_barrier
	s_setprio 1
	s_waitcnt lgkmcnt(0)
	v_mfma_f32_16x16x32_bf16 v[166:169], v[106:109], v[158:161], v[166:169]
	v_mfma_f32_16x16x32_bf16 v[146:149], v[122:125], v[158:161], v[146:149]
	v_mfma_f32_16x16x32_bf16 v[118:121], v[106:109], v[170:173], v[118:121]
	v_mfma_f32_16x16x32_bf16 v[114:117], v[122:125], v[170:173], v[114:117]
	v_mfma_f32_16x16x32_bf16 v[94:97], v[106:109], v[178:181], v[94:97]
	v_mfma_f32_16x16x32_bf16 v[90:93], v[122:125], v[178:181], v[90:93]
	v_mfma_f32_16x16x32_bf16 v[78:81], v[106:109], v[186:189], v[78:81]
	v_mfma_f32_16x16x32_bf16 v[74:77], v[122:125], v[186:189], v[74:77]
	v_mfma_f32_16x16x32_bf16 v[166:169], v[110:113], v[162:165], v[166:169]
	v_mfma_f32_16x16x32_bf16 v[146:149], v[130:133], v[162:165], v[146:149]
	v_mfma_f32_16x16x32_bf16 v[118:121], v[110:113], v[174:177], v[118:121]
	v_mfma_f32_16x16x32_bf16 v[114:117], v[130:133], v[174:177], v[114:117]
	v_mfma_f32_16x16x32_bf16 v[94:97], v[110:113], v[182:185], v[94:97]
	v_mfma_f32_16x16x32_bf16 v[90:93], v[130:133], v[182:185], v[90:93]
	v_mfma_f32_16x16x32_bf16 v[78:81], v[110:113], v[190:193], v[78:81]
	v_mfma_f32_16x16x32_bf16 v[74:77], v[130:133], v[190:193], v[74:77]
	s_setprio 0
	s_setprio 1
	v_mfma_f32_16x16x32_bf16 v[142:145], v[134:137], v[158:161], v[142:145]
	v_mfma_f32_16x16x32_bf16 v[126:129], v[150:153], v[158:161], v[126:129]
	v_mfma_f32_16x16x32_bf16 v[102:105], v[134:137], v[170:173], v[102:105]
	v_mfma_f32_16x16x32_bf16 v[98:101], v[150:153], v[170:173], v[98:101]
	v_mfma_f32_16x16x32_bf16 v[86:89], v[134:137], v[178:181], v[86:89]
	v_mfma_f32_16x16x32_bf16 v[82:85], v[150:153], v[178:181], v[82:85]
	v_mfma_f32_16x16x32_bf16 v[70:73], v[134:137], v[186:189], v[70:73]
	v_mfma_f32_16x16x32_bf16 v[66:69], v[150:153], v[186:189], v[66:69]
	v_mfma_f32_16x16x32_bf16 v[142:145], v[138:141], v[162:165], v[142:145]
	v_mfma_f32_16x16x32_bf16 v[126:129], v[154:157], v[162:165], v[126:129]
	v_mfma_f32_16x16x32_bf16 v[102:105], v[138:141], v[174:177], v[102:105]
	v_mfma_f32_16x16x32_bf16 v[98:101], v[154:157], v[174:177], v[98:101]
	v_mfma_f32_16x16x32_bf16 v[86:89], v[138:141], v[182:185], v[86:89]
	v_mfma_f32_16x16x32_bf16 v[82:85], v[154:157], v[182:185], v[82:85]
	v_mfma_f32_16x16x32_bf16 v[70:73], v[138:141], v[190:193], v[70:73]
	v_mfma_f32_16x16x32_bf16 v[66:69], v[154:157], v[190:193], v[66:69]
	s_setprio 0
	s_barrier
; #define PG8_STAGE(bufoff, gbase, voff) do { _Pragma("unroll") for (int _i = 0; _i < 2; ++_i) \
;         __builtin_amdgcn_global_load_lds((const unsigned*)((const char*)(gbase) + (voff)[_i]), (PG8_LAS unsigned*)(lds + (bufoff) + ldsw + _i * 8192), 16, 0, 0); } while (0)
; #define PG8_LDA(dst, b, h) do { _Pragma("unroll") for (int m = 0; m < 4; ++m) _Pragma("unroll") for (int k = 0; k < 2; ++k) dst[m][k] = *(const PG8_LAS bf16x8*)(lds + PG8_SA(b, h) + aoff + m * 2048 + k * 1024); } while (0)
; #define PG8_MMA(ai, bj, At, Bt) do { __builtin_amdgcn_s_setprio(1); _Pragma("unroll") for (int m = 0; m < 4; ++m) _Pragma("unroll") for (int n = 0; n < 2; ++n) _Pragma("unroll") for (int k = 0; k < 2; ++k) \
;         acc[ai][bj][m][n] = __builtin_amdgcn_mfma_f32_16x16x32_bf16(Bt[n][k], At[m][k], acc[ai][bj][m][n], 0, 0, 0); __builtin_amdgcn_s_setprio(0); } while (0)
; #define PG8_WAIT_V(n) asm volatile("s_waitcnt vmcnt(" #n ")" ::: "memory")
; #define PG8_WAIT_L(n) asm volatile("s_waitcnt lgkmcnt(" #n ")" ::: "memory")
; #define PG8_BAR __builtin_amdgcn_s_barrier()
; #define PG8_SCHED __builtin_amdgcn_sched_barrier(0)
; template <class Epi, class Sched, bool ALIGN_EPI = false, bool SP2 = false, bool KHOOK = false>
; __device__ __forceinline__ void gemm_phase(PG8_LAS unsigned char* lds, const Gemm g, const Sched& S, const Epi& E, const int tid_in) {
;     ...
;         for (int t = 0; t < nt; t += 2) {
;     ...
;             PG8_LDA(At, 1, 1); PG8_STAGE(PG8_SB(1, 0), b3, voffB); PG8_STAGE(PG8_SB(1, 1), b3 + hstep, voffB); PG8_STAGE(PG8_SA(1, 0), a3, voffA);
;             PG8_WAIT_V(8); PG8_WAIT_L(0); PG8_BAR; PG8_MMA(1, 0, At, B0); PG8_MMA(1, 1, At, B1); PG8_BAR; PG8_SCHED;
	s_add_i32 s26, s45, s19
	v_lshl_add_u64 v[198:199], v[198:199], 0, s[90:91]
	s_mov_b32 m0, s26
	ds_read_b128 v[158:161], v249 offset:49152
	ds_read_b128 v[162:165], v249 offset:50176
	ds_read_b128 v[170:173], v249 offset:51200
	ds_read_b128 v[174:177], v249 offset:52224
	ds_read_b128 v[178:181], v249 offset:53248
	ds_read_b128 v[182:185], v249 offset:54272
	ds_read_b128 v[186:189], v249 offset:55296
	ds_read_b128 v[190:193], v249 offset:56320
	global_load_lds_dwordx4 v[198:199], off
	s_add_i32 m0, s26, 0x2000
	s_add_u32 s22, s22, 0x80080
	v_lshl_add_u64 v[198:199], v[200:201], 0, s[90:91]
	s_addc_u32 s23, s23, 0
	s_add_i32 s26, s46, s19
	global_load_lds_dwordx4 v[198:199], off
	s_mov_b32 m0, s26
	v_lshl_add_u64 v[198:199], s[22:23], 0, v[32:33]
	global_load_lds_dwordx4 v[198:199], off
	s_add_i32 m0, s26, 0x2000
	v_lshl_add_u64 v[198:199], s[22:23], 0, v[202:203]
	global_load_lds_dwordx4 v[198:199], off
	s_mov_b32 m0, s36
	v_lshl_add_u64 v[198:199], v[212:213], 0, s[90:91]
	global_load_lds_dwordx4 v[198:199], off
	s_mov_b32 m0, s37
	v_lshl_add_u64 v[198:199], v[214:215], 0, s[90:91]
	global_load_lds_dwordx4 v[198:199], off
	s_waitcnt vmcnt(8)
	s_waitcnt lgkmcnt(0)
	s_barrier
	s_setprio 1
	s_waitcnt lgkmcnt(0)
	v_mfma_f32_16x16x32_bf16 v[62:65], v[106:109], v[158:161], v[62:65]
	v_mfma_f32_16x16x32_bf16 v[58:61], v[122:125], v[158:161], v[58:61]
	v_mfma_f32_16x16x32_bf16 v[46:49], v[106:109], v[170:173], v[46:49]
	v_mfma_f32_16x16x32_bf16 v[42:45], v[122:125], v[170:173], v[42:45]
	v_mfma_f32_16x16x32_bf16 v[28:31], v[106:109], v[178:181], v[28:31]
	v_mfma_f32_16x16x32_bf16 v[24:27], v[122:125], v[178:181], v[24:27]
	v_mfma_f32_16x16x32_bf16 v[12:15], v[106:109], v[186:189], v[12:15]
	v_mfma_f32_16x16x32_bf16 v[8:11], v[122:125], v[186:189], v[8:11]
	v_mfma_f32_16x16x32_bf16 v[62:65], v[110:113], v[162:165], v[62:65]
	v_mfma_f32_16x16x32_bf16 v[58:61], v[130:133], v[162:165], v[58:61]
	v_mfma_f32_16x16x32_bf16 v[46:49], v[110:113], v[174:177], v[46:49]
	v_mfma_f32_16x16x32_bf16 v[42:45], v[130:133], v[174:177], v[42:45]
	v_mfma_f32_16x16x32_bf16 v[28:31], v[110:113], v[182:185], v[28:31]
	v_mfma_f32_16x16x32_bf16 v[24:27], v[130:133], v[182:185], v[24:27]
	v_mfma_f32_16x16x32_bf16 v[12:15], v[110:113], v[190:193], v[12:15]
	v_mfma_f32_16x16x32_bf16 v[8:11], v[130:133], v[190:193], v[8:11]
	s_setprio 0
	s_setprio 1
	v_mfma_f32_16x16x32_bf16 v[54:57], v[134:137], v[158:161], v[54:57]
	v_mfma_f32_16x16x32_bf16 v[50:53], v[150:153], v[158:161], v[50:53]
	v_mfma_f32_16x16x32_bf16 v[38:41], v[134:137], v[170:173], v[38:41]
	v_mfma_f32_16x16x32_bf16 v[34:37], v[150:153], v[170:173], v[34:37]
	v_mfma_f32_16x16x32_bf16 v[20:23], v[134:137], v[178:181], v[20:23]
	v_mfma_f32_16x16x32_bf16 v[16:19], v[150:153], v[178:181], v[16:19]
	v_mfma_f32_16x16x32_bf16 v[4:7], v[134:137], v[186:189], v[4:7]
	v_mfma_f32_16x16x32_bf16 v[0:3], v[150:153], v[186:189], v[0:3]
	v_mfma_f32_16x16x32_bf16 v[54:57], v[138:141], v[162:165], v[54:57]
	v_mfma_f32_16x16x32_bf16 v[50:53], v[154:157], v[162:165], v[50:53]
	v_mfma_f32_16x16x32_bf16 v[38:41], v[138:141], v[174:177], v[38:41]
	v_mfma_f32_16x16x32_bf16 v[34:37], v[154:157], v[174:177], v[34:37]
	v_mfma_f32_16x16x32_bf16 v[20:23], v[138:141], v[182:185], v[20:23]
	v_mfma_f32_16x16x32_bf16 v[16:19], v[154:157], v[182:185], v[16:19]
	v_mfma_f32_16x16x32_bf16 v[4:7], v[138:141], v[190:193], v[4:7]
	v_mfma_f32_16x16x32_bf16 v[0:3], v[154:157], v[190:193], v[0:3]
	s_setprio 0
	s_barrier
	s_add_i32 s44, s44, 2
	s_add_u32 s16, s16, 0x100
	s_addc_u32 s17, s17, 0
	s_add_u32 s41, s41, 0x100
	s_addc_u32 s42, s42, 0
	s_cmp_gt_u32 s44, 29
	s_cbranch_scc0 .LBB0_867
	s_and_b64 vcc, exec, s[4:5]
	s_cbranch_vccz .LBB0_870
	s_barrier

; #define GPROBE_BEGIN(id) do { if (((PROBE_GEMM_SEL >> (id)) & 1) && blockIdx.x == 0 && tid_in < 64 && g.N == 20480) { volatile PG8_LAS unsigned long long* PW_ = (volatile PG8_LAS unsigned long long*)(lds + 163840 - 512 + 64); PW_[0] = __builtin_amdgcn_s_memrealtime(); } } while (0)
; #define PG8_BAR __builtin_amdgcn_s_barrier()
; template <class Epi, class Sched, bool ALIGN_EPI = false, bool SP2 = false, bool KHOOK = false>
; __device__ __forceinline__ void gemm_phase(PG8_LAS unsigned char* lds, const Gemm g, const Sched& S, const Epi& E, const int tid_in) {
;     ...
;         const bool has_next = S.next(ui + 1, nxt);
;         const char* nA = has_next ? (const char*)g.A + (size_t)nxt.pm * tstep + (size_t)nxt.pn * ksl : cA; const char* nB = has_next ? (const char*)g.Bt + (size_t)nxt.pn * bts + (size_t)nxt.pn * ksl + (gdv ? (size_t)(nxt.pm / gdv) * gst : 0) : cB;
;         GPROBE_END(2); GPROBE_BEGIN(1);
;         for (int t = 0; t < nt; t += 2) {
;             const bool last = (t == nt - 2);
;             const char* a1 = cA + (size_t)(t + 1) * kstep;
;             const char* a2 = last ? nA : cA + (size_t)(t + 2) * kstep; const char* b2 = last ? nB : cB + (size_t)(t + 2) * kstep;
;             const char* a3 = a2 + kstep; const char* b3 = b2 + kstep;
;             if (last && has_next) S.a_ready(nxt);
;             if constexpr (SP2) {
;             PG8_LDB(B0, 0, 0); PG8_LDB(B1, 0, 1); PG8_SCHED; PG8_LDA(At, 0, 0); PG8_STAGE(PG8_SA(1, 1), a1 + hstep, voffA);
;             PG8_WAIT_V(8); PG8_WAIT_L(0); PG8_BAR; PG8_MMA(0, 0, At, B0); PG8_MMA(0, 1, At, B1); PG8_BAR; PG8_SCHED;
;             PG8_LDA(At, 0, 1); PG8_STAGE(PG8_SB(0, 0), b2, voffB); PG8_STAGE(PG8_SB(0, 1), b2 + hstep, voffB); PG8_STAGE(PG8_SA(0, 0), a2, voffA);
;             PG8_WAIT_V(8); PG8_WAIT_L(0); PG8_BAR; PG8_MMA(1, 0, At, B0); PG8_MMA(1, 1, At, B1); PG8_BAR; PG8_SCHED;
;             PG8_LDB(B0, 1, 0); PG8_LDB(B1, 1, 1); PG8_SCHED; PG8_LDA(At, 1, 0); PG8_STAGE(PG8_SA(0, 1), a2 + hstep, voffA);
;             PG8_WAIT_V(8); PG8_WAIT_L(0); PG8_BAR; PG8_MMA(0, 0, At, B0); PG8_MMA(0, 1, At, B1); PG8_BAR; PG8_SCHED;
;             PG8_LDA(At, 1, 1); PG8_STAGE(PG8_SB(1, 0), b3, voffB); PG8_STAGE(PG8_SB(1, 1), b3 + hstep, voffB); PG8_STAGE(PG8_SA(1, 0), a3, voffA);
;             PG8_WAIT_V(8); PG8_WAIT_L(0); PG8_BAR; PG8_MMA(1, 0, At, B0); PG8_MMA(1, 1, At, B1); PG8_BAR; PG8_SCHED;
.LBB0_948:
	s_add_u32 s48, s4, s22
	s_addc_u32 s49, s5, s23
	s_add_u32 s48, s48, 0x100
	s_addc_u32 s49, s49, 0
	s_add_u32 s57, s18, s22
	s_addc_u32 s58, s19, s23
	s_add_i32 s59, 0, 0x10000
	s_cmpk_eq_i32 s22, 0xf00
	s_cselect_b32 s53, s13, s49
	s_cselect_b32 s52, s25, s48
	s_cselect_b32 s49, s11, s58
	s_cselect_b32 s48, s51, s57
	s_add_i32 s57, 0, 0x14000
	v_add_u32_e32 v158, s59, v144
	v_add_u32_e32 v170, s57, v144
	ds_read_b128 v[146:149], v158
	ds_read_b128 v[150:153], v158 offset:1024
	ds_read_b128 v[154:157], v158 offset:2048
	ds_read_b128 v[158:161], v158 offset:3072
	ds_read_b128 v[162:165], v170
	ds_read_b128 v[166:169], v170 offset:1024
	ds_read_b128 v[176:179], v170 offset:2048
	ds_read_b128 v[180:183], v170 offset:3072
	v_lshl_add_u64 v[170:171], v[140:141], 0, s[22:23]
	s_add_i32 m0, s40, 0xc000
	ds_read_b128 v[184:187], v145
	ds_read_b128 v[188:191], v145 offset:1024
	ds_read_b128 v[198:201], v145 offset:2048
	ds_read_b128 v[202:205], v145 offset:3072
	ds_read_b128 v[206:209], v145 offset:4096
	ds_read_b128 v[210:213], v145 offset:5120
	ds_read_b128 v[214:217], v145 offset:6144
	ds_read_b128 v[218:221], v145 offset:7168
	global_load_lds_dwordx4 v[170:171], off
	s_add_i32 m0, s40, 0xe000
	v_lshl_add_u64 v[170:171], v[142:143], 0, s[22:23]
	global_load_lds_dwordx4 v[170:171], off
	s_waitcnt vmcnt(8)
	s_waitcnt lgkmcnt(0)
	s_barrier
	s_setprio 1
	s_waitcnt lgkmcnt(0)
	v_mfma_f32_16x16x32_bf16 v[118:121], v[146:149], v[184:187], v[118:121]
	v_mfma_f32_16x16x32_bf16 v[114:117], v[154:157], v[184:187], v[114:117]
	v_mfma_f32_16x16x32_bf16 v[134:137], v[146:149], v[198:201], v[134:137]
	v_mfma_f32_16x16x32_bf16 v[130:133], v[154:157], v[198:201], v[130:133]
	v_mfma_f32_16x16x32_bf16 v[94:97], v[146:149], v[206:209], v[94:97]
	v_mfma_f32_16x16x32_bf16 v[90:93], v[154:157], v[206:209], v[90:93]
	v_mfma_f32_16x16x32_bf16 v[78:81], v[146:149], v[214:217], v[78:81]
	v_mfma_f32_16x16x32_bf16 v[74:77], v[154:157], v[214:217], v[74:77]
	v_mfma_f32_16x16x32_bf16 v[118:121], v[150:153], v[188:191], v[118:121]
	v_mfma_f32_16x16x32_bf16 v[114:117], v[158:161], v[188:191], v[114:117]
	v_mfma_f32_16x16x32_bf16 v[134:137], v[150:153], v[202:205], v[134:137]
	v_mfma_f32_16x16x32_bf16 v[130:133], v[158:161], v[202:205], v[130:133]
	v_mfma_f32_16x16x32_bf16 v[94:97], v[150:153], v[210:213], v[94:97]
	v_mfma_f32_16x16x32_bf16 v[90:93], v[158:161], v[210:213], v[90:93]
	v_mfma_f32_16x16x32_bf16 v[78:81], v[150:153], v[218:221], v[78:81]
	v_mfma_f32_16x16x32_bf16 v[74:77], v[158:161], v[218:221], v[74:77]
	s_setprio 0
	s_setprio 1
	v_mfma_f32_16x16x32_bf16 v[106:109], v[162:165], v[184:187], v[106:109]
	v_mfma_f32_16x16x32_bf16 v[102:105], v[176:179], v[184:187], v[102:105]
	v_mfma_f32_16x16x32_bf16 v[110:113], v[162:165], v[198:201], v[110:113]
	v_mfma_f32_16x16x32_bf16 v[98:101], v[176:179], v[198:201], v[98:101]
	v_mfma_f32_16x16x32_bf16 v[86:89], v[162:165], v[206:209], v[86:89]
	v_mfma_f32_16x16x32_bf16 v[82:85], v[176:179], v[206:209], v[82:85]
	v_mfma_f32_16x16x32_bf16 v[70:73], v[162:165], v[214:217], v[70:73]
	v_mfma_f32_16x16x32_bf16 v[66:69], v[176:179], v[214:217], v[66:69]
	v_mfma_f32_16x16x32_bf16 v[106:109], v[166:169], v[188:191], v[106:109]
	v_mfma_f32_16x16x32_bf16 v[102:105], v[180:183], v[188:191], v[102:105]
	v_mfma_f32_16x16x32_bf16 v[110:113], v[166:169], v[202:205], v[110:113]
	v_mfma_f32_16x16x32_bf16 v[98:101], v[180:183], v[202:205], v[98:101]
	v_mfma_f32_16x16x32_bf16 v[86:89], v[166:169], v[210:213], v[86:89]
	v_mfma_f32_16x16x32_bf16 v[82:85], v[180:183], v[210:213], v[82:85]
	v_mfma_f32_16x16x32_bf16 v[70:73], v[166:169], v[218:221], v[70:73]
	v_mfma_f32_16x16x32_bf16 v[66:69], v[180:183], v[218:221], v[66:69]
	s_setprio 0
	s_barrier
	s_add_i32 s58, s59, s39
	v_lshl_add_u64 v[170:171], s[48:49], 0, v[32:33]
	s_mov_b32 m0, s58
	ds_read_b128 v[184:187], v145 offset:16384
	ds_read_b128 v[188:191], v145 offset:17408
	ds_read_b128 v[198:201], v145 offset:18432
	ds_read_b128 v[202:205], v145 offset:19456
	ds_read_b128 v[206:209], v145 offset:20480
	ds_read_b128 v[210:213], v145 offset:21504
	ds_read_b128 v[214:217], v145 offset:22528
	ds_read_b128 v[218:221], v145 offset:23552
	global_load_lds_dwordx4 v[170:171], off
	s_add_i32 m0, s58, 0x2000
	s_add_u32 s58, s48, 0x80000
	v_lshl_add_u64 v[192:193], s[48:49], 0, v[122:123]
	s_addc_u32 s59, s49, 0
	s_add_i32 s57, s57, s39
	global_load_lds_dwordx4 v[192:193], off
	v_lshl_add_u64 v[222:223], s[58:59], 0, v[32:33]
	s_mov_b32 m0, s57
	v_lshl_add_u64 v[224:225], s[52:53], 0, v[124:125]
	global_load_lds_dwordx4 v[222:223], off
	s_add_i32 m0, s57, 0x2000
	v_lshl_add_u64 v[222:223], s[58:59], 0, v[122:123]
	global_load_lds_dwordx4 v[222:223], off
	s_mov_b32 m0, s40
	v_lshl_add_u64 v[222:223], s[52:53], 0, v[126:127]
	global_load_lds_dwordx4 v[222:223], off
	s_mov_b32 m0, s41
	s_nop 0
	global_load_lds_dwordx4 v[224:225], off
	s_waitcnt vmcnt(8)
	s_waitcnt lgkmcnt(0)
	s_barrier
; #define PG8_STAGE(bufoff, gbase, voff) do { _Pragma("unroll") for (int _i = 0; _i < 2; ++_i) \
;         __builtin_amdgcn_global_load_lds((const unsigned*)((const char*)(gbase) + (voff)[_i]), (PG8_LAS unsigned*)(lds + (bufoff) + ldsw + _i * 8192), 16, 0, 0); } while (0)
; #define PG8_LDA(dst, b, h) do { _Pragma("unroll") for (int m = 0; m < 4; ++m) _Pragma("unroll") for (int k = 0; k < 2; ++k) dst[m][k] = *(const PG8_LAS bf16x8*)(lds + PG8_SA(b, h) + aoff + m * 2048 + k * 1024); } while (0)
; #define PG8_LDB(dst, b, h) do { _Pragma("unroll") for (int n = 0; n < 2; ++n) _Pragma("unroll") for (int k = 0; k < 2; ++k) dst[n][k] = *(const PG8_LAS bf16x8*)(lds + PG8_SB(b, h) + boff + n * 2048 + k * 1024); } while (0)
; #define PG8_MMA(ai, bj, At, Bt) do { __builtin_amdgcn_s_setprio(1); _Pragma("unroll") for (int m = 0; m < 4; ++m) _Pragma("unroll") for (int n = 0; n < 2; ++n) _Pragma("unroll") for (int k = 0; k < 2; ++k) \
;         acc[ai][bj][m][n] = __builtin_amdgcn_mfma_f32_16x16x32_bf16(Bt[n][k], At[m][k], acc[ai][bj][m][n], 0, 0, 0); __builtin_amdgcn_s_setprio(0); } while (0)
; #define PG8_WAIT_V(n) asm volatile("s_waitcnt vmcnt(" #n ")" ::: "memory")
; #define PG8_WAIT_L(n) asm volatile("s_waitcnt lgkmcnt(" #n ")" ::: "memory")
; #define PG8_BAR __builtin_amdgcn_s_barrier()
; #define PG8_SCHED __builtin_amdgcn_sched_barrier(0)
; template <class Epi, class Sched, bool ALIGN_EPI = false, bool SP2 = false, bool KHOOK = false>
; __device__ __forceinline__ void gemm_phase(PG8_LAS unsigned char* lds, const Gemm g, const Sched& S, const Epi& E, const int tid_in) {
;     ...
;             PG8_LDA(At, 0, 1); PG8_STAGE(PG8_SB(0, 0), b2, voffB); PG8_STAGE(PG8_SB(0, 1), b2 + hstep, voffB); PG8_STAGE(PG8_SA(0, 0), a2, voffA);
;             PG8_WAIT_V(8); PG8_WAIT_L(0); PG8_BAR; PG8_MMA(1, 0, At, B0); PG8_MMA(1, 1, At, B1); PG8_BAR; PG8_SCHED;
;             PG8_LDB(B0, 1, 0); PG8_LDB(B1, 1, 1); PG8_SCHED; PG8_LDA(At, 1, 0); PG8_STAGE(PG8_SA(0, 1), a2 + hstep, voffA);
;             PG8_WAIT_V(8); PG8_WAIT_L(0); PG8_BAR; PG8_MMA(0, 0, At, B0); PG8_MMA(0, 1, At, B1); PG8_BAR; PG8_SCHED;
	s_setprio 1
	s_waitcnt lgkmcnt(0)
	v_mfma_f32_16x16x32_bf16 v[62:65], v[146:149], v[184:187], v[62:65]
	v_mfma_f32_16x16x32_bf16 v[58:61], v[154:157], v[184:187], v[58:61]
	v_mfma_f32_16x16x32_bf16 v[46:49], v[146:149], v[198:201], v[46:49]
	v_mfma_f32_16x16x32_bf16 v[42:45], v[154:157], v[198:201], v[42:45]
	v_mfma_f32_16x16x32_bf16 v[28:31], v[146:149], v[206:209], v[28:31]
	v_mfma_f32_16x16x32_bf16 v[24:27], v[154:157], v[206:209], v[24:27]
	v_mfma_f32_16x16x32_bf16 v[12:15], v[146:149], v[214:217], v[12:15]
	v_mfma_f32_16x16x32_bf16 v[8:11], v[154:157], v[214:217], v[8:11]
	v_mfma_f32_16x16x32_bf16 v[62:65], v[150:153], v[188:191], v[62:65]
	v_mfma_f32_16x16x32_bf16 v[58:61], v[158:161], v[188:191], v[58:61]
	v_mfma_f32_16x16x32_bf16 v[46:49], v[150:153], v[202:205], v[46:49]
	v_mfma_f32_16x16x32_bf16 v[42:45], v[158:161], v[202:205], v[42:45]
	v_mfma_f32_16x16x32_bf16 v[28:31], v[150:153], v[210:213], v[28:31]
	v_mfma_f32_16x16x32_bf16 v[24:27], v[158:161], v[210:213], v[24:27]
	v_mfma_f32_16x16x32_bf16 v[12:15], v[150:153], v[218:221], v[12:15]
	v_mfma_f32_16x16x32_bf16 v[8:11], v[158:161], v[218:221], v[8:11]
	s_setprio 0
	s_setprio 1
	v_mfma_f32_16x16x32_bf16 v[54:57], v[162:165], v[184:187], v[54:57]
	v_mfma_f32_16x16x32_bf16 v[50:53], v[176:179], v[184:187], v[50:53]
	v_mfma_f32_16x16x32_bf16 v[38:41], v[162:165], v[198:201], v[38:41]
	v_mfma_f32_16x16x32_bf16 v[34:37], v[176:179], v[198:201], v[34:37]
	v_mfma_f32_16x16x32_bf16 v[20:23], v[162:165], v[206:209], v[20:23]
	v_mfma_f32_16x16x32_bf16 v[16:19], v[176:179], v[206:209], v[16:19]
	v_mfma_f32_16x16x32_bf16 v[4:7], v[162:165], v[214:217], v[4:7]
	v_mfma_f32_16x16x32_bf16 v[0:3], v[176:179], v[214:217], v[0:3]
	v_mfma_f32_16x16x32_bf16 v[54:57], v[166:169], v[188:191], v[54:57]
	v_mfma_f32_16x16x32_bf16 v[50:53], v[180:183], v[188:191], v[50:53]
	v_mfma_f32_16x16x32_bf16 v[38:41], v[166:169], v[202:205], v[38:41]
	v_mfma_f32_16x16x32_bf16 v[34:37], v[180:183], v[202:205], v[34:37]
	v_mfma_f32_16x16x32_bf16 v[20:23], v[166:169], v[210:213], v[20:23]
	v_mfma_f32_16x16x32_bf16 v[16:19], v[180:183], v[210:213], v[16:19]
	v_mfma_f32_16x16x32_bf16 v[4:7], v[166:169], v[218:221], v[4:7]
	v_mfma_f32_16x16x32_bf16 v[0:3], v[180:183], v[218:221], v[0:3]
	s_setprio 0
	s_barrier
	s_add_i32 s57, 0, 0x18000
	s_add_i32 s58, 0, 0x1c000
	v_add_u32_e32 v158, s57, v144
	v_add_u32_e32 v175, s58, v144
	ds_read_b128 v[146:149], v158
	ds_read_b128 v[150:153], v158 offset:1024
	ds_read_b128 v[154:157], v158 offset:2048
	ds_read_b128 v[158:161], v158 offset:3072
	ds_read_b128 v[162:165], v175
	ds_read_b128 v[166:169], v175 offset:1024
	ds_read_b128 v[176:179], v175 offset:2048
	ds_read_b128 v[180:183], v175 offset:3072
	s_add_u32 s52, s52, 0x80000
	s_addc_u32 s53, s53, 0
	s_mov_b32 m0, s42
	v_lshl_add_u64 v[226:227], s[52:53], 0, v[126:127]
	ds_read_b128 v[184:187], v145 offset:32768
	ds_read_b128 v[188:191], v145 offset:33792
	ds_read_b128 v[198:201], v145 offset:34816
	ds_read_b128 v[202:205], v145 offset:35840
	ds_read_b128 v[206:209], v145 offset:36864
	ds_read_b128 v[210:213], v145 offset:37888
	ds_read_b128 v[214:217], v145 offset:38912
	ds_read_b128 v[218:221], v145 offset:39936
	global_load_lds_dwordx4 v[226:227], off
	s_mov_b32 m0, s44
	v_lshl_add_u64 v[226:227], s[52:53], 0, v[124:125]
	global_load_lds_dwordx4 v[226:227], off
	s_waitcnt vmcnt(8)
	s_waitcnt lgkmcnt(0)
	s_barrier
	s_setprio 1
	s_waitcnt lgkmcnt(0)
	v_mfma_f32_16x16x32_bf16 v[118:121], v[146:149], v[184:187], v[118:121]
	v_mfma_f32_16x16x32_bf16 v[114:117], v[154:157], v[184:187], v[114:117]
	v_mfma_f32_16x16x32_bf16 v[134:137], v[146:149], v[198:201], v[134:137]
	v_mfma_f32_16x16x32_bf16 v[130:133], v[154:157], v[198:201], v[130:133]
	v_mfma_f32_16x16x32_bf16 v[94:97], v[146:149], v[206:209], v[94:97]
	v_mfma_f32_16x16x32_bf16 v[90:93], v[154:157], v[206:209], v[90:93]
	v_mfma_f32_16x16x32_bf16 v[78:81], v[146:149], v[214:217], v[78:81]
	v_mfma_f32_16x16x32_bf16 v[74:77], v[154:157], v[214:217], v[74:77]
	v_mfma_f32_16x16x32_bf16 v[118:121], v[150:153], v[188:191], v[118:121]
	v_mfma_f32_16x16x32_bf16 v[114:117], v[158:161], v[188:191], v[114:117]
	v_mfma_f32_16x16x32_bf16 v[134:137], v[150:153], v[202:205], v[134:137]
	v_mfma_f32_16x16x32_bf16 v[130:133], v[158:161], v[202:205], v[130:133]
	v_mfma_f32_16x16x32_bf16 v[94:97], v[150:153], v[210:213], v[94:97]
	v_mfma_f32_16x16x32_bf16 v[90:93], v[158:161], v[210:213], v[90:93]
	v_mfma_f32_16x16x32_bf16 v[78:81], v[150:153], v[218:221], v[78:81]
	v_mfma_f32_16x16x32_bf16 v[74:77], v[158:161], v[218:221], v[74:77]
	s_setprio 0
	s_setprio 1
	v_mfma_f32_16x16x32_bf16 v[106:109], v[162:165], v[184:187], v[106:109]
	v_mfma_f32_16x16x32_bf16 v[102:105], v[176:179], v[184:187], v[102:105]
	v_mfma_f32_16x16x32_bf16 v[110:113], v[162:165], v[198:201], v[110:113]
	v_mfma_f32_16x16x32_bf16 v[98:101], v[176:179], v[198:201], v[98:101]
	v_mfma_f32_16x16x32_bf16 v[86:89], v[162:165], v[206:209], v[86:89]
	v_mfma_f32_16x16x32_bf16 v[82:85], v[176:179], v[206:209], v[82:85]
	v_mfma_f32_16x16x32_bf16 v[70:73], v[162:165], v[214:217], v[70:73]
	v_mfma_f32_16x16x32_bf16 v[66:69], v[176:179], v[214:217], v[66:69]
	v_mfma_f32_16x16x32_bf16 v[106:109], v[166:169], v[188:191], v[106:109]
	v_mfma_f32_16x16x32_bf16 v[102:105], v[180:183], v[188:191], v[102:105]
	v_mfma_f32_16x16x32_bf16 v[110:113], v[166:169], v[202:205], v[110:113]
	v_mfma_f32_16x16x32_bf16 v[98:101], v[180:183], v[202:205], v[98:101]
	v_mfma_f32_16x16x32_bf16 v[86:89], v[166:169], v[210:213], v[86:89]
	v_mfma_f32_16x16x32_bf16 v[82:85], v[180:183], v[210:213], v[82:85]
	v_mfma_f32_16x16x32_bf16 v[70:73], v[166:169], v[218:221], v[70:73]
	v_mfma_f32_16x16x32_bf16 v[66:69], v[180:183], v[218:221], v[66:69]
	s_setprio 0
	s_barrier
; #define PG8_STAGE(bufoff, gbase, voff) do { _Pragma("unroll") for (int _i = 0; _i < 2; ++_i) \
;         __builtin_amdgcn_global_load_lds((const unsigned*)((const char*)(gbase) + (voff)[_i]), (PG8_LAS unsigned*)(lds + (bufoff) + ldsw + _i * 8192), 16, 0, 0); } while (0)
; #define PG8_LDA(dst, b, h) do { _Pragma("unroll") for (int m = 0; m < 4; ++m) _Pragma("unroll") for (int k = 0; k < 2; ++k) dst[m][k] = *(const PG8_LAS bf16x8*)(lds + PG8_SA(b, h) + aoff + m * 2048 + k * 1024); } while (0)
; #define PG8_MMA(ai, bj, At, Bt) do { __builtin_amdgcn_s_setprio(1); _Pragma("unroll") for (int m = 0; m < 4; ++m) _Pragma("unroll") for (int n = 0; n < 2; ++n) _Pragma("unroll") for (int k = 0; k < 2; ++k) \
;         acc[ai][bj][m][n] = __builtin_amdgcn_mfma_f32_16x16x32_bf16(Bt[n][k], At[m][k], acc[ai][bj][m][n], 0, 0, 0); __builtin_amdgcn_s_setprio(0); } while (0)
; #define PG8_WAIT_V(n) asm volatile("s_waitcnt vmcnt(" #n ")" ::: "memory")
; #define PG8_WAIT_L(n) asm volatile("s_waitcnt lgkmcnt(" #n ")" ::: "memory")
; #define PG8_BAR __builtin_amdgcn_s_barrier()
; #define PG8_SCHED __builtin_amdgcn_sched_barrier(0)
; template <class Epi, class Sched, bool ALIGN_EPI = false, bool SP2 = false, bool KHOOK = false>
; __device__ __forceinline__ void gemm_phase(PG8_LAS unsigned char* lds, const Gemm g, const Sched& S, const Epi& E, const int tid_in) {
;     ...
;             PG8_LDA(At, 1, 1); PG8_STAGE(PG8_SB(1, 0), b3, voffB); PG8_STAGE(PG8_SB(1, 1), b3 + hstep, voffB); PG8_STAGE(PG8_SA(1, 0), a3, voffA);
;             PG8_WAIT_V(8); PG8_WAIT_L(0); PG8_BAR; PG8_MMA(1, 0, At, B0); PG8_MMA(1, 1, At, B1); PG8_BAR; PG8_SCHED;
;     ...
;         if (!has_next) break;
; #pragma unroll
;         for (int a = 0; a < 2; ++a)
; #pragma unroll
;             for (int b = 0; b < 2; ++b)
; #pragma unroll
;                 for (int m = 0; m < 4; ++m)
; #pragma unroll
;                     for (int n = 0; n < 2; ++n) acc[a][b][m][n] = (f32x4){0.f, 0.f, 0.f, 0.f};
;         cur = nxt; cA = nA; cB = nB; ++ui; load_rr(cur);
	s_add_i32 s52, s57, s39
	v_lshl_add_u64 v[170:171], v[170:171], 0, s[90:91]
	s_mov_b32 m0, s52
	ds_read_b128 v[184:187], v145 offset:49152
	ds_read_b128 v[188:191], v145 offset:50176
	ds_read_b128 v[198:201], v145 offset:51200
	ds_read_b128 v[202:205], v145 offset:52224
	ds_read_b128 v[206:209], v145 offset:53248
	ds_read_b128 v[210:213], v145 offset:54272
	ds_read_b128 v[214:217], v145 offset:55296
	ds_read_b128 v[218:221], v145 offset:56320
	global_load_lds_dwordx4 v[170:171], off
	s_add_i32 m0, s52, 0x2000
	s_add_u32 s48, s48, 0x80080
	v_lshl_add_u64 v[170:171], v[192:193], 0, s[90:91]
	s_addc_u32 s49, s49, 0
	s_add_i32 s52, s58, s39
	global_load_lds_dwordx4 v[170:171], off
	s_mov_b32 m0, s52
	v_lshl_add_u64 v[170:171], s[48:49], 0, v[32:33]
	global_load_lds_dwordx4 v[170:171], off
	s_add_i32 m0, s52, 0x2000
	v_lshl_add_u64 v[170:171], s[48:49], 0, v[122:123]
	global_load_lds_dwordx4 v[170:171], off
	s_mov_b32 m0, s46
	v_lshl_add_u64 v[170:171], v[222:223], 0, s[90:91]
	global_load_lds_dwordx4 v[170:171], off
	s_mov_b32 m0, s47
	v_lshl_add_u64 v[170:171], v[224:225], 0, s[90:91]
	global_load_lds_dwordx4 v[170:171], off
	s_waitcnt vmcnt(8)
	s_waitcnt lgkmcnt(0)
	s_barrier
	s_setprio 1
	s_waitcnt lgkmcnt(0)
	v_mfma_f32_16x16x32_bf16 v[62:65], v[146:149], v[184:187], v[62:65]
	v_mfma_f32_16x16x32_bf16 v[58:61], v[154:157], v[184:187], v[58:61]
	v_mfma_f32_16x16x32_bf16 v[46:49], v[146:149], v[198:201], v[46:49]
	v_mfma_f32_16x16x32_bf16 v[42:45], v[154:157], v[198:201], v[42:45]
	v_mfma_f32_16x16x32_bf16 v[28:31], v[146:149], v[206:209], v[28:31]
	v_mfma_f32_16x16x32_bf16 v[24:27], v[154:157], v[206:209], v[24:27]
	v_mfma_f32_16x16x32_bf16 v[12:15], v[146:149], v[214:217], v[12:15]
	v_mfma_f32_16x16x32_bf16 v[8:11], v[154:157], v[214:217], v[8:11]
	v_mfma_f32_16x16x32_bf16 v[62:65], v[150:153], v[188:191], v[62:65]
	v_mfma_f32_16x16x32_bf16 v[58:61], v[158:161], v[188:191], v[58:61]
	v_mfma_f32_16x16x32_bf16 v[46:49], v[150:153], v[202:205], v[46:49]
	v_mfma_f32_16x16x32_bf16 v[42:45], v[158:161], v[202:205], v[42:45]
	v_mfma_f32_16x16x32_bf16 v[28:31], v[150:153], v[210:213], v[28:31]
	v_mfma_f32_16x16x32_bf16 v[24:27], v[158:161], v[210:213], v[24:27]
	v_mfma_f32_16x16x32_bf16 v[12:15], v[150:153], v[218:221], v[12:15]
	v_mfma_f32_16x16x32_bf16 v[8:11], v[158:161], v[218:221], v[8:11]
	s_setprio 0
	s_setprio 1
	v_mfma_f32_16x16x32_bf16 v[54:57], v[162:165], v[184:187], v[54:57]
	v_mfma_f32_16x16x32_bf16 v[50:53], v[176:179], v[184:187], v[50:53]
	v_mfma_f32_16x16x32_bf16 v[38:41], v[162:165], v[198:201], v[38:41]
	v_mfma_f32_16x16x32_bf16 v[34:37], v[176:179], v[198:201], v[34:37]
	v_mfma_f32_16x16x32_bf16 v[20:23], v[162:165], v[206:209], v[20:23]
	v_mfma_f32_16x16x32_bf16 v[16:19], v[176:179], v[206:209], v[16:19]
	v_mfma_f32_16x16x32_bf16 v[4:7], v[162:165], v[214:217], v[4:7]
	v_mfma_f32_16x16x32_bf16 v[0:3], v[176:179], v[214:217], v[0:3]
	v_mfma_f32_16x16x32_bf16 v[54:57], v[166:169], v[188:191], v[54:57]
	v_mfma_f32_16x16x32_bf16 v[50:53], v[180:183], v[188:191], v[50:53]
	v_mfma_f32_16x16x32_bf16 v[38:41], v[166:169], v[202:205], v[38:41]
	v_mfma_f32_16x16x32_bf16 v[34:37], v[180:183], v[202:205], v[34:37]
	v_mfma_f32_16x16x32_bf16 v[20:23], v[166:169], v[210:213], v[20:23]
	v_mfma_f32_16x16x32_bf16 v[16:19], v[180:183], v[210:213], v[16:19]
	v_mfma_f32_16x16x32_bf16 v[4:7], v[166:169], v[218:221], v[4:7]
	v_mfma_f32_16x16x32_bf16 v[0:3], v[180:183], v[218:221], v[0:3]
	s_setprio 0
	s_barrier
	s_add_i32 s56, s56, 2
	s_add_u32 s22, s22, 0x100
	s_addc_u32 s23, s23, 0
	s_cmp_gt_u32 s56, 29
	s_cbranch_scc0 .LBB0_948
	s_add_u32 s18, s18, 0xffffff00
	s_addc_u32 s19, s19, -1
	s_andn2_b64 vcc, exec, s[26:27]
	s_cbranch_vccnz .LBB0_951
	v_mov_b32_e32 v0, 0
	s_mov_b32 s33, s12
	s_mov_b32 s0, s10
	s_mov_b64 s[4:5], s[30:31]
	s_mov_b32 s50, s24
	v_mov_b32_e32 v1, v0
	v_mov_b32_e32 v2, v0
	v_mov_b32_e32 v3, v0
	v_mov_b32_e32 v4, v0
	v_mov_b32_e32 v5, v0
	v_mov_b32_e32 v6, v0
	v_mov_b32_e32 v7, v0
	v_mov_b32_e32 v16, v0
	v_mov_b32_e32 v17, v0
	v_mov_b32_e32 v18, v0
	v_mov_b32_e32 v19, v0
	v_mov_b32_e32 v20, v0
	v_mov_b32_e32 v21, v0
	v_mov_b32_e32 v22, v0
	v_mov_b32_e32 v23, v0
	v_mov_b32_e32 v34, v0
	v_mov_b32_e32 v35, v0
	v_mov_b32_e32 v36, v0
	v_mov_b32_e32 v37, v0
	v_mov_b32_e32 v38, v0
	v_mov_b32_e32 v39, v0
	v_mov_b32_e32 v40, v0
	v_mov_b32_e32 v41, v0
	v_mov_b32_e32 v50, v0
	v_mov_b32_e32 v51, v0
	v_mov_b32_e32 v52, v0
	v_mov_b32_e32 v53, v0
	v_mov_b32_e32 v54, v0
	v_mov_b32_e32 v55, v0
	v_mov_b32_e32 v56, v0
	v_mov_b32_e32 v57, v0
	v_mov_b32_e32 v8, v0
	v_mov_b32_e32 v9, v0
	v_mov_b32_e32 v10, v0
	v_mov_b32_e32 v11, v0
	v_mov_b32_e32 v12, v0
	v_mov_b32_e32 v13, v0
	v_mov_b32_e32 v14, v0
	v_mov_b32_e32 v15, v0
	v_mov_b32_e32 v24, v0
	v_mov_b32_e32 v25, v0
	v_mov_b32_e32 v26, v0
	v_mov_b32_e32 v27, v0
	v_mov_b32_e32 v28, v0
	v_mov_b32_e32 v29, v0
	v_mov_b32_e32 v30, v0
	v_mov_b32_e32 v31, v0
	v_mov_b32_e32 v42, v0
	v_mov_b32_e32 v43, v0
	v_mov_b32_e32 v44, v0
	v_mov_b32_e32 v45, v0
	v_mov_b32_e32 v46, v0
	v_mov_b32_e32 v47, v0
	v_mov_b32_e32 v48, v0
	v_mov_b32_e32 v49, v0
	v_mov_b32_e32 v58, v0
	v_mov_b32_e32 v59, v0
	v_mov_b32_e32 v60, v0
	v_mov_b32_e32 v61, v0
	v_mov_b32_e32 v62, v0
	v_mov_b32_e32 v63, v0
	v_mov_b32_e32 v64, v0
	v_mov_b32_e32 v65, v0
	v_mov_b32_e32 v66, v0
	v_mov_b32_e32 v67, v0
	v_mov_b32_e32 v68, v0
	v_mov_b32_e32 v69, v0
	v_mov_b32_e32 v70, v0
	v_mov_b32_e32 v71, v0
	v_mov_b32_e32 v72, v0
	v_mov_b32_e32 v73, v0
	v_mov_b32_e32 v82, v0
	v_mov_b32_e32 v83, v0
	v_mov_b32_e32 v84, v0
	v_mov_b32_e32 v85, v0
	v_mov_b32_e32 v86, v0
	v_mov_b32_e32 v87, v0
	v_mov_b32_e32 v88, v0
	v_mov_b32_e32 v89, v0
	v_mov_b32_e32 v98, v0
	v_mov_b32_e32 v99, v0
	v_mov_b32_e32 v100, v0
	v_mov_b32_e32 v101, v0
	v_mov_b32_e32 v110, v0
	v_mov_b32_e32 v111, v0
	v_mov_b32_e32 v112, v0
	v_mov_b32_e32 v113, v0
	v_mov_b32_e32 v102, v0
	v_mov_b32_e32 v103, v0
	v_mov_b32_e32 v104, v0
	v_mov_b32_e32 v105, v0
	v_mov_b32_e32 v106, v0
	v_mov_b32_e32 v107, v0
	v_mov_b32_e32 v108, v0
	v_mov_b32_e32 v109, v0
	v_mov_b32_e32 v74, v0
	v_mov_b32_e32 v75, v0
	v_mov_b32_e32 v76, v0
	v_mov_b32_e32 v77, v0
	v_mov_b32_e32 v78, v0
	v_mov_b32_e32 v79, v0
	v_mov_b32_e32 v80, v0
	v_mov_b32_e32 v81, v0
	v_mov_b32_e32 v90, v0
	v_mov_b32_e32 v91, v0
	v_mov_b32_e32 v92, v0
	v_mov_b32_e32 v93, v0
	v_mov_b32_e32 v94, v0
	v_mov_b32_e32 v95, v0
	v_mov_b32_e32 v96, v0
	v_mov_b32_e32 v97, v0
	v_mov_b32_e32 v130, v0
	v_mov_b32_e32 v131, v0
	v_mov_b32_e32 v132, v0
	v_mov_b32_e32 v133, v0
	v_mov_b32_e32 v134, v0
	v_mov_b32_e32 v135, v0
	v_mov_b32_e32 v136, v0
	v_mov_b32_e32 v137, v0
	v_mov_b32_e32 v114, v0
	v_mov_b32_e32 v115, v0
	v_mov_b32_e32 v116, v0
	v_mov_b32_e32 v117, v0
	v_mov_b32_e32 v118, v0
	v_mov_b32_e32 v119, v0
	v_mov_b32_e32 v120, v0
	v_mov_b32_e32 v121, v0
	s_andn2_b64 vcc, exec, s[14:15]
	s_cbranch_vccnz .LBB0_952
	s_branch .LBB0_953

; #define GPROBE_BEGIN(id) do { if (((PROBE_GEMM_SEL >> (id)) & 1) && blockIdx.x == 0 && tid_in < 64 && g.N == 20480) { volatile PG8_LAS unsigned long long* PW_ = (volatile PG8_LAS unsigned long long*)(lds + 163840 - 512 + 64); PW_[0] = __builtin_amdgcn_s_memrealtime(); } } while (0)
; #define PG8_BAR __builtin_amdgcn_s_barrier()
; template <class Epi, class Sched, bool ALIGN_EPI = false, bool SP2 = false, bool KHOOK = false>
; __device__ __forceinline__ void gemm_phase(PG8_LAS unsigned char* lds, const Gemm g, const Sched& S, const Epi& E, const int tid_in) {
;     ...
;         const bool has_next = S.next(ui + 1, nxt);
;         const char* nA = has_next ? (const char*)g.A + (size_t)nxt.pm * tstep + (size_t)nxt.pn * ksl : cA; const char* nB = has_next ? (const char*)g.Bt + (size_t)nxt.pn * bts + (size_t)nxt.pn * ksl + (gdv ? (size_t)(nxt.pm / gdv) * gst : 0) : cB;
;         GPROBE_END(2); GPROBE_BEGIN(1);
;         for (int t = 0; t < nt; t += 2) {
;             const bool last = (t == nt - 2);
;             const char* a1 = cA + (size_t)(t + 1) * kstep;
;             const char* a2 = last ? nA : cA + (size_t)(t + 2) * kstep; const char* b2 = last ? nB : cB + (size_t)(t + 2) * kstep;
;             const char* a3 = a2 + kstep; const char* b3 = b2 + kstep;
;             if (last && has_next) S.a_ready(nxt);
;             if constexpr (SP2) {
;             PG8_LDB(B0, 0, 0); PG8_LDB(B1, 0, 1); PG8_SCHED; PG8_LDA(At, 0, 0); PG8_STAGE(PG8_SA(1, 1), a1 + hstep, voffA);
;             PG8_WAIT_V(8); PG8_WAIT_L(0); PG8_BAR; PG8_MMA(0, 0, At, B0); PG8_MMA(0, 1, At, B1); PG8_BAR; PG8_SCHED;
;             PG8_LDA(At, 0, 1); PG8_STAGE(PG8_SB(0, 0), b2, voffB); PG8_STAGE(PG8_SB(0, 1), b2 + hstep, voffB); PG8_STAGE(PG8_SA(0, 0), a2, voffA);
;             PG8_WAIT_V(8); PG8_WAIT_L(0); PG8_BAR; PG8_MMA(1, 0, At, B0); PG8_MMA(1, 1, At, B1); PG8_BAR; PG8_SCHED;
;             PG8_LDB(B0, 1, 0); PG8_LDB(B1, 1, 1); PG8_SCHED; PG8_LDA(At, 1, 0); PG8_STAGE(PG8_SA(0, 1), a2 + hstep, voffA);
;             PG8_WAIT_V(8); PG8_WAIT_L(0); PG8_BAR; PG8_MMA(0, 0, At, B0); PG8_MMA(0, 1, At, B1); PG8_BAR; PG8_SCHED;
;             PG8_LDA(At, 1, 1); PG8_STAGE(PG8_SB(1, 0), b3, voffB); PG8_STAGE(PG8_SB(1, 1), b3 + hstep, voffB); PG8_STAGE(PG8_SA(1, 0), a3, voffA);
;             PG8_WAIT_V(8); PG8_WAIT_L(0); PG8_BAR; PG8_MMA(1, 0, At, B0); PG8_MMA(1, 1, At, B1); PG8_BAR; PG8_SCHED;
.LBB0_1062:
	s_ashr_i32 s13, s12, 31
	s_lshl_b64 s[16:17], s[12:13], 20
	v_readlane_b32 s22, v254, 34
	v_readlane_b32 s23, v254, 35
	s_add_u32 s16, s22, s16
	s_addc_u32 s17, s23, s17
	s_and_b64 s[22:23], s[14:15], exec
	s_cselect_b32 s13, s17, s27
	s_cselect_b32 s24, s16, s26
	s_ashr_i32 s11, s10, 31
	s_lshl_b64 s[22:23], s[10:11], 20
	s_add_u32 s22, s2, s22
	s_addc_u32 s23, s20, s23
	s_and_b64 s[44:45], s[14:15], exec
	s_cselect_b32 s11, s23, s31
	s_cselect_b32 s25, s22, s30
	s_add_u32 s26, s26, 0x80080
	s_addc_u32 s27, s27, 0
	s_add_u32 s44, s30, 0x100
	s_addc_u32 s45, s31, 0
	s_mov_b32 s46, -2
	s_add_u32 s30, s26, 0xfff80080
	s_addc_u32 s31, s27, -1
	s_add_i32 s47, 0, 0x10000
	s_cmp_eq_u32 s46, 28
	s_cselect_b32 s49, s13, s31
	s_cselect_b32 s48, s24, s30
	s_cselect_b32 s31, s11, s45
	s_cselect_b32 s30, s25, s44
	s_add_i32 s52, 0, 0x14000
	v_add_u32_e32 v152, s47, v137
	v_add_u32_e32 v168, s52, v137
	ds_read_b128 v[140:143], v152
	ds_read_b128 v[144:147], v152 offset:1024
	ds_read_b128 v[148:151], v152 offset:2048
	ds_read_b128 v[152:155], v152 offset:3072
	ds_read_b128 v[156:159], v168
	ds_read_b128 v[160:163], v168 offset:1024
	ds_read_b128 v[164:167], v168 offset:2048
	ds_read_b128 v[168:171], v168 offset:3072
	v_lshl_add_u64 v[192:193], s[26:27], 0, v[132:133]
	s_add_i32 m0, s36, 0xc000
	ds_read_b128 v[172:175], v139
	ds_read_b128 v[176:179], v139 offset:1024
	ds_read_b128 v[180:183], v139 offset:2048
	ds_read_b128 v[184:187], v139 offset:3072
	ds_read_b128 v[188:191], v139 offset:4096
	ds_read_b128 v[198:201], v139 offset:5120
	ds_read_b128 v[202:205], v139 offset:6144
	ds_read_b128 v[206:209], v139 offset:7168
	global_load_lds_dwordx4 v[192:193], off
	s_add_i32 m0, s36, 0xe000
	v_lshl_add_u64 v[192:193], s[26:27], 0, v[134:135]
	global_load_lds_dwordx4 v[192:193], off
	s_waitcnt vmcnt(10)
	s_waitcnt lgkmcnt(0)
	s_barrier
	s_setprio 1
	s_waitcnt lgkmcnt(0)
	v_mfma_f32_16x16x32_bf16 v[126:129], v[140:143], v[172:175], 0
	v_mfma_f32_16x16x32_bf16 v[122:125], v[148:151], v[172:175], 0
	v_mfma_f32_16x16x32_bf16 v[110:113], v[140:143], v[180:183], 0
	v_mfma_f32_16x16x32_bf16 v[106:109], v[148:151], v[180:183], 0
	v_mfma_f32_16x16x32_bf16 v[94:97], v[140:143], v[188:191], 0
	v_mfma_f32_16x16x32_bf16 v[90:93], v[148:151], v[188:191], 0
	v_mfma_f32_16x16x32_bf16 v[78:81], v[140:143], v[202:205], 0
	v_mfma_f32_16x16x32_bf16 v[74:77], v[148:151], v[202:205], 0
	v_mfma_f32_16x16x32_bf16 v[126:129], v[144:147], v[176:179], v[126:129]
	v_mfma_f32_16x16x32_bf16 v[122:125], v[152:155], v[176:179], v[122:125]
	v_mfma_f32_16x16x32_bf16 v[110:113], v[144:147], v[184:187], v[110:113]
	v_mfma_f32_16x16x32_bf16 v[106:109], v[152:155], v[184:187], v[106:109]
	v_mfma_f32_16x16x32_bf16 v[94:97], v[144:147], v[198:201], v[94:97]
	v_mfma_f32_16x16x32_bf16 v[90:93], v[152:155], v[198:201], v[90:93]
	v_mfma_f32_16x16x32_bf16 v[78:81], v[144:147], v[206:209], v[78:81]
	v_mfma_f32_16x16x32_bf16 v[74:77], v[152:155], v[206:209], v[74:77]
	s_setprio 0
	s_setprio 1
	v_mfma_f32_16x16x32_bf16 v[118:121], v[156:159], v[172:175], 0
	v_mfma_f32_16x16x32_bf16 v[114:117], v[164:167], v[172:175], 0
	v_mfma_f32_16x16x32_bf16 v[102:105], v[156:159], v[180:183], 0
	v_mfma_f32_16x16x32_bf16 v[98:101], v[164:167], v[180:183], 0
	v_mfma_f32_16x16x32_bf16 v[86:89], v[156:159], v[188:191], 0
	v_mfma_f32_16x16x32_bf16 v[82:85], v[164:167], v[188:191], 0
	v_mfma_f32_16x16x32_bf16 v[70:73], v[156:159], v[202:205], 0
	v_mfma_f32_16x16x32_bf16 v[66:69], v[164:167], v[202:205], 0
	v_mfma_f32_16x16x32_bf16 v[118:121], v[160:163], v[176:179], v[118:121]
	v_mfma_f32_16x16x32_bf16 v[114:117], v[168:171], v[176:179], v[114:117]
	v_mfma_f32_16x16x32_bf16 v[102:105], v[160:163], v[184:187], v[102:105]
	v_mfma_f32_16x16x32_bf16 v[98:101], v[168:171], v[184:187], v[98:101]
	v_mfma_f32_16x16x32_bf16 v[86:89], v[160:163], v[198:201], v[86:89]
	v_mfma_f32_16x16x32_bf16 v[82:85], v[168:171], v[198:201], v[82:85]
	v_mfma_f32_16x16x32_bf16 v[70:73], v[160:163], v[206:209], v[70:73]
	v_mfma_f32_16x16x32_bf16 v[66:69], v[168:171], v[206:209], v[66:69]
	s_setprio 0
	s_barrier
	s_add_i32 s47, s47, s33
	v_lshl_add_u64 v[192:193], s[30:31], 0, v[32:33]
	s_mov_b32 m0, s47
	ds_read_b128 v[172:175], v139 offset:16384
	ds_read_b128 v[176:179], v139 offset:17408
	ds_read_b128 v[180:183], v139 offset:18432
	ds_read_b128 v[184:187], v139 offset:19456
	ds_read_b128 v[188:191], v139 offset:20480
	ds_read_b128 v[198:201], v139 offset:21504
	ds_read_b128 v[202:205], v139 offset:22528
	ds_read_b128 v[206:209], v139 offset:23552
	global_load_lds_dwordx4 v[192:193], off
	s_add_i32 m0, s47, 0x2000
	s_add_u32 s50, s30, 0x80000
	v_lshl_add_u64 v[210:211], s[30:31], 0, v[130:131]
	s_addc_u32 s51, s31, 0
	s_add_i32 s47, s52, s33
	global_load_lds_dwordx4 v[210:211], off
	v_lshl_add_u64 v[212:213], s[50:51], 0, v[32:33]
	s_mov_b32 m0, s47
	v_lshl_add_u64 v[214:215], s[48:49], 0, v[130:131]
	global_load_lds_dwordx4 v[212:213], off
	s_add_i32 m0, s47, 0x2000
	v_lshl_add_u64 v[212:213], s[50:51], 0, v[130:131]
	global_load_lds_dwordx4 v[212:213], off
	s_mov_b32 m0, s36
	v_lshl_add_u64 v[212:213], s[48:49], 0, v[32:33]
	global_load_lds_dwordx4 v[212:213], off
	s_mov_b32 m0, s37
	s_nop 0
	global_load_lds_dwordx4 v[214:215], off
	s_waitcnt vmcnt(16)
	s_waitcnt lgkmcnt(0)
	s_barrier
; #define PG8_STAGE(bufoff, gbase, voff) do { _Pragma("unroll") for (int _i = 0; _i < 2; ++_i) \
;         __builtin_amdgcn_global_load_lds((const unsigned*)((const char*)(gbase) + (voff)[_i]), (PG8_LAS unsigned*)(lds + (bufoff) + ldsw + _i * 8192), 16, 0, 0); } while (0)
; #define PG8_LDA(dst, b, h) do { _Pragma("unroll") for (int m = 0; m < 4; ++m) _Pragma("unroll") for (int k = 0; k < 2; ++k) dst[m][k] = *(const PG8_LAS bf16x8*)(lds + PG8_SA(b, h) + aoff + m * 2048 + k * 1024); } while (0)
; #define PG8_LDB(dst, b, h) do { _Pragma("unroll") for (int n = 0; n < 2; ++n) _Pragma("unroll") for (int k = 0; k < 2; ++k) dst[n][k] = *(const PG8_LAS bf16x8*)(lds + PG8_SB(b, h) + boff + n * 2048 + k * 1024); } while (0)
; #define PG8_MMA(ai, bj, At, Bt) do { __builtin_amdgcn_s_setprio(1); _Pragma("unroll") for (int m = 0; m < 4; ++m) _Pragma("unroll") for (int n = 0; n < 2; ++n) _Pragma("unroll") for (int k = 0; k < 2; ++k) \
;         acc[ai][bj][m][n] = __builtin_amdgcn_mfma_f32_16x16x32_bf16(Bt[n][k], At[m][k], acc[ai][bj][m][n], 0, 0, 0); __builtin_amdgcn_s_setprio(0); } while (0)
; #define PG8_WAIT_V(n) asm volatile("s_waitcnt vmcnt(" #n ")" ::: "memory")
; #define PG8_WAIT_L(n) asm volatile("s_waitcnt lgkmcnt(" #n ")" ::: "memory")
; #define PG8_BAR __builtin_amdgcn_s_barrier()
; #define PG8_SCHED __builtin_amdgcn_sched_barrier(0)
; template <class Epi, class Sched, bool ALIGN_EPI = false, bool SP2 = false, bool KHOOK = false>
; __device__ __forceinline__ void gemm_phase(PG8_LAS unsigned char* lds, const Gemm g, const Sched& S, const Epi& E, const int tid_in) {
;     ...
;             PG8_LDA(At, 0, 1); PG8_STAGE(PG8_SB(0, 0), b2, voffB); PG8_STAGE(PG8_SB(0, 1), b2 + hstep, voffB); PG8_STAGE(PG8_SA(0, 0), a2, voffA);
;             PG8_WAIT_V(8); PG8_WAIT_L(0); PG8_BAR; PG8_MMA(1, 0, At, B0); PG8_MMA(1, 1, At, B1); PG8_BAR; PG8_SCHED;
;             PG8_LDB(B0, 1, 0); PG8_LDB(B1, 1, 1); PG8_SCHED; PG8_LDA(At, 1, 0); PG8_STAGE(PG8_SA(0, 1), a2 + hstep, voffA);
;             PG8_WAIT_V(8); PG8_WAIT_L(0); PG8_BAR; PG8_MMA(0, 0, At, B0); PG8_MMA(0, 1, At, B1); PG8_BAR; PG8_SCHED;
	s_setprio 1
	s_waitcnt lgkmcnt(0)
	v_mfma_f32_16x16x32_bf16 v[62:65], v[140:143], v[172:175], 0
	v_mfma_f32_16x16x32_bf16 v[58:61], v[148:151], v[172:175], 0
	v_mfma_f32_16x16x32_bf16 v[46:49], v[140:143], v[180:183], 0
	v_mfma_f32_16x16x32_bf16 v[42:45], v[148:151], v[180:183], 0
	v_mfma_f32_16x16x32_bf16 v[28:31], v[140:143], v[188:191], 0
	v_mfma_f32_16x16x32_bf16 v[24:27], v[148:151], v[188:191], 0
	v_mfma_f32_16x16x32_bf16 v[12:15], v[140:143], v[202:205], 0
	v_mfma_f32_16x16x32_bf16 v[8:11], v[148:151], v[202:205], 0
	v_mfma_f32_16x16x32_bf16 v[62:65], v[144:147], v[176:179], v[62:65]
	v_mfma_f32_16x16x32_bf16 v[58:61], v[152:155], v[176:179], v[58:61]
	v_mfma_f32_16x16x32_bf16 v[46:49], v[144:147], v[184:187], v[46:49]
	v_mfma_f32_16x16x32_bf16 v[42:45], v[152:155], v[184:187], v[42:45]
	v_mfma_f32_16x16x32_bf16 v[28:31], v[144:147], v[198:201], v[28:31]
	v_mfma_f32_16x16x32_bf16 v[24:27], v[152:155], v[198:201], v[24:27]
	v_mfma_f32_16x16x32_bf16 v[12:15], v[144:147], v[206:209], v[12:15]
	v_mfma_f32_16x16x32_bf16 v[8:11], v[152:155], v[206:209], v[8:11]
	s_setprio 0
	s_setprio 1
	v_mfma_f32_16x16x32_bf16 v[54:57], v[156:159], v[172:175], 0
	v_mfma_f32_16x16x32_bf16 v[50:53], v[164:167], v[172:175], 0
	v_mfma_f32_16x16x32_bf16 v[38:41], v[156:159], v[180:183], 0
	v_mfma_f32_16x16x32_bf16 v[34:37], v[164:167], v[180:183], 0
	v_mfma_f32_16x16x32_bf16 v[20:23], v[156:159], v[188:191], 0
	v_mfma_f32_16x16x32_bf16 v[16:19], v[164:167], v[188:191], 0
	v_mfma_f32_16x16x32_bf16 v[4:7], v[156:159], v[202:205], 0
	v_mfma_f32_16x16x32_bf16 v[0:3], v[164:167], v[202:205], 0
	v_mfma_f32_16x16x32_bf16 v[54:57], v[160:163], v[176:179], v[54:57]
	v_mfma_f32_16x16x32_bf16 v[50:53], v[168:171], v[176:179], v[50:53]
	v_mfma_f32_16x16x32_bf16 v[38:41], v[160:163], v[184:187], v[38:41]
	v_mfma_f32_16x16x32_bf16 v[34:37], v[168:171], v[184:187], v[34:37]
	v_mfma_f32_16x16x32_bf16 v[20:23], v[160:163], v[198:201], v[20:23]
	v_mfma_f32_16x16x32_bf16 v[16:19], v[168:171], v[198:201], v[16:19]
	v_mfma_f32_16x16x32_bf16 v[4:7], v[160:163], v[206:209], v[4:7]
	v_mfma_f32_16x16x32_bf16 v[0:3], v[168:171], v[206:209], v[0:3]
	s_setprio 0
	s_barrier
	s_add_i32 s47, 0, 0x18000
	s_add_i32 s50, 0, 0x1c000
	v_add_u32_e32 v152, s47, v137
	v_add_u32_e32 v168, s50, v137
	ds_read_b128 v[140:143], v152
	ds_read_b128 v[144:147], v152 offset:1024
	ds_read_b128 v[148:151], v152 offset:2048
	ds_read_b128 v[152:155], v152 offset:3072
	ds_read_b128 v[156:159], v168
	ds_read_b128 v[160:163], v168 offset:1024
	ds_read_b128 v[164:167], v168 offset:2048
	ds_read_b128 v[168:171], v168 offset:3072
	s_add_u32 s48, s48, 0x80000
	s_addc_u32 s49, s49, 0
	s_mov_b32 m0, s38
	v_lshl_add_u64 v[216:217], s[48:49], 0, v[32:33]
	ds_read_b128 v[172:175], v139 offset:32768
	ds_read_b128 v[176:179], v139 offset:33792
	ds_read_b128 v[180:183], v139 offset:34816
	ds_read_b128 v[184:187], v139 offset:35840
	ds_read_b128 v[188:191], v139 offset:36864
	ds_read_b128 v[198:201], v139 offset:37888
	ds_read_b128 v[202:205], v139 offset:38912
	ds_read_b128 v[206:209], v139 offset:39936
	global_load_lds_dwordx4 v[216:217], off
	s_mov_b32 m0, s39
	v_lshl_add_u64 v[216:217], s[48:49], 0, v[130:131]
	global_load_lds_dwordx4 v[216:217], off
	s_waitcnt vmcnt(8)
	s_waitcnt lgkmcnt(0)
	s_barrier
	s_setprio 1
	s_waitcnt lgkmcnt(0)
	v_mfma_f32_16x16x32_bf16 v[126:129], v[140:143], v[172:175], v[126:129]
	v_mfma_f32_16x16x32_bf16 v[122:125], v[148:151], v[172:175], v[122:125]
	v_mfma_f32_16x16x32_bf16 v[110:113], v[140:143], v[180:183], v[110:113]
	v_mfma_f32_16x16x32_bf16 v[106:109], v[148:151], v[180:183], v[106:109]
	v_mfma_f32_16x16x32_bf16 v[94:97], v[140:143], v[188:191], v[94:97]
	v_mfma_f32_16x16x32_bf16 v[90:93], v[148:151], v[188:191], v[90:93]
	v_mfma_f32_16x16x32_bf16 v[78:81], v[140:143], v[202:205], v[78:81]
	v_mfma_f32_16x16x32_bf16 v[74:77], v[148:151], v[202:205], v[74:77]
	v_mfma_f32_16x16x32_bf16 v[126:129], v[144:147], v[176:179], v[126:129]
	v_mfma_f32_16x16x32_bf16 v[122:125], v[152:155], v[176:179], v[122:125]
	v_mfma_f32_16x16x32_bf16 v[110:113], v[144:147], v[184:187], v[110:113]
	v_mfma_f32_16x16x32_bf16 v[106:109], v[152:155], v[184:187], v[106:109]
	v_mfma_f32_16x16x32_bf16 v[94:97], v[144:147], v[198:201], v[94:97]
	v_mfma_f32_16x16x32_bf16 v[90:93], v[152:155], v[198:201], v[90:93]
	v_mfma_f32_16x16x32_bf16 v[78:81], v[144:147], v[206:209], v[78:81]
	v_mfma_f32_16x16x32_bf16 v[74:77], v[152:155], v[206:209], v[74:77]
	s_setprio 0
	s_setprio 1
	v_mfma_f32_16x16x32_bf16 v[118:121], v[156:159], v[172:175], v[118:121]
	v_mfma_f32_16x16x32_bf16 v[114:117], v[164:167], v[172:175], v[114:117]
	v_mfma_f32_16x16x32_bf16 v[102:105], v[156:159], v[180:183], v[102:105]
	v_mfma_f32_16x16x32_bf16 v[98:101], v[164:167], v[180:183], v[98:101]
	v_mfma_f32_16x16x32_bf16 v[86:89], v[156:159], v[188:191], v[86:89]
	v_mfma_f32_16x16x32_bf16 v[82:85], v[164:167], v[188:191], v[82:85]
	v_mfma_f32_16x16x32_bf16 v[70:73], v[156:159], v[202:205], v[70:73]
	v_mfma_f32_16x16x32_bf16 v[66:69], v[164:167], v[202:205], v[66:69]
	v_mfma_f32_16x16x32_bf16 v[118:121], v[160:163], v[176:179], v[118:121]
	v_mfma_f32_16x16x32_bf16 v[114:117], v[168:171], v[176:179], v[114:117]
	v_mfma_f32_16x16x32_bf16 v[102:105], v[160:163], v[184:187], v[102:105]
	v_mfma_f32_16x16x32_bf16 v[98:101], v[168:171], v[184:187], v[98:101]
	v_mfma_f32_16x16x32_bf16 v[86:89], v[160:163], v[198:201], v[86:89]
	v_mfma_f32_16x16x32_bf16 v[82:85], v[168:171], v[198:201], v[82:85]
	v_mfma_f32_16x16x32_bf16 v[70:73], v[160:163], v[206:209], v[70:73]
	v_mfma_f32_16x16x32_bf16 v[66:69], v[168:171], v[206:209], v[66:69]
	s_setprio 0
	s_barrier
; #define PG8_STAGE(bufoff, gbase, voff) do { _Pragma("unroll") for (int _i = 0; _i < 2; ++_i) \
;         __builtin_amdgcn_global_load_lds((const unsigned*)((const char*)(gbase) + (voff)[_i]), (PG8_LAS unsigned*)(lds + (bufoff) + ldsw + _i * 8192), 16, 0, 0); } while (0)
; #define PG8_LDA(dst, b, h) do { _Pragma("unroll") for (int m = 0; m < 4; ++m) _Pragma("unroll") for (int k = 0; k < 2; ++k) dst[m][k] = *(const PG8_LAS bf16x8*)(lds + PG8_SA(b, h) + aoff + m * 2048 + k * 1024); } while (0)
; #define PG8_MMA(ai, bj, At, Bt) do { __builtin_amdgcn_s_setprio(1); _Pragma("unroll") for (int m = 0; m < 4; ++m) _Pragma("unroll") for (int n = 0; n < 2; ++n) _Pragma("unroll") for (int k = 0; k < 2; ++k) \
;         acc[ai][bj][m][n] = __builtin_amdgcn_mfma_f32_16x16x32_bf16(Bt[n][k], At[m][k], acc[ai][bj][m][n], 0, 0, 0); __builtin_amdgcn_s_setprio(0); } while (0)
; #define PG8_WAIT_V(n) asm volatile("s_waitcnt vmcnt(" #n ")" ::: "memory")
; #define PG8_WAIT_L(n) asm volatile("s_waitcnt lgkmcnt(" #n ")" ::: "memory")
; #define PG8_BAR __builtin_amdgcn_s_barrier()
; #define PG8_SCHED __builtin_amdgcn_sched_barrier(0)
; template <class Epi, class Sched, bool ALIGN_EPI = false, bool SP2 = false, bool KHOOK = false>
; __device__ __forceinline__ void gemm_phase(PG8_LAS unsigned char* lds, const Gemm g, const Sched& S, const Epi& E, const int tid_in) {
;     ...
;         for (int t = 0; t < nt; t += 2) {
;     ...
;             PG8_LDA(At, 1, 1); PG8_STAGE(PG8_SB(1, 0), b3, voffB); PG8_STAGE(PG8_SB(1, 1), b3 + hstep, voffB); PG8_STAGE(PG8_SA(1, 0), a3, voffA);
;             PG8_WAIT_V(8); PG8_WAIT_L(0); PG8_BAR; PG8_MMA(1, 0, At, B0); PG8_MMA(1, 1, At, B1); PG8_BAR; PG8_SCHED;
	s_add_i32 s47, s47, s33
	v_lshl_add_u64 v[192:193], v[192:193], 0, s[90:91]
	s_mov_b32 m0, s47
	ds_read_b128 v[172:175], v139 offset:49152
	ds_read_b128 v[176:179], v139 offset:50176
	ds_read_b128 v[180:183], v139 offset:51200
	ds_read_b128 v[184:187], v139 offset:52224
	ds_read_b128 v[188:191], v139 offset:53248
	ds_read_b128 v[198:201], v139 offset:54272
	ds_read_b128 v[202:205], v139 offset:55296
	ds_read_b128 v[206:209], v139 offset:56320
	global_load_lds_dwordx4 v[192:193], off
	s_add_i32 m0, s47, 0x2000
	s_add_u32 s30, s30, 0x80080
	v_lshl_add_u64 v[192:193], v[210:211], 0, s[90:91]
	s_addc_u32 s31, s31, 0
	s_add_i32 s47, s50, s33
	global_load_lds_dwordx4 v[192:193], off
	s_mov_b32 m0, s47
	v_lshl_add_u64 v[192:193], s[30:31], 0, v[32:33]
	global_load_lds_dwordx4 v[192:193], off
	s_add_i32 m0, s47, 0x2000
	v_lshl_add_u64 v[192:193], s[30:31], 0, v[130:131]
	global_load_lds_dwordx4 v[192:193], off
	s_mov_b32 m0, s40
	v_lshl_add_u64 v[192:193], v[212:213], 0, s[90:91]
	global_load_lds_dwordx4 v[192:193], off
	s_mov_b32 m0, s41
	v_lshl_add_u64 v[192:193], v[214:215], 0, s[90:91]
	global_load_lds_dwordx4 v[192:193], off
	s_waitcnt vmcnt(8)
	s_waitcnt lgkmcnt(0)
	s_barrier
	s_setprio 1
	s_waitcnt lgkmcnt(0)
	v_mfma_f32_16x16x32_bf16 v[62:65], v[140:143], v[172:175], v[62:65]
	v_mfma_f32_16x16x32_bf16 v[58:61], v[148:151], v[172:175], v[58:61]
	v_mfma_f32_16x16x32_bf16 v[46:49], v[140:143], v[180:183], v[46:49]
	v_mfma_f32_16x16x32_bf16 v[42:45], v[148:151], v[180:183], v[42:45]
	v_mfma_f32_16x16x32_bf16 v[28:31], v[140:143], v[188:191], v[28:31]
	v_mfma_f32_16x16x32_bf16 v[24:27], v[148:151], v[188:191], v[24:27]
	v_mfma_f32_16x16x32_bf16 v[12:15], v[140:143], v[202:205], v[12:15]
	v_mfma_f32_16x16x32_bf16 v[8:11], v[148:151], v[202:205], v[8:11]
	v_mfma_f32_16x16x32_bf16 v[62:65], v[144:147], v[176:179], v[62:65]
	v_mfma_f32_16x16x32_bf16 v[58:61], v[152:155], v[176:179], v[58:61]
	v_mfma_f32_16x16x32_bf16 v[46:49], v[144:147], v[184:187], v[46:49]
	v_mfma_f32_16x16x32_bf16 v[42:45], v[152:155], v[184:187], v[42:45]
	v_mfma_f32_16x16x32_bf16 v[28:31], v[144:147], v[198:201], v[28:31]
	v_mfma_f32_16x16x32_bf16 v[24:27], v[152:155], v[198:201], v[24:27]
	v_mfma_f32_16x16x32_bf16 v[12:15], v[144:147], v[206:209], v[12:15]
	v_mfma_f32_16x16x32_bf16 v[8:11], v[152:155], v[206:209], v[8:11]
	s_setprio 0
	s_setprio 1
	v_mfma_f32_16x16x32_bf16 v[54:57], v[156:159], v[172:175], v[54:57]
	v_mfma_f32_16x16x32_bf16 v[50:53], v[164:167], v[172:175], v[50:53]
	v_mfma_f32_16x16x32_bf16 v[38:41], v[156:159], v[180:183], v[38:41]
	v_mfma_f32_16x16x32_bf16 v[34:37], v[164:167], v[180:183], v[34:37]
	v_mfma_f32_16x16x32_bf16 v[20:23], v[156:159], v[188:191], v[20:23]
	v_mfma_f32_16x16x32_bf16 v[16:19], v[164:167], v[188:191], v[16:19]
	v_mfma_f32_16x16x32_bf16 v[4:7], v[156:159], v[202:205], v[4:7]
	v_mfma_f32_16x16x32_bf16 v[0:3], v[164:167], v[202:205], v[0:3]
	v_mfma_f32_16x16x32_bf16 v[54:57], v[160:163], v[176:179], v[54:57]
	v_mfma_f32_16x16x32_bf16 v[50:53], v[168:171], v[176:179], v[50:53]
	v_mfma_f32_16x16x32_bf16 v[38:41], v[160:163], v[184:187], v[38:41]
	v_mfma_f32_16x16x32_bf16 v[34:37], v[168:171], v[184:187], v[34:37]
	v_mfma_f32_16x16x32_bf16 v[20:23], v[160:163], v[198:201], v[20:23]
	v_mfma_f32_16x16x32_bf16 v[16:19], v[168:171], v[198:201], v[16:19]
	v_mfma_f32_16x16x32_bf16 v[4:7], v[160:163], v[206:209], v[4:7]
	v_mfma_f32_16x16x32_bf16 v[0:3], v[168:171], v[206:209], v[0:3]
	s_setprio 0
	s_barrier
	s_add_i32 s46, s46, 2
	s_add_u32 s26, s26, 0x100
	s_addc_u32 s27, s27, 0
	s_add_u32 s44, s44, 0x100
	s_addc_u32 s45, s45, 0
	s_cmp_gt_u32 s46, 29
.LBB0_1063:
	s_add_u32 s30, s26, 0xfff80080
	s_addc_u32 s31, s27, -1
	s_add_i32 s47, 0, 0x10000
	s_cmp_eq_u32 s46, 28
	s_cselect_b32 s49, s13, s31
	s_cselect_b32 s48, s24, s30
	s_cselect_b32 s31, s11, s45
	s_cselect_b32 s30, s25, s44
	s_add_i32 s52, 0, 0x14000
	v_add_u32_e32 v152, s47, v137
	v_add_u32_e32 v168, s52, v137
	ds_read_b128 v[140:143], v152
	ds_read_b128 v[144:147], v152 offset:1024
	ds_read_b128 v[148:151], v152 offset:2048
	ds_read_b128 v[152:155], v152 offset:3072
	ds_read_b128 v[156:159], v168
	ds_read_b128 v[160:163], v168 offset:1024
	ds_read_b128 v[164:167], v168 offset:2048
	ds_read_b128 v[168:171], v168 offset:3072
	v_lshl_add_u64 v[192:193], s[26:27], 0, v[132:133]
	s_add_i32 m0, s36, 0xc000
	ds_read_b128 v[172:175], v139
	ds_read_b128 v[176:179], v139 offset:1024
	ds_read_b128 v[180:183], v139 offset:2048
	ds_read_b128 v[184:187], v139 offset:3072
	ds_read_b128 v[188:191], v139 offset:4096
	ds_read_b128 v[198:201], v139 offset:5120
	ds_read_b128 v[202:205], v139 offset:6144
	ds_read_b128 v[206:209], v139 offset:7168
	global_load_lds_dwordx4 v[192:193], off
	s_add_i32 m0, s36, 0xe000
	v_lshl_add_u64 v[192:193], s[26:27], 0, v[134:135]
	global_load_lds_dwordx4 v[192:193], off
	s_waitcnt vmcnt(8)
	s_waitcnt lgkmcnt(0)
	s_barrier
; #define PG8_STAGE(bufoff, gbase, voff) do { _Pragma("unroll") for (int _i = 0; _i < 2; ++_i) \
;         __builtin_amdgcn_global_load_lds((const unsigned*)((const char*)(gbase) + (voff)[_i]), (PG8_LAS unsigned*)(lds + (bufoff) + ldsw + _i * 8192), 16, 0, 0); } while (0)
; #define PG8_LDA(dst, b, h) do { _Pragma("unroll") for (int m = 0; m < 4; ++m) _Pragma("unroll") for (int k = 0; k < 2; ++k) dst[m][k] = *(const PG8_LAS bf16x8*)(lds + PG8_SA(b, h) + aoff + m * 2048 + k * 1024); } while (0)
; #define PG8_LDB(dst, b, h) do { _Pragma("unroll") for (int n = 0; n < 2; ++n) _Pragma("unroll") for (int k = 0; k < 2; ++k) dst[n][k] = *(const PG8_LAS bf16x8*)(lds + PG8_SB(b, h) + boff + n * 2048 + k * 1024); } while (0)
; #define PG8_MMA(ai, bj, At, Bt) do { __builtin_amdgcn_s_setprio(1); _Pragma("unroll") for (int m = 0; m < 4; ++m) _Pragma("unroll") for (int n = 0; n < 2; ++n) _Pragma("unroll") for (int k = 0; k < 2; ++k) \
;         acc[ai][bj][m][n] = __builtin_amdgcn_mfma_f32_16x16x32_bf16(Bt[n][k], At[m][k], acc[ai][bj][m][n], 0, 0, 0); __builtin_amdgcn_s_setprio(0); } while (0)
; #define PG8_WAIT_V(n) asm volatile("s_waitcnt vmcnt(" #n ")" ::: "memory")
; #define PG8_WAIT_L(n) asm volatile("s_waitcnt lgkmcnt(" #n ")" ::: "memory")
; #define PG8_BAR __builtin_amdgcn_s_barrier()
; #define PG8_SCHED __builtin_amdgcn_sched_barrier(0)
; template <class Epi, class Sched, bool ALIGN_EPI = false, bool SP2 = false, bool KHOOK = false>
; __device__ __forceinline__ void gemm_phase(PG8_LAS unsigned char* lds, const Gemm g, const Sched& S, const Epi& E, const int tid_in) {
;     ...
;             PG8_LDB(B0, 0, 0); PG8_LDB(B1, 0, 1); PG8_SCHED; PG8_LDA(At, 0, 0); PG8_STAGE(PG8_SA(1, 1), a1 + hstep, voffA);
;             PG8_WAIT_V(8); PG8_WAIT_L(0); PG8_BAR; PG8_MMA(0, 0, At, B0); PG8_MMA(0, 1, At, B1); PG8_BAR; PG8_SCHED;
;             PG8_LDA(At, 0, 1); PG8_STAGE(PG8_SB(0, 0), b2, voffB); PG8_STAGE(PG8_SB(0, 1), b2 + hstep, voffB); PG8_STAGE(PG8_SA(0, 0), a2, voffA);
;             PG8_WAIT_V(8); PG8_WAIT_L(0); PG8_BAR; PG8_MMA(1, 0, At, B0); PG8_MMA(1, 1, At, B1); PG8_BAR; PG8_SCHED;
	s_setprio 1
	s_waitcnt lgkmcnt(0)
	v_mfma_f32_16x16x32_bf16 v[126:129], v[140:143], v[172:175], v[126:129]
	v_mfma_f32_16x16x32_bf16 v[122:125], v[148:151], v[172:175], v[122:125]
	v_mfma_f32_16x16x32_bf16 v[110:113], v[140:143], v[180:183], v[110:113]
	v_mfma_f32_16x16x32_bf16 v[106:109], v[148:151], v[180:183], v[106:109]
	v_mfma_f32_16x16x32_bf16 v[94:97], v[140:143], v[188:191], v[94:97]
	v_mfma_f32_16x16x32_bf16 v[90:93], v[148:151], v[188:191], v[90:93]
	v_mfma_f32_16x16x32_bf16 v[78:81], v[140:143], v[202:205], v[78:81]
	v_mfma_f32_16x16x32_bf16 v[74:77], v[148:151], v[202:205], v[74:77]
	v_mfma_f32_16x16x32_bf16 v[126:129], v[144:147], v[176:179], v[126:129]
	v_mfma_f32_16x16x32_bf16 v[122:125], v[152:155], v[176:179], v[122:125]
	v_mfma_f32_16x16x32_bf16 v[110:113], v[144:147], v[184:187], v[110:113]
	v_mfma_f32_16x16x32_bf16 v[106:109], v[152:155], v[184:187], v[106:109]
	v_mfma_f32_16x16x32_bf16 v[94:97], v[144:147], v[198:201], v[94:97]
	v_mfma_f32_16x16x32_bf16 v[90:93], v[152:155], v[198:201], v[90:93]
	v_mfma_f32_16x16x32_bf16 v[78:81], v[144:147], v[206:209], v[78:81]
	v_mfma_f32_16x16x32_bf16 v[74:77], v[152:155], v[206:209], v[74:77]
	s_setprio 0
	s_setprio 1
	v_mfma_f32_16x16x32_bf16 v[118:121], v[156:159], v[172:175], v[118:121]
	v_mfma_f32_16x16x32_bf16 v[114:117], v[164:167], v[172:175], v[114:117]
	v_mfma_f32_16x16x32_bf16 v[102:105], v[156:159], v[180:183], v[102:105]
	v_mfma_f32_16x16x32_bf16 v[98:101], v[164:167], v[180:183], v[98:101]
	v_mfma_f32_16x16x32_bf16 v[86:89], v[156:159], v[188:191], v[86:89]
	v_mfma_f32_16x16x32_bf16 v[82:85], v[164:167], v[188:191], v[82:85]
	v_mfma_f32_16x16x32_bf16 v[70:73], v[156:159], v[202:205], v[70:73]
	v_mfma_f32_16x16x32_bf16 v[66:69], v[164:167], v[202:205], v[66:69]
	v_mfma_f32_16x16x32_bf16 v[118:121], v[160:163], v[176:179], v[118:121]
	v_mfma_f32_16x16x32_bf16 v[114:117], v[168:171], v[176:179], v[114:117]
	v_mfma_f32_16x16x32_bf16 v[102:105], v[160:163], v[184:187], v[102:105]
	v_mfma_f32_16x16x32_bf16 v[98:101], v[168:171], v[184:187], v[98:101]
	v_mfma_f32_16x16x32_bf16 v[86:89], v[160:163], v[198:201], v[86:89]
	v_mfma_f32_16x16x32_bf16 v[82:85], v[168:171], v[198:201], v[82:85]
	v_mfma_f32_16x16x32_bf16 v[70:73], v[160:163], v[206:209], v[70:73]
	v_mfma_f32_16x16x32_bf16 v[66:69], v[168:171], v[206:209], v[66:69]
	s_setprio 0
	s_barrier
	s_add_i32 s47, s47, s33
	v_lshl_add_u64 v[192:193], s[30:31], 0, v[32:33]
	s_mov_b32 m0, s47
	ds_read_b128 v[172:175], v139 offset:16384
	ds_read_b128 v[176:179], v139 offset:17408
	ds_read_b128 v[180:183], v139 offset:18432
	ds_read_b128 v[184:187], v139 offset:19456
	ds_read_b128 v[188:191], v139 offset:20480
	ds_read_b128 v[198:201], v139 offset:21504
	ds_read_b128 v[202:205], v139 offset:22528
	ds_read_b128 v[206:209], v139 offset:23552
	global_load_lds_dwordx4 v[192:193], off
	s_add_i32 m0, s47, 0x2000
	s_add_u32 s50, s30, 0x80000
	v_lshl_add_u64 v[210:211], s[30:31], 0, v[130:131]
	s_addc_u32 s51, s31, 0
	s_add_i32 s47, s52, s33
	global_load_lds_dwordx4 v[210:211], off
	v_lshl_add_u64 v[212:213], s[50:51], 0, v[32:33]
	s_mov_b32 m0, s47
	v_lshl_add_u64 v[214:215], s[48:49], 0, v[130:131]
	global_load_lds_dwordx4 v[212:213], off
	s_add_i32 m0, s47, 0x2000
	v_lshl_add_u64 v[212:213], s[50:51], 0, v[130:131]
	global_load_lds_dwordx4 v[212:213], off
	s_mov_b32 m0, s36
	v_lshl_add_u64 v[212:213], s[48:49], 0, v[32:33]
	global_load_lds_dwordx4 v[212:213], off
	s_mov_b32 m0, s37
	s_nop 0
	global_load_lds_dwordx4 v[214:215], off
	s_waitcnt vmcnt(8)
	s_waitcnt lgkmcnt(0)
	s_barrier
	s_setprio 1
	s_waitcnt lgkmcnt(0)
	v_mfma_f32_16x16x32_bf16 v[62:65], v[140:143], v[172:175], v[62:65]
	v_mfma_f32_16x16x32_bf16 v[58:61], v[148:151], v[172:175], v[58:61]
	v_mfma_f32_16x16x32_bf16 v[46:49], v[140:143], v[180:183], v[46:49]
	v_mfma_f32_16x16x32_bf16 v[42:45], v[148:151], v[180:183], v[42:45]
	v_mfma_f32_16x16x32_bf16 v[28:31], v[140:143], v[188:191], v[28:31]
	v_mfma_f32_16x16x32_bf16 v[24:27], v[148:151], v[188:191], v[24:27]
	v_mfma_f32_16x16x32_bf16 v[12:15], v[140:143], v[202:205], v[12:15]
	v_mfma_f32_16x16x32_bf16 v[8:11], v[148:151], v[202:205], v[8:11]
	v_mfma_f32_16x16x32_bf16 v[62:65], v[144:147], v[176:179], v[62:65]
	v_mfma_f32_16x16x32_bf16 v[58:61], v[152:155], v[176:179], v[58:61]
	v_mfma_f32_16x16x32_bf16 v[46:49], v[144:147], v[184:187], v[46:49]
	v_mfma_f32_16x16x32_bf16 v[42:45], v[152:155], v[184:187], v[42:45]
	v_mfma_f32_16x16x32_bf16 v[28:31], v[144:147], v[198:201], v[28:31]
	v_mfma_f32_16x16x32_bf16 v[24:27], v[152:155], v[198:201], v[24:27]
	v_mfma_f32_16x16x32_bf16 v[12:15], v[144:147], v[206:209], v[12:15]
	v_mfma_f32_16x16x32_bf16 v[8:11], v[152:155], v[206:209], v[8:11]
	s_setprio 0
	s_setprio 1
	v_mfma_f32_16x16x32_bf16 v[54:57], v[156:159], v[172:175], v[54:57]
	v_mfma_f32_16x16x32_bf16 v[50:53], v[164:167], v[172:175], v[50:53]
	v_mfma_f32_16x16x32_bf16 v[38:41], v[156:159], v[180:183], v[38:41]
	v_mfma_f32_16x16x32_bf16 v[34:37], v[164:167], v[180:183], v[34:37]
	v_mfma_f32_16x16x32_bf16 v[20:23], v[156:159], v[188:191], v[20:23]
	v_mfma_f32_16x16x32_bf16 v[16:19], v[164:167], v[188:191], v[16:19]
	v_mfma_f32_16x16x32_bf16 v[4:7], v[156:159], v[202:205], v[4:7]
	v_mfma_f32_16x16x32_bf16 v[0:3], v[164:167], v[202:205], v[0:3]
	v_mfma_f32_16x16x32_bf16 v[54:57], v[160:163], v[176:179], v[54:57]
	v_mfma_f32_16x16x32_bf16 v[50:53], v[168:171], v[176:179], v[50:53]
	v_mfma_f32_16x16x32_bf16 v[38:41], v[160:163], v[184:187], v[38:41]
	v_mfma_f32_16x16x32_bf16 v[34:37], v[168:171], v[184:187], v[34:37]
	v_mfma_f32_16x16x32_bf16 v[20:23], v[160:163], v[198:201], v[20:23]
	v_mfma_f32_16x16x32_bf16 v[16:19], v[168:171], v[198:201], v[16:19]
	v_mfma_f32_16x16x32_bf16 v[4:7], v[160:163], v[206:209], v[4:7]
	v_mfma_f32_16x16x32_bf16 v[0:3], v[168:171], v[206:209], v[0:3]
	s_setprio 0
	s_barrier
; #define PG8_STAGE(bufoff, gbase, voff) do { _Pragma("unroll") for (int _i = 0; _i < 2; ++_i) \
;         __builtin_amdgcn_global_load_lds((const unsigned*)((const char*)(gbase) + (voff)[_i]), (PG8_LAS unsigned*)(lds + (bufoff) + ldsw + _i * 8192), 16, 0, 0); } while (0)
; #define PG8_LDA(dst, b, h) do { _Pragma("unroll") for (int m = 0; m < 4; ++m) _Pragma("unroll") for (int k = 0; k < 2; ++k) dst[m][k] = *(const PG8_LAS bf16x8*)(lds + PG8_SA(b, h) + aoff + m * 2048 + k * 1024); } while (0)
; #define PG8_LDB(dst, b, h) do { _Pragma("unroll") for (int n = 0; n < 2; ++n) _Pragma("unroll") for (int k = 0; k < 2; ++k) dst[n][k] = *(const PG8_LAS bf16x8*)(lds + PG8_SB(b, h) + boff + n * 2048 + k * 1024); } while (0)
; #define PG8_MMA(ai, bj, At, Bt) do { __builtin_amdgcn_s_setprio(1); _Pragma("unroll") for (int m = 0; m < 4; ++m) _Pragma("unroll") for (int n = 0; n < 2; ++n) _Pragma("unroll") for (int k = 0; k < 2; ++k) \
;         acc[ai][bj][m][n] = __builtin_amdgcn_mfma_f32_16x16x32_bf16(Bt[n][k], At[m][k], acc[ai][bj][m][n], 0, 0, 0); __builtin_amdgcn_s_setprio(0); } while (0)
; #define PG8_WAIT_V(n) asm volatile("s_waitcnt vmcnt(" #n ")" ::: "memory")
; #define PG8_WAIT_L(n) asm volatile("s_waitcnt lgkmcnt(" #n ")" ::: "memory")
; #define PG8_BAR __builtin_amdgcn_s_barrier()
; #define PG8_SCHED __builtin_amdgcn_sched_barrier(0)
; template <class Epi, class Sched, bool ALIGN_EPI = false, bool SP2 = false, bool KHOOK = false>
; __device__ __forceinline__ void gemm_phase(PG8_LAS unsigned char* lds, const Gemm g, const Sched& S, const Epi& E, const int tid_in) {
;     ...
;             PG8_LDB(B0, 1, 0); PG8_LDB(B1, 1, 1); PG8_SCHED; PG8_LDA(At, 1, 0); PG8_STAGE(PG8_SA(0, 1), a2 + hstep, voffA);
;             PG8_WAIT_V(8); PG8_WAIT_L(0); PG8_BAR; PG8_MMA(0, 0, At, B0); PG8_MMA(0, 1, At, B1); PG8_BAR; PG8_SCHED;
	s_add_i32 s47, 0, 0x18000
	s_add_i32 s50, 0, 0x1c000
	v_add_u32_e32 v152, s47, v137
	v_add_u32_e32 v168, s50, v137
	ds_read_b128 v[140:143], v152
	ds_read_b128 v[144:147], v152 offset:1024
	ds_read_b128 v[148:151], v152 offset:2048
	ds_read_b128 v[152:155], v152 offset:3072
	ds_read_b128 v[156:159], v168
	ds_read_b128 v[160:163], v168 offset:1024
	ds_read_b128 v[164:167], v168 offset:2048
	ds_read_b128 v[168:171], v168 offset:3072
	s_add_u32 s48, s48, 0x80000
	s_addc_u32 s49, s49, 0
	s_mov_b32 m0, s38
	v_lshl_add_u64 v[216:217], s[48:49], 0, v[32:33]
	ds_read_b128 v[172:175], v139 offset:32768
	ds_read_b128 v[176:179], v139 offset:33792
	ds_read_b128 v[180:183], v139 offset:34816
	ds_read_b128 v[184:187], v139 offset:35840
	ds_read_b128 v[188:191], v139 offset:36864
	ds_read_b128 v[198:201], v139 offset:37888
	ds_read_b128 v[202:205], v139 offset:38912
	ds_read_b128 v[206:209], v139 offset:39936
	global_load_lds_dwordx4 v[216:217], off
	s_mov_b32 m0, s39
	v_lshl_add_u64 v[216:217], s[48:49], 0, v[130:131]
	global_load_lds_dwordx4 v[216:217], off
	s_waitcnt vmcnt(8)
	s_waitcnt lgkmcnt(0)
	s_barrier
	s_setprio 1
	s_waitcnt lgkmcnt(0)
	v_mfma_f32_16x16x32_bf16 v[126:129], v[140:143], v[172:175], v[126:129]
	v_mfma_f32_16x16x32_bf16 v[122:125], v[148:151], v[172:175], v[122:125]
	v_mfma_f32_16x16x32_bf16 v[110:113], v[140:143], v[180:183], v[110:113]
	v_mfma_f32_16x16x32_bf16 v[106:109], v[148:151], v[180:183], v[106:109]
	v_mfma_f32_16x16x32_bf16 v[94:97], v[140:143], v[188:191], v[94:97]
	v_mfma_f32_16x16x32_bf16 v[90:93], v[148:151], v[188:191], v[90:93]
	v_mfma_f32_16x16x32_bf16 v[78:81], v[140:143], v[202:205], v[78:81]
	v_mfma_f32_16x16x32_bf16 v[74:77], v[148:151], v[202:205], v[74:77]
	v_mfma_f32_16x16x32_bf16 v[126:129], v[144:147], v[176:179], v[126:129]
	v_mfma_f32_16x16x32_bf16 v[122:125], v[152:155], v[176:179], v[122:125]
	v_mfma_f32_16x16x32_bf16 v[110:113], v[144:147], v[184:187], v[110:113]
	v_mfma_f32_16x16x32_bf16 v[106:109], v[152:155], v[184:187], v[106:109]
	v_mfma_f32_16x16x32_bf16 v[94:97], v[144:147], v[198:201], v[94:97]
	v_mfma_f32_16x16x32_bf16 v[90:93], v[152:155], v[198:201], v[90:93]
	v_mfma_f32_16x16x32_bf16 v[78:81], v[144:147], v[206:209], v[78:81]
	v_mfma_f32_16x16x32_bf16 v[74:77], v[152:155], v[206:209], v[74:77]
	s_setprio 0
	s_setprio 1
	v_mfma_f32_16x16x32_bf16 v[118:121], v[156:159], v[172:175], v[118:121]
	v_mfma_f32_16x16x32_bf16 v[114:117], v[164:167], v[172:175], v[114:117]
	v_mfma_f32_16x16x32_bf16 v[102:105], v[156:159], v[180:183], v[102:105]
	v_mfma_f32_16x16x32_bf16 v[98:101], v[164:167], v[180:183], v[98:101]
	v_mfma_f32_16x16x32_bf16 v[86:89], v[156:159], v[188:191], v[86:89]
	v_mfma_f32_16x16x32_bf16 v[82:85], v[164:167], v[188:191], v[82:85]
	v_mfma_f32_16x16x32_bf16 v[70:73], v[156:159], v[202:205], v[70:73]
	v_mfma_f32_16x16x32_bf16 v[66:69], v[164:167], v[202:205], v[66:69]
	v_mfma_f32_16x16x32_bf16 v[118:121], v[160:163], v[176:179], v[118:121]
	v_mfma_f32_16x16x32_bf16 v[114:117], v[168:171], v[176:179], v[114:117]
	v_mfma_f32_16x16x32_bf16 v[102:105], v[160:163], v[184:187], v[102:105]
	v_mfma_f32_16x16x32_bf16 v[98:101], v[168:171], v[184:187], v[98:101]
	v_mfma_f32_16x16x32_bf16 v[86:89], v[160:163], v[198:201], v[86:89]
	v_mfma_f32_16x16x32_bf16 v[82:85], v[168:171], v[198:201], v[82:85]
	v_mfma_f32_16x16x32_bf16 v[70:73], v[160:163], v[206:209], v[70:73]
	v_mfma_f32_16x16x32_bf16 v[66:69], v[168:171], v[206:209], v[66:69]
	s_setprio 0
	s_barrier
; #define PG8_STAGE(bufoff, gbase, voff) do { _Pragma("unroll") for (int _i = 0; _i < 2; ++_i) \
;         __builtin_amdgcn_global_load_lds((const unsigned*)((const char*)(gbase) + (voff)[_i]), (PG8_LAS unsigned*)(lds + (bufoff) + ldsw + _i * 8192), 16, 0, 0); } while (0)
; #define PG8_LDA(dst, b, h) do { _Pragma("unroll") for (int m = 0; m < 4; ++m) _Pragma("unroll") for (int k = 0; k < 2; ++k) dst[m][k] = *(const PG8_LAS bf16x8*)(lds + PG8_SA(b, h) + aoff + m * 2048 + k * 1024); } while (0)
; #define PG8_LDB(dst, b, h) do { _Pragma("unroll") for (int n = 0; n < 2; ++n) _Pragma("unroll") for (int k = 0; k < 2; ++k) dst[n][k] = *(const PG8_LAS bf16x8*)(lds + PG8_SB(b, h) + boff + n * 2048 + k * 1024); } while (0)
; #define PG8_MMA(ai, bj, At, Bt) do { __builtin_amdgcn_s_setprio(1); _Pragma("unroll") for (int m = 0; m < 4; ++m) _Pragma("unroll") for (int n = 0; n < 2; ++n) _Pragma("unroll") for (int k = 0; k < 2; ++k) \
;         acc[ai][bj][m][n] = __builtin_amdgcn_mfma_f32_16x16x32_bf16(Bt[n][k], At[m][k], acc[ai][bj][m][n], 0, 0, 0); __builtin_amdgcn_s_setprio(0); } while (0)
; template <class Epi, class Sched, bool ALIGN_EPI = false, bool SP2 = false, bool KHOOK = false>
; __device__ __forceinline__ void gemm_phase(PG8_LAS unsigned char* lds, const Gemm g, const Sched& S, const Epi& E, const int tid_in) {
;     ...
;             PG8_LDB(B0, 0, 0); PG8_LDB(B1, 0, 1); PG8_SCHED; PG8_LDA(At, 0, 0); PG8_STAGE(PG8_SA(1, 1), a1 + hstep, voffA);
;             PG8_WAIT_V(8); PG8_WAIT_L(0); PG8_BAR; PG8_MMA(0, 0, At, B0); PG8_MMA(0, 1, At, B1); PG8_BAR; PG8_SCHED;
;             PG8_LDA(At, 0, 1); PG8_STAGE(PG8_SB(0, 0), b2, voffB); PG8_STAGE(PG8_SB(0, 1), b2 + hstep, voffB); PG8_STAGE(PG8_SA(0, 0), a2, voffA);
;             PG8_WAIT_V(8); PG8_WAIT_L(0); PG8_BAR; PG8_MMA(1, 0, At, B0); PG8_MMA(1, 1, At, B1); PG8_BAR; PG8_SCHED;
;             PG8_LDB(B0, 1, 0); PG8_LDB(B1, 1, 1); PG8_SCHED; PG8_LDA(At, 1, 0); PG8_STAGE(PG8_SA(0, 1), a2 + hstep, voffA);
;             PG8_WAIT_V(8); PG8_WAIT_L(0); PG8_BAR; PG8_MMA(0, 0, At, B0); PG8_MMA(0, 1, At, B1); PG8_BAR; PG8_SCHED;
;             PG8_LDA(At, 1, 1); PG8_STAGE(PG8_SB(1, 0), b3, voffB); PG8_STAGE(PG8_SB(1, 1), b3 + hstep, voffB); PG8_STAGE(PG8_SA(1, 0), a3, voffA);
;             PG8_WAIT_V(8); PG8_WAIT_L(0); PG8_BAR; PG8_MMA(1, 0, At, B0); PG8_MMA(1, 1, At, B1); PG8_BAR; PG8_SCHED;
	s_add_i32 s47, s47, s33
	v_lshl_add_u64 v[192:193], v[192:193], 0, s[90:91]
	s_mov_b32 m0, s47
	ds_read_b128 v[172:175], v139 offset:49152
	ds_read_b128 v[176:179], v139 offset:50176
	ds_read_b128 v[180:183], v139 offset:51200
	ds_read_b128 v[184:187], v139 offset:52224
	ds_read_b128 v[188:191], v139 offset:53248
	ds_read_b128 v[198:201], v139 offset:54272
	ds_read_b128 v[202:205], v139 offset:55296
	ds_read_b128 v[206:209], v139 offset:56320
	global_load_lds_dwordx4 v[192:193], off
	s_add_i32 m0, s47, 0x2000
	s_add_u32 s30, s30, 0x80080
	v_lshl_add_u64 v[192:193], v[210:211], 0, s[90:91]
	s_addc_u32 s31, s31, 0
	s_add_i32 s47, s50, s33
	global_load_lds_dwordx4 v[192:193], off
	s_mov_b32 m0, s47
	v_lshl_add_u64 v[192:193], s[30:31], 0, v[32:33]
	global_load_lds_dwordx4 v[192:193], off
	s_add_i32 m0, s47, 0x2000
	v_lshl_add_u64 v[192:193], s[30:31], 0, v[130:131]
	global_load_lds_dwordx4 v[192:193], off
	s_mov_b32 m0, s40
	v_lshl_add_u64 v[192:193], v[212:213], 0, s[90:91]
	global_load_lds_dwordx4 v[192:193], off
	s_mov_b32 m0, s41
	v_lshl_add_u64 v[192:193], v[214:215], 0, s[90:91]
	global_load_lds_dwordx4 v[192:193], off
	s_waitcnt vmcnt(8)
	s_waitcnt lgkmcnt(0)
	s_barrier
	s_setprio 1
	s_waitcnt lgkmcnt(0)
	v_mfma_f32_16x16x32_bf16 v[62:65], v[140:143], v[172:175], v[62:65]
	v_mfma_f32_16x16x32_bf16 v[58:61], v[148:151], v[172:175], v[58:61]
	v_mfma_f32_16x16x32_bf16 v[46:49], v[140:143], v[180:183], v[46:49]
	v_mfma_f32_16x16x32_bf16 v[42:45], v[148:151], v[180:183], v[42:45]
	v_mfma_f32_16x16x32_bf16 v[28:31], v[140:143], v[188:191], v[28:31]
	v_mfma_f32_16x16x32_bf16 v[24:27], v[148:151], v[188:191], v[24:27]
	v_mfma_f32_16x16x32_bf16 v[12:15], v[140:143], v[202:205], v[12:15]
	v_mfma_f32_16x16x32_bf16 v[8:11], v[148:151], v[202:205], v[8:11]
	v_mfma_f32_16x16x32_bf16 v[62:65], v[144:147], v[176:179], v[62:65]
	v_mfma_f32_16x16x32_bf16 v[58:61], v[152:155], v[176:179], v[58:61]
	v_mfma_f32_16x16x32_bf16 v[46:49], v[144:147], v[184:187], v[46:49]
	v_mfma_f32_16x16x32_bf16 v[42:45], v[152:155], v[184:187], v[42:45]
	v_mfma_f32_16x16x32_bf16 v[28:31], v[144:147], v[198:201], v[28:31]
	v_mfma_f32_16x16x32_bf16 v[24:27], v[152:155], v[198:201], v[24:27]
	v_mfma_f32_16x16x32_bf16 v[12:15], v[144:147], v[206:209], v[12:15]
	v_mfma_f32_16x16x32_bf16 v[8:11], v[152:155], v[206:209], v[8:11]
	s_setprio 0
	s_setprio 1
	v_mfma_f32_16x16x32_bf16 v[54:57], v[156:159], v[172:175], v[54:57]
	v_mfma_f32_16x16x32_bf16 v[50:53], v[164:167], v[172:175], v[50:53]
	v_mfma_f32_16x16x32_bf16 v[38:41], v[156:159], v[180:183], v[38:41]
	v_mfma_f32_16x16x32_bf16 v[34:37], v[164:167], v[180:183], v[34:37]
	v_mfma_f32_16x16x32_bf16 v[20:23], v[156:159], v[188:191], v[20:23]
	v_mfma_f32_16x16x32_bf16 v[16:19], v[164:167], v[188:191], v[16:19]
	v_mfma_f32_16x16x32_bf16 v[4:7], v[156:159], v[202:205], v[4:7]
	v_mfma_f32_16x16x32_bf16 v[0:3], v[164:167], v[202:205], v[0:3]
	v_mfma_f32_16x16x32_bf16 v[54:57], v[160:163], v[176:179], v[54:57]
	v_mfma_f32_16x16x32_bf16 v[50:53], v[168:171], v[176:179], v[50:53]
	v_mfma_f32_16x16x32_bf16 v[38:41], v[160:163], v[184:187], v[38:41]
	v_mfma_f32_16x16x32_bf16 v[34:37], v[168:171], v[184:187], v[34:37]
	v_mfma_f32_16x16x32_bf16 v[20:23], v[160:163], v[198:201], v[20:23]
	v_mfma_f32_16x16x32_bf16 v[16:19], v[168:171], v[198:201], v[16:19]
	v_mfma_f32_16x16x32_bf16 v[4:7], v[160:163], v[206:209], v[4:7]
	v_mfma_f32_16x16x32_bf16 v[0:3], v[168:171], v[206:209], v[0:3]
	s_setprio 0
	s_barrier
	s_add_i32 s46, s46, 2
	s_add_u32 s26, s26, 0x100
	s_addc_u32 s27, s27, 0
	s_add_u32 s44, s44, 0x100
	s_addc_u32 s45, s45, 0
	s_cmp_gt_u32 s46, 29
	s_cbranch_scc0 .LBB0_1063
	s_and_b64 vcc, exec, s[4:5]
	s_cbranch_vccz .LBB0_1066
	s_barrier

; #define PG8_STAGE(bufoff, gbase, voff) do { _Pragma("unroll") for (int _i = 0; _i < 2; ++_i) \
;         __builtin_amdgcn_global_load_lds((const unsigned*)((const char*)(gbase) + (voff)[_i]), (PG8_LAS unsigned*)(lds + (bufoff) + ldsw + _i * 8192), 16, 0, 0); } while (0)
; #define PG8_LDA(dst, b, h) do { _Pragma("unroll") for (int m = 0; m < 4; ++m) _Pragma("unroll") for (int k = 0; k < 2; ++k) dst[m][k] = *(const PG8_LAS bf16x8*)(lds + PG8_SA(b, h) + aoff + m * 2048 + k * 1024); } while (0)
; #define PG8_WAIT_V(n) asm volatile("s_waitcnt vmcnt(" #n ")" ::: "memory")
; #define PG8_WAIT_L(n) asm volatile("s_waitcnt lgkmcnt(" #n ")" ::: "memory")
; template <class Epi, class Sched, bool ALIGN_EPI = false, bool SP2 = false, bool KHOOK = false>
; __device__ __forceinline__ void gemm_phase(PG8_LAS unsigned char* lds, const Gemm g, const Sched& S, const Epi& E, const int tid_in) {
;     ...
;         for (int t = 0; t < nt; t += 2) {
;             const bool last = (t == nt - 2);
;             const char* a1 = cA + (size_t)(t + 1) * kstep;
;             const char* a2 = last ? nA : cA + (size_t)(t + 2) * kstep; const char* b2 = last ? nB : cB + (size_t)(t + 2) * kstep;
;             const char* a3 = a2 + kstep; const char* b3 = b2 + kstep;
;             if (last && has_next) S.a_ready(nxt);
;             if constexpr (SP2) {
;             PG8_LDB(B0, 0, 0); PG8_LDB(B1, 0, 1); PG8_SCHED; PG8_LDA(At, 0, 0); PG8_STAGE(PG8_SA(1, 1), a1 + hstep, voffA);
;             PG8_WAIT_V(8); PG8_WAIT_L(0); PG8_BAR; PG8_MMA(0, 0, At, B0); PG8_MMA(0, 1, At, B1); PG8_BAR; PG8_SCHED;
;             PG8_LDA(At, 0, 1); PG8_STAGE(PG8_SB(0, 0), b2, voffB); PG8_STAGE(PG8_SB(0, 1), b2 + hstep, voffB); PG8_STAGE(PG8_SA(0, 0), a2, voffA);
;             PG8_WAIT_V(8); PG8_WAIT_L(0); PG8_BAR; PG8_MMA(1, 0, At, B0); PG8_MMA(1, 1, At, B1); PG8_BAR; PG8_SCHED;
;             PG8_LDB(B0, 1, 0); PG8_LDB(B1, 1, 1); PG8_SCHED; PG8_LDA(At, 1, 0); PG8_STAGE(PG8_SA(0, 1), a2 + hstep, voffA);
;             PG8_WAIT_V(8); PG8_WAIT_L(0); PG8_BAR; PG8_MMA(0, 0, At, B0); PG8_MMA(0, 1, At, B1); PG8_BAR; PG8_SCHED;
;             PG8_LDA(At, 1, 1); PG8_STAGE(PG8_SB(1, 0), b3, voffB); PG8_STAGE(PG8_SB(1, 1), b3 + hstep, voffB); PG8_STAGE(PG8_SA(1, 0), a3, voffA);
;             PG8_WAIT_V(8); PG8_WAIT_L(0); PG8_BAR; PG8_MMA(1, 0, At, B0); PG8_MMA(1, 1, At, B1); PG8_BAR; PG8_SCHED;
.LBB0_1086:
	v_cndmask_b32_e64 v172, 0, 1, s[56:57]
	s_add_u32 s56, s14, s46
	s_addc_u32 s57, s15, 0
	s_add_u32 s47, s56, 0x100
	s_addc_u32 s58, s57, 0
	s_and_b64 s[50:51], s[52:53], exec
	s_cselect_b32 s59, s18, s58
	s_cselect_b32 s58, s19, s47
	s_add_u32 s46, s12, s46
	s_addc_u32 s47, s13, 0
	s_add_u32 s50, s46, 0x100
	s_addc_u32 s51, s47, 0
	s_add_i32 s75, 0, 0x10000
	s_and_b64 s[46:47], s[52:53], exec
	s_cselect_b32 s65, s17, s51
	s_cselect_b32 s64, s23, s50
	s_add_i32 s53, 0, 0x14000
	s_add_u32 s70, s56, 0x10080
	s_addc_u32 s71, s57, 0
	s_add_i32 s74, s75, s37
	s_add_i32 m0, s38, 0xc000
	s_add_i32 s81, s38, 0xe000
	s_add_i32 s60, s74, 0x2000
	s_add_u32 s68, s64, 0x10000
	v_add_u32_e32 v152, s75, v137
	v_add_u32_e32 v168, s53, v137
	s_addc_u32 s69, s65, 0
	s_add_i32 s66, s53, s37
	ds_read_b128 v[140:143], v152
	ds_read_b128 v[144:147], v152 offset:1024
	ds_read_b128 v[148:151], v152 offset:2048
	ds_read_b128 v[152:155], v152 offset:3072
	ds_read_b128 v[156:159], v168
	ds_read_b128 v[160:163], v168 offset:1024
	ds_read_b128 v[164:167], v168 offset:2048
	ds_read_b128 v[168:171], v168 offset:3072
	s_add_i32 s61, s66, 0x2000
	s_add_i32 s51, 0, 0x18000
	s_add_i32 s50, 0, 0x1c000
	s_add_u32 s56, s58, 0x10000
	s_addc_u32 s57, s59, 0
	s_add_i32 s47, s51, s37
	s_add_i32 s46, s47, 0x2000
	s_add_u32 s52, s64, 0x10080
	s_addc_u32 s53, s65, 0
	s_add_i32 s79, s50, s37
	s_add_i32 s75, s79, 0x2000
	v_cmp_ne_u32_e32 vcc, 1, v172
	v_lshl_add_u64 v[192:193], s[70:71], 0, v[134:135]
	ds_read_b128 v[172:175], v139
	ds_read_b128 v[176:179], v139 offset:1024
	ds_read_b128 v[180:183], v139 offset:2048
	ds_read_b128 v[184:187], v139 offset:3072
	ds_read_b128 v[188:191], v139 offset:4096
	ds_read_b128 v[198:201], v139 offset:5120
	ds_read_b128 v[202:205], v139 offset:6144
	ds_read_b128 v[206:209], v139 offset:7168
	global_load_lds_dwordx4 v[192:193], off
	s_mov_b32 m0, s81
	v_lshl_add_u64 v[192:193], s[70:71], 0, v[132:133]
	global_load_lds_dwordx4 v[192:193], off
	s_waitcnt vmcnt(8)
	s_waitcnt lgkmcnt(0)
	s_barrier
	s_setprio 1
	s_waitcnt lgkmcnt(0)
	v_mfma_f32_16x16x32_bf16 v[126:129], v[140:143], v[172:175], v[126:129]
	v_mfma_f32_16x16x32_bf16 v[122:125], v[148:151], v[172:175], v[122:125]
	v_mfma_f32_16x16x32_bf16 v[118:121], v[140:143], v[180:183], v[118:121]
	v_mfma_f32_16x16x32_bf16 v[114:117], v[148:151], v[180:183], v[114:117]
	v_mfma_f32_16x16x32_bf16 v[102:105], v[140:143], v[188:191], v[102:105]
	v_mfma_f32_16x16x32_bf16 v[98:101], v[148:151], v[188:191], v[98:101]
	v_mfma_f32_16x16x32_bf16 v[86:89], v[140:143], v[202:205], v[86:89]
	v_mfma_f32_16x16x32_bf16 v[82:85], v[148:151], v[202:205], v[82:85]
	v_mfma_f32_16x16x32_bf16 v[126:129], v[144:147], v[176:179], v[126:129]
	v_mfma_f32_16x16x32_bf16 v[122:125], v[152:155], v[176:179], v[122:125]
	v_mfma_f32_16x16x32_bf16 v[118:121], v[144:147], v[184:187], v[118:121]
	v_mfma_f32_16x16x32_bf16 v[114:117], v[152:155], v[184:187], v[114:117]
	v_mfma_f32_16x16x32_bf16 v[102:105], v[144:147], v[198:201], v[102:105]
	v_mfma_f32_16x16x32_bf16 v[98:101], v[152:155], v[198:201], v[98:101]
	v_mfma_f32_16x16x32_bf16 v[86:89], v[144:147], v[206:209], v[86:89]
	v_mfma_f32_16x16x32_bf16 v[82:85], v[152:155], v[206:209], v[82:85]
	s_setprio 0
	s_setprio 1
	v_mfma_f32_16x16x32_bf16 v[110:113], v[156:159], v[172:175], v[110:113]
	v_mfma_f32_16x16x32_bf16 v[106:109], v[164:167], v[172:175], v[106:109]
	v_mfma_f32_16x16x32_bf16 v[94:97], v[156:159], v[180:183], v[94:97]
	v_mfma_f32_16x16x32_bf16 v[90:93], v[164:167], v[180:183], v[90:93]
	v_mfma_f32_16x16x32_bf16 v[78:81], v[156:159], v[188:191], v[78:81]
	v_mfma_f32_16x16x32_bf16 v[74:77], v[164:167], v[188:191], v[74:77]
	v_mfma_f32_16x16x32_bf16 v[70:73], v[156:159], v[202:205], v[70:73]
	v_mfma_f32_16x16x32_bf16 v[66:69], v[164:167], v[202:205], v[66:69]
	v_mfma_f32_16x16x32_bf16 v[110:113], v[160:163], v[176:179], v[110:113]
	v_mfma_f32_16x16x32_bf16 v[106:109], v[168:171], v[176:179], v[106:109]
	v_mfma_f32_16x16x32_bf16 v[94:97], v[160:163], v[184:187], v[94:97]
	v_mfma_f32_16x16x32_bf16 v[90:93], v[168:171], v[184:187], v[90:93]
	v_mfma_f32_16x16x32_bf16 v[78:81], v[160:163], v[198:201], v[78:81]
	v_mfma_f32_16x16x32_bf16 v[74:77], v[168:171], v[198:201], v[74:77]
	v_mfma_f32_16x16x32_bf16 v[70:73], v[160:163], v[206:209], v[70:73]
	v_mfma_f32_16x16x32_bf16 v[66:69], v[168:171], v[206:209], v[66:69]
	s_setprio 0
	s_barrier
	s_mov_b32 m0, s74
	v_lshl_add_u64 v[192:193], s[64:65], 0, v[32:33]
	ds_read_b128 v[172:175], v139 offset:16384
	ds_read_b128 v[176:179], v139 offset:17408
	ds_read_b128 v[180:183], v139 offset:18432
	ds_read_b128 v[184:187], v139 offset:19456
	ds_read_b128 v[188:191], v139 offset:20480
	ds_read_b128 v[198:201], v139 offset:21504
	ds_read_b128 v[202:205], v139 offset:22528
	ds_read_b128 v[206:209], v139 offset:23552
	global_load_lds_dwordx4 v[192:193], off
	v_lshl_add_u64 v[210:211], s[64:65], 0, v[130:131]
	s_mov_b32 m0, s60
	v_lshl_add_u64 v[212:213], s[68:69], 0, v[32:33]
	global_load_lds_dwordx4 v[210:211], off
	s_mov_b32 m0, s66
	v_lshl_add_u64 v[214:215], s[58:59], 0, v[132:133]
	global_load_lds_dwordx4 v[212:213], off
	s_mov_b32 m0, s61
	v_lshl_add_u64 v[212:213], s[68:69], 0, v[130:131]
	global_load_lds_dwordx4 v[212:213], off
	s_mov_b32 m0, s38
	v_lshl_add_u64 v[212:213], s[58:59], 0, v[134:135]
	global_load_lds_dwordx4 v[212:213], off
	s_mov_b32 m0, s39
	s_nop 0
	global_load_lds_dwordx4 v[214:215], off
	s_waitcnt vmcnt(8)
	s_waitcnt lgkmcnt(0)
	s_barrier
; #define PG8_STAGE(bufoff, gbase, voff) do { _Pragma("unroll") for (int _i = 0; _i < 2; ++_i) \
;         __builtin_amdgcn_global_load_lds((const unsigned*)((const char*)(gbase) + (voff)[_i]), (PG8_LAS unsigned*)(lds + (bufoff) + ldsw + _i * 8192), 16, 0, 0); } while (0)
; #define PG8_LDA(dst, b, h) do { _Pragma("unroll") for (int m = 0; m < 4; ++m) _Pragma("unroll") for (int k = 0; k < 2; ++k) dst[m][k] = *(const PG8_LAS bf16x8*)(lds + PG8_SA(b, h) + aoff + m * 2048 + k * 1024); } while (0)
; #define PG8_LDB(dst, b, h) do { _Pragma("unroll") for (int n = 0; n < 2; ++n) _Pragma("unroll") for (int k = 0; k < 2; ++k) dst[n][k] = *(const PG8_LAS bf16x8*)(lds + PG8_SB(b, h) + boff + n * 2048 + k * 1024); } while (0)
; #define PG8_MMA(ai, bj, At, Bt) do { __builtin_amdgcn_s_setprio(1); _Pragma("unroll") for (int m = 0; m < 4; ++m) _Pragma("unroll") for (int n = 0; n < 2; ++n) _Pragma("unroll") for (int k = 0; k < 2; ++k) \
;         acc[ai][bj][m][n] = __builtin_amdgcn_mfma_f32_16x16x32_bf16(Bt[n][k], At[m][k], acc[ai][bj][m][n], 0, 0, 0); __builtin_amdgcn_s_setprio(0); } while (0)
; template <class Epi, class Sched, bool ALIGN_EPI = false, bool SP2 = false, bool KHOOK = false>
; __device__ __forceinline__ void gemm_phase(PG8_LAS unsigned char* lds, const Gemm g, const Sched& S, const Epi& E, const int tid_in) {
;     ...
;             PG8_LDB(B0, 0, 0); PG8_LDB(B1, 0, 1); PG8_SCHED; PG8_LDA(At, 0, 0); PG8_STAGE(PG8_SA(1, 1), a1 + hstep, voffA);
;             PG8_WAIT_V(8); PG8_WAIT_L(0); PG8_BAR; PG8_MMA(0, 0, At, B0); PG8_MMA(0, 1, At, B1); PG8_BAR; PG8_SCHED;
;             PG8_LDA(At, 0, 1); PG8_STAGE(PG8_SB(0, 0), b2, voffB); PG8_STAGE(PG8_SB(0, 1), b2 + hstep, voffB); PG8_STAGE(PG8_SA(0, 0), a2, voffA);
;             PG8_WAIT_V(8); PG8_WAIT_L(0); PG8_BAR; PG8_MMA(1, 0, At, B0); PG8_MMA(1, 1, At, B1); PG8_BAR; PG8_SCHED;
;             PG8_LDB(B0, 1, 0); PG8_LDB(B1, 1, 1); PG8_SCHED; PG8_LDA(At, 1, 0); PG8_STAGE(PG8_SA(0, 1), a2 + hstep, voffA);
;             PG8_WAIT_V(8); PG8_WAIT_L(0); PG8_BAR; PG8_MMA(0, 0, At, B0); PG8_MMA(0, 1, At, B1); PG8_BAR; PG8_SCHED;
;             PG8_LDA(At, 1, 1); PG8_STAGE(PG8_SB(1, 0), b3, voffB); PG8_STAGE(PG8_SB(1, 1), b3 + hstep, voffB); PG8_STAGE(PG8_SA(1, 0), a3, voffA);
;             PG8_WAIT_V(8); PG8_WAIT_L(0); PG8_BAR; PG8_MMA(1, 0, At, B0); PG8_MMA(1, 1, At, B1); PG8_BAR; PG8_SCHED;
	s_setprio 1
	s_waitcnt lgkmcnt(0)
	v_mfma_f32_16x16x32_bf16 v[62:65], v[140:143], v[172:175], v[62:65]
	v_mfma_f32_16x16x32_bf16 v[58:61], v[148:151], v[172:175], v[58:61]
	v_mfma_f32_16x16x32_bf16 v[54:57], v[140:143], v[180:183], v[54:57]
	v_mfma_f32_16x16x32_bf16 v[50:53], v[148:151], v[180:183], v[50:53]
	v_mfma_f32_16x16x32_bf16 v[38:41], v[140:143], v[188:191], v[38:41]
	v_mfma_f32_16x16x32_bf16 v[34:37], v[148:151], v[188:191], v[34:37]
	v_mfma_f32_16x16x32_bf16 v[20:23], v[140:143], v[202:205], v[20:23]
	v_mfma_f32_16x16x32_bf16 v[16:19], v[148:151], v[202:205], v[16:19]
	v_mfma_f32_16x16x32_bf16 v[62:65], v[144:147], v[176:179], v[62:65]
	v_mfma_f32_16x16x32_bf16 v[58:61], v[152:155], v[176:179], v[58:61]
	v_mfma_f32_16x16x32_bf16 v[54:57], v[144:147], v[184:187], v[54:57]
	v_mfma_f32_16x16x32_bf16 v[50:53], v[152:155], v[184:187], v[50:53]
	v_mfma_f32_16x16x32_bf16 v[38:41], v[144:147], v[198:201], v[38:41]
	v_mfma_f32_16x16x32_bf16 v[34:37], v[152:155], v[198:201], v[34:37]
	v_mfma_f32_16x16x32_bf16 v[20:23], v[144:147], v[206:209], v[20:23]
	v_mfma_f32_16x16x32_bf16 v[16:19], v[152:155], v[206:209], v[16:19]
	s_setprio 0
	s_setprio 1
	v_mfma_f32_16x16x32_bf16 v[46:49], v[156:159], v[172:175], v[46:49]
	v_mfma_f32_16x16x32_bf16 v[42:45], v[164:167], v[172:175], v[42:45]
	v_mfma_f32_16x16x32_bf16 v[28:31], v[156:159], v[180:183], v[28:31]
	v_mfma_f32_16x16x32_bf16 v[24:27], v[164:167], v[180:183], v[24:27]
	v_mfma_f32_16x16x32_bf16 v[12:15], v[156:159], v[188:191], v[12:15]
	v_mfma_f32_16x16x32_bf16 v[8:11], v[164:167], v[188:191], v[8:11]
	v_mfma_f32_16x16x32_bf16 v[4:7], v[156:159], v[202:205], v[4:7]
	v_mfma_f32_16x16x32_bf16 v[0:3], v[164:167], v[202:205], v[0:3]
	v_mfma_f32_16x16x32_bf16 v[46:49], v[160:163], v[176:179], v[46:49]
	v_mfma_f32_16x16x32_bf16 v[42:45], v[168:171], v[176:179], v[42:45]
	v_mfma_f32_16x16x32_bf16 v[28:31], v[160:163], v[184:187], v[28:31]
	v_mfma_f32_16x16x32_bf16 v[24:27], v[168:171], v[184:187], v[24:27]
	v_mfma_f32_16x16x32_bf16 v[12:15], v[160:163], v[198:201], v[12:15]
	v_mfma_f32_16x16x32_bf16 v[8:11], v[168:171], v[198:201], v[8:11]
	v_mfma_f32_16x16x32_bf16 v[4:7], v[160:163], v[206:209], v[4:7]
	v_mfma_f32_16x16x32_bf16 v[0:3], v[168:171], v[206:209], v[0:3]
	s_setprio 0
	s_barrier
	v_add_u32_e32 v152, s51, v137
	v_add_u32_e32 v168, s50, v137
	ds_read_b128 v[140:143], v152
	ds_read_b128 v[144:147], v152 offset:1024
	ds_read_b128 v[148:151], v152 offset:2048
	ds_read_b128 v[152:155], v152 offset:3072
	ds_read_b128 v[156:159], v168
	ds_read_b128 v[160:163], v168 offset:1024
	ds_read_b128 v[164:167], v168 offset:2048
	ds_read_b128 v[168:171], v168 offset:3072
	s_mov_b32 m0, s40
	v_lshl_add_u64 v[216:217], s[56:57], 0, v[134:135]
	ds_read_b128 v[172:175], v139 offset:32768
	ds_read_b128 v[176:179], v139 offset:33792
	ds_read_b128 v[180:183], v139 offset:34816
	ds_read_b128 v[184:187], v139 offset:35840
	ds_read_b128 v[188:191], v139 offset:36864
	ds_read_b128 v[198:201], v139 offset:37888
	ds_read_b128 v[202:205], v139 offset:38912
	ds_read_b128 v[206:209], v139 offset:39936
	global_load_lds_dwordx4 v[216:217], off
	s_mov_b32 m0, s41
	v_lshl_add_u64 v[216:217], s[56:57], 0, v[132:133]
	global_load_lds_dwordx4 v[216:217], off
	s_waitcnt vmcnt(8)
	s_waitcnt lgkmcnt(0)
	s_barrier
	s_setprio 1
	s_waitcnt lgkmcnt(0)
	v_mfma_f32_16x16x32_bf16 v[126:129], v[140:143], v[172:175], v[126:129]
	v_mfma_f32_16x16x32_bf16 v[122:125], v[148:151], v[172:175], v[122:125]
	v_mfma_f32_16x16x32_bf16 v[118:121], v[140:143], v[180:183], v[118:121]
	v_mfma_f32_16x16x32_bf16 v[114:117], v[148:151], v[180:183], v[114:117]
	v_mfma_f32_16x16x32_bf16 v[102:105], v[140:143], v[188:191], v[102:105]
	v_mfma_f32_16x16x32_bf16 v[98:101], v[148:151], v[188:191], v[98:101]
	v_mfma_f32_16x16x32_bf16 v[86:89], v[140:143], v[202:205], v[86:89]
	v_mfma_f32_16x16x32_bf16 v[82:85], v[148:151], v[202:205], v[82:85]
	v_mfma_f32_16x16x32_bf16 v[126:129], v[144:147], v[176:179], v[126:129]
	v_mfma_f32_16x16x32_bf16 v[122:125], v[152:155], v[176:179], v[122:125]
	v_mfma_f32_16x16x32_bf16 v[118:121], v[144:147], v[184:187], v[118:121]
	v_mfma_f32_16x16x32_bf16 v[114:117], v[152:155], v[184:187], v[114:117]
	v_mfma_f32_16x16x32_bf16 v[102:105], v[144:147], v[198:201], v[102:105]
	v_mfma_f32_16x16x32_bf16 v[98:101], v[152:155], v[198:201], v[98:101]
	v_mfma_f32_16x16x32_bf16 v[86:89], v[144:147], v[206:209], v[86:89]
	v_mfma_f32_16x16x32_bf16 v[82:85], v[152:155], v[206:209], v[82:85]
	s_setprio 0
	s_setprio 1
	v_mfma_f32_16x16x32_bf16 v[110:113], v[156:159], v[172:175], v[110:113]
	v_mfma_f32_16x16x32_bf16 v[106:109], v[164:167], v[172:175], v[106:109]
	v_mfma_f32_16x16x32_bf16 v[94:97], v[156:159], v[180:183], v[94:97]
	v_mfma_f32_16x16x32_bf16 v[90:93], v[164:167], v[180:183], v[90:93]
	v_mfma_f32_16x16x32_bf16 v[78:81], v[156:159], v[188:191], v[78:81]
	v_mfma_f32_16x16x32_bf16 v[74:77], v[164:167], v[188:191], v[74:77]
	v_mfma_f32_16x16x32_bf16 v[70:73], v[156:159], v[202:205], v[70:73]
	v_mfma_f32_16x16x32_bf16 v[66:69], v[164:167], v[202:205], v[66:69]
	v_mfma_f32_16x16x32_bf16 v[110:113], v[160:163], v[176:179], v[110:113]
	v_mfma_f32_16x16x32_bf16 v[106:109], v[168:171], v[176:179], v[106:109]
	v_mfma_f32_16x16x32_bf16 v[94:97], v[160:163], v[184:187], v[94:97]
	v_mfma_f32_16x16x32_bf16 v[90:93], v[168:171], v[184:187], v[90:93]
	v_mfma_f32_16x16x32_bf16 v[78:81], v[160:163], v[198:201], v[78:81]
	v_mfma_f32_16x16x32_bf16 v[74:77], v[168:171], v[198:201], v[74:77]
	v_mfma_f32_16x16x32_bf16 v[70:73], v[160:163], v[206:209], v[70:73]
	v_mfma_f32_16x16x32_bf16 v[66:69], v[168:171], v[206:209], v[66:69]
	s_setprio 0
	s_barrier
; #define PG8_STAGE(bufoff, gbase, voff) do { _Pragma("unroll") for (int _i = 0; _i < 2; ++_i) \
;         __builtin_amdgcn_global_load_lds((const unsigned*)((const char*)(gbase) + (voff)[_i]), (PG8_LAS unsigned*)(lds + (bufoff) + ldsw + _i * 8192), 16, 0, 0); } while (0)
; #define PG8_LDA(dst, b, h) do { _Pragma("unroll") for (int m = 0; m < 4; ++m) _Pragma("unroll") for (int k = 0; k < 2; ++k) dst[m][k] = *(const PG8_LAS bf16x8*)(lds + PG8_SA(b, h) + aoff + m * 2048 + k * 1024); } while (0)
; #define PG8_LDB(dst, b, h) do { _Pragma("unroll") for (int n = 0; n < 2; ++n) _Pragma("unroll") for (int k = 0; k < 2; ++k) dst[n][k] = *(const PG8_LAS bf16x8*)(lds + PG8_SB(b, h) + boff + n * 2048 + k * 1024); } while (0)
; #define PG8_MMA(ai, bj, At, Bt) do { __builtin_amdgcn_s_setprio(1); _Pragma("unroll") for (int m = 0; m < 4; ++m) _Pragma("unroll") for (int n = 0; n < 2; ++n) _Pragma("unroll") for (int k = 0; k < 2; ++k) \
;         acc[ai][bj][m][n] = __builtin_amdgcn_mfma_f32_16x16x32_bf16(Bt[n][k], At[m][k], acc[ai][bj][m][n], 0, 0, 0); __builtin_amdgcn_s_setprio(0); } while (0)
; template <class Epi, class Sched, bool ALIGN_EPI = false, bool SP2 = false, bool KHOOK = false>
; __device__ __forceinline__ void gemm_phase(PG8_LAS unsigned char* lds, const Gemm g, const Sched& S, const Epi& E, const int tid_in) {
;     ...
;             PG8_LDB(B0, 0, 0); PG8_LDB(B1, 0, 1); PG8_SCHED; PG8_LDA(At, 0, 0); PG8_STAGE(PG8_SA(1, 1), a1 + hstep, voffA);
;             PG8_WAIT_V(8); PG8_WAIT_L(0); PG8_BAR; PG8_MMA(0, 0, At, B0); PG8_MMA(0, 1, At, B1); PG8_BAR; PG8_SCHED;
;             PG8_LDA(At, 0, 1); PG8_STAGE(PG8_SB(0, 0), b2, voffB); PG8_STAGE(PG8_SB(0, 1), b2 + hstep, voffB); PG8_STAGE(PG8_SA(0, 0), a2, voffA);
;             PG8_WAIT_V(8); PG8_WAIT_L(0); PG8_BAR; PG8_MMA(1, 0, At, B0); PG8_MMA(1, 1, At, B1); PG8_BAR; PG8_SCHED;
;             PG8_LDB(B0, 1, 0); PG8_LDB(B1, 1, 1); PG8_SCHED; PG8_LDA(At, 1, 0); PG8_STAGE(PG8_SA(0, 1), a2 + hstep, voffA);
;             PG8_WAIT_V(8); PG8_WAIT_L(0); PG8_BAR; PG8_MMA(0, 0, At, B0); PG8_MMA(0, 1, At, B1); PG8_BAR; PG8_SCHED;
;             PG8_LDA(At, 1, 1); PG8_STAGE(PG8_SB(1, 0), b3, voffB); PG8_STAGE(PG8_SB(1, 1), b3 + hstep, voffB); PG8_STAGE(PG8_SA(1, 0), a3, voffA);
;             PG8_WAIT_V(8); PG8_WAIT_L(0); PG8_BAR; PG8_MMA(1, 0, At, B0); PG8_MMA(1, 1, At, B1); PG8_BAR; PG8_SCHED;
	s_mov_b32 m0, s47
	v_lshl_add_u64 v[192:193], v[192:193], 0, s[90:91]
	ds_read_b128 v[172:175], v139 offset:49152
	ds_read_b128 v[176:179], v139 offset:50176
	ds_read_b128 v[180:183], v139 offset:51200
	ds_read_b128 v[184:187], v139 offset:52224
	ds_read_b128 v[188:191], v139 offset:53248
	ds_read_b128 v[198:201], v139 offset:54272
	ds_read_b128 v[202:205], v139 offset:55296
	ds_read_b128 v[206:209], v139 offset:56320
	global_load_lds_dwordx4 v[192:193], off
	s_mov_b32 m0, s46
	v_lshl_add_u64 v[192:193], v[210:211], 0, s[90:91]
	global_load_lds_dwordx4 v[192:193], off
	s_mov_b32 m0, s79
	v_lshl_add_u64 v[192:193], s[52:53], 0, v[32:33]
	global_load_lds_dwordx4 v[192:193], off
	s_mov_b32 m0, s75
	v_lshl_add_u64 v[192:193], s[52:53], 0, v[130:131]
	global_load_lds_dwordx4 v[192:193], off
	s_mov_b32 m0, s24
	v_lshl_add_u64 v[192:193], v[212:213], 0, s[90:91]
	global_load_lds_dwordx4 v[192:193], off
	s_mov_b32 m0, s25
	v_lshl_add_u64 v[192:193], v[214:215], 0, s[90:91]
	global_load_lds_dwordx4 v[192:193], off
	s_waitcnt vmcnt(8)
	s_waitcnt lgkmcnt(0)
	s_barrier
	s_setprio 1
	s_waitcnt lgkmcnt(0)
	v_mfma_f32_16x16x32_bf16 v[62:65], v[140:143], v[172:175], v[62:65]
	v_mfma_f32_16x16x32_bf16 v[58:61], v[148:151], v[172:175], v[58:61]
	v_mfma_f32_16x16x32_bf16 v[54:57], v[140:143], v[180:183], v[54:57]
	v_mfma_f32_16x16x32_bf16 v[50:53], v[148:151], v[180:183], v[50:53]
	v_mfma_f32_16x16x32_bf16 v[38:41], v[140:143], v[188:191], v[38:41]
	v_mfma_f32_16x16x32_bf16 v[34:37], v[148:151], v[188:191], v[34:37]
	v_mfma_f32_16x16x32_bf16 v[20:23], v[140:143], v[202:205], v[20:23]
	v_mfma_f32_16x16x32_bf16 v[16:19], v[148:151], v[202:205], v[16:19]
	v_mfma_f32_16x16x32_bf16 v[62:65], v[144:147], v[176:179], v[62:65]
	v_mfma_f32_16x16x32_bf16 v[58:61], v[152:155], v[176:179], v[58:61]
	v_mfma_f32_16x16x32_bf16 v[54:57], v[144:147], v[184:187], v[54:57]
	v_mfma_f32_16x16x32_bf16 v[50:53], v[152:155], v[184:187], v[50:53]
	v_mfma_f32_16x16x32_bf16 v[38:41], v[144:147], v[198:201], v[38:41]
	v_mfma_f32_16x16x32_bf16 v[34:37], v[152:155], v[198:201], v[34:37]
	v_mfma_f32_16x16x32_bf16 v[20:23], v[144:147], v[206:209], v[20:23]
	v_mfma_f32_16x16x32_bf16 v[16:19], v[152:155], v[206:209], v[16:19]
	s_setprio 0
	s_setprio 1
	v_mfma_f32_16x16x32_bf16 v[46:49], v[156:159], v[172:175], v[46:49]
	v_mfma_f32_16x16x32_bf16 v[42:45], v[164:167], v[172:175], v[42:45]
	v_mfma_f32_16x16x32_bf16 v[28:31], v[156:159], v[180:183], v[28:31]
	v_mfma_f32_16x16x32_bf16 v[24:27], v[164:167], v[180:183], v[24:27]
	v_mfma_f32_16x16x32_bf16 v[12:15], v[156:159], v[188:191], v[12:15]
	v_mfma_f32_16x16x32_bf16 v[8:11], v[164:167], v[188:191], v[8:11]
	v_mfma_f32_16x16x32_bf16 v[4:7], v[156:159], v[202:205], v[4:7]
	v_mfma_f32_16x16x32_bf16 v[0:3], v[164:167], v[202:205], v[0:3]
	v_mfma_f32_16x16x32_bf16 v[46:49], v[160:163], v[176:179], v[46:49]
	v_mfma_f32_16x16x32_bf16 v[42:45], v[168:171], v[176:179], v[42:45]
	v_mfma_f32_16x16x32_bf16 v[28:31], v[160:163], v[184:187], v[28:31]
	v_mfma_f32_16x16x32_bf16 v[24:27], v[168:171], v[184:187], v[24:27]
	v_mfma_f32_16x16x32_bf16 v[12:15], v[160:163], v[198:201], v[12:15]
	v_mfma_f32_16x16x32_bf16 v[8:11], v[168:171], v[198:201], v[8:11]
	v_mfma_f32_16x16x32_bf16 v[4:7], v[160:163], v[206:209], v[4:7]
	v_mfma_f32_16x16x32_bf16 v[0:3], v[168:171], v[206:209], v[0:3]
	s_setprio 0
	s_barrier
	s_movk_i32 s46, 0x100
	s_mov_b64 s[56:57], 0
	s_mov_b64 s[52:53], -1
	s_cbranch_vccz .LBB0_1086
	s_and_b64 vcc, exec, s[10:11]
	s_cbranch_vccz .LBB0_1089
	s_barrier

; #define PG8_STAGE(bufoff, gbase, voff) do { _Pragma("unroll") for (int _i = 0; _i < 2; ++_i) \
;         __builtin_amdgcn_global_load_lds((const unsigned*)((const char*)(gbase) + (voff)[_i]), (PG8_LAS unsigned*)(lds + (bufoff) + ldsw + _i * 8192), 16, 0, 0); } while (0)
; #define PG8_LDA(dst, b, h) do { _Pragma("unroll") for (int m = 0; m < 4; ++m) _Pragma("unroll") for (int k = 0; k < 2; ++k) dst[m][k] = *(const PG8_LAS bf16x8*)(lds + PG8_SA(b, h) + aoff + m * 2048 + k * 1024); } while (0)
; #define PG8_WAIT_V(n) asm volatile("s_waitcnt vmcnt(" #n ")" ::: "memory")
; #define PG8_WAIT_L(n) asm volatile("s_waitcnt lgkmcnt(" #n ")" ::: "memory")
; template <class Epi, class Sched, bool ALIGN_EPI = false, bool SP2 = false, bool KHOOK = false>
; __device__ __forceinline__ void gemm_phase(PG8_LAS unsigned char* lds, const Gemm g, const Sched& S, const Epi& E, const int tid_in) {
;     ...
;         for (int t = 0; t < nt; t += 2) {
;             const bool last = (t == nt - 2);
;             const char* a1 = cA + (size_t)(t + 1) * kstep;
;             const char* a2 = last ? nA : cA + (size_t)(t + 2) * kstep; const char* b2 = last ? nB : cB + (size_t)(t + 2) * kstep;
;             const char* a3 = a2 + kstep; const char* b3 = b2 + kstep;
;             if (last && has_next) S.a_ready(nxt);
;             if constexpr (SP2) {
;             PG8_LDB(B0, 0, 0); PG8_LDB(B1, 0, 1); PG8_SCHED; PG8_LDA(At, 0, 0); PG8_STAGE(PG8_SA(1, 1), a1 + hstep, voffA);
;             PG8_WAIT_V(8); PG8_WAIT_L(0); PG8_BAR; PG8_MMA(0, 0, At, B0); PG8_MMA(0, 1, At, B1); PG8_BAR; PG8_SCHED;
;             PG8_LDA(At, 0, 1); PG8_STAGE(PG8_SB(0, 0), b2, voffB); PG8_STAGE(PG8_SB(0, 1), b2 + hstep, voffB); PG8_STAGE(PG8_SA(0, 0), a2, voffA);
;             PG8_WAIT_V(8); PG8_WAIT_L(0); PG8_BAR; PG8_MMA(1, 0, At, B0); PG8_MMA(1, 1, At, B1); PG8_BAR; PG8_SCHED;
;             PG8_LDB(B0, 1, 0); PG8_LDB(B1, 1, 1); PG8_SCHED; PG8_LDA(At, 1, 0); PG8_STAGE(PG8_SA(0, 1), a2 + hstep, voffA);
;             PG8_WAIT_V(8); PG8_WAIT_L(0); PG8_BAR; PG8_MMA(0, 0, At, B0); PG8_MMA(0, 1, At, B1); PG8_BAR; PG8_SCHED;
;             PG8_LDA(At, 1, 1); PG8_STAGE(PG8_SB(1, 0), b3, voffB); PG8_STAGE(PG8_SB(1, 1), b3 + hstep, voffB); PG8_STAGE(PG8_SA(1, 0), a3, voffA);
;             PG8_WAIT_V(8); PG8_WAIT_L(0); PG8_BAR; PG8_MMA(1, 0, At, B0); PG8_MMA(1, 1, At, B1); PG8_BAR; PG8_SCHED;
.LBB0_1170:
	s_add_u32 s26, s10, s22
	s_addc_u32 s27, s11, s23
	s_add_u32 s26, s26, 0x100
	s_addc_u32 s27, s27, 0
	s_add_u32 s51, s18, s22
	s_addc_u32 s52, s19, s23
	s_add_i32 s53, 0, 0x10000
	s_cmpk_eq_i32 s22, 0x2b00
	s_cselect_b32 s31, s17, s27
	s_cselect_b32 s30, s16, s26
	s_cselect_b32 s27, s15, s52
	s_cselect_b32 s26, s14, s51
	s_add_i32 s51, 0, 0x14000
	v_add_u32_e32 v158, s53, v144
	v_add_u32_e32 v170, s51, v144
	ds_read_b128 v[146:149], v158
	ds_read_b128 v[150:153], v158 offset:1024
	ds_read_b128 v[154:157], v158 offset:2048
	ds_read_b128 v[158:161], v158 offset:3072
	ds_read_b128 v[162:165], v170
	ds_read_b128 v[166:169], v170 offset:1024
	ds_read_b128 v[176:179], v170 offset:2048
	ds_read_b128 v[180:183], v170 offset:3072
	v_lshl_add_u64 v[170:171], v[140:141], 0, s[22:23]
	s_add_i32 m0, s40, 0xc000
	ds_read_b128 v[184:187], v145
	ds_read_b128 v[188:191], v145 offset:1024
	ds_read_b128 v[198:201], v145 offset:2048
	ds_read_b128 v[202:205], v145 offset:3072
	ds_read_b128 v[206:209], v145 offset:4096
	ds_read_b128 v[210:213], v145 offset:5120
	ds_read_b128 v[214:217], v145 offset:6144
	ds_read_b128 v[218:221], v145 offset:7168
	global_load_lds_dwordx4 v[170:171], off
	s_add_i32 m0, s40, 0xe000
	v_lshl_add_u64 v[170:171], v[142:143], 0, s[22:23]
	global_load_lds_dwordx4 v[170:171], off
	s_waitcnt vmcnt(8)
	s_waitcnt lgkmcnt(0)
	s_barrier
	s_setprio 1
	s_waitcnt lgkmcnt(0)
	v_mfma_f32_16x16x32_bf16 v[118:121], v[146:149], v[184:187], v[118:121]
	v_mfma_f32_16x16x32_bf16 v[114:117], v[154:157], v[184:187], v[114:117]
	v_mfma_f32_16x16x32_bf16 v[134:137], v[146:149], v[198:201], v[134:137]
	v_mfma_f32_16x16x32_bf16 v[130:133], v[154:157], v[198:201], v[130:133]
	v_mfma_f32_16x16x32_bf16 v[94:97], v[146:149], v[206:209], v[94:97]
	v_mfma_f32_16x16x32_bf16 v[90:93], v[154:157], v[206:209], v[90:93]
	v_mfma_f32_16x16x32_bf16 v[78:81], v[146:149], v[214:217], v[78:81]
	v_mfma_f32_16x16x32_bf16 v[74:77], v[154:157], v[214:217], v[74:77]
	v_mfma_f32_16x16x32_bf16 v[118:121], v[150:153], v[188:191], v[118:121]
	v_mfma_f32_16x16x32_bf16 v[114:117], v[158:161], v[188:191], v[114:117]
	v_mfma_f32_16x16x32_bf16 v[134:137], v[150:153], v[202:205], v[134:137]
	v_mfma_f32_16x16x32_bf16 v[130:133], v[158:161], v[202:205], v[130:133]
	v_mfma_f32_16x16x32_bf16 v[94:97], v[150:153], v[210:213], v[94:97]
	v_mfma_f32_16x16x32_bf16 v[90:93], v[158:161], v[210:213], v[90:93]
	v_mfma_f32_16x16x32_bf16 v[78:81], v[150:153], v[218:221], v[78:81]
	v_mfma_f32_16x16x32_bf16 v[74:77], v[158:161], v[218:221], v[74:77]
	s_setprio 0
	s_setprio 1
	v_mfma_f32_16x16x32_bf16 v[102:105], v[162:165], v[184:187], v[102:105]
	v_mfma_f32_16x16x32_bf16 v[98:101], v[176:179], v[184:187], v[98:101]
	v_mfma_f32_16x16x32_bf16 v[110:113], v[162:165], v[198:201], v[110:113]
	v_mfma_f32_16x16x32_bf16 v[106:109], v[176:179], v[198:201], v[106:109]
	v_mfma_f32_16x16x32_bf16 v[86:89], v[162:165], v[206:209], v[86:89]
	v_mfma_f32_16x16x32_bf16 v[82:85], v[176:179], v[206:209], v[82:85]
	v_mfma_f32_16x16x32_bf16 v[70:73], v[162:165], v[214:217], v[70:73]
	v_mfma_f32_16x16x32_bf16 v[66:69], v[176:179], v[214:217], v[66:69]
	v_mfma_f32_16x16x32_bf16 v[102:105], v[166:169], v[188:191], v[102:105]
	v_mfma_f32_16x16x32_bf16 v[98:101], v[180:183], v[188:191], v[98:101]
	v_mfma_f32_16x16x32_bf16 v[110:113], v[166:169], v[202:205], v[110:113]
	v_mfma_f32_16x16x32_bf16 v[106:109], v[180:183], v[202:205], v[106:109]
	v_mfma_f32_16x16x32_bf16 v[86:89], v[166:169], v[210:213], v[86:89]
	v_mfma_f32_16x16x32_bf16 v[82:85], v[180:183], v[210:213], v[82:85]
	v_mfma_f32_16x16x32_bf16 v[70:73], v[166:169], v[218:221], v[70:73]
	v_mfma_f32_16x16x32_bf16 v[66:69], v[180:183], v[218:221], v[66:69]
	s_setprio 0
	s_barrier
	s_add_i32 s52, s53, s39
	v_lshl_add_u64 v[170:171], s[26:27], 0, v[32:33]
	s_mov_b32 m0, s52
	ds_read_b128 v[184:187], v145 offset:16384
	ds_read_b128 v[188:191], v145 offset:17408
	ds_read_b128 v[198:201], v145 offset:18432
	ds_read_b128 v[202:205], v145 offset:19456
	ds_read_b128 v[206:209], v145 offset:20480
	ds_read_b128 v[210:213], v145 offset:21504
	ds_read_b128 v[214:217], v145 offset:22528
	ds_read_b128 v[218:221], v145 offset:23552
	global_load_lds_dwordx4 v[170:171], off
	s_add_i32 m0, s52, 0x2000
	s_add_u32 s52, s26, 0x160000
	v_lshl_add_u64 v[192:193], s[26:27], 0, v[122:123]
	s_addc_u32 s53, s27, 0
	s_add_i32 s51, s51, s39
	global_load_lds_dwordx4 v[192:193], off
	v_lshl_add_u64 v[222:223], s[52:53], 0, v[32:33]
	s_mov_b32 m0, s51
	v_lshl_add_u64 v[224:225], s[30:31], 0, v[124:125]
	global_load_lds_dwordx4 v[222:223], off
	s_add_i32 m0, s51, 0x2000
	v_lshl_add_u64 v[222:223], s[52:53], 0, v[122:123]
	global_load_lds_dwordx4 v[222:223], off
	s_mov_b32 m0, s40
	v_lshl_add_u64 v[222:223], s[30:31], 0, v[126:127]
	global_load_lds_dwordx4 v[222:223], off
	s_mov_b32 m0, s41
	s_nop 0
	global_load_lds_dwordx4 v[224:225], off
	s_waitcnt vmcnt(8)
	s_waitcnt lgkmcnt(0)
	s_barrier
; #define PG8_STAGE(bufoff, gbase, voff) do { _Pragma("unroll") for (int _i = 0; _i < 2; ++_i) \
;         __builtin_amdgcn_global_load_lds((const unsigned*)((const char*)(gbase) + (voff)[_i]), (PG8_LAS unsigned*)(lds + (bufoff) + ldsw + _i * 8192), 16, 0, 0); } while (0)
; #define PG8_LDA(dst, b, h) do { _Pragma("unroll") for (int m = 0; m < 4; ++m) _Pragma("unroll") for (int k = 0; k < 2; ++k) dst[m][k] = *(const PG8_LAS bf16x8*)(lds + PG8_SA(b, h) + aoff + m * 2048 + k * 1024); } while (0)
; #define PG8_LDB(dst, b, h) do { _Pragma("unroll") for (int n = 0; n < 2; ++n) _Pragma("unroll") for (int k = 0; k < 2; ++k) dst[n][k] = *(const PG8_LAS bf16x8*)(lds + PG8_SB(b, h) + boff + n * 2048 + k * 1024); } while (0)
; #define PG8_MMA(ai, bj, At, Bt) do { __builtin_amdgcn_s_setprio(1); _Pragma("unroll") for (int m = 0; m < 4; ++m) _Pragma("unroll") for (int n = 0; n < 2; ++n) _Pragma("unroll") for (int k = 0; k < 2; ++k) \
;         acc[ai][bj][m][n] = __builtin_amdgcn_mfma_f32_16x16x32_bf16(Bt[n][k], At[m][k], acc[ai][bj][m][n], 0, 0, 0); __builtin_amdgcn_s_setprio(0); } while (0)
; template <class Epi, class Sched, bool ALIGN_EPI = false, bool SP2 = false, bool KHOOK = false>
; __device__ __forceinline__ void gemm_phase(PG8_LAS unsigned char* lds, const Gemm g, const Sched& S, const Epi& E, const int tid_in) {
;     ...
;             PG8_LDB(B0, 0, 0); PG8_LDB(B1, 0, 1); PG8_SCHED; PG8_LDA(At, 0, 0); PG8_STAGE(PG8_SA(1, 1), a1 + hstep, voffA);
;             PG8_WAIT_V(8); PG8_WAIT_L(0); PG8_BAR; PG8_MMA(0, 0, At, B0); PG8_MMA(0, 1, At, B1); PG8_BAR; PG8_SCHED;
;             PG8_LDA(At, 0, 1); PG8_STAGE(PG8_SB(0, 0), b2, voffB); PG8_STAGE(PG8_SB(0, 1), b2 + hstep, voffB); PG8_STAGE(PG8_SA(0, 0), a2, voffA);
;             PG8_WAIT_V(8); PG8_WAIT_L(0); PG8_BAR; PG8_MMA(1, 0, At, B0); PG8_MMA(1, 1, At, B1); PG8_BAR; PG8_SCHED;
;             PG8_LDB(B0, 1, 0); PG8_LDB(B1, 1, 1); PG8_SCHED; PG8_LDA(At, 1, 0); PG8_STAGE(PG8_SA(0, 1), a2 + hstep, voffA);
;             PG8_WAIT_V(8); PG8_WAIT_L(0); PG8_BAR; PG8_MMA(0, 0, At, B0); PG8_MMA(0, 1, At, B1); PG8_BAR; PG8_SCHED;
;             PG8_LDA(At, 1, 1); PG8_STAGE(PG8_SB(1, 0), b3, voffB); PG8_STAGE(PG8_SB(1, 1), b3 + hstep, voffB); PG8_STAGE(PG8_SA(1, 0), a3, voffA);
;             PG8_WAIT_V(8); PG8_WAIT_L(0); PG8_BAR; PG8_MMA(1, 0, At, B0); PG8_MMA(1, 1, At, B1); PG8_BAR; PG8_SCHED;
	s_setprio 1
	s_waitcnt lgkmcnt(0)
	v_mfma_f32_16x16x32_bf16 v[62:65], v[146:149], v[184:187], v[62:65]
	v_mfma_f32_16x16x32_bf16 v[58:61], v[154:157], v[184:187], v[58:61]
	v_mfma_f32_16x16x32_bf16 v[46:49], v[146:149], v[198:201], v[46:49]
	v_mfma_f32_16x16x32_bf16 v[42:45], v[154:157], v[198:201], v[42:45]
	v_mfma_f32_16x16x32_bf16 v[28:31], v[146:149], v[206:209], v[28:31]
	v_mfma_f32_16x16x32_bf16 v[24:27], v[154:157], v[206:209], v[24:27]
	v_mfma_f32_16x16x32_bf16 v[12:15], v[146:149], v[214:217], v[12:15]
	v_mfma_f32_16x16x32_bf16 v[8:11], v[154:157], v[214:217], v[8:11]
	v_mfma_f32_16x16x32_bf16 v[62:65], v[150:153], v[188:191], v[62:65]
	v_mfma_f32_16x16x32_bf16 v[58:61], v[158:161], v[188:191], v[58:61]
	v_mfma_f32_16x16x32_bf16 v[46:49], v[150:153], v[202:205], v[46:49]
	v_mfma_f32_16x16x32_bf16 v[42:45], v[158:161], v[202:205], v[42:45]
	v_mfma_f32_16x16x32_bf16 v[28:31], v[150:153], v[210:213], v[28:31]
	v_mfma_f32_16x16x32_bf16 v[24:27], v[158:161], v[210:213], v[24:27]
	v_mfma_f32_16x16x32_bf16 v[12:15], v[150:153], v[218:221], v[12:15]
	v_mfma_f32_16x16x32_bf16 v[8:11], v[158:161], v[218:221], v[8:11]
	s_setprio 0
	s_setprio 1
	v_mfma_f32_16x16x32_bf16 v[54:57], v[162:165], v[184:187], v[54:57]
	v_mfma_f32_16x16x32_bf16 v[50:53], v[176:179], v[184:187], v[50:53]
	v_mfma_f32_16x16x32_bf16 v[38:41], v[162:165], v[198:201], v[38:41]
	v_mfma_f32_16x16x32_bf16 v[34:37], v[176:179], v[198:201], v[34:37]
	v_mfma_f32_16x16x32_bf16 v[20:23], v[162:165], v[206:209], v[20:23]
	v_mfma_f32_16x16x32_bf16 v[16:19], v[176:179], v[206:209], v[16:19]
	v_mfma_f32_16x16x32_bf16 v[4:7], v[162:165], v[214:217], v[4:7]
	v_mfma_f32_16x16x32_bf16 v[0:3], v[176:179], v[214:217], v[0:3]
	v_mfma_f32_16x16x32_bf16 v[54:57], v[166:169], v[188:191], v[54:57]
	v_mfma_f32_16x16x32_bf16 v[50:53], v[180:183], v[188:191], v[50:53]
	v_mfma_f32_16x16x32_bf16 v[38:41], v[166:169], v[202:205], v[38:41]
	v_mfma_f32_16x16x32_bf16 v[34:37], v[180:183], v[202:205], v[34:37]
	v_mfma_f32_16x16x32_bf16 v[20:23], v[166:169], v[210:213], v[20:23]
	v_mfma_f32_16x16x32_bf16 v[16:19], v[180:183], v[210:213], v[16:19]
	v_mfma_f32_16x16x32_bf16 v[4:7], v[166:169], v[218:221], v[4:7]
	v_mfma_f32_16x16x32_bf16 v[0:3], v[180:183], v[218:221], v[0:3]
	s_setprio 0
	s_barrier
	s_add_i32 s51, 0, 0x18000
	s_add_i32 s52, 0, 0x1c000
	v_add_u32_e32 v158, s51, v144
	v_add_u32_e32 v175, s52, v144
	ds_read_b128 v[146:149], v158
	ds_read_b128 v[150:153], v158 offset:1024
	ds_read_b128 v[154:157], v158 offset:2048
	ds_read_b128 v[158:161], v158 offset:3072
	ds_read_b128 v[162:165], v175
	ds_read_b128 v[166:169], v175 offset:1024
	ds_read_b128 v[176:179], v175 offset:2048
	ds_read_b128 v[180:183], v175 offset:3072
	s_add_u32 s30, s30, 0x160000
	s_addc_u32 s31, s31, 0
	s_mov_b32 m0, s42
	v_lshl_add_u64 v[226:227], s[30:31], 0, v[126:127]
	ds_read_b128 v[184:187], v145 offset:32768
	ds_read_b128 v[188:191], v145 offset:33792
	ds_read_b128 v[198:201], v145 offset:34816
	ds_read_b128 v[202:205], v145 offset:35840
	ds_read_b128 v[206:209], v145 offset:36864
	ds_read_b128 v[210:213], v145 offset:37888
	ds_read_b128 v[214:217], v145 offset:38912
	ds_read_b128 v[218:221], v145 offset:39936
	global_load_lds_dwordx4 v[226:227], off
	s_mov_b32 m0, s44
	v_lshl_add_u64 v[226:227], s[30:31], 0, v[124:125]
	global_load_lds_dwordx4 v[226:227], off
	s_waitcnt vmcnt(8)
	s_waitcnt lgkmcnt(0)
	s_barrier
	s_setprio 1
	s_waitcnt lgkmcnt(0)
	v_mfma_f32_16x16x32_bf16 v[118:121], v[146:149], v[184:187], v[118:121]
	v_mfma_f32_16x16x32_bf16 v[114:117], v[154:157], v[184:187], v[114:117]
	v_mfma_f32_16x16x32_bf16 v[134:137], v[146:149], v[198:201], v[134:137]
	v_mfma_f32_16x16x32_bf16 v[130:133], v[154:157], v[198:201], v[130:133]
	v_mfma_f32_16x16x32_bf16 v[94:97], v[146:149], v[206:209], v[94:97]
	v_mfma_f32_16x16x32_bf16 v[90:93], v[154:157], v[206:209], v[90:93]
	v_mfma_f32_16x16x32_bf16 v[78:81], v[146:149], v[214:217], v[78:81]
	v_mfma_f32_16x16x32_bf16 v[74:77], v[154:157], v[214:217], v[74:77]
	v_mfma_f32_16x16x32_bf16 v[118:121], v[150:153], v[188:191], v[118:121]
	v_mfma_f32_16x16x32_bf16 v[114:117], v[158:161], v[188:191], v[114:117]
	v_mfma_f32_16x16x32_bf16 v[134:137], v[150:153], v[202:205], v[134:137]
	v_mfma_f32_16x16x32_bf16 v[130:133], v[158:161], v[202:205], v[130:133]
	v_mfma_f32_16x16x32_bf16 v[94:97], v[150:153], v[210:213], v[94:97]
	v_mfma_f32_16x16x32_bf16 v[90:93], v[158:161], v[210:213], v[90:93]
	v_mfma_f32_16x16x32_bf16 v[78:81], v[150:153], v[218:221], v[78:81]
	v_mfma_f32_16x16x32_bf16 v[74:77], v[158:161], v[218:221], v[74:77]
	s_setprio 0
	s_setprio 1
	v_mfma_f32_16x16x32_bf16 v[102:105], v[162:165], v[184:187], v[102:105]
	v_mfma_f32_16x16x32_bf16 v[98:101], v[176:179], v[184:187], v[98:101]
	v_mfma_f32_16x16x32_bf16 v[110:113], v[162:165], v[198:201], v[110:113]
	v_mfma_f32_16x16x32_bf16 v[106:109], v[176:179], v[198:201], v[106:109]
	v_mfma_f32_16x16x32_bf16 v[86:89], v[162:165], v[206:209], v[86:89]
	v_mfma_f32_16x16x32_bf16 v[82:85], v[176:179], v[206:209], v[82:85]
	v_mfma_f32_16x16x32_bf16 v[70:73], v[162:165], v[214:217], v[70:73]
	v_mfma_f32_16x16x32_bf16 v[66:69], v[176:179], v[214:217], v[66:69]
	v_mfma_f32_16x16x32_bf16 v[102:105], v[166:169], v[188:191], v[102:105]
	v_mfma_f32_16x16x32_bf16 v[98:101], v[180:183], v[188:191], v[98:101]
	v_mfma_f32_16x16x32_bf16 v[110:113], v[166:169], v[202:205], v[110:113]
	v_mfma_f32_16x16x32_bf16 v[106:109], v[180:183], v[202:205], v[106:109]
	v_mfma_f32_16x16x32_bf16 v[86:89], v[166:169], v[210:213], v[86:89]
	v_mfma_f32_16x16x32_bf16 v[82:85], v[180:183], v[210:213], v[82:85]
	v_mfma_f32_16x16x32_bf16 v[70:73], v[166:169], v[218:221], v[70:73]
	v_mfma_f32_16x16x32_bf16 v[66:69], v[180:183], v[218:221], v[66:69]
	s_setprio 0
	s_barrier
; #define PG8_STAGE(bufoff, gbase, voff) do { _Pragma("unroll") for (int _i = 0; _i < 2; ++_i) \
;         __builtin_amdgcn_global_load_lds((const unsigned*)((const char*)(gbase) + (voff)[_i]), (PG8_LAS unsigned*)(lds + (bufoff) + ldsw + _i * 8192), 16, 0, 0); } while (0)
; #define PG8_LDA(dst, b, h) do { _Pragma("unroll") for (int m = 0; m < 4; ++m) _Pragma("unroll") for (int k = 0; k < 2; ++k) dst[m][k] = *(const PG8_LAS bf16x8*)(lds + PG8_SA(b, h) + aoff + m * 2048 + k * 1024); } while (0)
; #define PG8_LDB(dst, b, h) do { _Pragma("unroll") for (int n = 0; n < 2; ++n) _Pragma("unroll") for (int k = 0; k < 2; ++k) dst[n][k] = *(const PG8_LAS bf16x8*)(lds + PG8_SB(b, h) + boff + n * 2048 + k * 1024); } while (0)
; #define PG8_BAR __builtin_amdgcn_s_barrier()
; template <class Epi, class Sched, bool ALIGN_EPI = false, bool SP2 = false, bool KHOOK = false>
; __device__ __forceinline__ void gemm_phase(PG8_LAS unsigned char* lds, const Gemm g, const Sched& S, const Epi& E, const int tid_in) {
;     ...
;             PG8_LDB(B0, 0, 0); PG8_LDB(B1, 0, 1); PG8_SCHED; PG8_LDA(At, 0, 0); PG8_STAGE(PG8_SA(1, 1), a1 + hstep, voffA);
;             PG8_WAIT_V(8); PG8_WAIT_L(0); PG8_BAR; PG8_MMA(0, 0, At, B0); PG8_MMA(0, 1, At, B1); PG8_BAR; PG8_SCHED;
;             PG8_LDA(At, 0, 1); PG8_STAGE(PG8_SB(0, 0), b2, voffB); PG8_STAGE(PG8_SB(0, 1), b2 + hstep, voffB); PG8_STAGE(PG8_SA(0, 0), a2, voffA);
;             PG8_WAIT_V(8); PG8_WAIT_L(0); PG8_BAR; PG8_MMA(1, 0, At, B0); PG8_MMA(1, 1, At, B1); PG8_BAR; PG8_SCHED;
;             PG8_LDB(B0, 1, 0); PG8_LDB(B1, 1, 1); PG8_SCHED; PG8_LDA(At, 1, 0); PG8_STAGE(PG8_SA(0, 1), a2 + hstep, voffA);
;             PG8_WAIT_V(8); PG8_WAIT_L(0); PG8_BAR; PG8_MMA(0, 0, At, B0); PG8_MMA(0, 1, At, B1); PG8_BAR; PG8_SCHED;
;             PG8_LDA(At, 1, 1); PG8_STAGE(PG8_SB(1, 0), b3, voffB); PG8_STAGE(PG8_SB(1, 1), b3 + hstep, voffB); PG8_STAGE(PG8_SA(1, 0), a3, voffA);
;             PG8_WAIT_V(8); PG8_WAIT_L(0); PG8_BAR; PG8_MMA(1, 0, At, B0); PG8_MMA(1, 1, At, B1); PG8_BAR; PG8_SCHED;
;     ...
; #pragma unroll
;         for (int a = 0; a < 2; ++a)
; #pragma unroll
;             for (int b = 0; b < 2; ++b)
; #pragma unroll
;                 for (int m = 0; m < 4; ++m)
; #pragma unroll
;                     for (int n = 0; n < 2; ++n) acc[a][b][m][n] = (f32x4){0.f, 0.f, 0.f, 0.f};
;         cur = nxt; cA = nA; cB = nB; ++ui; load_rr(cur);
	s_add_i32 s30, s51, s39
	v_lshl_add_u64 v[170:171], v[170:171], 0, s[90:91]
	s_mov_b32 m0, s30
	ds_read_b128 v[184:187], v145 offset:49152
	ds_read_b128 v[188:191], v145 offset:50176
	ds_read_b128 v[198:201], v145 offset:51200
	ds_read_b128 v[202:205], v145 offset:52224
	ds_read_b128 v[206:209], v145 offset:53248
	ds_read_b128 v[210:213], v145 offset:54272
	ds_read_b128 v[214:217], v145 offset:55296
	ds_read_b128 v[218:221], v145 offset:56320
	global_load_lds_dwordx4 v[170:171], off
	s_add_i32 m0, s30, 0x2000
	s_add_u32 s26, s26, 0x160080
	v_lshl_add_u64 v[170:171], v[192:193], 0, s[90:91]
	s_addc_u32 s27, s27, 0
	s_add_i32 s30, s52, s39
	global_load_lds_dwordx4 v[170:171], off
	s_mov_b32 m0, s30
	v_lshl_add_u64 v[170:171], s[26:27], 0, v[32:33]
	global_load_lds_dwordx4 v[170:171], off
	s_add_i32 m0, s30, 0x2000
	v_lshl_add_u64 v[170:171], s[26:27], 0, v[122:123]
	global_load_lds_dwordx4 v[170:171], off
	s_mov_b32 m0, s46
	v_lshl_add_u64 v[170:171], v[222:223], 0, s[90:91]
	global_load_lds_dwordx4 v[170:171], off
	s_mov_b32 m0, s47
	v_lshl_add_u64 v[170:171], v[224:225], 0, s[90:91]
	global_load_lds_dwordx4 v[170:171], off
	s_waitcnt vmcnt(8)
	s_waitcnt lgkmcnt(0)
	s_barrier
	s_setprio 1
	s_waitcnt lgkmcnt(0)
	v_mfma_f32_16x16x32_bf16 v[62:65], v[146:149], v[184:187], v[62:65]
	v_mfma_f32_16x16x32_bf16 v[58:61], v[154:157], v[184:187], v[58:61]
	v_mfma_f32_16x16x32_bf16 v[46:49], v[146:149], v[198:201], v[46:49]
	v_mfma_f32_16x16x32_bf16 v[42:45], v[154:157], v[198:201], v[42:45]
	v_mfma_f32_16x16x32_bf16 v[28:31], v[146:149], v[206:209], v[28:31]
	v_mfma_f32_16x16x32_bf16 v[24:27], v[154:157], v[206:209], v[24:27]
	v_mfma_f32_16x16x32_bf16 v[12:15], v[146:149], v[214:217], v[12:15]
	v_mfma_f32_16x16x32_bf16 v[8:11], v[154:157], v[214:217], v[8:11]
	v_mfma_f32_16x16x32_bf16 v[62:65], v[150:153], v[188:191], v[62:65]
	v_mfma_f32_16x16x32_bf16 v[58:61], v[158:161], v[188:191], v[58:61]
	v_mfma_f32_16x16x32_bf16 v[46:49], v[150:153], v[202:205], v[46:49]
	v_mfma_f32_16x16x32_bf16 v[42:45], v[158:161], v[202:205], v[42:45]
	v_mfma_f32_16x16x32_bf16 v[28:31], v[150:153], v[210:213], v[28:31]
	v_mfma_f32_16x16x32_bf16 v[24:27], v[158:161], v[210:213], v[24:27]
	v_mfma_f32_16x16x32_bf16 v[12:15], v[150:153], v[218:221], v[12:15]
	v_mfma_f32_16x16x32_bf16 v[8:11], v[158:161], v[218:221], v[8:11]
	s_setprio 0
	s_setprio 1
	v_mfma_f32_16x16x32_bf16 v[54:57], v[162:165], v[184:187], v[54:57]
	v_mfma_f32_16x16x32_bf16 v[50:53], v[176:179], v[184:187], v[50:53]
	v_mfma_f32_16x16x32_bf16 v[38:41], v[162:165], v[198:201], v[38:41]
	v_mfma_f32_16x16x32_bf16 v[34:37], v[176:179], v[198:201], v[34:37]
	v_mfma_f32_16x16x32_bf16 v[20:23], v[162:165], v[206:209], v[20:23]
	v_mfma_f32_16x16x32_bf16 v[16:19], v[176:179], v[206:209], v[16:19]
	v_mfma_f32_16x16x32_bf16 v[4:7], v[162:165], v[214:217], v[4:7]
	v_mfma_f32_16x16x32_bf16 v[0:3], v[176:179], v[214:217], v[0:3]
	v_mfma_f32_16x16x32_bf16 v[54:57], v[166:169], v[188:191], v[54:57]
	v_mfma_f32_16x16x32_bf16 v[50:53], v[180:183], v[188:191], v[50:53]
	v_mfma_f32_16x16x32_bf16 v[38:41], v[166:169], v[202:205], v[38:41]
	v_mfma_f32_16x16x32_bf16 v[34:37], v[180:183], v[202:205], v[34:37]
	v_mfma_f32_16x16x32_bf16 v[20:23], v[166:169], v[210:213], v[20:23]
	v_mfma_f32_16x16x32_bf16 v[16:19], v[180:183], v[210:213], v[16:19]
	v_mfma_f32_16x16x32_bf16 v[4:7], v[166:169], v[218:221], v[4:7]
	v_mfma_f32_16x16x32_bf16 v[0:3], v[180:183], v[218:221], v[0:3]
	s_setprio 0
	s_barrier
	s_add_i32 s25, s25, 2
	s_add_u32 s22, s22, 0x100
	s_addc_u32 s23, s23, 0
	s_cmpk_gt_u32 s25, 0x55
	s_cbranch_scc0 .LBB0_1170
	s_add_u32 s18, s18, 0xffffff00
	s_addc_u32 s19, s19, -1
	s_and_b64 vcc, exec, s[4:5]
	s_cbranch_vccnz .LBB0_1173
	v_mov_b32_e32 v0, 0
	s_mov_b32 s33, s50
	s_mov_b32 s0, s49
	s_mov_b64 s[10:11], s[16:17]
	s_mov_b32 s48, s24
	v_mov_b32_e32 v1, v0
	v_mov_b32_e32 v2, v0
	v_mov_b32_e32 v3, v0
	v_mov_b32_e32 v4, v0
	v_mov_b32_e32 v5, v0
	v_mov_b32_e32 v6, v0
	v_mov_b32_e32 v7, v0
	v_mov_b32_e32 v16, v0
	v_mov_b32_e32 v17, v0
	v_mov_b32_e32 v18, v0
	v_mov_b32_e32 v19, v0
	v_mov_b32_e32 v20, v0
	v_mov_b32_e32 v21, v0
	v_mov_b32_e32 v22, v0
	v_mov_b32_e32 v23, v0
	v_mov_b32_e32 v34, v0
	v_mov_b32_e32 v35, v0
	v_mov_b32_e32 v36, v0
	v_mov_b32_e32 v37, v0
	v_mov_b32_e32 v38, v0
	v_mov_b32_e32 v39, v0
	v_mov_b32_e32 v40, v0
	v_mov_b32_e32 v41, v0
	v_mov_b32_e32 v50, v0
	v_mov_b32_e32 v51, v0
	v_mov_b32_e32 v52, v0
	v_mov_b32_e32 v53, v0
	v_mov_b32_e32 v54, v0
	v_mov_b32_e32 v55, v0
	v_mov_b32_e32 v56, v0
	v_mov_b32_e32 v57, v0
	v_mov_b32_e32 v8, v0
	v_mov_b32_e32 v9, v0
	v_mov_b32_e32 v10, v0
	v_mov_b32_e32 v11, v0
	v_mov_b32_e32 v12, v0
	v_mov_b32_e32 v13, v0
	v_mov_b32_e32 v14, v0
	v_mov_b32_e32 v15, v0
	v_mov_b32_e32 v24, v0
	v_mov_b32_e32 v25, v0
	v_mov_b32_e32 v26, v0
	v_mov_b32_e32 v27, v0
	v_mov_b32_e32 v28, v0
	v_mov_b32_e32 v29, v0
	v_mov_b32_e32 v30, v0
	v_mov_b32_e32 v31, v0
	v_mov_b32_e32 v42, v0
	v_mov_b32_e32 v43, v0
	v_mov_b32_e32 v44, v0
	v_mov_b32_e32 v45, v0
	v_mov_b32_e32 v46, v0
	v_mov_b32_e32 v47, v0
	v_mov_b32_e32 v48, v0
	v_mov_b32_e32 v49, v0
	v_mov_b32_e32 v58, v0
	v_mov_b32_e32 v59, v0
	v_mov_b32_e32 v60, v0
	v_mov_b32_e32 v61, v0
	v_mov_b32_e32 v62, v0
	v_mov_b32_e32 v63, v0
	v_mov_b32_e32 v64, v0
	v_mov_b32_e32 v65, v0
	v_mov_b32_e32 v66, v0
	v_mov_b32_e32 v67, v0
	v_mov_b32_e32 v68, v0
	v_mov_b32_e32 v69, v0
	v_mov_b32_e32 v70, v0
	v_mov_b32_e32 v71, v0
	v_mov_b32_e32 v72, v0
	v_mov_b32_e32 v73, v0
	v_mov_b32_e32 v82, v0
	v_mov_b32_e32 v83, v0
	v_mov_b32_e32 v84, v0
	v_mov_b32_e32 v85, v0
	v_mov_b32_e32 v86, v0
	v_mov_b32_e32 v87, v0
	v_mov_b32_e32 v88, v0
	v_mov_b32_e32 v89, v0
	v_mov_b32_e32 v106, v0
	v_mov_b32_e32 v107, v0
	v_mov_b32_e32 v108, v0
	v_mov_b32_e32 v109, v0
	v_mov_b32_e32 v110, v0
	v_mov_b32_e32 v111, v0
	v_mov_b32_e32 v112, v0
	v_mov_b32_e32 v113, v0
	v_mov_b32_e32 v98, v0
	v_mov_b32_e32 v99, v0
	v_mov_b32_e32 v100, v0
	v_mov_b32_e32 v101, v0
	v_mov_b32_e32 v102, v0
	v_mov_b32_e32 v103, v0
	v_mov_b32_e32 v104, v0
	v_mov_b32_e32 v105, v0
	v_mov_b32_e32 v74, v0
	v_mov_b32_e32 v75, v0
	v_mov_b32_e32 v76, v0
	v_mov_b32_e32 v77, v0
	v_mov_b32_e32 v78, v0
	v_mov_b32_e32 v79, v0
	v_mov_b32_e32 v80, v0
	v_mov_b32_e32 v81, v0
	v_mov_b32_e32 v90, v0
	v_mov_b32_e32 v91, v0
	v_mov_b32_e32 v92, v0
	v_mov_b32_e32 v93, v0
	v_mov_b32_e32 v94, v0
	v_mov_b32_e32 v95, v0
	v_mov_b32_e32 v96, v0
	v_mov_b32_e32 v97, v0
	v_mov_b32_e32 v130, v0
	v_mov_b32_e32 v131, v0
	v_mov_b32_e32 v132, v0
	v_mov_b32_e32 v133, v0
	v_mov_b32_e32 v134, v0
	v_mov_b32_e32 v135, v0
	v_mov_b32_e32 v136, v0
	v_mov_b32_e32 v137, v0
	v_mov_b32_e32 v114, v0
	v_mov_b32_e32 v115, v0
	v_mov_b32_e32 v116, v0
	v_mov_b32_e32 v117, v0
	v_mov_b32_e32 v118, v0
	v_mov_b32_e32 v119, v0
	v_mov_b32_e32 v120, v0
	v_mov_b32_e32 v121, v0
	s_andn2_b64 vcc, exec, s[12:13]
	s_cbranch_vccnz .LBB0_1174
	s_branch .LBB0_1175

; #define PG8_STAGE(bufoff, gbase, voff) do { _Pragma("unroll") for (int _i = 0; _i < 2; ++_i) \
;         __builtin_amdgcn_global_load_lds((const unsigned*)((const char*)(gbase) + (voff)[_i]), (PG8_LAS unsigned*)(lds + (bufoff) + ldsw + _i * 8192), 16, 0, 0); } while (0)
; #define PG8_LDA(dst, b, h) do { _Pragma("unroll") for (int m = 0; m < 4; ++m) _Pragma("unroll") for (int k = 0; k < 2; ++k) dst[m][k] = *(const PG8_LAS bf16x8*)(lds + PG8_SA(b, h) + aoff + m * 2048 + k * 1024); } while (0)
; #define PG8_WAIT_V(n) asm volatile("s_waitcnt vmcnt(" #n ")" ::: "memory")
; #define PG8_WAIT_L(n) asm volatile("s_waitcnt lgkmcnt(" #n ")" ::: "memory")
; template <class Epi, class Sched, bool ALIGN_EPI = false, bool SP2 = false, bool KHOOK = false>
; __device__ __forceinline__ void gemm_phase(PG8_LAS unsigned char* lds, const Gemm g, const Sched& S, const Epi& E, const int tid_in) {
;     ...
;         for (int t = 0; t < nt; t += 2) {
;             const bool last = (t == nt - 2);
;             const char* a1 = cA + (size_t)(t + 1) * kstep;
;             const char* a2 = last ? nA : cA + (size_t)(t + 2) * kstep; const char* b2 = last ? nB : cB + (size_t)(t + 2) * kstep;
;             const char* a3 = a2 + kstep; const char* b3 = b2 + kstep;
;             if (last && has_next) S.a_ready(nxt);
;             if constexpr (SP2) {
;             PG8_LDB(B0, 0, 0); PG8_LDB(B1, 0, 1); PG8_SCHED; PG8_LDA(At, 0, 0); PG8_STAGE(PG8_SA(1, 1), a1 + hstep, voffA);
;             PG8_WAIT_V(8); PG8_WAIT_L(0); PG8_BAR; PG8_MMA(0, 0, At, B0); PG8_MMA(0, 1, At, B1); PG8_BAR; PG8_SCHED;
;             PG8_LDA(At, 0, 1); PG8_STAGE(PG8_SB(0, 0), b2, voffB); PG8_STAGE(PG8_SB(0, 1), b2 + hstep, voffB); PG8_STAGE(PG8_SA(0, 0), a2, voffA);
;             PG8_WAIT_V(8); PG8_WAIT_L(0); PG8_BAR; PG8_MMA(1, 0, At, B0); PG8_MMA(1, 1, At, B1); PG8_BAR; PG8_SCHED;
;             PG8_LDB(B0, 1, 0); PG8_LDB(B1, 1, 1); PG8_SCHED; PG8_LDA(At, 1, 0); PG8_STAGE(PG8_SA(0, 1), a2 + hstep, voffA);
;             PG8_WAIT_V(8); PG8_WAIT_L(0); PG8_BAR; PG8_MMA(0, 0, At, B0); PG8_MMA(0, 1, At, B1); PG8_BAR; PG8_SCHED;
;             PG8_LDA(At, 1, 1); PG8_STAGE(PG8_SB(1, 0), b3, voffB); PG8_STAGE(PG8_SB(1, 1), b3 + hstep, voffB); PG8_STAGE(PG8_SA(1, 0), a3, voffA);
;             PG8_WAIT_V(8); PG8_WAIT_L(0); PG8_BAR; PG8_MMA(1, 0, At, B0); PG8_MMA(1, 1, At, B1); PG8_BAR; PG8_SCHED;
.LBB0_1287:
	s_add_u32 s30, s4, s16
	s_addc_u32 s31, s5, s17
	s_add_u32 s30, s30, 0x100
	s_addc_u32 s31, s31, 0
	s_add_u32 s53, s25, s16
	s_addc_u32 s56, s47, s17
	s_add_i32 s57, 0, 0x10000
	s_cmpk_eq_i32 s16, 0xf00
	s_cselect_b32 s49, s11, s31
	s_cselect_b32 s48, s50, s30
	s_cselect_b32 s31, s9, s56
	s_cselect_b32 s30, s51, s53
	s_add_i32 s53, 0, 0x14000
	v_add_u32_e32 v158, s57, v144
	v_add_u32_e32 v174, s53, v144
	ds_read_b128 v[146:149], v158
	ds_read_b128 v[150:153], v158 offset:1024
	ds_read_b128 v[154:157], v158 offset:2048
	ds_read_b128 v[158:161], v158 offset:3072
	ds_read_b128 v[162:165], v174
	ds_read_b128 v[166:169], v174 offset:1024
	ds_read_b128 v[170:173], v174 offset:2048
	ds_read_b128 v[174:177], v174 offset:3072
	v_lshl_add_u64 v[218:219], v[140:141], 0, s[16:17]
	s_add_i32 m0, s38, 0xc000
	ds_read_b128 v[178:181], v145
	ds_read_b128 v[182:185], v145 offset:1024
	ds_read_b128 v[186:189], v145 offset:2048
	ds_read_b128 v[190:193], v145 offset:3072
	ds_read_b128 v[198:201], v145 offset:4096
	ds_read_b128 v[202:205], v145 offset:5120
	ds_read_b128 v[206:209], v145 offset:6144
	ds_read_b128 v[210:213], v145 offset:7168
	global_load_lds_dwordx4 v[218:219], off
	s_add_i32 m0, s38, 0xe000
	v_lshl_add_u64 v[218:219], v[142:143], 0, s[16:17]
	global_load_lds_dwordx4 v[218:219], off
	s_waitcnt vmcnt(8)
	s_waitcnt lgkmcnt(0)
	s_barrier
	s_setprio 1
	s_waitcnt lgkmcnt(0)
	v_mfma_f32_16x16x32_bf16 v[54:57], v[146:149], v[178:181], v[54:57]
	v_mfma_f32_16x16x32_bf16 v[62:65], v[154:157], v[178:181], v[62:65]
	v_mfma_f32_16x16x32_bf16 v[82:85], v[146:149], v[186:189], v[82:85]
	v_mfma_f32_16x16x32_bf16 v[86:89], v[154:157], v[186:189], v[86:89]
	v_mfma_f32_16x16x32_bf16 v[106:109], v[146:149], v[198:201], v[106:109]
	v_mfma_f32_16x16x32_bf16 v[110:113], v[154:157], v[198:201], v[110:113]
	v_mfma_f32_16x16x32_bf16 v[126:129], v[146:149], v[206:209], v[126:129]
	v_mfma_f32_16x16x32_bf16 v[122:125], v[154:157], v[206:209], v[122:125]
	v_mfma_f32_16x16x32_bf16 v[54:57], v[150:153], v[182:185], v[54:57]
	v_mfma_f32_16x16x32_bf16 v[62:65], v[158:161], v[182:185], v[62:65]
	v_mfma_f32_16x16x32_bf16 v[82:85], v[150:153], v[190:193], v[82:85]
	v_mfma_f32_16x16x32_bf16 v[86:89], v[158:161], v[190:193], v[86:89]
	v_mfma_f32_16x16x32_bf16 v[106:109], v[150:153], v[202:205], v[106:109]
	v_mfma_f32_16x16x32_bf16 v[110:113], v[158:161], v[202:205], v[110:113]
	v_mfma_f32_16x16x32_bf16 v[126:129], v[150:153], v[210:213], v[126:129]
	v_mfma_f32_16x16x32_bf16 v[122:125], v[158:161], v[210:213], v[122:125]
	s_setprio 0
	s_setprio 1
	v_mfma_f32_16x16x32_bf16 v[70:73], v[162:165], v[178:181], v[70:73]
	v_mfma_f32_16x16x32_bf16 v[78:81], v[170:173], v[178:181], v[78:81]
	v_mfma_f32_16x16x32_bf16 v[90:93], v[162:165], v[186:189], v[90:93]
	v_mfma_f32_16x16x32_bf16 v[98:101], v[170:173], v[186:189], v[98:101]
	v_mfma_f32_16x16x32_bf16 v[114:117], v[162:165], v[198:201], v[114:117]
	v_mfma_f32_16x16x32_bf16 v[118:121], v[170:173], v[198:201], v[118:121]
	v_mfma_f32_16x16x32_bf16 v[102:105], v[162:165], v[206:209], v[102:105]
	v_mfma_f32_16x16x32_bf16 v[94:97], v[170:173], v[206:209], v[94:97]
	v_mfma_f32_16x16x32_bf16 v[70:73], v[166:169], v[182:185], v[70:73]
	v_mfma_f32_16x16x32_bf16 v[78:81], v[174:177], v[182:185], v[78:81]
	v_mfma_f32_16x16x32_bf16 v[90:93], v[166:169], v[190:193], v[90:93]
	v_mfma_f32_16x16x32_bf16 v[98:101], v[174:177], v[190:193], v[98:101]
	v_mfma_f32_16x16x32_bf16 v[114:117], v[166:169], v[202:205], v[114:117]
	v_mfma_f32_16x16x32_bf16 v[118:121], v[174:177], v[202:205], v[118:121]
	v_mfma_f32_16x16x32_bf16 v[102:105], v[166:169], v[210:213], v[102:105]
	v_mfma_f32_16x16x32_bf16 v[94:97], v[174:177], v[210:213], v[94:97]
	s_setprio 0
	s_barrier
	s_add_i32 s56, s57, s37
	v_lshl_add_u64 v[218:219], s[30:31], 0, v[32:33]
	s_mov_b32 m0, s56
	ds_read_b128 v[178:181], v145 offset:16384
	ds_read_b128 v[182:185], v145 offset:17408
	ds_read_b128 v[186:189], v145 offset:18432
	ds_read_b128 v[190:193], v145 offset:19456
	ds_read_b128 v[198:201], v145 offset:20480
	ds_read_b128 v[202:205], v145 offset:21504
	ds_read_b128 v[206:209], v145 offset:22528
	ds_read_b128 v[210:213], v145 offset:23552
	global_load_lds_dwordx4 v[218:219], off
	s_add_i32 m0, s56, 0x2000
	s_add_u32 s56, s30, 0x80000
	v_lshl_add_u64 v[220:221], s[30:31], 0, v[130:131]
	s_addc_u32 s57, s31, 0
	s_add_i32 s53, s53, s37
	global_load_lds_dwordx4 v[220:221], off
	v_lshl_add_u64 v[222:223], s[56:57], 0, v[32:33]
	s_mov_b32 m0, s53
	v_lshl_add_u64 v[224:225], s[48:49], 0, v[132:133]
	global_load_lds_dwordx4 v[222:223], off
	s_add_i32 m0, s53, 0x2000
	v_lshl_add_u64 v[222:223], s[56:57], 0, v[130:131]
	global_load_lds_dwordx4 v[222:223], off
	s_mov_b32 m0, s38
	v_lshl_add_u64 v[222:223], s[48:49], 0, v[134:135]
	global_load_lds_dwordx4 v[222:223], off
	s_mov_b32 m0, s39
	s_nop 0
	global_load_lds_dwordx4 v[224:225], off
	s_waitcnt vmcnt(8)
	s_waitcnt lgkmcnt(0)
	s_barrier
; #define PG8_STAGE(bufoff, gbase, voff) do { _Pragma("unroll") for (int _i = 0; _i < 2; ++_i) \
;         __builtin_amdgcn_global_load_lds((const unsigned*)((const char*)(gbase) + (voff)[_i]), (PG8_LAS unsigned*)(lds + (bufoff) + ldsw + _i * 8192), 16, 0, 0); } while (0)
; #define PG8_LDA(dst, b, h) do { _Pragma("unroll") for (int m = 0; m < 4; ++m) _Pragma("unroll") for (int k = 0; k < 2; ++k) dst[m][k] = *(const PG8_LAS bf16x8*)(lds + PG8_SA(b, h) + aoff + m * 2048 + k * 1024); } while (0)
; #define PG8_LDB(dst, b, h) do { _Pragma("unroll") for (int n = 0; n < 2; ++n) _Pragma("unroll") for (int k = 0; k < 2; ++k) dst[n][k] = *(const PG8_LAS bf16x8*)(lds + PG8_SB(b, h) + boff + n * 2048 + k * 1024); } while (0)
; #define PG8_MMA(ai, bj, At, Bt) do { __builtin_amdgcn_s_setprio(1); _Pragma("unroll") for (int m = 0; m < 4; ++m) _Pragma("unroll") for (int n = 0; n < 2; ++n) _Pragma("unroll") for (int k = 0; k < 2; ++k) \
;         acc[ai][bj][m][n] = __builtin_amdgcn_mfma_f32_16x16x32_bf16(Bt[n][k], At[m][k], acc[ai][bj][m][n], 0, 0, 0); __builtin_amdgcn_s_setprio(0); } while (0)
; template <class Epi, class Sched, bool ALIGN_EPI = false, bool SP2 = false, bool KHOOK = false>
; __device__ __forceinline__ void gemm_phase(PG8_LAS unsigned char* lds, const Gemm g, const Sched& S, const Epi& E, const int tid_in) {
;     ...
;             PG8_LDB(B0, 0, 0); PG8_LDB(B1, 0, 1); PG8_SCHED; PG8_LDA(At, 0, 0); PG8_STAGE(PG8_SA(1, 1), a1 + hstep, voffA);
;             PG8_WAIT_V(8); PG8_WAIT_L(0); PG8_BAR; PG8_MMA(0, 0, At, B0); PG8_MMA(0, 1, At, B1); PG8_BAR; PG8_SCHED;
;             PG8_LDA(At, 0, 1); PG8_STAGE(PG8_SB(0, 0), b2, voffB); PG8_STAGE(PG8_SB(0, 1), b2 + hstep, voffB); PG8_STAGE(PG8_SA(0, 0), a2, voffA);
;             PG8_WAIT_V(8); PG8_WAIT_L(0); PG8_BAR; PG8_MMA(1, 0, At, B0); PG8_MMA(1, 1, At, B1); PG8_BAR; PG8_SCHED;
;             PG8_LDB(B0, 1, 0); PG8_LDB(B1, 1, 1); PG8_SCHED; PG8_LDA(At, 1, 0); PG8_STAGE(PG8_SA(0, 1), a2 + hstep, voffA);
;             PG8_WAIT_V(8); PG8_WAIT_L(0); PG8_BAR; PG8_MMA(0, 0, At, B0); PG8_MMA(0, 1, At, B1); PG8_BAR; PG8_SCHED;
;             PG8_LDA(At, 1, 1); PG8_STAGE(PG8_SB(1, 0), b3, voffB); PG8_STAGE(PG8_SB(1, 1), b3 + hstep, voffB); PG8_STAGE(PG8_SA(1, 0), a3, voffA);
;             PG8_WAIT_V(8); PG8_WAIT_L(0); PG8_BAR; PG8_MMA(1, 0, At, B0); PG8_MMA(1, 1, At, B1); PG8_BAR; PG8_SCHED;
	s_setprio 1
	s_waitcnt lgkmcnt(0)
	v_mfma_f32_16x16x32_bf16 v[74:77], v[146:149], v[178:181], v[74:77]
	v_mfma_f32_16x16x32_bf16 v[66:69], v[154:157], v[178:181], v[66:69]
	v_mfma_f32_16x16x32_bf16 v[46:49], v[146:149], v[186:189], v[46:49]
	v_mfma_f32_16x16x32_bf16 v[42:45], v[154:157], v[186:189], v[42:45]
	v_mfma_f32_16x16x32_bf16 v[28:31], v[146:149], v[198:201], v[28:31]
	v_mfma_f32_16x16x32_bf16 v[24:27], v[154:157], v[198:201], v[24:27]
	v_mfma_f32_16x16x32_bf16 v[12:15], v[146:149], v[206:209], v[12:15]
	v_mfma_f32_16x16x32_bf16 v[8:11], v[154:157], v[206:209], v[8:11]
	v_mfma_f32_16x16x32_bf16 v[74:77], v[150:153], v[182:185], v[74:77]
	v_mfma_f32_16x16x32_bf16 v[66:69], v[158:161], v[182:185], v[66:69]
	v_mfma_f32_16x16x32_bf16 v[46:49], v[150:153], v[190:193], v[46:49]
	v_mfma_f32_16x16x32_bf16 v[42:45], v[158:161], v[190:193], v[42:45]
	v_mfma_f32_16x16x32_bf16 v[28:31], v[150:153], v[202:205], v[28:31]
	v_mfma_f32_16x16x32_bf16 v[24:27], v[158:161], v[202:205], v[24:27]
	v_mfma_f32_16x16x32_bf16 v[12:15], v[150:153], v[210:213], v[12:15]
	v_mfma_f32_16x16x32_bf16 v[8:11], v[158:161], v[210:213], v[8:11]
	s_setprio 0
	s_setprio 1
	v_mfma_f32_16x16x32_bf16 v[58:61], v[162:165], v[178:181], v[58:61]
	v_mfma_f32_16x16x32_bf16 v[50:53], v[170:173], v[178:181], v[50:53]
	v_mfma_f32_16x16x32_bf16 v[38:41], v[162:165], v[186:189], v[38:41]
	v_mfma_f32_16x16x32_bf16 v[34:37], v[170:173], v[186:189], v[34:37]
	v_mfma_f32_16x16x32_bf16 v[20:23], v[162:165], v[198:201], v[20:23]
	v_mfma_f32_16x16x32_bf16 v[16:19], v[170:173], v[198:201], v[16:19]
	v_mfma_f32_16x16x32_bf16 v[4:7], v[162:165], v[206:209], v[4:7]
	v_mfma_f32_16x16x32_bf16 v[0:3], v[170:173], v[206:209], v[0:3]
	v_mfma_f32_16x16x32_bf16 v[58:61], v[166:169], v[182:185], v[58:61]
	v_mfma_f32_16x16x32_bf16 v[50:53], v[174:177], v[182:185], v[50:53]
	v_mfma_f32_16x16x32_bf16 v[38:41], v[166:169], v[190:193], v[38:41]
	v_mfma_f32_16x16x32_bf16 v[34:37], v[174:177], v[190:193], v[34:37]
	v_mfma_f32_16x16x32_bf16 v[20:23], v[166:169], v[202:205], v[20:23]
	v_mfma_f32_16x16x32_bf16 v[16:19], v[174:177], v[202:205], v[16:19]
	v_mfma_f32_16x16x32_bf16 v[4:7], v[166:169], v[210:213], v[4:7]
	v_mfma_f32_16x16x32_bf16 v[0:3], v[174:177], v[210:213], v[0:3]
	s_setprio 0
	s_barrier
	s_add_i32 s53, 0, 0x18000
	s_add_i32 s56, 0, 0x1c000
	v_add_u32_e32 v158, s53, v144
	v_add_u32_e32 v174, s56, v144
	ds_read_b128 v[146:149], v158
	ds_read_b128 v[150:153], v158 offset:1024
	ds_read_b128 v[154:157], v158 offset:2048
	ds_read_b128 v[158:161], v158 offset:3072
	ds_read_b128 v[162:165], v174
	ds_read_b128 v[166:169], v174 offset:1024
	ds_read_b128 v[170:173], v174 offset:2048
	ds_read_b128 v[174:177], v174 offset:3072
	s_add_u32 s48, s48, 0x80000
	s_addc_u32 s49, s49, 0
	s_mov_b32 m0, s40
	v_lshl_add_u64 v[226:227], s[48:49], 0, v[134:135]
	ds_read_b128 v[178:181], v145 offset:32768
	ds_read_b128 v[182:185], v145 offset:33792
	ds_read_b128 v[186:189], v145 offset:34816
	ds_read_b128 v[190:193], v145 offset:35840
	ds_read_b128 v[198:201], v145 offset:36864
	ds_read_b128 v[202:205], v145 offset:37888
	ds_read_b128 v[206:209], v145 offset:38912
	ds_read_b128 v[210:213], v145 offset:39936
	global_load_lds_dwordx4 v[226:227], off
	s_mov_b32 m0, s42
	v_lshl_add_u64 v[226:227], s[48:49], 0, v[132:133]
	global_load_lds_dwordx4 v[226:227], off
	s_waitcnt vmcnt(8)
	s_waitcnt lgkmcnt(0)
	s_barrier
	s_setprio 1
	s_waitcnt lgkmcnt(0)
	v_mfma_f32_16x16x32_bf16 v[54:57], v[146:149], v[178:181], v[54:57]
	v_mfma_f32_16x16x32_bf16 v[62:65], v[154:157], v[178:181], v[62:65]
	v_mfma_f32_16x16x32_bf16 v[82:85], v[146:149], v[186:189], v[82:85]
	v_mfma_f32_16x16x32_bf16 v[86:89], v[154:157], v[186:189], v[86:89]
	v_mfma_f32_16x16x32_bf16 v[106:109], v[146:149], v[198:201], v[106:109]
	v_mfma_f32_16x16x32_bf16 v[110:113], v[154:157], v[198:201], v[110:113]
	v_mfma_f32_16x16x32_bf16 v[126:129], v[146:149], v[206:209], v[126:129]
	v_mfma_f32_16x16x32_bf16 v[122:125], v[154:157], v[206:209], v[122:125]
	v_mfma_f32_16x16x32_bf16 v[54:57], v[150:153], v[182:185], v[54:57]
	v_mfma_f32_16x16x32_bf16 v[62:65], v[158:161], v[182:185], v[62:65]
	v_mfma_f32_16x16x32_bf16 v[82:85], v[150:153], v[190:193], v[82:85]
	v_mfma_f32_16x16x32_bf16 v[86:89], v[158:161], v[190:193], v[86:89]
	v_mfma_f32_16x16x32_bf16 v[106:109], v[150:153], v[202:205], v[106:109]
	v_mfma_f32_16x16x32_bf16 v[110:113], v[158:161], v[202:205], v[110:113]
	v_mfma_f32_16x16x32_bf16 v[126:129], v[150:153], v[210:213], v[126:129]
	v_mfma_f32_16x16x32_bf16 v[122:125], v[158:161], v[210:213], v[122:125]
	s_setprio 0
	s_setprio 1
	v_mfma_f32_16x16x32_bf16 v[70:73], v[162:165], v[178:181], v[70:73]
	v_mfma_f32_16x16x32_bf16 v[78:81], v[170:173], v[178:181], v[78:81]
	v_mfma_f32_16x16x32_bf16 v[90:93], v[162:165], v[186:189], v[90:93]
	v_mfma_f32_16x16x32_bf16 v[98:101], v[170:173], v[186:189], v[98:101]
	v_mfma_f32_16x16x32_bf16 v[114:117], v[162:165], v[198:201], v[114:117]
	v_mfma_f32_16x16x32_bf16 v[118:121], v[170:173], v[198:201], v[118:121]
	v_mfma_f32_16x16x32_bf16 v[102:105], v[162:165], v[206:209], v[102:105]
	v_mfma_f32_16x16x32_bf16 v[94:97], v[170:173], v[206:209], v[94:97]
	v_mfma_f32_16x16x32_bf16 v[70:73], v[166:169], v[182:185], v[70:73]
	v_mfma_f32_16x16x32_bf16 v[78:81], v[174:177], v[182:185], v[78:81]
	v_mfma_f32_16x16x32_bf16 v[90:93], v[166:169], v[190:193], v[90:93]
	v_mfma_f32_16x16x32_bf16 v[98:101], v[174:177], v[190:193], v[98:101]
	v_mfma_f32_16x16x32_bf16 v[114:117], v[166:169], v[202:205], v[114:117]
	v_mfma_f32_16x16x32_bf16 v[118:121], v[174:177], v[202:205], v[118:121]
	v_mfma_f32_16x16x32_bf16 v[102:105], v[166:169], v[210:213], v[102:105]
	v_mfma_f32_16x16x32_bf16 v[94:97], v[174:177], v[210:213], v[94:97]
	s_setprio 0
	s_barrier
; #define PG8_STAGE(bufoff, gbase, voff) do { _Pragma("unroll") for (int _i = 0; _i < 2; ++_i) \
;         __builtin_amdgcn_global_load_lds((const unsigned*)((const char*)(gbase) + (voff)[_i]), (PG8_LAS unsigned*)(lds + (bufoff) + ldsw + _i * 8192), 16, 0, 0); } while (0)
; #define PG8_LDA(dst, b, h) do { _Pragma("unroll") for (int m = 0; m < 4; ++m) _Pragma("unroll") for (int k = 0; k < 2; ++k) dst[m][k] = *(const PG8_LAS bf16x8*)(lds + PG8_SA(b, h) + aoff + m * 2048 + k * 1024); } while (0)
; #define PG8_LDB(dst, b, h) do { _Pragma("unroll") for (int n = 0; n < 2; ++n) _Pragma("unroll") for (int k = 0; k < 2; ++k) dst[n][k] = *(const PG8_LAS bf16x8*)(lds + PG8_SB(b, h) + boff + n * 2048 + k * 1024); } while (0)
; #define PG8_BAR __builtin_amdgcn_s_barrier()
; template <class Epi, class Sched, bool ALIGN_EPI = false, bool SP2 = false, bool KHOOK = false>
; __device__ __forceinline__ void gemm_phase(PG8_LAS unsigned char* lds, const Gemm g, const Sched& S, const Epi& E, const int tid_in) {
;     ...
;             PG8_LDB(B0, 0, 0); PG8_LDB(B1, 0, 1); PG8_SCHED; PG8_LDA(At, 0, 0); PG8_STAGE(PG8_SA(1, 1), a1 + hstep, voffA);
;             PG8_WAIT_V(8); PG8_WAIT_L(0); PG8_BAR; PG8_MMA(0, 0, At, B0); PG8_MMA(0, 1, At, B1); PG8_BAR; PG8_SCHED;
;             PG8_LDA(At, 0, 1); PG8_STAGE(PG8_SB(0, 0), b2, voffB); PG8_STAGE(PG8_SB(0, 1), b2 + hstep, voffB); PG8_STAGE(PG8_SA(0, 0), a2, voffA);
;             PG8_WAIT_V(8); PG8_WAIT_L(0); PG8_BAR; PG8_MMA(1, 0, At, B0); PG8_MMA(1, 1, At, B1); PG8_BAR; PG8_SCHED;
;             PG8_LDB(B0, 1, 0); PG8_LDB(B1, 1, 1); PG8_SCHED; PG8_LDA(At, 1, 0); PG8_STAGE(PG8_SA(0, 1), a2 + hstep, voffA);
;             PG8_WAIT_V(8); PG8_WAIT_L(0); PG8_BAR; PG8_MMA(0, 0, At, B0); PG8_MMA(0, 1, At, B1); PG8_BAR; PG8_SCHED;
;             PG8_LDA(At, 1, 1); PG8_STAGE(PG8_SB(1, 0), b3, voffB); PG8_STAGE(PG8_SB(1, 1), b3 + hstep, voffB); PG8_STAGE(PG8_SA(1, 0), a3, voffA);
;             PG8_WAIT_V(8); PG8_WAIT_L(0); PG8_BAR; PG8_MMA(1, 0, At, B0); PG8_MMA(1, 1, At, B1); PG8_BAR; PG8_SCHED;
;     ...
; #pragma unroll
;         for (int a = 0; a < 2; ++a)
; #pragma unroll
;             for (int b = 0; b < 2; ++b)
; #pragma unroll
;                 for (int m = 0; m < 4; ++m)
; #pragma unroll
;                     for (int n = 0; n < 2; ++n) acc[a][b][m][n] = (f32x4){0.f, 0.f, 0.f, 0.f};
;         cur = nxt; cA = nA; cB = nB; ++ui; load_rr(cur);
	s_add_i32 s48, s53, s37
	v_lshl_add_u64 v[218:219], v[218:219], 0, s[90:91]
	s_mov_b32 m0, s48
	ds_read_b128 v[178:181], v145 offset:49152
	ds_read_b128 v[182:185], v145 offset:50176
	ds_read_b128 v[186:189], v145 offset:51200
	ds_read_b128 v[190:193], v145 offset:52224
	ds_read_b128 v[198:201], v145 offset:53248
	ds_read_b128 v[202:205], v145 offset:54272
	ds_read_b128 v[206:209], v145 offset:55296
	ds_read_b128 v[210:213], v145 offset:56320
	global_load_lds_dwordx4 v[218:219], off
	s_add_i32 m0, s48, 0x2000
	s_add_u32 s30, s30, 0x80080
	v_lshl_add_u64 v[218:219], v[220:221], 0, s[90:91]
	s_addc_u32 s31, s31, 0
	s_add_i32 s48, s56, s37
	global_load_lds_dwordx4 v[218:219], off
	s_mov_b32 m0, s48
	v_lshl_add_u64 v[218:219], s[30:31], 0, v[32:33]
	global_load_lds_dwordx4 v[218:219], off
	s_add_i32 m0, s48, 0x2000
	v_lshl_add_u64 v[218:219], s[30:31], 0, v[130:131]
	global_load_lds_dwordx4 v[218:219], off
	s_mov_b32 m0, s44
	v_lshl_add_u64 v[218:219], v[222:223], 0, s[90:91]
	global_load_lds_dwordx4 v[218:219], off
	s_mov_b32 m0, s45
	v_lshl_add_u64 v[218:219], v[224:225], 0, s[90:91]
	global_load_lds_dwordx4 v[218:219], off
	s_waitcnt vmcnt(8)
	s_waitcnt lgkmcnt(0)
	s_barrier
	s_setprio 1
	s_waitcnt lgkmcnt(0)
	v_mfma_f32_16x16x32_bf16 v[74:77], v[146:149], v[178:181], v[74:77]
	v_mfma_f32_16x16x32_bf16 v[66:69], v[154:157], v[178:181], v[66:69]
	v_mfma_f32_16x16x32_bf16 v[46:49], v[146:149], v[186:189], v[46:49]
	v_mfma_f32_16x16x32_bf16 v[42:45], v[154:157], v[186:189], v[42:45]
	v_mfma_f32_16x16x32_bf16 v[28:31], v[146:149], v[198:201], v[28:31]
	v_mfma_f32_16x16x32_bf16 v[24:27], v[154:157], v[198:201], v[24:27]
	v_mfma_f32_16x16x32_bf16 v[12:15], v[146:149], v[206:209], v[12:15]
	v_mfma_f32_16x16x32_bf16 v[8:11], v[154:157], v[206:209], v[8:11]
	v_mfma_f32_16x16x32_bf16 v[74:77], v[150:153], v[182:185], v[74:77]
	v_mfma_f32_16x16x32_bf16 v[66:69], v[158:161], v[182:185], v[66:69]
	v_mfma_f32_16x16x32_bf16 v[46:49], v[150:153], v[190:193], v[46:49]
	v_mfma_f32_16x16x32_bf16 v[42:45], v[158:161], v[190:193], v[42:45]
	v_mfma_f32_16x16x32_bf16 v[28:31], v[150:153], v[202:205], v[28:31]
	v_mfma_f32_16x16x32_bf16 v[24:27], v[158:161], v[202:205], v[24:27]
	v_mfma_f32_16x16x32_bf16 v[12:15], v[150:153], v[210:213], v[12:15]
	v_mfma_f32_16x16x32_bf16 v[8:11], v[158:161], v[210:213], v[8:11]
	s_setprio 0
	s_setprio 1
	v_mfma_f32_16x16x32_bf16 v[58:61], v[162:165], v[178:181], v[58:61]
	v_mfma_f32_16x16x32_bf16 v[50:53], v[170:173], v[178:181], v[50:53]
	v_mfma_f32_16x16x32_bf16 v[38:41], v[162:165], v[186:189], v[38:41]
	v_mfma_f32_16x16x32_bf16 v[34:37], v[170:173], v[186:189], v[34:37]
	v_mfma_f32_16x16x32_bf16 v[20:23], v[162:165], v[198:201], v[20:23]
	v_mfma_f32_16x16x32_bf16 v[16:19], v[170:173], v[198:201], v[16:19]
	v_mfma_f32_16x16x32_bf16 v[4:7], v[162:165], v[206:209], v[4:7]
	v_mfma_f32_16x16x32_bf16 v[0:3], v[170:173], v[206:209], v[0:3]
	v_mfma_f32_16x16x32_bf16 v[58:61], v[166:169], v[182:185], v[58:61]
	v_mfma_f32_16x16x32_bf16 v[50:53], v[174:177], v[182:185], v[50:53]
	v_mfma_f32_16x16x32_bf16 v[38:41], v[166:169], v[190:193], v[38:41]
	v_mfma_f32_16x16x32_bf16 v[34:37], v[174:177], v[190:193], v[34:37]
	v_mfma_f32_16x16x32_bf16 v[20:23], v[166:169], v[202:205], v[20:23]
	v_mfma_f32_16x16x32_bf16 v[16:19], v[174:177], v[202:205], v[16:19]
	v_mfma_f32_16x16x32_bf16 v[4:7], v[166:169], v[210:213], v[4:7]
	v_mfma_f32_16x16x32_bf16 v[0:3], v[174:177], v[210:213], v[0:3]
	s_setprio 0
	s_barrier
	s_add_i32 s52, s52, 2
	s_add_u32 s16, s16, 0x100
	s_addc_u32 s17, s17, 0
	s_cmp_gt_u32 s52, 29
	s_cbranch_scc0 .LBB0_1287
	s_add_u32 s16, s25, 0xffffff00
	s_addc_u32 s17, s47, -1
	s_andn2_b64 vcc, exec, s[22:23]
	s_cbranch_vccnz .LBB0_1290
	v_mov_b32_e32 v0, 0
	s_mov_b32 s20, s10
	s_mov_b32 s0, s8
	s_mov_b64 s[4:5], s[26:27]
	s_mov_b32 s46, s24
	v_mov_b32_e32 v1, v0
	v_mov_b32_e32 v2, v0
	v_mov_b32_e32 v3, v0
	v_mov_b32_e32 v4, v0
	v_mov_b32_e32 v5, v0
	v_mov_b32_e32 v6, v0
	v_mov_b32_e32 v7, v0
	v_mov_b32_e32 v16, v0
	v_mov_b32_e32 v17, v0
	v_mov_b32_e32 v18, v0
	v_mov_b32_e32 v19, v0
	v_mov_b32_e32 v20, v0
	v_mov_b32_e32 v21, v0
	v_mov_b32_e32 v22, v0
	v_mov_b32_e32 v23, v0
	v_mov_b32_e32 v34, v0
	v_mov_b32_e32 v35, v0
	v_mov_b32_e32 v36, v0
	v_mov_b32_e32 v37, v0
	v_mov_b32_e32 v38, v0
	v_mov_b32_e32 v39, v0
	v_mov_b32_e32 v40, v0
	v_mov_b32_e32 v41, v0
	v_mov_b32_e32 v50, v0
	v_mov_b32_e32 v51, v0
	v_mov_b32_e32 v52, v0
	v_mov_b32_e32 v53, v0
	v_mov_b32_e32 v58, v0
	v_mov_b32_e32 v59, v0
	v_mov_b32_e32 v60, v0
	v_mov_b32_e32 v61, v0
	v_mov_b32_e32 v8, v0
	v_mov_b32_e32 v9, v0
	v_mov_b32_e32 v10, v0
	v_mov_b32_e32 v11, v0
	v_mov_b32_e32 v12, v0
	v_mov_b32_e32 v13, v0
	v_mov_b32_e32 v14, v0
	v_mov_b32_e32 v15, v0
	v_mov_b32_e32 v24, v0
	v_mov_b32_e32 v25, v0
	v_mov_b32_e32 v26, v0
	v_mov_b32_e32 v27, v0
	v_mov_b32_e32 v28, v0
	v_mov_b32_e32 v29, v0
	v_mov_b32_e32 v30, v0
	v_mov_b32_e32 v31, v0
	v_mov_b32_e32 v42, v0
	v_mov_b32_e32 v43, v0
	v_mov_b32_e32 v44, v0
	v_mov_b32_e32 v45, v0
	v_mov_b32_e32 v46, v0
	v_mov_b32_e32 v47, v0
	v_mov_b32_e32 v48, v0
	v_mov_b32_e32 v49, v0
	v_mov_b32_e32 v66, v0
	v_mov_b32_e32 v67, v0
	v_mov_b32_e32 v68, v0
	v_mov_b32_e32 v69, v0
	v_mov_b32_e32 v74, v0
	v_mov_b32_e32 v75, v0
	v_mov_b32_e32 v76, v0
	v_mov_b32_e32 v77, v0
	v_mov_b32_e32 v94, v0
	v_mov_b32_e32 v95, v0
	v_mov_b32_e32 v96, v0
	v_mov_b32_e32 v97, v0
	v_mov_b32_e32 v102, v0
	v_mov_b32_e32 v103, v0
	v_mov_b32_e32 v104, v0
	v_mov_b32_e32 v105, v0
	v_mov_b32_e32 v118, v0
	v_mov_b32_e32 v119, v0
	v_mov_b32_e32 v120, v0
	v_mov_b32_e32 v121, v0
	v_mov_b32_e32 v114, v0
	v_mov_b32_e32 v115, v0
	v_mov_b32_e32 v116, v0
	v_mov_b32_e32 v117, v0
	v_mov_b32_e32 v98, v0
	v_mov_b32_e32 v99, v0
	v_mov_b32_e32 v100, v0
	v_mov_b32_e32 v101, v0
	v_mov_b32_e32 v90, v0
	v_mov_b32_e32 v91, v0
	v_mov_b32_e32 v92, v0
	v_mov_b32_e32 v93, v0
	v_mov_b32_e32 v78, v0
	v_mov_b32_e32 v79, v0
	v_mov_b32_e32 v80, v0
	v_mov_b32_e32 v81, v0
	v_mov_b32_e32 v70, v0
	v_mov_b32_e32 v71, v0
	v_mov_b32_e32 v72, v0
	v_mov_b32_e32 v73, v0
	v_mov_b32_e32 v122, v0
	v_mov_b32_e32 v123, v0
	v_mov_b32_e32 v124, v0
	v_mov_b32_e32 v125, v0
	v_mov_b32_e32 v126, v0
	v_mov_b32_e32 v127, v0
	v_mov_b32_e32 v128, v0
	v_mov_b32_e32 v129, v0
	v_mov_b32_e32 v110, v0
	v_mov_b32_e32 v111, v0
	v_mov_b32_e32 v112, v0
	v_mov_b32_e32 v113, v0
	v_mov_b32_e32 v106, v0
	v_mov_b32_e32 v107, v0
	v_mov_b32_e32 v108, v0
	v_mov_b32_e32 v109, v0
	v_mov_b32_e32 v86, v0
	v_mov_b32_e32 v87, v0
	v_mov_b32_e32 v88, v0
	v_mov_b32_e32 v89, v0
	v_mov_b32_e32 v82, v0
	v_mov_b32_e32 v83, v0
	v_mov_b32_e32 v84, v0
	v_mov_b32_e32 v85, v0
	v_mov_b32_e32 v62, v0
	v_mov_b32_e32 v63, v0
	v_mov_b32_e32 v64, v0
	v_mov_b32_e32 v65, v0
	v_mov_b32_e32 v54, v0
	v_mov_b32_e32 v55, v0
	v_mov_b32_e32 v56, v0
	v_mov_b32_e32 v57, v0
	s_andn2_b64 vcc, exec, s[12:13]
	s_cbranch_vccnz .LBB0_1291
	s_branch .LBB0_1292
